# GEMM mainloops: redundant second lgkmcnt(0) wait before each MFMA cluster removed (88 sites)
# speedup vs baseline: 1.0048x; 1.0048x over previous
; #define PG8_STAGE(bufoff, gbase, voff) do { _Pragma("unroll") for (int _i = 0; _i < 2; ++_i) \
;         __builtin_amdgcn_global_load_lds((const unsigned*)((const char*)(gbase) + (voff)[_i]), (LAS unsigned*)(lds + (bufoff) + ldsw + _i * 8192), 16, 0, 0); } while (0)
; #define PG8_LDA(dst, b, h) do { _Pragma("unroll") for (int m = 0; m < 4; ++m) _Pragma("unroll") for (int k = 0; k < 2; ++k) dst[m][k] = *(const LAS bf16x8*)(lds + PG8_SA(b, h) + aoff + m * 2048 + k * 1024); } while (0)
; #define PG8_LDB(dst, b, h) do { _Pragma("unroll") for (int n = 0; n < 2; ++n) _Pragma("unroll") for (int k = 0; k < 2; ++k) dst[n][k] = *(const LAS bf16x8*)(lds + PG8_SB(b, h) + boff + n * 2048 + k * 1024); } while (0)
; #define PG8_MMA(ai, bj, At, Bt) do { __builtin_amdgcn_s_setprio(1); _Pragma("unroll") for (int m = 0; m < 4; ++m) _Pragma("unroll") for (int n = 0; n < 2; ++n) _Pragma("unroll") for (int k = 0; k < 2; ++k) \
;         acc[ai][bj][m][n] = __builtin_amdgcn_mfma_f32_16x16x32_bf16(Bt[n][k], At[m][k], acc[ai][bj][m][n], 0, 0, 0); __builtin_amdgcn_s_setprio(0); } while (0)
; #define PG8_WAIT_V(n) asm volatile("s_waitcnt vmcnt(" #n ")" ::: "memory")
; #define PG8_WAIT_L(n) asm volatile("s_waitcnt lgkmcnt(" #n ")" ::: "memory")
; #define PG8_BAR __builtin_amdgcn_s_barrier()
; #define PG8_SCHED __builtin_amdgcn_sched_barrier(0)
; template <class Epi>
; DEVI void gemm_phase(LAS unsigned char* lds, const Gemm g, const Epi& E) {
;     ...
;             PG8_LDB(B0, 0, 0); PG8_SCHED; PG8_LDA(At, 0, 0); PG8_STAGE(PG8_SA(1, 1), a1 + hstepA, voffA);
;             PG8_WAIT_L(8); PG8_BAR; PG8_WAIT_L(0); PG8_MMA(0, 0, At, B0); PG8_BAR; PG8_SCHED;
;             PG8_LDB(B1, 0, 1); PG8_STAGE(PG8_SB(0, 0), b2, voffB);
;             PG8_BAR; PG8_WAIT_L(0); PG8_MMA(0, 1, At, B1); PG8_BAR;
;             PG8_LDA(At, 0, 1); PG8_STAGE(PG8_SA(0, 0), a2, voffA);
;             PG8_BAR; PG8_WAIT_L(0); PG8_MMA(1, 0, At, B0); PG8_BAR; PG8_SCHED;
;             PG8_STAGE(PG8_SB(0, 1), b2 + hstepB, voffB);
;             PG8_WAIT_V(6); PG8_BAR; PG8_MMA(1, 1, At, B1); PG8_BAR;
.LBB0_187:
	ds_read_b128 v[156:159], v150
	ds_read_b128 v[160:163], v150 offset:1024
	ds_read_b128 v[164:167], v150 offset:2048
	ds_read_b128 v[168:171], v150 offset:3072
	s_add_u32 s26, s0, 0xfffc0080
	s_addc_u32 s27, s1, -1
	s_cmp_eq_u32 s50, 12
	s_cselect_b32 s29, s13, s27
	s_cselect_b32 s28, s15, s26
	s_cselect_b32 s27, s19, s49
	s_cselect_b32 s26, s18, s17
	v_lshl_add_u64 v[204:205], s[0:1], 0, v[138:139]
	s_add_i32 m0, s38, 0xc000
	ds_read_b128 v[172:175], v151
	ds_read_b128 v[176:179], v151 offset:1024
	ds_read_b128 v[180:183], v151 offset:2048
	ds_read_b128 v[184:187], v151 offset:3072
	ds_read_b128 v[188:191], v151 offset:4096
	ds_read_b128 v[192:195], v151 offset:5120
	ds_read_b128 v[196:199], v151 offset:6144
	ds_read_b128 v[200:203], v151 offset:7168
	global_load_lds_dwordx4 v[204:205], off
	v_lshl_add_u64 v[204:205], s[0:1], 0, v[140:141]
	s_add_i32 m0, s38, 0xe000
	s_nop 0
	global_load_lds_dwordx4 v[204:205], off
	s_waitcnt lgkmcnt(8)
	s_barrier
	s_waitcnt lgkmcnt(0)
	s_setprio 1
	v_mfma_f32_16x16x32_bf16 v[124:127], v[156:159], v[172:175], v[124:127]
	v_mfma_f32_16x16x32_bf16 v[120:123], v[164:167], v[172:175], v[120:123]
	v_mfma_f32_16x16x32_bf16 v[116:119], v[156:159], v[180:183], v[116:119]
	v_mfma_f32_16x16x32_bf16 v[108:111], v[164:167], v[180:183], v[108:111]
	v_mfma_f32_16x16x32_bf16 v[100:103], v[156:159], v[188:191], v[100:103]
	v_mfma_f32_16x16x32_bf16 v[96:99], v[164:167], v[188:191], v[96:99]
	v_mfma_f32_16x16x32_bf16 v[84:87], v[156:159], v[196:199], v[84:87]
	v_mfma_f32_16x16x32_bf16 v[80:83], v[164:167], v[196:199], v[80:83]
	v_mfma_f32_16x16x32_bf16 v[124:127], v[160:163], v[176:179], v[124:127]
	v_mfma_f32_16x16x32_bf16 v[120:123], v[168:171], v[176:179], v[120:123]
	v_mfma_f32_16x16x32_bf16 v[116:119], v[160:163], v[184:187], v[116:119]
	v_mfma_f32_16x16x32_bf16 v[108:111], v[168:171], v[184:187], v[108:111]
	v_mfma_f32_16x16x32_bf16 v[100:103], v[160:163], v[192:195], v[100:103]
	v_mfma_f32_16x16x32_bf16 v[96:99], v[168:171], v[192:195], v[96:99]
	v_mfma_f32_16x16x32_bf16 v[84:87], v[160:163], v[200:203], v[84:87]
	v_mfma_f32_16x16x32_bf16 v[80:83], v[168:171], v[200:203], v[80:83]
	s_setprio 0
	s_barrier
	s_add_i32 s51, s46, s35
	v_lshl_add_u64 v[220:221], s[26:27], 0, v[130:131]
	s_mov_b32 m0, s51
	ds_read_b128 v[204:207], v152
	ds_read_b128 v[208:211], v152 offset:1024
	ds_read_b128 v[212:215], v152 offset:2048
	ds_read_b128 v[216:219], v152 offset:3072
	global_load_lds_dwordx4 v[220:221], off
	v_lshl_add_u64 v[222:223], s[26:27], 0, v[134:135]
	s_add_i32 m0, s51, 0x2000
	s_nop 0
	global_load_lds_dwordx4 v[222:223], off
	s_barrier
	s_waitcnt lgkmcnt(0)
	s_setprio 1
	v_mfma_f32_16x16x32_bf16 v[112:115], v[204:207], v[172:175], v[112:115]
	v_mfma_f32_16x16x32_bf16 v[104:107], v[212:215], v[172:175], v[104:107]
	v_mfma_f32_16x16x32_bf16 v[92:95], v[204:207], v[180:183], v[92:95]
	v_mfma_f32_16x16x32_bf16 v[88:91], v[212:215], v[180:183], v[88:91]
	v_mfma_f32_16x16x32_bf16 v[76:79], v[204:207], v[188:191], v[76:79]
	v_mfma_f32_16x16x32_bf16 v[72:75], v[212:215], v[188:191], v[72:75]
	v_mfma_f32_16x16x32_bf16 v[68:71], v[204:207], v[196:199], v[68:71]
	v_mfma_f32_16x16x32_bf16 v[64:67], v[212:215], v[196:199], v[64:67]
	v_mfma_f32_16x16x32_bf16 v[112:115], v[208:211], v[176:179], v[112:115]
	v_mfma_f32_16x16x32_bf16 v[104:107], v[216:219], v[176:179], v[104:107]
	v_mfma_f32_16x16x32_bf16 v[92:95], v[208:211], v[184:187], v[92:95]
	v_mfma_f32_16x16x32_bf16 v[88:91], v[216:219], v[184:187], v[88:91]
	v_mfma_f32_16x16x32_bf16 v[76:79], v[208:211], v[192:195], v[76:79]
	v_mfma_f32_16x16x32_bf16 v[72:75], v[216:219], v[192:195], v[72:75]
	v_mfma_f32_16x16x32_bf16 v[68:71], v[208:211], v[200:203], v[68:71]
	v_mfma_f32_16x16x32_bf16 v[64:67], v[216:219], v[200:203], v[64:67]
	s_setprio 0
	s_mov_b32 m0, s38
	v_lshl_add_u64 v[224:225], s[28:29], 0, v[128:129]
	s_barrier
	ds_read_b128 v[172:175], v151 offset:16384
	ds_read_b128 v[176:179], v151 offset:17408
	ds_read_b128 v[180:183], v151 offset:18432
	ds_read_b128 v[184:187], v151 offset:19456
	ds_read_b128 v[188:191], v151 offset:20480
	ds_read_b128 v[192:195], v151 offset:21504
	ds_read_b128 v[196:199], v151 offset:22528
	ds_read_b128 v[200:203], v151 offset:23552
	global_load_lds_dwordx4 v[224:225], off
	v_lshl_add_u64 v[226:227], s[28:29], 0, v[132:133]
	s_mov_b32 m0, s39
	s_nop 0
	global_load_lds_dwordx4 v[226:227], off
	s_barrier
	s_waitcnt lgkmcnt(0)
	s_setprio 1
	v_mfma_f32_16x16x32_bf16 v[60:63], v[156:159], v[172:175], v[60:63]
	v_mfma_f32_16x16x32_bf16 v[56:59], v[164:167], v[172:175], v[56:59]
	v_mfma_f32_16x16x32_bf16 v[52:55], v[156:159], v[180:183], v[52:55]
	v_mfma_f32_16x16x32_bf16 v[48:51], v[164:167], v[180:183], v[48:51]
	v_mfma_f32_16x16x32_bf16 v[36:39], v[156:159], v[188:191], v[36:39]
	v_mfma_f32_16x16x32_bf16 v[32:35], v[164:167], v[188:191], v[32:35]
	v_mfma_f32_16x16x32_bf16 v[20:23], v[156:159], v[196:199], v[20:23]
	v_mfma_f32_16x16x32_bf16 v[16:19], v[164:167], v[196:199], v[16:19]
	v_mfma_f32_16x16x32_bf16 v[60:63], v[160:163], v[176:179], v[60:63]
	v_mfma_f32_16x16x32_bf16 v[56:59], v[168:171], v[176:179], v[56:59]
	v_mfma_f32_16x16x32_bf16 v[52:55], v[160:163], v[184:187], v[52:55]
	v_mfma_f32_16x16x32_bf16 v[48:51], v[168:171], v[184:187], v[48:51]
	v_mfma_f32_16x16x32_bf16 v[36:39], v[160:163], v[192:195], v[36:39]
	v_mfma_f32_16x16x32_bf16 v[32:35], v[168:171], v[192:195], v[32:35]
	v_mfma_f32_16x16x32_bf16 v[20:23], v[160:163], v[200:203], v[20:23]
	v_mfma_f32_16x16x32_bf16 v[16:19], v[168:171], v[200:203], v[16:19]
	s_setprio 0
	s_barrier
; #define PG8_STAGE(bufoff, gbase, voff) do { _Pragma("unroll") for (int _i = 0; _i < 2; ++_i) \
;         __builtin_amdgcn_global_load_lds((const unsigned*)((const char*)(gbase) + (voff)[_i]), (LAS unsigned*)(lds + (bufoff) + ldsw + _i * 8192), 16, 0, 0); } while (0)
; #define PG8_LDA(dst, b, h) do { _Pragma("unroll") for (int m = 0; m < 4; ++m) _Pragma("unroll") for (int k = 0; k < 2; ++k) dst[m][k] = *(const LAS bf16x8*)(lds + PG8_SA(b, h) + aoff + m * 2048 + k * 1024); } while (0)
; #define PG8_LDB(dst, b, h) do { _Pragma("unroll") for (int n = 0; n < 2; ++n) _Pragma("unroll") for (int k = 0; k < 2; ++k) dst[n][k] = *(const LAS bf16x8*)(lds + PG8_SB(b, h) + boff + n * 2048 + k * 1024); } while (0)
; #define PG8_MMA(ai, bj, At, Bt) do { __builtin_amdgcn_s_setprio(1); _Pragma("unroll") for (int m = 0; m < 4; ++m) _Pragma("unroll") for (int n = 0; n < 2; ++n) _Pragma("unroll") for (int k = 0; k < 2; ++k) \
;         acc[ai][bj][m][n] = __builtin_amdgcn_mfma_f32_16x16x32_bf16(Bt[n][k], At[m][k], acc[ai][bj][m][n], 0, 0, 0); __builtin_amdgcn_s_setprio(0); } while (0)
; #define PG8_WAIT_V(n) asm volatile("s_waitcnt vmcnt(" #n ")" ::: "memory")
; #define PG8_WAIT_L(n) asm volatile("s_waitcnt lgkmcnt(" #n ")" ::: "memory")
; #define PG8_BAR __builtin_amdgcn_s_barrier()
; #define PG8_SCHED __builtin_amdgcn_sched_barrier(0)
; template <class Epi>
; DEVI void gemm_phase(LAS unsigned char* lds, const Gemm g, const Epi& E) {
;     ...
;             PG8_WAIT_V(6); PG8_BAR; PG8_MMA(1, 1, At, B1); PG8_BAR;
;             PG8_LDB(B0, 1, 0); PG8_SCHED; PG8_LDA(At, 1, 0); PG8_STAGE(PG8_SA(0, 1), a2 + hstepA, voffA);
;             PG8_WAIT_L(8); PG8_BAR; PG8_WAIT_L(0); PG8_MMA(0, 0, At, B0); PG8_BAR; PG8_SCHED;
;             PG8_LDB(B1, 1, 1); PG8_STAGE(PG8_SB(1, 0), b3, voffB);
;             PG8_BAR; PG8_WAIT_L(0); PG8_MMA(0, 1, At, B1); PG8_BAR;
;             PG8_LDA(At, 1, 1); PG8_STAGE(PG8_SA(1, 0), a3, voffA);
;             PG8_BAR; PG8_WAIT_L(0); PG8_MMA(1, 0, At, B0); PG8_BAR; PG8_SCHED;
	s_add_u32 s52, s26, 0x40000
	s_addc_u32 s53, s27, 0
	s_add_i32 s51, s47, s35
	v_lshl_add_u64 v[156:157], s[52:53], 0, v[130:131]
	s_mov_b32 m0, s51
	s_nop 0
	global_load_lds_dwordx4 v[156:157], off
	v_lshl_add_u64 v[156:157], s[52:53], 0, v[134:135]
	s_add_i32 m0, s51, 0x2000
	s_nop 0
	global_load_lds_dwordx4 v[156:157], off
	s_waitcnt vmcnt(6)
	s_barrier
	s_setprio 1
	v_mfma_f32_16x16x32_bf16 v[44:47], v[204:207], v[172:175], v[44:47]
	v_mfma_f32_16x16x32_bf16 v[40:43], v[212:215], v[172:175], v[40:43]
	v_mfma_f32_16x16x32_bf16 v[28:31], v[204:207], v[180:183], v[28:31]
	v_mfma_f32_16x16x32_bf16 v[24:27], v[212:215], v[180:183], v[24:27]
	v_mfma_f32_16x16x32_bf16 v[12:15], v[204:207], v[188:191], v[12:15]
	v_mfma_f32_16x16x32_bf16 v[8:11], v[212:215], v[188:191], v[8:11]
	v_mfma_f32_16x16x32_bf16 v[4:7], v[204:207], v[196:199], v[4:7]
	v_mfma_f32_16x16x32_bf16 v[0:3], v[212:215], v[196:199], v[0:3]
	v_mfma_f32_16x16x32_bf16 v[44:47], v[208:211], v[176:179], v[44:47]
	v_mfma_f32_16x16x32_bf16 v[40:43], v[216:219], v[176:179], v[40:43]
	v_mfma_f32_16x16x32_bf16 v[28:31], v[208:211], v[184:187], v[28:31]
	v_mfma_f32_16x16x32_bf16 v[24:27], v[216:219], v[184:187], v[24:27]
	v_mfma_f32_16x16x32_bf16 v[12:15], v[208:211], v[192:195], v[12:15]
	v_mfma_f32_16x16x32_bf16 v[8:11], v[216:219], v[192:195], v[8:11]
	v_mfma_f32_16x16x32_bf16 v[4:7], v[208:211], v[200:203], v[4:7]
	v_mfma_f32_16x16x32_bf16 v[0:3], v[216:219], v[200:203], v[0:3]
	s_setprio 0
	s_add_i32 s51, 0, 0x18000
	v_add_u32_e32 v136, s51, v148
	s_barrier
	ds_read_b128 v[156:159], v136
	ds_read_b128 v[160:163], v136 offset:1024
	ds_read_b128 v[164:167], v136 offset:2048
	ds_read_b128 v[168:171], v136 offset:3072
	s_add_u32 s28, s28, 0x40000
	s_addc_u32 s29, s29, 0
	s_mov_b32 m0, s40
	v_lshl_add_u64 v[204:205], s[28:29], 0, v[128:129]
	ds_read_b128 v[172:175], v151 offset:32768
	ds_read_b128 v[176:179], v151 offset:33792
	ds_read_b128 v[180:183], v151 offset:34816
	ds_read_b128 v[184:187], v151 offset:35840
	ds_read_b128 v[188:191], v151 offset:36864
	ds_read_b128 v[192:195], v151 offset:37888
	ds_read_b128 v[196:199], v151 offset:38912
	ds_read_b128 v[200:203], v151 offset:39936
	global_load_lds_dwordx4 v[204:205], off
	v_lshl_add_u64 v[204:205], s[28:29], 0, v[132:133]
	s_mov_b32 m0, s41
	s_nop 0
	global_load_lds_dwordx4 v[204:205], off
	s_waitcnt lgkmcnt(8)
	s_barrier
	s_waitcnt lgkmcnt(0)
	s_setprio 1
	v_mfma_f32_16x16x32_bf16 v[124:127], v[156:159], v[172:175], v[124:127]
	v_mfma_f32_16x16x32_bf16 v[120:123], v[164:167], v[172:175], v[120:123]
	v_mfma_f32_16x16x32_bf16 v[116:119], v[156:159], v[180:183], v[116:119]
	v_mfma_f32_16x16x32_bf16 v[108:111], v[164:167], v[180:183], v[108:111]
	v_mfma_f32_16x16x32_bf16 v[100:103], v[156:159], v[188:191], v[100:103]
	v_mfma_f32_16x16x32_bf16 v[96:99], v[164:167], v[188:191], v[96:99]
	v_mfma_f32_16x16x32_bf16 v[84:87], v[156:159], v[196:199], v[84:87]
	v_mfma_f32_16x16x32_bf16 v[80:83], v[164:167], v[196:199], v[80:83]
	v_mfma_f32_16x16x32_bf16 v[124:127], v[160:163], v[176:179], v[124:127]
	v_mfma_f32_16x16x32_bf16 v[120:123], v[168:171], v[176:179], v[120:123]
	v_mfma_f32_16x16x32_bf16 v[116:119], v[160:163], v[184:187], v[116:119]
	v_mfma_f32_16x16x32_bf16 v[108:111], v[168:171], v[184:187], v[108:111]
	v_mfma_f32_16x16x32_bf16 v[100:103], v[160:163], v[192:195], v[100:103]
	v_mfma_f32_16x16x32_bf16 v[96:99], v[168:171], v[192:195], v[96:99]
	v_mfma_f32_16x16x32_bf16 v[84:87], v[160:163], v[200:203], v[84:87]
	v_mfma_f32_16x16x32_bf16 v[80:83], v[168:171], v[200:203], v[80:83]
	s_setprio 0
	s_barrier
	s_add_i32 s28, 0, 0x1c000
	s_add_i32 s29, s51, s35
	v_add_u32_e32 v136, s28, v148
	v_lshl_add_u64 v[220:221], v[220:221], 0, s[8:9]
	s_mov_b32 m0, s29
	ds_read_b128 v[204:207], v136
	ds_read_b128 v[208:211], v136 offset:1024
	ds_read_b128 v[212:215], v136 offset:2048
	ds_read_b128 v[216:219], v136 offset:3072
	global_load_lds_dwordx4 v[220:221], off
	v_lshl_add_u64 v[220:221], v[222:223], 0, s[8:9]
	s_add_i32 m0, s29, 0x2000
	s_nop 0
	global_load_lds_dwordx4 v[220:221], off
	s_barrier
	s_waitcnt lgkmcnt(0)
	s_setprio 1
	v_mfma_f32_16x16x32_bf16 v[112:115], v[204:207], v[172:175], v[112:115]
	v_mfma_f32_16x16x32_bf16 v[104:107], v[212:215], v[172:175], v[104:107]
	v_mfma_f32_16x16x32_bf16 v[92:95], v[204:207], v[180:183], v[92:95]
	v_mfma_f32_16x16x32_bf16 v[88:91], v[212:215], v[180:183], v[88:91]
	v_mfma_f32_16x16x32_bf16 v[76:79], v[204:207], v[188:191], v[76:79]
	v_mfma_f32_16x16x32_bf16 v[72:75], v[212:215], v[188:191], v[72:75]
	v_mfma_f32_16x16x32_bf16 v[68:71], v[204:207], v[196:199], v[68:71]
	v_mfma_f32_16x16x32_bf16 v[64:67], v[212:215], v[196:199], v[64:67]
	v_mfma_f32_16x16x32_bf16 v[112:115], v[208:211], v[176:179], v[112:115]
	v_mfma_f32_16x16x32_bf16 v[104:107], v[216:219], v[176:179], v[104:107]
	v_mfma_f32_16x16x32_bf16 v[92:95], v[208:211], v[184:187], v[92:95]
	v_mfma_f32_16x16x32_bf16 v[88:91], v[216:219], v[184:187], v[88:91]
	v_mfma_f32_16x16x32_bf16 v[76:79], v[208:211], v[192:195], v[76:79]
	v_mfma_f32_16x16x32_bf16 v[72:75], v[216:219], v[192:195], v[72:75]
	v_mfma_f32_16x16x32_bf16 v[68:71], v[208:211], v[200:203], v[68:71]
	v_mfma_f32_16x16x32_bf16 v[64:67], v[216:219], v[200:203], v[64:67]
	s_setprio 0
	s_mov_b32 m0, s44
	v_lshl_add_u64 v[220:221], v[224:225], 0, s[8:9]
	s_barrier
	ds_read_b128 v[172:175], v151 offset:49152
	ds_read_b128 v[176:179], v151 offset:50176
	ds_read_b128 v[180:183], v151 offset:51200
	ds_read_b128 v[184:187], v151 offset:52224
	ds_read_b128 v[188:191], v151 offset:53248
	ds_read_b128 v[192:195], v151 offset:54272
	ds_read_b128 v[196:199], v151 offset:55296
	ds_read_b128 v[200:203], v151 offset:56320
	global_load_lds_dwordx4 v[220:221], off
	v_lshl_add_u64 v[220:221], v[226:227], 0, s[8:9]
	s_mov_b32 m0, s45
	s_nop 0
	global_load_lds_dwordx4 v[220:221], off
	s_barrier
; #define PG8_STAGE(bufoff, gbase, voff) do { _Pragma("unroll") for (int _i = 0; _i < 2; ++_i) \
;         __builtin_amdgcn_global_load_lds((const unsigned*)((const char*)(gbase) + (voff)[_i]), (LAS unsigned*)(lds + (bufoff) + ldsw + _i * 8192), 16, 0, 0); } while (0)
; #define PG8_LDA(dst, b, h) do { _Pragma("unroll") for (int m = 0; m < 4; ++m) _Pragma("unroll") for (int k = 0; k < 2; ++k) dst[m][k] = *(const LAS bf16x8*)(lds + PG8_SA(b, h) + aoff + m * 2048 + k * 1024); } while (0)
; #define PG8_MMA(ai, bj, At, Bt) do { __builtin_amdgcn_s_setprio(1); _Pragma("unroll") for (int m = 0; m < 4; ++m) _Pragma("unroll") for (int n = 0; n < 2; ++n) _Pragma("unroll") for (int k = 0; k < 2; ++k) \
;         acc[ai][bj][m][n] = __builtin_amdgcn_mfma_f32_16x16x32_bf16(Bt[n][k], At[m][k], acc[ai][bj][m][n], 0, 0, 0); __builtin_amdgcn_s_setprio(0); } while (0)
; #define PG8_WAIT_V(n) asm volatile("s_waitcnt vmcnt(" #n ")" ::: "memory")
; #define PG8_WAIT_L(n) asm volatile("s_waitcnt lgkmcnt(" #n ")" ::: "memory")
; #define PG8_BAR __builtin_amdgcn_s_barrier()
; #define PG8_SCHED __builtin_amdgcn_sched_barrier(0)
; template <class Epi>
; DEVI void gemm_phase(LAS unsigned char* lds, const Gemm g, const Epi& E) {
;     ...
;             PG8_BAR; PG8_WAIT_L(0); PG8_MMA(0, 1, At, B1); PG8_BAR;
;             PG8_LDA(At, 1, 1); PG8_STAGE(PG8_SA(1, 0), a3, voffA);
;             PG8_BAR; PG8_WAIT_L(0); PG8_MMA(1, 0, At, B0); PG8_BAR; PG8_SCHED;
;             PG8_STAGE(PG8_SB(1, 1), b3 + hstepB, voffB);
;             PG8_WAIT_V(6); PG8_BAR; PG8_MMA(1, 1, At, B1); PG8_BAR;
	s_waitcnt lgkmcnt(0)
	s_setprio 1
	v_mfma_f32_16x16x32_bf16 v[60:63], v[156:159], v[172:175], v[60:63]
	v_mfma_f32_16x16x32_bf16 v[56:59], v[164:167], v[172:175], v[56:59]
	v_mfma_f32_16x16x32_bf16 v[52:55], v[156:159], v[180:183], v[52:55]
	v_mfma_f32_16x16x32_bf16 v[48:51], v[164:167], v[180:183], v[48:51]
	v_mfma_f32_16x16x32_bf16 v[36:39], v[156:159], v[188:191], v[36:39]
	v_mfma_f32_16x16x32_bf16 v[32:35], v[164:167], v[188:191], v[32:35]
	v_mfma_f32_16x16x32_bf16 v[20:23], v[156:159], v[196:199], v[20:23]
	v_mfma_f32_16x16x32_bf16 v[16:19], v[164:167], v[196:199], v[16:19]
	v_mfma_f32_16x16x32_bf16 v[60:63], v[160:163], v[176:179], v[60:63]
	v_mfma_f32_16x16x32_bf16 v[56:59], v[168:171], v[176:179], v[56:59]
	v_mfma_f32_16x16x32_bf16 v[52:55], v[160:163], v[184:187], v[52:55]
	v_mfma_f32_16x16x32_bf16 v[48:51], v[168:171], v[184:187], v[48:51]
	v_mfma_f32_16x16x32_bf16 v[36:39], v[160:163], v[192:195], v[36:39]
	v_mfma_f32_16x16x32_bf16 v[32:35], v[168:171], v[192:195], v[32:35]
	v_mfma_f32_16x16x32_bf16 v[20:23], v[160:163], v[200:203], v[20:23]
	v_mfma_f32_16x16x32_bf16 v[16:19], v[168:171], v[200:203], v[16:19]
	s_setprio 0
	s_barrier
	s_add_u32 s26, s26, 0x40080
	s_addc_u32 s27, s27, 0
	s_add_i32 s28, s28, s35
	v_lshl_add_u64 v[156:157], s[26:27], 0, v[130:131]
	s_mov_b32 m0, s28
	s_nop 0
	global_load_lds_dwordx4 v[156:157], off
	v_lshl_add_u64 v[156:157], s[26:27], 0, v[134:135]
	s_add_i32 m0, s28, 0x2000
	s_nop 0
	global_load_lds_dwordx4 v[156:157], off
	s_waitcnt vmcnt(6)
	s_barrier
	s_setprio 1
	v_mfma_f32_16x16x32_bf16 v[44:47], v[204:207], v[172:175], v[44:47]
	v_mfma_f32_16x16x32_bf16 v[40:43], v[212:215], v[172:175], v[40:43]
	v_mfma_f32_16x16x32_bf16 v[28:31], v[204:207], v[180:183], v[28:31]
	v_mfma_f32_16x16x32_bf16 v[24:27], v[212:215], v[180:183], v[24:27]
	v_mfma_f32_16x16x32_bf16 v[12:15], v[204:207], v[188:191], v[12:15]
	v_mfma_f32_16x16x32_bf16 v[8:11], v[212:215], v[188:191], v[8:11]
	v_mfma_f32_16x16x32_bf16 v[4:7], v[204:207], v[196:199], v[4:7]
	v_mfma_f32_16x16x32_bf16 v[0:3], v[212:215], v[196:199], v[0:3]
	v_mfma_f32_16x16x32_bf16 v[44:47], v[208:211], v[176:179], v[44:47]
	v_mfma_f32_16x16x32_bf16 v[40:43], v[216:219], v[176:179], v[40:43]
	v_mfma_f32_16x16x32_bf16 v[28:31], v[208:211], v[184:187], v[28:31]
	v_mfma_f32_16x16x32_bf16 v[24:27], v[216:219], v[184:187], v[24:27]
	v_mfma_f32_16x16x32_bf16 v[12:15], v[208:211], v[192:195], v[12:15]
	v_mfma_f32_16x16x32_bf16 v[8:11], v[216:219], v[192:195], v[8:11]
	v_mfma_f32_16x16x32_bf16 v[4:7], v[208:211], v[200:203], v[4:7]
	v_mfma_f32_16x16x32_bf16 v[0:3], v[216:219], v[200:203], v[0:3]
	s_setprio 0
	s_add_i32 s50, s50, 2
	s_add_u32 s0, s0, 0x100
	s_addc_u32 s1, s1, 0
	s_add_u32 s17, s17, 0x100
	s_addc_u32 s49, s49, 0
	s_cmp_gt_u32 s50, 13
	s_barrier
	s_cbranch_scc0 .LBB0_187
; template <class Epi>
; DEVI void gemm_phase(LAS unsigned char* lds, const Gemm g, const Epi& E) {
;     ...
;                     for (int bj = 0; bj < 2; ++bj) {
;                         const int c = col0 + bj * HALF; f32x4 v0 = acc[ai][bj][m][0], v1 = acc[ai][bj][m][1];
;                         if constexpr (Epi::RS) { v0 = v0 * rs; v1 = v1 * rs; }
;                         if constexpr (Epi::PRE) part += E.frag_pre8(cur.b, r, c, v0, v1, pre[mm][bj][0], pre[mm][bj][1]);
;                         else if constexpr (Epi::PERM) E.frag8(cur.b, r, c, v0, v1);
	v_lshl_add_u32 v156, s48, 8, v147
	v_ashrrev_i32_e32 v157, 31, v156
	v_readlane_b32 s2, v252, 39
	v_lshlrev_b64 v[158:159], 11, v[156:157]
	v_lshl_or_b32 v155, s11, 8, v149
	v_mov_b32_e32 v157, s2
	v_readlane_b32 s2, v252, 37
	s_ashr_i32 s11, s10, 31
	v_cmp_gt_i32_e32 vcc, s42, v155
	v_mov_b32_e32 v162, s2
	v_readlane_b32 s2, v252, 38
	s_lshl_b64 s[0:1], s[10:11], 21
	v_cndmask_b32_e32 v161, v157, v162, vcc
	v_mov_b32_e32 v163, s2
	v_readlane_b32 s2, v252, 36
	v_cvt_pk_bf16_f32 v124, v124, v125
	v_cvt_pk_bf16_f32 v125, v126, v127
	v_mov_b32_e32 v164, s2
	v_cndmask_b32_e32 v160, v163, v164, vcc
	v_cvt_pk_bf16_f32 v126, v120, v121
	v_lshl_add_u64 v[120:121], v[160:161], 0, s[0:1]
	v_and_b32_e32 v136, 0x378, v155
	v_cvt_pk_bf16_f32 v127, v122, v123
	v_lshl_add_u64 v[122:123], v[120:121], 0, v[158:159]
	v_lshlrev_b32_e32 v136, 1, v136
	v_lshl_add_u64 v[122:123], v[122:123], 0, v[136:137]
	global_store_dwordx4 v[122:123], v[124:127], off
	v_or_b32_e32 v122, 0x80, v155
	v_cmp_gt_i32_e32 vcc, s42, v122
	v_cvt_pk_bf16_f32 v112, v112, v113
	v_cvt_pk_bf16_f32 v113, v114, v115
	v_cndmask_b32_e32 v123, v157, v162, vcc
	v_cndmask_b32_e32 v122, v163, v164, vcc
	v_lshl_add_u64 v[122:123], v[122:123], 0, s[0:1]
	s_movk_i32 s0, 0x3f8
	v_cvt_pk_bf16_f32 v115, v106, v107
	v_bitop3_b32 v106, v155, s0, v153 bitop3:0xc8
	v_cvt_pk_bf16_f32 v114, v104, v105
	v_lshl_add_u64 v[104:105], v[122:123], 0, v[158:159]
	v_lshlrev_b32_e32 v124, 1, v106
	v_mov_b32_e32 v125, v137
	v_lshl_add_u64 v[104:105], v[104:105], 0, v[124:125]
	global_store_dwordx4 v[104:105], v[112:115], off
	v_or_b32_e32 v104, 16, v156
	v_ashrrev_i32_e32 v105, 31, v104
	v_lshlrev_b64 v[112:113], 11, v[104:105]
	v_cvt_pk_bf16_f32 v106, v108, v109
	v_lshl_add_u64 v[108:109], v[120:121], 0, v[112:113]
	v_cvt_pk_bf16_f32 v92, v92, v93
	v_cvt_pk_bf16_f32 v93, v94, v95
	v_cvt_pk_bf16_f32 v94, v88, v89
	v_lshl_add_u64 v[88:89], v[122:123], 0, v[112:113]
	v_cvt_pk_bf16_f32 v104, v116, v117
	v_cvt_pk_bf16_f32 v105, v118, v119
	v_cvt_pk_bf16_f32 v107, v110, v111
	v_lshl_add_u64 v[108:109], v[108:109], 0, v[136:137]
	v_cvt_pk_bf16_f32 v95, v90, v91
	v_lshl_add_u64 v[88:89], v[88:89], 0, v[124:125]
	global_store_dwordx4 v[108:109], v[104:107], off
	global_store_dwordx4 v[88:89], v[92:95], off
	v_or_b32_e32 v88, 32, v156
	v_ashrrev_i32_e32 v89, 31, v88
	v_lshlrev_b64 v[92:93], 11, v[88:89]
	v_lshl_add_u64 v[94:95], v[120:121], 0, v[92:93]
	v_cvt_pk_bf16_f32 v76, v76, v77
	v_cvt_pk_bf16_f32 v77, v78, v79
	v_cvt_pk_bf16_f32 v78, v72, v73
	v_lshl_add_u64 v[72:73], v[122:123], 0, v[92:93]
	v_cvt_pk_bf16_f32 v88, v100, v101
	v_cvt_pk_bf16_f32 v89, v102, v103
	v_cvt_pk_bf16_f32 v90, v96, v97
	v_cvt_pk_bf16_f32 v91, v98, v99
	v_lshl_add_u64 v[94:95], v[94:95], 0, v[136:137]
	v_cvt_pk_bf16_f32 v79, v74, v75
	v_lshl_add_u64 v[72:73], v[72:73], 0, v[124:125]
	global_store_dwordx4 v[94:95], v[88:91], off
	global_store_dwordx4 v[72:73], v[76:79], off
	v_or_b32_e32 v72, 48, v156
	v_ashrrev_i32_e32 v73, 31, v72
	v_lshlrev_b64 v[76:77], 11, v[72:73]
	v_lshl_add_u64 v[78:79], v[120:121], 0, v[76:77]
	v_cvt_pk_bf16_f32 v68, v68, v69
	v_cvt_pk_bf16_f32 v69, v70, v71
	v_cvt_pk_bf16_f32 v70, v64, v65
	v_lshl_add_u64 v[64:65], v[122:123], 0, v[76:77]
	v_cvt_pk_bf16_f32 v72, v84, v85
	v_cvt_pk_bf16_f32 v73, v86, v87
	v_cvt_pk_bf16_f32 v74, v80, v81
	v_cvt_pk_bf16_f32 v75, v82, v83
	v_lshl_add_u64 v[78:79], v[78:79], 0, v[136:137]
	v_cvt_pk_bf16_f32 v71, v66, v67
	v_lshl_add_u64 v[64:65], v[64:65], 0, v[124:125]
	s_mov_b64 s[0:1], 0x40000
	global_store_dwordx4 v[78:79], v[72:75], off
	global_store_dwordx4 v[64:65], v[68:71], off
	v_lshl_add_u64 v[64:65], v[158:159], 0, s[0:1]
	v_cvt_pk_bf16_f32 v60, v60, v61
	v_cvt_pk_bf16_f32 v61, v62, v63
	v_cvt_pk_bf16_f32 v62, v56, v57
	v_lshl_add_u64 v[56:57], v[120:121], 0, v[64:65]
	v_cvt_pk_bf16_f32 v44, v44, v45
	v_cvt_pk_bf16_f32 v45, v46, v47
	v_cvt_pk_bf16_f32 v46, v40, v41
	v_lshl_add_u64 v[40:41], v[122:123], 0, v[64:65]
	v_cvt_pk_bf16_f32 v63, v58, v59
	v_lshl_add_u64 v[56:57], v[56:57], 0, v[136:137]
	v_cvt_pk_bf16_f32 v47, v42, v43
	v_lshl_add_u64 v[40:41], v[40:41], 0, v[124:125]
	s_mov_b64 s[0:1], 0x48000
	global_store_dwordx4 v[56:57], v[60:63], off
	global_store_dwordx4 v[40:41], v[44:47], off
	v_cvt_pk_bf16_f32 v28, v28, v29
	v_cvt_pk_bf16_f32 v29, v30, v31
	v_lshl_add_u64 v[44:45], v[158:159], 0, s[0:1]
	v_lshl_add_u64 v[46:47], v[120:121], 0, v[44:45]
	v_cvt_pk_bf16_f32 v30, v24, v25
	v_lshl_add_u64 v[24:25], v[122:123], 0, v[44:45]
	v_cvt_pk_bf16_f32 v40, v52, v53
	v_cvt_pk_bf16_f32 v41, v54, v55
	v_cvt_pk_bf16_f32 v42, v48, v49
	v_cvt_pk_bf16_f32 v43, v50, v51
	v_lshl_add_u64 v[46:47], v[46:47], 0, v[136:137]
	v_cvt_pk_bf16_f32 v31, v26, v27
	v_lshl_add_u64 v[24:25], v[24:25], 0, v[124:125]
	s_mov_b64 s[0:1], 0x50000
	global_store_dwordx4 v[46:47], v[40:43], off
	global_store_dwordx4 v[24:25], v[28:31], off
	v_cvt_pk_bf16_f32 v12, v12, v13
	v_cvt_pk_bf16_f32 v13, v14, v15
	v_lshl_add_u64 v[28:29], v[158:159], 0, s[0:1]
	v_lshl_add_u64 v[30:31], v[120:121], 0, v[28:29]
	v_cvt_pk_bf16_f32 v14, v8, v9
	v_lshl_add_u64 v[8:9], v[122:123], 0, v[28:29]
	v_cvt_pk_bf16_f32 v24, v36, v37
	v_cvt_pk_bf16_f32 v25, v38, v39
	v_cvt_pk_bf16_f32 v26, v32, v33
	v_cvt_pk_bf16_f32 v27, v34, v35
	v_lshl_add_u64 v[30:31], v[30:31], 0, v[136:137]
	v_cvt_pk_bf16_f32 v15, v10, v11
	v_lshl_add_u64 v[8:9], v[8:9], 0, v[124:125]
	s_mov_b64 s[0:1], 0x58000
	global_store_dwordx4 v[30:31], v[24:27], off
	global_store_dwordx4 v[8:9], v[12:15], off
	v_cvt_pk_bf16_f32 v4, v4, v5
	v_cvt_pk_bf16_f32 v5, v6, v7
	v_lshl_add_u64 v[12:13], v[158:159], 0, s[0:1]
	v_lshl_add_u64 v[14:15], v[120:121], 0, v[12:13]
	v_cvt_pk_bf16_f32 v6, v0, v1
	v_lshl_add_u64 v[0:1], v[122:123], 0, v[12:13]
	v_cvt_pk_bf16_f32 v8, v20, v21
	v_cvt_pk_bf16_f32 v9, v22, v23
	v_cvt_pk_bf16_f32 v10, v16, v17
	v_cvt_pk_bf16_f32 v11, v18, v19
	v_lshl_add_u64 v[14:15], v[14:15], 0, v[136:137]
	v_cvt_pk_bf16_f32 v7, v2, v3
	v_lshl_add_u64 v[0:1], v[0:1], 0, v[124:125]
	s_and_b64 vcc, exec, s[4:5]
	s_mov_b32 s10, s12
	s_mov_b32 s11, s14
	s_mov_b32 s48, s16
	s_mov_b64 s[28:29], s[18:19]
	s_mov_b64 s[26:27], s[24:25]
	global_store_dwordx4 v[14:15], v[8:11], off
	global_store_dwordx4 v[0:1], v[4:7], off
	s_cbranch_vccz .LBB0_178
	s_waitcnt vmcnt(0)
	s_cmpk_gt_u32 s34, 0xff
	s_cbranch_scc1 .LBB0_191
	s_barrier

; #define PG8_STAGE(bufoff, gbase, voff) do { _Pragma("unroll") for (int _i = 0; _i < 2; ++_i) \
;         __builtin_amdgcn_global_load_lds((const unsigned*)((const char*)(gbase) + (voff)[_i]), (LAS unsigned*)(lds + (bufoff) + ldsw + _i * 8192), 16, 0, 0); } while (0)
; #define PG8_LDA(dst, b, h) do { _Pragma("unroll") for (int m = 0; m < 4; ++m) _Pragma("unroll") for (int k = 0; k < 2; ++k) dst[m][k] = *(const LAS bf16x8*)(lds + PG8_SA(b, h) + aoff + m * 2048 + k * 1024); } while (0)
; #define PG8_LDB(dst, b, h) do { _Pragma("unroll") for (int n = 0; n < 2; ++n) _Pragma("unroll") for (int k = 0; k < 2; ++k) dst[n][k] = *(const LAS bf16x8*)(lds + PG8_SB(b, h) + boff + n * 2048 + k * 1024); } while (0)
; #define PG8_MMA(ai, bj, At, Bt) do { __builtin_amdgcn_s_setprio(1); _Pragma("unroll") for (int m = 0; m < 4; ++m) _Pragma("unroll") for (int n = 0; n < 2; ++n) _Pragma("unroll") for (int k = 0; k < 2; ++k) \
;         acc[ai][bj][m][n] = __builtin_amdgcn_mfma_f32_16x16x32_bf16(Bt[n][k], At[m][k], acc[ai][bj][m][n], 0, 0, 0); __builtin_amdgcn_s_setprio(0); } while (0)
; #define PG8_WAIT_V(n) asm volatile("s_waitcnt vmcnt(" #n ")" ::: "memory")
; #define PG8_WAIT_L(n) asm volatile("s_waitcnt lgkmcnt(" #n ")" ::: "memory")
; #define PG8_BAR __builtin_amdgcn_s_barrier()
; #define PG8_SCHED __builtin_amdgcn_sched_barrier(0)
; template <class Epi>
; DEVI void gemm_phase(LAS unsigned char* lds, const Gemm g, const Epi& E) {
;     ...
;             PG8_LDB(B0, 0, 0); PG8_SCHED; PG8_LDA(At, 0, 0); PG8_STAGE(PG8_SA(1, 1), a1 + hstepA, voffA);
;             PG8_WAIT_L(8); PG8_BAR; PG8_WAIT_L(0); PG8_MMA(0, 0, At, B0); PG8_BAR; PG8_SCHED;
;             PG8_LDB(B1, 0, 1); PG8_STAGE(PG8_SB(0, 0), b2, voffB);
;             PG8_BAR; PG8_WAIT_L(0); PG8_MMA(0, 1, At, B1); PG8_BAR;
;             PG8_LDA(At, 0, 1); PG8_STAGE(PG8_SA(0, 0), a2, voffA);
;             PG8_BAR; PG8_WAIT_L(0); PG8_MMA(1, 0, At, B0); PG8_BAR; PG8_SCHED;
;             PG8_STAGE(PG8_SB(0, 1), b2 + hstepB, voffB);
;             PG8_WAIT_V(6); PG8_BAR; PG8_MMA(1, 1, At, B1); PG8_BAR;
.LBB0_436:
	s_add_u32 s11, s6, s5
	s_addc_u32 s13, s7, 0
	s_add_u32 s49, s11, 0x100
	s_addc_u32 s52, s13, 0
	s_and_b64 s[50:51], s[68:69], exec
	s_cselect_b32 s89, s17, s52
	s_cselect_b32 s88, s16, s49
	s_add_u32 s5, s8, s5
	s_addc_u32 s49, s9, 0
	s_add_u32 s5, s5, 0x100
	s_addc_u32 s49, s49, 0
	s_add_i32 vcc_hi, 0, 0x10000
	s_and_b64 s[50:51], s[68:69], exec
	s_cselect_b32 s91, s3, s49
	s_cselect_b32 s90, s2, s5
	s_add_u32 s92, s11, 0x40080
	s_addc_u32 s93, s13, 0
	s_add_i32 s53, vcc_hi, s38
	s_add_i32 m0, s54, 0xc000
	s_add_i32 s39, s54, 0xe000
	s_add_i32 vcc_lo, 0, 0x14000
	s_add_i32 s51, s53, 0x2000
	s_add_u32 s86, s90, 0x40000
	v_add_u32_e32 v162, vcc_hi, v152
	s_addc_u32 s87, s91, 0
	s_add_i32 s66, vcc_lo, s38
	ds_read_b128 v[178:181], v162
	ds_read_b128 v[182:185], v162 offset:1024
	ds_read_b128 v[186:189], v162 offset:2048
	ds_read_b128 v[190:193], v162 offset:3072
	s_add_i32 s52, s66, 0x2000
	s_add_i32 s49, 0, 0x18000
	s_add_u32 s82, s88, 0x40000
	s_addc_u32 s83, s89, 0
	s_add_i32 s13, s49, s38
	s_add_i32 s11, 0, 0x1c000
	s_add_i32 s5, s13, 0x2000
	s_add_u32 s68, s90, 0x40080
	s_addc_u32 s69, s91, 0
	s_add_i32 vcc_hi, s11, s38
	s_add_i32 s50, vcc_hi, 0x2000
	v_lshl_add_u64 v[230:231], s[92:93], 0, v[134:135]
	ds_read_b128 v[194:197], v176
	ds_read_b128 v[198:201], v176 offset:1024
	ds_read_b128 v[202:205], v176 offset:2048
	ds_read_b128 v[206:209], v176 offset:3072
	ds_read_b128 v[214:217], v176 offset:4096
	ds_read_b128 v[218:221], v176 offset:5120
	ds_read_b128 v[222:225], v176 offset:6144
	ds_read_b128 v[226:229], v176 offset:7168
	global_load_lds_dwordx4 v[230:231], off
	v_lshl_add_u64 v[230:231], s[92:93], 0, v[132:133]
	s_mov_b32 m0, s39
	s_nop 0
	global_load_lds_dwordx4 v[230:231], off
	s_waitcnt lgkmcnt(8)
	s_barrier
	s_waitcnt lgkmcnt(0)
	s_setprio 1
	v_mfma_f32_16x16x32_bf16 v[126:129], v[178:181], v[194:197], v[126:129]
	v_mfma_f32_16x16x32_bf16 v[122:125], v[186:189], v[194:197], v[122:125]
	v_mfma_f32_16x16x32_bf16 v[118:121], v[178:181], v[202:205], v[118:121]
	v_mfma_f32_16x16x32_bf16 v[114:117], v[186:189], v[202:205], v[114:117]
	v_mfma_f32_16x16x32_bf16 v[102:105], v[178:181], v[214:217], v[102:105]
	v_mfma_f32_16x16x32_bf16 v[98:101], v[186:189], v[214:217], v[98:101]
	v_mfma_f32_16x16x32_bf16 v[86:89], v[178:181], v[222:225], v[86:89]
	v_mfma_f32_16x16x32_bf16 v[82:85], v[186:189], v[222:225], v[82:85]
	v_mfma_f32_16x16x32_bf16 v[126:129], v[182:185], v[198:201], v[126:129]
	v_mfma_f32_16x16x32_bf16 v[122:125], v[190:193], v[198:201], v[122:125]
	v_mfma_f32_16x16x32_bf16 v[118:121], v[182:185], v[206:209], v[118:121]
	v_mfma_f32_16x16x32_bf16 v[114:117], v[190:193], v[206:209], v[114:117]
	v_mfma_f32_16x16x32_bf16 v[102:105], v[182:185], v[218:221], v[102:105]
	v_mfma_f32_16x16x32_bf16 v[98:101], v[190:193], v[218:221], v[98:101]
	v_mfma_f32_16x16x32_bf16 v[86:89], v[182:185], v[226:229], v[86:89]
	v_mfma_f32_16x16x32_bf16 v[82:85], v[190:193], v[226:229], v[82:85]
	s_setprio 0
	s_barrier
	s_mov_b32 m0, s53
	v_add_u32_e32 v162, vcc_lo, v152
	v_lshl_add_u64 v[246:247], s[90:91], 0, v[8:9]
	ds_read_b128 v[230:233], v162
	ds_read_b128 v[234:237], v162 offset:1024
	ds_read_b128 v[238:241], v162 offset:2048
	ds_read_b128 v[242:245], v162 offset:3072
	global_load_lds_dwordx4 v[246:247], off
	v_lshl_add_u64 v[248:249], s[90:91], 0, v[130:131]
	s_mov_b32 m0, s51
	s_nop 0
	global_load_lds_dwordx4 v[248:249], off
	s_barrier
	s_waitcnt lgkmcnt(0)
	s_setprio 1
	v_mfma_f32_16x16x32_bf16 v[110:113], v[230:233], v[194:197], v[110:113]
	v_mfma_f32_16x16x32_bf16 v[106:109], v[238:241], v[194:197], v[106:109]
	v_mfma_f32_16x16x32_bf16 v[94:97], v[230:233], v[202:205], v[94:97]
	v_mfma_f32_16x16x32_bf16 v[90:93], v[238:241], v[202:205], v[90:93]
	v_mfma_f32_16x16x32_bf16 v[78:81], v[230:233], v[214:217], v[78:81]
	v_mfma_f32_16x16x32_bf16 v[74:77], v[238:241], v[214:217], v[74:77]
	v_mfma_f32_16x16x32_bf16 v[70:73], v[230:233], v[222:225], v[70:73]
	v_mfma_f32_16x16x32_bf16 v[66:69], v[238:241], v[222:225], v[66:69]
	v_mfma_f32_16x16x32_bf16 v[110:113], v[234:237], v[198:201], v[110:113]
	v_mfma_f32_16x16x32_bf16 v[106:109], v[242:245], v[198:201], v[106:109]
	v_mfma_f32_16x16x32_bf16 v[94:97], v[234:237], v[206:209], v[94:97]
	v_mfma_f32_16x16x32_bf16 v[90:93], v[242:245], v[206:209], v[90:93]
	v_mfma_f32_16x16x32_bf16 v[78:81], v[234:237], v[218:221], v[78:81]
	v_mfma_f32_16x16x32_bf16 v[74:77], v[242:245], v[218:221], v[74:77]
	v_mfma_f32_16x16x32_bf16 v[70:73], v[234:237], v[226:229], v[70:73]
	v_mfma_f32_16x16x32_bf16 v[66:69], v[242:245], v[226:229], v[66:69]
	s_setprio 0
	s_mov_b32 m0, s54
	v_lshl_add_u64 v[162:163], s[88:89], 0, v[134:135]
	s_barrier
	ds_read_b128 v[194:197], v176 offset:16384
	ds_read_b128 v[198:201], v176 offset:17408
	ds_read_b128 v[202:205], v176 offset:18432
	ds_read_b128 v[206:209], v176 offset:19456
	ds_read_b128 v[214:217], v176 offset:20480
	ds_read_b128 v[218:221], v176 offset:21504
	ds_read_b128 v[222:225], v176 offset:22528
	ds_read_b128 v[226:229], v176 offset:23552
	global_load_lds_dwordx4 v[162:163], off
	v_lshl_add_u64 v[164:165], s[88:89], 0, v[132:133]
	s_mov_b32 m0, s40
	s_nop 0
	global_load_lds_dwordx4 v[164:165], off
	s_barrier
; #define PG8_STAGE(bufoff, gbase, voff) do { _Pragma("unroll") for (int _i = 0; _i < 2; ++_i) \
;         __builtin_amdgcn_global_load_lds((const unsigned*)((const char*)(gbase) + (voff)[_i]), (LAS unsigned*)(lds + (bufoff) + ldsw + _i * 8192), 16, 0, 0); } while (0)
; #define PG8_LDA(dst, b, h) do { _Pragma("unroll") for (int m = 0; m < 4; ++m) _Pragma("unroll") for (int k = 0; k < 2; ++k) dst[m][k] = *(const LAS bf16x8*)(lds + PG8_SA(b, h) + aoff + m * 2048 + k * 1024); } while (0)
; #define PG8_LDB(dst, b, h) do { _Pragma("unroll") for (int n = 0; n < 2; ++n) _Pragma("unroll") for (int k = 0; k < 2; ++k) dst[n][k] = *(const LAS bf16x8*)(lds + PG8_SB(b, h) + boff + n * 2048 + k * 1024); } while (0)
; #define PG8_MMA(ai, bj, At, Bt) do { __builtin_amdgcn_s_setprio(1); _Pragma("unroll") for (int m = 0; m < 4; ++m) _Pragma("unroll") for (int n = 0; n < 2; ++n) _Pragma("unroll") for (int k = 0; k < 2; ++k) \
;         acc[ai][bj][m][n] = __builtin_amdgcn_mfma_f32_16x16x32_bf16(Bt[n][k], At[m][k], acc[ai][bj][m][n], 0, 0, 0); __builtin_amdgcn_s_setprio(0); } while (0)
; #define PG8_WAIT_V(n) asm volatile("s_waitcnt vmcnt(" #n ")" ::: "memory")
; #define PG8_WAIT_L(n) asm volatile("s_waitcnt lgkmcnt(" #n ")" ::: "memory")
; #define PG8_BAR __builtin_amdgcn_s_barrier()
; #define PG8_SCHED __builtin_amdgcn_sched_barrier(0)
; template <class Epi>
; DEVI void gemm_phase(LAS unsigned char* lds, const Gemm g, const Epi& E) {
;     ...
;             PG8_WAIT_V(6); PG8_BAR; PG8_MMA(1, 1, At, B1); PG8_BAR;
;             PG8_LDB(B0, 1, 0); PG8_SCHED; PG8_LDA(At, 1, 0); PG8_STAGE(PG8_SA(0, 1), a2 + hstepA, voffA);
;             PG8_WAIT_L(8); PG8_BAR; PG8_WAIT_L(0); PG8_MMA(0, 0, At, B0); PG8_BAR; PG8_SCHED;
;             PG8_LDB(B1, 1, 1); PG8_STAGE(PG8_SB(1, 0), b3, voffB);
;             PG8_BAR; PG8_WAIT_L(0); PG8_MMA(0, 1, At, B1); PG8_BAR;
;             PG8_LDA(At, 1, 1); PG8_STAGE(PG8_SA(1, 0), a3, voffA);
;             PG8_BAR; PG8_WAIT_L(0); PG8_MMA(1, 0, At, B0); PG8_BAR; PG8_SCHED;
	s_waitcnt lgkmcnt(0)
	s_setprio 1
	v_mfma_f32_16x16x32_bf16 v[62:65], v[178:181], v[194:197], v[62:65]
	v_mfma_f32_16x16x32_bf16 v[58:61], v[186:189], v[194:197], v[58:61]
	v_mfma_f32_16x16x32_bf16 v[54:57], v[178:181], v[202:205], v[54:57]
	v_mfma_f32_16x16x32_bf16 v[50:53], v[186:189], v[202:205], v[50:53]
	v_mfma_f32_16x16x32_bf16 v[38:41], v[178:181], v[214:217], v[38:41]
	v_mfma_f32_16x16x32_bf16 v[34:37], v[186:189], v[214:217], v[34:37]
	v_mfma_f32_16x16x32_bf16 v[22:25], v[178:181], v[222:225], v[22:25]
	v_mfma_f32_16x16x32_bf16 v[18:21], v[186:189], v[222:225], v[18:21]
	v_mfma_f32_16x16x32_bf16 v[62:65], v[182:185], v[198:201], v[62:65]
	v_mfma_f32_16x16x32_bf16 v[58:61], v[190:193], v[198:201], v[58:61]
	v_mfma_f32_16x16x32_bf16 v[54:57], v[182:185], v[206:209], v[54:57]
	v_mfma_f32_16x16x32_bf16 v[50:53], v[190:193], v[206:209], v[50:53]
	v_mfma_f32_16x16x32_bf16 v[38:41], v[182:185], v[218:221], v[38:41]
	v_mfma_f32_16x16x32_bf16 v[34:37], v[190:193], v[218:221], v[34:37]
	v_mfma_f32_16x16x32_bf16 v[22:25], v[182:185], v[226:229], v[22:25]
	v_mfma_f32_16x16x32_bf16 v[18:21], v[190:193], v[226:229], v[18:21]
	s_setprio 0
	s_barrier
	s_mov_b32 m0, s66
	v_lshl_add_u64 v[178:179], s[86:87], 0, v[8:9]
	global_load_lds_dwordx4 v[178:179], off
	v_lshl_add_u64 v[178:179], s[86:87], 0, v[130:131]
	s_mov_b32 m0, s52
	s_nop 0
	global_load_lds_dwordx4 v[178:179], off
	s_waitcnt vmcnt(6)
	s_barrier
	s_setprio 1
	v_mfma_f32_16x16x32_bf16 v[46:49], v[230:233], v[194:197], v[46:49]
	v_mfma_f32_16x16x32_bf16 v[42:45], v[238:241], v[194:197], v[42:45]
	v_mfma_f32_16x16x32_bf16 v[30:33], v[230:233], v[202:205], v[30:33]
	v_mfma_f32_16x16x32_bf16 v[26:29], v[238:241], v[202:205], v[26:29]
	v_mfma_f32_16x16x32_bf16 v[14:17], v[230:233], v[214:217], v[14:17]
	v_mfma_f32_16x16x32_bf16 v[10:13], v[238:241], v[214:217], v[10:13]
	v_mfma_f32_16x16x32_bf16 v[4:7], v[230:233], v[222:225], v[4:7]
	v_mfma_f32_16x16x32_bf16 v[0:3], v[238:241], v[222:225], v[0:3]
	v_mfma_f32_16x16x32_bf16 v[46:49], v[234:237], v[198:201], v[46:49]
	v_mfma_f32_16x16x32_bf16 v[42:45], v[242:245], v[198:201], v[42:45]
	v_mfma_f32_16x16x32_bf16 v[30:33], v[234:237], v[206:209], v[30:33]
	v_mfma_f32_16x16x32_bf16 v[26:29], v[242:245], v[206:209], v[26:29]
	v_mfma_f32_16x16x32_bf16 v[14:17], v[234:237], v[218:221], v[14:17]
	v_mfma_f32_16x16x32_bf16 v[10:13], v[242:245], v[218:221], v[10:13]
	v_mfma_f32_16x16x32_bf16 v[4:7], v[234:237], v[226:229], v[4:7]
	v_mfma_f32_16x16x32_bf16 v[0:3], v[242:245], v[226:229], v[0:3]
	s_setprio 0
	v_add_u32_e32 v177, s49, v152
	s_barrier
	ds_read_b128 v[178:181], v177
	ds_read_b128 v[182:185], v177 offset:1024
	ds_read_b128 v[186:189], v177 offset:2048
	ds_read_b128 v[190:193], v177 offset:3072
	s_mov_b32 m0, s41
	v_lshl_add_u64 v[230:231], s[82:83], 0, v[134:135]
	ds_read_b128 v[194:197], v176 offset:32768
	ds_read_b128 v[198:201], v176 offset:33792
	ds_read_b128 v[202:205], v176 offset:34816
	ds_read_b128 v[206:209], v176 offset:35840
	ds_read_b128 v[214:217], v176 offset:36864
	ds_read_b128 v[218:221], v176 offset:37888
	ds_read_b128 v[222:225], v176 offset:38912
	ds_read_b128 v[226:229], v176 offset:39936
	global_load_lds_dwordx4 v[230:231], off
	v_lshl_add_u64 v[230:231], s[82:83], 0, v[132:133]
	s_mov_b32 m0, s42
	s_nop 0
	global_load_lds_dwordx4 v[230:231], off
	s_waitcnt lgkmcnt(8)
	s_barrier
	s_waitcnt lgkmcnt(0)
	s_setprio 1
	v_mfma_f32_16x16x32_bf16 v[126:129], v[178:181], v[194:197], v[126:129]
	v_mfma_f32_16x16x32_bf16 v[122:125], v[186:189], v[194:197], v[122:125]
	v_mfma_f32_16x16x32_bf16 v[118:121], v[178:181], v[202:205], v[118:121]
	v_mfma_f32_16x16x32_bf16 v[114:117], v[186:189], v[202:205], v[114:117]
	v_mfma_f32_16x16x32_bf16 v[102:105], v[178:181], v[214:217], v[102:105]
	v_mfma_f32_16x16x32_bf16 v[98:101], v[186:189], v[214:217], v[98:101]
	v_mfma_f32_16x16x32_bf16 v[86:89], v[178:181], v[222:225], v[86:89]
	v_mfma_f32_16x16x32_bf16 v[82:85], v[186:189], v[222:225], v[82:85]
	v_mfma_f32_16x16x32_bf16 v[126:129], v[182:185], v[198:201], v[126:129]
	v_mfma_f32_16x16x32_bf16 v[122:125], v[190:193], v[198:201], v[122:125]
	v_mfma_f32_16x16x32_bf16 v[118:121], v[182:185], v[206:209], v[118:121]
	v_mfma_f32_16x16x32_bf16 v[114:117], v[190:193], v[206:209], v[114:117]
	v_mfma_f32_16x16x32_bf16 v[102:105], v[182:185], v[218:221], v[102:105]
	v_mfma_f32_16x16x32_bf16 v[98:101], v[190:193], v[218:221], v[98:101]
	v_mfma_f32_16x16x32_bf16 v[86:89], v[182:185], v[226:229], v[86:89]
	v_mfma_f32_16x16x32_bf16 v[82:85], v[190:193], v[226:229], v[82:85]
	s_setprio 0
	s_barrier
	s_mov_b32 m0, s13
	v_add_u32_e32 v177, s11, v152
	v_lshl_add_u64 v[246:247], v[246:247], 0, s[70:71]
	ds_read_b128 v[230:233], v177
	ds_read_b128 v[234:237], v177 offset:1024
	ds_read_b128 v[238:241], v177 offset:2048
	ds_read_b128 v[242:245], v177 offset:3072
	global_load_lds_dwordx4 v[246:247], off
	v_lshl_add_u64 v[246:247], v[248:249], 0, s[70:71]
	s_mov_b32 m0, s5
	s_nop 0
	global_load_lds_dwordx4 v[246:247], off
	s_barrier
	s_waitcnt lgkmcnt(0)
	s_setprio 1
	v_mfma_f32_16x16x32_bf16 v[110:113], v[230:233], v[194:197], v[110:113]
	v_mfma_f32_16x16x32_bf16 v[106:109], v[238:241], v[194:197], v[106:109]
	v_mfma_f32_16x16x32_bf16 v[94:97], v[230:233], v[202:205], v[94:97]
	v_mfma_f32_16x16x32_bf16 v[90:93], v[238:241], v[202:205], v[90:93]
	v_mfma_f32_16x16x32_bf16 v[78:81], v[230:233], v[214:217], v[78:81]
	v_mfma_f32_16x16x32_bf16 v[74:77], v[238:241], v[214:217], v[74:77]
	v_mfma_f32_16x16x32_bf16 v[70:73], v[230:233], v[222:225], v[70:73]
	v_mfma_f32_16x16x32_bf16 v[66:69], v[238:241], v[222:225], v[66:69]
	v_mfma_f32_16x16x32_bf16 v[110:113], v[234:237], v[198:201], v[110:113]
	v_mfma_f32_16x16x32_bf16 v[106:109], v[242:245], v[198:201], v[106:109]
	v_mfma_f32_16x16x32_bf16 v[94:97], v[234:237], v[206:209], v[94:97]
	v_mfma_f32_16x16x32_bf16 v[90:93], v[242:245], v[206:209], v[90:93]
	v_mfma_f32_16x16x32_bf16 v[78:81], v[234:237], v[218:221], v[78:81]
	v_mfma_f32_16x16x32_bf16 v[74:77], v[242:245], v[218:221], v[74:77]
	v_mfma_f32_16x16x32_bf16 v[70:73], v[234:237], v[226:229], v[70:73]
	v_mfma_f32_16x16x32_bf16 v[66:69], v[242:245], v[226:229], v[66:69]
	s_setprio 0
	s_mov_b32 m0, s43
	v_lshl_add_u64 v[162:163], v[162:163], 0, s[70:71]
	s_barrier
; #define PG8_STAGE(bufoff, gbase, voff) do { _Pragma("unroll") for (int _i = 0; _i < 2; ++_i) \
;         __builtin_amdgcn_global_load_lds((const unsigned*)((const char*)(gbase) + (voff)[_i]), (LAS unsigned*)(lds + (bufoff) + ldsw + _i * 8192), 16, 0, 0); } while (0)
; #define PG8_LDA(dst, b, h) do { _Pragma("unroll") for (int m = 0; m < 4; ++m) _Pragma("unroll") for (int k = 0; k < 2; ++k) dst[m][k] = *(const LAS bf16x8*)(lds + PG8_SA(b, h) + aoff + m * 2048 + k * 1024); } while (0)
; #define PG8_MMA(ai, bj, At, Bt) do { __builtin_amdgcn_s_setprio(1); _Pragma("unroll") for (int m = 0; m < 4; ++m) _Pragma("unroll") for (int n = 0; n < 2; ++n) _Pragma("unroll") for (int k = 0; k < 2; ++k) \
;         acc[ai][bj][m][n] = __builtin_amdgcn_mfma_f32_16x16x32_bf16(Bt[n][k], At[m][k], acc[ai][bj][m][n], 0, 0, 0); __builtin_amdgcn_s_setprio(0); } while (0)
; #define PG8_WAIT_V(n) asm volatile("s_waitcnt vmcnt(" #n ")" ::: "memory")
; #define PG8_WAIT_L(n) asm volatile("s_waitcnt lgkmcnt(" #n ")" ::: "memory")
; #define PG8_BAR __builtin_amdgcn_s_barrier()
; #define PG8_SCHED __builtin_amdgcn_sched_barrier(0)
; template <class Epi>
; DEVI void gemm_phase(LAS unsigned char* lds, const Gemm g, const Epi& E) {
;     ...
;             PG8_BAR; PG8_WAIT_L(0); PG8_MMA(0, 1, At, B1); PG8_BAR;
;             PG8_LDA(At, 1, 1); PG8_STAGE(PG8_SA(1, 0), a3, voffA);
;             PG8_BAR; PG8_WAIT_L(0); PG8_MMA(1, 0, At, B0); PG8_BAR; PG8_SCHED;
;             PG8_STAGE(PG8_SB(1, 1), b3 + hstepB, voffB);
;             PG8_WAIT_V(6); PG8_BAR; PG8_MMA(1, 1, At, B1); PG8_BAR;
	ds_read_b128 v[194:197], v176 offset:49152
	ds_read_b128 v[198:201], v176 offset:50176
	ds_read_b128 v[202:205], v176 offset:51200
	ds_read_b128 v[206:209], v176 offset:52224
	ds_read_b128 v[214:217], v176 offset:53248
	ds_read_b128 v[218:221], v176 offset:54272
	ds_read_b128 v[222:225], v176 offset:55296
	ds_read_b128 v[226:229], v176 offset:56320
	global_load_lds_dwordx4 v[162:163], off
	v_lshl_add_u64 v[162:163], v[164:165], 0, s[70:71]
	s_mov_b32 m0, s44
	s_nop 0
	global_load_lds_dwordx4 v[162:163], off
	s_barrier
	s_waitcnt lgkmcnt(0)
	s_setprio 1
	v_mfma_f32_16x16x32_bf16 v[62:65], v[178:181], v[194:197], v[62:65]
	v_mfma_f32_16x16x32_bf16 v[58:61], v[186:189], v[194:197], v[58:61]
	v_mfma_f32_16x16x32_bf16 v[54:57], v[178:181], v[202:205], v[54:57]
	v_mfma_f32_16x16x32_bf16 v[50:53], v[186:189], v[202:205], v[50:53]
	v_mfma_f32_16x16x32_bf16 v[38:41], v[178:181], v[214:217], v[38:41]
	v_mfma_f32_16x16x32_bf16 v[34:37], v[186:189], v[214:217], v[34:37]
	v_mfma_f32_16x16x32_bf16 v[22:25], v[178:181], v[222:225], v[22:25]
	v_mfma_f32_16x16x32_bf16 v[18:21], v[186:189], v[222:225], v[18:21]
	v_mfma_f32_16x16x32_bf16 v[62:65], v[182:185], v[198:201], v[62:65]
	v_mfma_f32_16x16x32_bf16 v[58:61], v[190:193], v[198:201], v[58:61]
	v_mfma_f32_16x16x32_bf16 v[54:57], v[182:185], v[206:209], v[54:57]
	v_mfma_f32_16x16x32_bf16 v[50:53], v[190:193], v[206:209], v[50:53]
	v_mfma_f32_16x16x32_bf16 v[38:41], v[182:185], v[218:221], v[38:41]
	v_mfma_f32_16x16x32_bf16 v[34:37], v[190:193], v[218:221], v[34:37]
	v_mfma_f32_16x16x32_bf16 v[22:25], v[182:185], v[226:229], v[22:25]
	v_mfma_f32_16x16x32_bf16 v[18:21], v[190:193], v[226:229], v[18:21]
	s_setprio 0
	s_barrier
	s_mov_b32 m0, vcc_hi
	v_lshl_add_u64 v[162:163], s[68:69], 0, v[8:9]
	global_load_lds_dwordx4 v[162:163], off
	v_lshl_add_u64 v[162:163], s[68:69], 0, v[130:131]
	s_mov_b32 m0, s50
	s_nop 0
	global_load_lds_dwordx4 v[162:163], off
	s_waitcnt vmcnt(6)
	s_barrier
	s_setprio 1
	v_mfma_f32_16x16x32_bf16 v[46:49], v[230:233], v[194:197], v[46:49]
	v_mfma_f32_16x16x32_bf16 v[42:45], v[238:241], v[194:197], v[42:45]
	v_mfma_f32_16x16x32_bf16 v[30:33], v[230:233], v[202:205], v[30:33]
	v_mfma_f32_16x16x32_bf16 v[26:29], v[238:241], v[202:205], v[26:29]
	v_mfma_f32_16x16x32_bf16 v[14:17], v[230:233], v[214:217], v[14:17]
	v_mfma_f32_16x16x32_bf16 v[10:13], v[238:241], v[214:217], v[10:13]
	v_mfma_f32_16x16x32_bf16 v[4:7], v[230:233], v[222:225], v[4:7]
	v_mfma_f32_16x16x32_bf16 v[0:3], v[238:241], v[222:225], v[0:3]
	v_mfma_f32_16x16x32_bf16 v[46:49], v[234:237], v[198:201], v[46:49]
	v_mfma_f32_16x16x32_bf16 v[42:45], v[242:245], v[198:201], v[42:45]
	v_mfma_f32_16x16x32_bf16 v[30:33], v[234:237], v[206:209], v[30:33]
	v_mfma_f32_16x16x32_bf16 v[26:29], v[242:245], v[206:209], v[26:29]
	v_mfma_f32_16x16x32_bf16 v[14:17], v[234:237], v[218:221], v[14:17]
	v_mfma_f32_16x16x32_bf16 v[10:13], v[242:245], v[218:221], v[10:13]
	v_mfma_f32_16x16x32_bf16 v[4:7], v[234:237], v[226:229], v[4:7]
	v_mfma_f32_16x16x32_bf16 v[0:3], v[242:245], v[226:229], v[0:3]
	s_setprio 0
	s_movk_i32 s5, 0x100
	s_andn2_b64 vcc, exec, s[46:47]
	s_mov_b64 s[68:69], -1
	s_mov_b64 s[46:47], 0
	s_barrier
	s_cbranch_vccz .LBB0_436
; template <class Epi>
; DEVI void gemm_phase(LAS unsigned char* lds, const Gemm g, const Epi& E) {
;     ...
;                     for (int bj = 0; bj < 2; ++bj) {
;                         const int c = col0 + bj * HALF; f32x4 v0 = acc[ai][bj][m][0], v1 = acc[ai][bj][m][1];
;                         if constexpr (Epi::RS) { v0 = v0 * rs; v1 = v1 * rs; }
;                         if constexpr (Epi::PRE) part += E.frag_pre8(cur.b, r, c, v0, v1, pre[mm][bj][0], pre[mm][bj][1]);
;                         else if constexpr (Epi::PERM) E.frag8(cur.b, r, c, v0, v1);
	v_lshl_or_b32 v178, s4, 8, v153
	s_ashr_i32 s4, s45, 2
	s_ashr_i32 s5, s4, 31
	s_lshl_b32 s6, s45, 8
	s_and_b32 s66, s6, 0x300
	s_lshl_b64 s[4:5], s[4:5], 21
	s_add_u32 s4, s60, s4
	v_lshl_add_u64 v[180:181], v[136:137], 0, s[66:67]
	v_cvt_pk_bf16_f32 v70, v70, v71
	v_cvt_pk_bf16_f32 v71, v72, v73
	v_cvt_pk_bf16_f32 v72, v66, v67
	v_lshl_add_u64 v[66:67], v[144:145], 0, s[66:67]
	s_addc_u32 s5, s61, s5
	v_lshlrev_b64 v[180:181], 11, v[180:181]
	v_ashrrev_i32_e32 v179, 31, v178
	v_lshlrev_b64 v[66:67], 11, v[66:67]
	v_lshl_add_u64 v[180:181], s[4:5], 0, v[180:181]
	v_cvt_pk_bf16_f32 v126, v126, v127
	v_cvt_pk_bf16_f32 v127, v128, v129
	v_cvt_pk_bf16_f32 v128, v122, v123
	v_lshlrev_b64 v[122:123], 1, v[178:179]
	v_cvt_pk_bf16_f32 v110, v110, v111
	v_cvt_pk_bf16_f32 v111, v112, v113
	v_cvt_pk_bf16_f32 v112, v106, v107
	v_lshl_add_u64 v[106:107], v[138:139], 0, s[66:67]
	v_lshl_add_u64 v[66:67], s[4:5], 0, v[66:67]
	v_cvt_pk_bf16_f32 v46, v46, v47
	v_cvt_pk_bf16_f32 v47, v48, v49
	v_cvt_pk_bf16_f32 v48, v42, v43
	v_lshl_add_u64 v[42:43], v[146:147], 0, s[66:67]
	v_cvt_pk_bf16_f32 v129, v124, v125
	v_lshl_add_u64 v[124:125], v[180:181], 0, v[122:123]
	v_cvt_pk_bf16_f32 v113, v108, v109
	v_lshlrev_b64 v[106:107], 11, v[106:107]
	v_cvt_pk_bf16_f32 v62, v62, v63
	v_cvt_pk_bf16_f32 v63, v64, v65
	v_cvt_pk_bf16_f32 v64, v58, v59
	v_lshl_add_u64 v[58:59], v[66:67], 0, v[122:123]
	v_cvt_pk_bf16_f32 v49, v44, v45
	v_lshlrev_b64 v[42:43], 11, v[42:43]
	global_store_dwordx4 v[124:125], v[110:113], off offset:256
	v_cvt_pk_bf16_f32 v94, v94, v95
	v_cvt_pk_bf16_f32 v95, v96, v97
	v_lshl_add_u64 v[110:111], s[4:5], 0, v[106:107]
	v_cvt_pk_bf16_f32 v96, v90, v91
	v_lshl_add_u64 v[90:91], v[140:141], 0, s[66:67]
	global_store_dwordx4 v[58:59], v[46:49], off offset:256
	v_cvt_pk_bf16_f32 v30, v30, v31
	v_cvt_pk_bf16_f32 v31, v32, v33
	v_lshl_add_u64 v[46:47], s[4:5], 0, v[42:43]
	v_cvt_pk_bf16_f32 v32, v26, v27
	v_lshl_add_u64 v[26:27], v[148:149], 0, s[66:67]
	v_lshl_add_u64 v[110:111], v[110:111], 0, v[122:123]
	v_cvt_pk_bf16_f32 v97, v92, v93
	v_lshlrev_b64 v[90:91], 11, v[90:91]
	v_lshl_add_u64 v[46:47], v[46:47], 0, v[122:123]
	v_cvt_pk_bf16_f32 v33, v28, v29
	v_lshlrev_b64 v[26:27], 11, v[26:27]
	global_store_dwordx4 v[110:111], v[94:97], off offset:256
	v_cvt_pk_bf16_f32 v78, v78, v79
	v_cvt_pk_bf16_f32 v79, v80, v81
	v_lshl_add_u64 v[94:95], s[4:5], 0, v[90:91]
	v_cvt_pk_bf16_f32 v80, v74, v75
	v_lshl_add_u64 v[74:75], v[142:143], 0, s[66:67]
	global_store_dwordx4 v[46:47], v[30:33], off offset:256
	v_cvt_pk_bf16_f32 v14, v14, v15
	v_cvt_pk_bf16_f32 v15, v16, v17
	v_lshl_add_u64 v[30:31], s[4:5], 0, v[26:27]
	v_cvt_pk_bf16_f32 v16, v10, v11
	v_lshl_add_u64 v[10:11], v[150:151], 0, s[66:67]
	v_lshl_add_u64 v[94:95], v[94:95], 0, v[122:123]
	v_cvt_pk_bf16_f32 v81, v76, v77
	v_lshlrev_b64 v[74:75], 11, v[74:75]
	v_lshl_add_u64 v[30:31], v[30:31], 0, v[122:123]
	v_cvt_pk_bf16_f32 v17, v12, v13
	v_lshlrev_b64 v[10:11], 11, v[10:11]
	global_store_dwordx4 v[94:95], v[78:81], off offset:256
	global_store_dwordx4 v[30:31], v[14:17], off offset:256
	v_cvt_pk_bf16_f32 v106, v118, v119
	v_lshl_add_u64 v[78:79], s[4:5], 0, v[74:75]
	v_lshl_add_u64 v[14:15], s[4:5], 0, v[10:11]
	v_cvt_pk_bf16_f32 v107, v120, v121
	v_cvt_pk_bf16_f32 v108, v114, v115
	v_cvt_pk_bf16_f32 v109, v116, v117
	v_cvt_pk_bf16_f32 v90, v102, v103
	v_cvt_pk_bf16_f32 v91, v104, v105
	v_cvt_pk_bf16_f32 v92, v98, v99
	v_cvt_pk_bf16_f32 v93, v100, v101
	v_cvt_pk_bf16_f32 v74, v86, v87
	v_cvt_pk_bf16_f32 v75, v88, v89
	v_cvt_pk_bf16_f32 v76, v82, v83
	v_cvt_pk_bf16_f32 v77, v84, v85
	v_lshl_add_u64 v[78:79], v[78:79], 0, v[122:123]
	v_cvt_pk_bf16_f32 v73, v68, v69
	v_cvt_pk_bf16_f32 v65, v60, v61
	v_cvt_pk_bf16_f32 v42, v54, v55
	v_cvt_pk_bf16_f32 v43, v56, v57
	v_cvt_pk_bf16_f32 v44, v50, v51
	v_cvt_pk_bf16_f32 v45, v52, v53
	v_cvt_pk_bf16_f32 v26, v38, v39
	v_cvt_pk_bf16_f32 v27, v40, v41
	v_cvt_pk_bf16_f32 v28, v34, v35
	v_cvt_pk_bf16_f32 v29, v36, v37
	v_cvt_pk_bf16_f32 v10, v22, v23
	v_cvt_pk_bf16_f32 v11, v24, v25
	v_cvt_pk_bf16_f32 v12, v18, v19
	v_cvt_pk_bf16_f32 v13, v20, v21
	v_lshl_add_u64 v[14:15], v[14:15], 0, v[122:123]
	v_cvt_pk_bf16_f32 v4, v4, v5
	v_cvt_pk_bf16_f32 v5, v6, v7
	v_cvt_pk_bf16_f32 v6, v0, v1
	v_cvt_pk_bf16_f32 v7, v2, v3
	s_and_b64 vcc, exec, s[14:15]
	s_mov_b32 s45, s10
	s_mov_b32 s4, s12
	s_mov_b64 s[8:9], s[2:3]
	s_mov_b64 s[6:7], s[16:17]
	s_movk_i32 s49, 0x2000
	s_movk_i32 s50, 0x1000
	s_movk_i32 s51, 0x800
	s_movk_i32 s52, 0x110
	s_movk_i32 s53, 0x3000
	global_store_dwordx4 v[124:125], v[126:129], off
	global_store_dwordx4 v[110:111], v[106:109], off
	global_store_dwordx4 v[94:95], v[90:93], off
	global_store_dwordx4 v[78:79], v[74:77], off
	global_store_dwordx4 v[78:79], v[70:73], off offset:256
	global_store_dwordx4 v[58:59], v[62:65], off
	global_store_dwordx4 v[46:47], v[42:45], off
	global_store_dwordx4 v[30:31], v[26:29], off
	global_store_dwordx4 v[14:15], v[10:13], off
	global_store_dwordx4 v[14:15], v[4:7], off offset:256
	s_cbranch_vccz .LBB0_429
	s_waitcnt vmcnt(0)
	s_cmpk_gt_u32 s19, 0xff
	v_readlane_b32 s40, v254, 1
	s_cbranch_scc1 .LBB0_440
	s_barrier

; #define PG8_STAGE(bufoff, gbase, voff) do { _Pragma("unroll") for (int _i = 0; _i < 2; ++_i) \
;         __builtin_amdgcn_global_load_lds((const unsigned*)((const char*)(gbase) + (voff)[_i]), (LAS unsigned*)(lds + (bufoff) + ldsw + _i * 8192), 16, 0, 0); } while (0)
; #define PG8_LDA(dst, b, h) do { _Pragma("unroll") for (int m = 0; m < 4; ++m) _Pragma("unroll") for (int k = 0; k < 2; ++k) dst[m][k] = *(const LAS bf16x8*)(lds + PG8_SA(b, h) + aoff + m * 2048 + k * 1024); } while (0)
; #define PG8_LDB(dst, b, h) do { _Pragma("unroll") for (int n = 0; n < 2; ++n) _Pragma("unroll") for (int k = 0; k < 2; ++k) dst[n][k] = *(const LAS bf16x8*)(lds + PG8_SB(b, h) + boff + n * 2048 + k * 1024); } while (0)
; #define PG8_MMA(ai, bj, At, Bt) do { __builtin_amdgcn_s_setprio(1); _Pragma("unroll") for (int m = 0; m < 4; ++m) _Pragma("unroll") for (int n = 0; n < 2; ++n) _Pragma("unroll") for (int k = 0; k < 2; ++k) \
;         acc[ai][bj][m][n] = __builtin_amdgcn_mfma_f32_16x16x32_bf16(Bt[n][k], At[m][k], acc[ai][bj][m][n], 0, 0, 0); __builtin_amdgcn_s_setprio(0); } while (0)
; #define PG8_WAIT_V(n) asm volatile("s_waitcnt vmcnt(" #n ")" ::: "memory")
; #define PG8_WAIT_L(n) asm volatile("s_waitcnt lgkmcnt(" #n ")" ::: "memory")
; #define PG8_BAR __builtin_amdgcn_s_barrier()
; #define PG8_SCHED __builtin_amdgcn_sched_barrier(0)
; template <class Epi>
; DEVI void gemm_phase(LAS unsigned char* lds, const Gemm g, const Epi& E) {
;     ...
;             PG8_LDB(B0, 0, 0); PG8_SCHED; PG8_LDA(At, 0, 0); PG8_STAGE(PG8_SA(1, 1), a1 + hstepA, voffA);
;             PG8_WAIT_L(8); PG8_BAR; PG8_WAIT_L(0); PG8_MMA(0, 0, At, B0); PG8_BAR; PG8_SCHED;
;             PG8_LDB(B1, 0, 1); PG8_STAGE(PG8_SB(0, 0), b2, voffB);
;             PG8_BAR; PG8_WAIT_L(0); PG8_MMA(0, 1, At, B1); PG8_BAR;
;             PG8_LDA(At, 0, 1); PG8_STAGE(PG8_SA(0, 0), a2, voffA);
;             PG8_BAR; PG8_WAIT_L(0); PG8_MMA(1, 0, At, B0); PG8_BAR; PG8_SCHED;
;             PG8_STAGE(PG8_SB(0, 1), b2 + hstepB, voffB);
;             PG8_WAIT_V(6); PG8_BAR; PG8_MMA(1, 1, At, B1); PG8_BAR;
.LBB0_452:
	s_add_u32 s7, s8, s5
	s_addc_u32 s50, s9, 0
	s_add_u32 s51, s7, 0x100
	s_addc_u32 s52, s50, 0
	s_and_b64 s[48:49], s[46:47], exec
	s_cselect_b32 s87, s15, s52
	s_cselect_b32 s86, s14, s51
	s_add_u32 s5, s10, s5
	s_addc_u32 s48, s11, 0
	s_add_u32 s5, s5, 0x100
	s_addc_u32 s48, s48, 0
	s_add_i32 s54, 0, 0x10000
	s_and_b64 s[46:47], s[46:47], exec
	s_cselect_b32 s89, s3, s48
	s_cselect_b32 s88, s2, s5
	s_add_u32 s90, s7, 0x40080
	s_addc_u32 s91, s50, 0
	s_add_i32 s53, s54, s27
	s_add_i32 m0, s38, 0xc000
	s_add_i32 s55, s38, 0xe000
	s_add_i32 s52, 0, 0x14000
	s_add_i32 s51, s53, 0x2000
	s_add_u32 s82, s88, 0x40000
	v_add_u32_e32 v141, s54, v139
	s_addc_u32 s83, s89, 0
	s_add_i32 s93, s52, s27
	ds_read_b128 v[142:145], v141
	ds_read_b128 v[146:149], v141 offset:1024
	ds_read_b128 v[150:153], v141 offset:2048
	ds_read_b128 v[176:179], v141 offset:3072
	s_add_i32 s92, s93, 0x2000
	s_add_i32 s49, 0, 0x18000
	s_add_u32 s68, s86, 0x40000
	s_addc_u32 s69, s87, 0
	s_add_i32 s48, s49, s27
	s_add_i32 s7, 0, 0x1c000
	s_add_i32 s5, s48, 0x2000
	s_add_u32 s46, s88, 0x40080
	s_addc_u32 s47, s89, 0
	s_add_i32 s50, s7, s27
	s_add_i32 vcc_lo, s50, 0x2000
	v_lshl_add_u64 v[162:163], s[90:91], 0, v[136:137]
	ds_read_b128 v[180:183], v140
	ds_read_b128 v[184:187], v140 offset:1024
	ds_read_b128 v[188:191], v140 offset:2048
	ds_read_b128 v[192:195], v140 offset:3072
	ds_read_b128 v[196:199], v140 offset:4096
	ds_read_b128 v[200:203], v140 offset:5120
	ds_read_b128 v[204:207], v140 offset:6144
	ds_read_b128 v[214:217], v140 offset:7168
	global_load_lds_dwordx4 v[162:163], off
	v_lshl_add_u64 v[162:163], s[90:91], 0, v[132:133]
	s_mov_b32 m0, s55
	s_nop 0
	global_load_lds_dwordx4 v[162:163], off
	s_waitcnt lgkmcnt(8)
	s_barrier
	s_waitcnt lgkmcnt(0)
	s_setprio 1
	v_mfma_f32_16x16x32_bf16 v[126:129], v[142:145], v[180:183], v[126:129]
	v_mfma_f32_16x16x32_bf16 v[122:125], v[150:153], v[180:183], v[122:125]
	v_mfma_f32_16x16x32_bf16 v[118:121], v[142:145], v[188:191], v[118:121]
	v_mfma_f32_16x16x32_bf16 v[114:117], v[150:153], v[188:191], v[114:117]
	v_mfma_f32_16x16x32_bf16 v[102:105], v[142:145], v[196:199], v[102:105]
	v_mfma_f32_16x16x32_bf16 v[98:101], v[150:153], v[196:199], v[98:101]
	v_mfma_f32_16x16x32_bf16 v[86:89], v[142:145], v[204:207], v[86:89]
	v_mfma_f32_16x16x32_bf16 v[82:85], v[150:153], v[204:207], v[82:85]
	v_mfma_f32_16x16x32_bf16 v[126:129], v[146:149], v[184:187], v[126:129]
	v_mfma_f32_16x16x32_bf16 v[122:125], v[176:179], v[184:187], v[122:125]
	v_mfma_f32_16x16x32_bf16 v[118:121], v[146:149], v[192:195], v[118:121]
	v_mfma_f32_16x16x32_bf16 v[114:117], v[176:179], v[192:195], v[114:117]
	v_mfma_f32_16x16x32_bf16 v[102:105], v[146:149], v[200:203], v[102:105]
	v_mfma_f32_16x16x32_bf16 v[98:101], v[176:179], v[200:203], v[98:101]
	v_mfma_f32_16x16x32_bf16 v[86:89], v[146:149], v[214:217], v[86:89]
	v_mfma_f32_16x16x32_bf16 v[82:85], v[176:179], v[214:217], v[82:85]
	s_setprio 0
	s_barrier
	s_mov_b32 m0, s53
	v_add_u32_e32 v141, s52, v139
	v_lshl_add_u64 v[162:163], s[88:89], 0, v[134:135]
	ds_read_b128 v[218:221], v141
	ds_read_b128 v[222:225], v141 offset:1024
	ds_read_b128 v[226:229], v141 offset:2048
	ds_read_b128 v[230:233], v141 offset:3072
	global_load_lds_dwordx4 v[162:163], off
	v_lshl_add_u64 v[164:165], s[88:89], 0, v[130:131]
	s_mov_b32 m0, s51
	s_nop 0
	global_load_lds_dwordx4 v[164:165], off
	s_barrier
	s_waitcnt lgkmcnt(0)
	s_setprio 1
	v_mfma_f32_16x16x32_bf16 v[110:113], v[218:221], v[180:183], v[110:113]
	v_mfma_f32_16x16x32_bf16 v[106:109], v[226:229], v[180:183], v[106:109]
	v_mfma_f32_16x16x32_bf16 v[94:97], v[218:221], v[188:191], v[94:97]
	v_mfma_f32_16x16x32_bf16 v[90:93], v[226:229], v[188:191], v[90:93]
	v_mfma_f32_16x16x32_bf16 v[78:81], v[218:221], v[196:199], v[78:81]
	v_mfma_f32_16x16x32_bf16 v[74:77], v[226:229], v[196:199], v[74:77]
	v_mfma_f32_16x16x32_bf16 v[70:73], v[218:221], v[204:207], v[70:73]
	v_mfma_f32_16x16x32_bf16 v[66:69], v[226:229], v[204:207], v[66:69]
	v_mfma_f32_16x16x32_bf16 v[110:113], v[222:225], v[184:187], v[110:113]
	v_mfma_f32_16x16x32_bf16 v[106:109], v[230:233], v[184:187], v[106:109]
	v_mfma_f32_16x16x32_bf16 v[94:97], v[222:225], v[192:195], v[94:97]
	v_mfma_f32_16x16x32_bf16 v[90:93], v[230:233], v[192:195], v[90:93]
	v_mfma_f32_16x16x32_bf16 v[78:81], v[222:225], v[200:203], v[78:81]
	v_mfma_f32_16x16x32_bf16 v[74:77], v[230:233], v[200:203], v[74:77]
	v_mfma_f32_16x16x32_bf16 v[70:73], v[222:225], v[214:217], v[70:73]
	v_mfma_f32_16x16x32_bf16 v[66:69], v[230:233], v[214:217], v[66:69]
	s_setprio 0
	s_mov_b32 m0, s38
	v_lshl_add_u64 v[208:209], s[86:87], 0, v[136:137]
	s_barrier
	ds_read_b128 v[180:183], v140 offset:16384
	ds_read_b128 v[184:187], v140 offset:17408
	ds_read_b128 v[188:191], v140 offset:18432
	ds_read_b128 v[192:195], v140 offset:19456
	ds_read_b128 v[196:199], v140 offset:20480
	ds_read_b128 v[200:203], v140 offset:21504
	ds_read_b128 v[204:207], v140 offset:22528
	ds_read_b128 v[214:217], v140 offset:23552
	global_load_lds_dwordx4 v[208:209], off
	v_lshl_add_u64 v[234:235], s[86:87], 0, v[132:133]
	s_mov_b32 m0, s39
	s_nop 0
	global_load_lds_dwordx4 v[234:235], off
	s_barrier
; #define PG8_STAGE(bufoff, gbase, voff) do { _Pragma("unroll") for (int _i = 0; _i < 2; ++_i) \
;         __builtin_amdgcn_global_load_lds((const unsigned*)((const char*)(gbase) + (voff)[_i]), (LAS unsigned*)(lds + (bufoff) + ldsw + _i * 8192), 16, 0, 0); } while (0)
; #define PG8_LDA(dst, b, h) do { _Pragma("unroll") for (int m = 0; m < 4; ++m) _Pragma("unroll") for (int k = 0; k < 2; ++k) dst[m][k] = *(const LAS bf16x8*)(lds + PG8_SA(b, h) + aoff + m * 2048 + k * 1024); } while (0)
; #define PG8_LDB(dst, b, h) do { _Pragma("unroll") for (int n = 0; n < 2; ++n) _Pragma("unroll") for (int k = 0; k < 2; ++k) dst[n][k] = *(const LAS bf16x8*)(lds + PG8_SB(b, h) + boff + n * 2048 + k * 1024); } while (0)
; #define PG8_WAIT_V(n) asm volatile("s_waitcnt vmcnt(" #n ")" ::: "memory")
; #define PG8_WAIT_L(n) asm volatile("s_waitcnt lgkmcnt(" #n ")" ::: "memory")
; #define PG8_BAR __builtin_amdgcn_s_barrier()
; #define PG8_SCHED __builtin_amdgcn_sched_barrier(0)
; template <class Epi>
; DEVI void gemm_phase(LAS unsigned char* lds, const Gemm g, const Epi& E) {
;     ...
;             PG8_LDB(B0, 0, 0); PG8_SCHED; PG8_LDA(At, 0, 0); PG8_STAGE(PG8_SA(1, 1), a1 + hstepA, voffA);
;             PG8_WAIT_L(8); PG8_BAR; PG8_WAIT_L(0); PG8_MMA(0, 0, At, B0); PG8_BAR; PG8_SCHED;
;             PG8_LDB(B1, 0, 1); PG8_STAGE(PG8_SB(0, 0), b2, voffB);
;             PG8_BAR; PG8_WAIT_L(0); PG8_MMA(0, 1, At, B1); PG8_BAR;
;             PG8_LDA(At, 0, 1); PG8_STAGE(PG8_SA(0, 0), a2, voffA);
;             PG8_BAR; PG8_WAIT_L(0); PG8_MMA(1, 0, At, B0); PG8_BAR; PG8_SCHED;
;             PG8_STAGE(PG8_SB(0, 1), b2 + hstepB, voffB);
;             PG8_WAIT_V(6); PG8_BAR; PG8_MMA(1, 1, At, B1); PG8_BAR;
;             PG8_LDB(B0, 1, 0); PG8_SCHED; PG8_LDA(At, 1, 0); PG8_STAGE(PG8_SA(0, 1), a2 + hstepA, voffA);
;             PG8_WAIT_L(8); PG8_BAR; PG8_WAIT_L(0); PG8_MMA(0, 0, At, B0); PG8_BAR; PG8_SCHED;
;             PG8_LDB(B1, 1, 1); PG8_STAGE(PG8_SB(1, 0), b3, voffB);
;             PG8_BAR; PG8_WAIT_L(0); PG8_MMA(0, 1, At, B1); PG8_BAR;
;             PG8_LDA(At, 1, 1); PG8_STAGE(PG8_SA(1, 0), a3, voffA);
;             PG8_BAR; PG8_WAIT_L(0); PG8_MMA(1, 0, At, B0); PG8_BAR; PG8_SCHED;
;             PG8_STAGE(PG8_SB(1, 1), b3 + hstepB, voffB);
;             PG8_WAIT_V(6); PG8_BAR; PG8_MMA(1, 1, At, B1); PG8_BAR;
	s_waitcnt lgkmcnt(0)
	s_setprio 1
	v_mfma_f32_16x16x32_bf16 v[62:65], v[142:145], v[180:183], v[62:65]
	v_mfma_f32_16x16x32_bf16 v[58:61], v[150:153], v[180:183], v[58:61]
	v_mfma_f32_16x16x32_bf16 v[54:57], v[142:145], v[188:191], v[54:57]
	v_mfma_f32_16x16x32_bf16 v[50:53], v[150:153], v[188:191], v[50:53]
	v_mfma_f32_16x16x32_bf16 v[38:41], v[142:145], v[196:199], v[38:41]
	v_mfma_f32_16x16x32_bf16 v[34:37], v[150:153], v[196:199], v[34:37]
	v_mfma_f32_16x16x32_bf16 v[22:25], v[142:145], v[204:207], v[22:25]
	v_mfma_f32_16x16x32_bf16 v[18:21], v[150:153], v[204:207], v[18:21]
	v_mfma_f32_16x16x32_bf16 v[62:65], v[146:149], v[184:187], v[62:65]
	v_mfma_f32_16x16x32_bf16 v[58:61], v[176:179], v[184:187], v[58:61]
	v_mfma_f32_16x16x32_bf16 v[54:57], v[146:149], v[192:195], v[54:57]
	v_mfma_f32_16x16x32_bf16 v[50:53], v[176:179], v[192:195], v[50:53]
	v_mfma_f32_16x16x32_bf16 v[38:41], v[146:149], v[200:203], v[38:41]
	v_mfma_f32_16x16x32_bf16 v[34:37], v[176:179], v[200:203], v[34:37]
	v_mfma_f32_16x16x32_bf16 v[22:25], v[146:149], v[214:217], v[22:25]
	v_mfma_f32_16x16x32_bf16 v[18:21], v[176:179], v[214:217], v[18:21]
	s_setprio 0
	s_barrier
	s_mov_b32 m0, s93
	v_lshl_add_u64 v[142:143], s[82:83], 0, v[134:135]
	global_load_lds_dwordx4 v[142:143], off
	v_lshl_add_u64 v[142:143], s[82:83], 0, v[130:131]
	s_mov_b32 m0, s92
	s_nop 0
	global_load_lds_dwordx4 v[142:143], off
	s_waitcnt vmcnt(6)
	s_barrier
	s_setprio 1
	v_mfma_f32_16x16x32_bf16 v[46:49], v[218:221], v[180:183], v[46:49]
	v_mfma_f32_16x16x32_bf16 v[42:45], v[226:229], v[180:183], v[42:45]
	v_mfma_f32_16x16x32_bf16 v[30:33], v[218:221], v[188:191], v[30:33]
	v_mfma_f32_16x16x32_bf16 v[26:29], v[226:229], v[188:191], v[26:29]
	v_mfma_f32_16x16x32_bf16 v[14:17], v[218:221], v[196:199], v[14:17]
	v_mfma_f32_16x16x32_bf16 v[10:13], v[226:229], v[196:199], v[10:13]
	v_mfma_f32_16x16x32_bf16 v[4:7], v[218:221], v[204:207], v[4:7]
	v_mfma_f32_16x16x32_bf16 v[0:3], v[226:229], v[204:207], v[0:3]
	v_mfma_f32_16x16x32_bf16 v[46:49], v[222:225], v[184:187], v[46:49]
	v_mfma_f32_16x16x32_bf16 v[42:45], v[230:233], v[184:187], v[42:45]
	v_mfma_f32_16x16x32_bf16 v[30:33], v[222:225], v[192:195], v[30:33]
	v_mfma_f32_16x16x32_bf16 v[26:29], v[230:233], v[192:195], v[26:29]
	v_mfma_f32_16x16x32_bf16 v[14:17], v[222:225], v[200:203], v[14:17]
	v_mfma_f32_16x16x32_bf16 v[10:13], v[230:233], v[200:203], v[10:13]
	v_mfma_f32_16x16x32_bf16 v[4:7], v[222:225], v[214:217], v[4:7]
	v_mfma_f32_16x16x32_bf16 v[0:3], v[230:233], v[214:217], v[0:3]
	s_setprio 0
	v_add_u32_e32 v141, s49, v139
	s_barrier
	ds_read_b128 v[142:145], v141
	ds_read_b128 v[146:149], v141 offset:1024
	ds_read_b128 v[150:153], v141 offset:2048
	ds_read_b128 v[176:179], v141 offset:3072
	s_mov_b32 m0, s40
	v_lshl_add_u64 v[218:219], s[68:69], 0, v[136:137]
	ds_read_b128 v[180:183], v140 offset:32768
	ds_read_b128 v[184:187], v140 offset:33792
	ds_read_b128 v[188:191], v140 offset:34816
	ds_read_b128 v[192:195], v140 offset:35840
	ds_read_b128 v[196:199], v140 offset:36864
	ds_read_b128 v[200:203], v140 offset:37888
	ds_read_b128 v[204:207], v140 offset:38912
	ds_read_b128 v[214:217], v140 offset:39936
	global_load_lds_dwordx4 v[218:219], off
	v_lshl_add_u64 v[218:219], s[68:69], 0, v[132:133]
	s_mov_b32 m0, s41
	s_nop 0
	global_load_lds_dwordx4 v[218:219], off
	s_waitcnt lgkmcnt(8)
	s_barrier
	s_waitcnt lgkmcnt(0)
	s_setprio 1
	v_mfma_f32_16x16x32_bf16 v[126:129], v[142:145], v[180:183], v[126:129]
	v_mfma_f32_16x16x32_bf16 v[122:125], v[150:153], v[180:183], v[122:125]
	v_mfma_f32_16x16x32_bf16 v[118:121], v[142:145], v[188:191], v[118:121]
	v_mfma_f32_16x16x32_bf16 v[114:117], v[150:153], v[188:191], v[114:117]
	v_mfma_f32_16x16x32_bf16 v[102:105], v[142:145], v[196:199], v[102:105]
	v_mfma_f32_16x16x32_bf16 v[98:101], v[150:153], v[196:199], v[98:101]
	v_mfma_f32_16x16x32_bf16 v[86:89], v[142:145], v[204:207], v[86:89]
	v_mfma_f32_16x16x32_bf16 v[82:85], v[150:153], v[204:207], v[82:85]
	v_mfma_f32_16x16x32_bf16 v[126:129], v[146:149], v[184:187], v[126:129]
	v_mfma_f32_16x16x32_bf16 v[122:125], v[176:179], v[184:187], v[122:125]
	v_mfma_f32_16x16x32_bf16 v[118:121], v[146:149], v[192:195], v[118:121]
	v_mfma_f32_16x16x32_bf16 v[114:117], v[176:179], v[192:195], v[114:117]
	v_mfma_f32_16x16x32_bf16 v[102:105], v[146:149], v[200:203], v[102:105]
	v_mfma_f32_16x16x32_bf16 v[98:101], v[176:179], v[200:203], v[98:101]
	v_mfma_f32_16x16x32_bf16 v[86:89], v[146:149], v[214:217], v[86:89]
	v_mfma_f32_16x16x32_bf16 v[82:85], v[176:179], v[214:217], v[82:85]
	s_setprio 0
	s_barrier
	s_mov_b32 m0, s48
	v_add_u32_e32 v141, s7, v139
	v_lshl_add_u64 v[162:163], v[162:163], 0, s[70:71]
	ds_read_b128 v[218:221], v141
	ds_read_b128 v[222:225], v141 offset:1024
	ds_read_b128 v[226:229], v141 offset:2048
	ds_read_b128 v[230:233], v141 offset:3072
	global_load_lds_dwordx4 v[162:163], off
	v_lshl_add_u64 v[162:163], v[164:165], 0, s[70:71]
	s_mov_b32 m0, s5
	s_nop 0
	global_load_lds_dwordx4 v[162:163], off
	s_barrier
	s_waitcnt lgkmcnt(0)
	s_setprio 1
	v_mfma_f32_16x16x32_bf16 v[110:113], v[218:221], v[180:183], v[110:113]
	v_mfma_f32_16x16x32_bf16 v[106:109], v[226:229], v[180:183], v[106:109]
	v_mfma_f32_16x16x32_bf16 v[94:97], v[218:221], v[188:191], v[94:97]
	v_mfma_f32_16x16x32_bf16 v[90:93], v[226:229], v[188:191], v[90:93]
	v_mfma_f32_16x16x32_bf16 v[78:81], v[218:221], v[196:199], v[78:81]
	v_mfma_f32_16x16x32_bf16 v[74:77], v[226:229], v[196:199], v[74:77]
	v_mfma_f32_16x16x32_bf16 v[70:73], v[218:221], v[204:207], v[70:73]
	v_mfma_f32_16x16x32_bf16 v[66:69], v[226:229], v[204:207], v[66:69]
	v_mfma_f32_16x16x32_bf16 v[110:113], v[222:225], v[184:187], v[110:113]
	v_mfma_f32_16x16x32_bf16 v[106:109], v[230:233], v[184:187], v[106:109]
	v_mfma_f32_16x16x32_bf16 v[94:97], v[222:225], v[192:195], v[94:97]
	v_mfma_f32_16x16x32_bf16 v[90:93], v[230:233], v[192:195], v[90:93]
	v_mfma_f32_16x16x32_bf16 v[78:81], v[222:225], v[200:203], v[78:81]
	v_mfma_f32_16x16x32_bf16 v[74:77], v[230:233], v[200:203], v[74:77]
	v_mfma_f32_16x16x32_bf16 v[70:73], v[222:225], v[214:217], v[70:73]
	v_mfma_f32_16x16x32_bf16 v[66:69], v[230:233], v[214:217], v[66:69]
	s_setprio 0
	s_mov_b32 m0, s42
	v_lshl_add_u64 v[162:163], v[208:209], 0, s[70:71]
	s_barrier
; #define PG8_STAGE(bufoff, gbase, voff) do { _Pragma("unroll") for (int _i = 0; _i < 2; ++_i) \
;         __builtin_amdgcn_global_load_lds((const unsigned*)((const char*)(gbase) + (voff)[_i]), (LAS unsigned*)(lds + (bufoff) + ldsw + _i * 8192), 16, 0, 0); } while (0)
; #define PG8_LDA(dst, b, h) do { _Pragma("unroll") for (int m = 0; m < 4; ++m) _Pragma("unroll") for (int k = 0; k < 2; ++k) dst[m][k] = *(const LAS bf16x8*)(lds + PG8_SA(b, h) + aoff + m * 2048 + k * 1024); } while (0)
; #define PG8_LDB(dst, b, h) do { _Pragma("unroll") for (int n = 0; n < 2; ++n) _Pragma("unroll") for (int k = 0; k < 2; ++k) dst[n][k] = *(const LAS bf16x8*)(lds + PG8_SB(b, h) + boff + n * 2048 + k * 1024); } while (0)
; #define PG8_WAIT_V(n) asm volatile("s_waitcnt vmcnt(" #n ")" ::: "memory")
; #define PG8_WAIT_L(n) asm volatile("s_waitcnt lgkmcnt(" #n ")" ::: "memory")
; #define PG8_BAR __builtin_amdgcn_s_barrier()
; #define PG8_SCHED __builtin_amdgcn_sched_barrier(0)
; template <class Epi>
; DEVI void gemm_phase(LAS unsigned char* lds, const Gemm g, const Epi& E) {
;     ...
;             PG8_LDB(B0, 0, 0); PG8_SCHED; PG8_LDA(At, 0, 0); PG8_STAGE(PG8_SA(1, 1), a1 + hstepA, voffA);
;             PG8_WAIT_L(8); PG8_BAR; PG8_WAIT_L(0); PG8_MMA(0, 0, At, B0); PG8_BAR; PG8_SCHED;
;             PG8_LDB(B1, 0, 1); PG8_STAGE(PG8_SB(0, 0), b2, voffB);
;             PG8_BAR; PG8_WAIT_L(0); PG8_MMA(0, 1, At, B1); PG8_BAR;
;             PG8_LDA(At, 0, 1); PG8_STAGE(PG8_SA(0, 0), a2, voffA);
;             PG8_BAR; PG8_WAIT_L(0); PG8_MMA(1, 0, At, B0); PG8_BAR; PG8_SCHED;
;             PG8_STAGE(PG8_SB(0, 1), b2 + hstepB, voffB);
;             PG8_WAIT_V(6); PG8_BAR; PG8_MMA(1, 1, At, B1); PG8_BAR;
;             PG8_LDB(B0, 1, 0); PG8_SCHED; PG8_LDA(At, 1, 0); PG8_STAGE(PG8_SA(0, 1), a2 + hstepA, voffA);
;             PG8_WAIT_L(8); PG8_BAR; PG8_WAIT_L(0); PG8_MMA(0, 0, At, B0); PG8_BAR; PG8_SCHED;
;             PG8_LDB(B1, 1, 1); PG8_STAGE(PG8_SB(1, 0), b3, voffB);
;             PG8_BAR; PG8_WAIT_L(0); PG8_MMA(0, 1, At, B1); PG8_BAR;
;             PG8_LDA(At, 1, 1); PG8_STAGE(PG8_SA(1, 0), a3, voffA);
;             PG8_BAR; PG8_WAIT_L(0); PG8_MMA(1, 0, At, B0); PG8_BAR; PG8_SCHED;
;             PG8_STAGE(PG8_SB(1, 1), b3 + hstepB, voffB);
;             PG8_WAIT_V(6); PG8_BAR; PG8_MMA(1, 1, At, B1); PG8_BAR;
;         }
	ds_read_b128 v[180:183], v140 offset:49152
	ds_read_b128 v[184:187], v140 offset:50176
	ds_read_b128 v[188:191], v140 offset:51200
	ds_read_b128 v[192:195], v140 offset:52224
	ds_read_b128 v[196:199], v140 offset:53248
	ds_read_b128 v[200:203], v140 offset:54272
	ds_read_b128 v[204:207], v140 offset:55296
	ds_read_b128 v[214:217], v140 offset:56320
	global_load_lds_dwordx4 v[162:163], off
	v_lshl_add_u64 v[162:163], v[234:235], 0, s[70:71]
	s_mov_b32 m0, s43
	s_nop 0
	global_load_lds_dwordx4 v[162:163], off
	s_barrier
	s_waitcnt lgkmcnt(0)
	s_setprio 1
	v_mfma_f32_16x16x32_bf16 v[62:65], v[142:145], v[180:183], v[62:65]
	v_mfma_f32_16x16x32_bf16 v[58:61], v[150:153], v[180:183], v[58:61]
	v_mfma_f32_16x16x32_bf16 v[54:57], v[142:145], v[188:191], v[54:57]
	v_mfma_f32_16x16x32_bf16 v[50:53], v[150:153], v[188:191], v[50:53]
	v_mfma_f32_16x16x32_bf16 v[38:41], v[142:145], v[196:199], v[38:41]
	v_mfma_f32_16x16x32_bf16 v[34:37], v[150:153], v[196:199], v[34:37]
	v_mfma_f32_16x16x32_bf16 v[22:25], v[142:145], v[204:207], v[22:25]
	v_mfma_f32_16x16x32_bf16 v[18:21], v[150:153], v[204:207], v[18:21]
	v_mfma_f32_16x16x32_bf16 v[62:65], v[146:149], v[184:187], v[62:65]
	v_mfma_f32_16x16x32_bf16 v[58:61], v[176:179], v[184:187], v[58:61]
	v_mfma_f32_16x16x32_bf16 v[54:57], v[146:149], v[192:195], v[54:57]
	v_mfma_f32_16x16x32_bf16 v[50:53], v[176:179], v[192:195], v[50:53]
	v_mfma_f32_16x16x32_bf16 v[38:41], v[146:149], v[200:203], v[38:41]
	v_mfma_f32_16x16x32_bf16 v[34:37], v[176:179], v[200:203], v[34:37]
	v_mfma_f32_16x16x32_bf16 v[22:25], v[146:149], v[214:217], v[22:25]
	v_mfma_f32_16x16x32_bf16 v[18:21], v[176:179], v[214:217], v[18:21]
	s_setprio 0
	s_barrier
	s_mov_b32 m0, s50
	v_lshl_add_u64 v[142:143], s[46:47], 0, v[134:135]
	global_load_lds_dwordx4 v[142:143], off
	v_lshl_add_u64 v[142:143], s[46:47], 0, v[130:131]
	s_mov_b32 m0, vcc_lo
	s_nop 0
	global_load_lds_dwordx4 v[142:143], off
	s_waitcnt vmcnt(6)
	s_barrier
	s_setprio 1
	v_mfma_f32_16x16x32_bf16 v[46:49], v[218:221], v[180:183], v[46:49]
	v_mfma_f32_16x16x32_bf16 v[42:45], v[226:229], v[180:183], v[42:45]
	v_mfma_f32_16x16x32_bf16 v[30:33], v[218:221], v[188:191], v[30:33]
	v_mfma_f32_16x16x32_bf16 v[26:29], v[226:229], v[188:191], v[26:29]
	v_mfma_f32_16x16x32_bf16 v[14:17], v[218:221], v[196:199], v[14:17]
	v_mfma_f32_16x16x32_bf16 v[10:13], v[226:229], v[196:199], v[10:13]
	v_mfma_f32_16x16x32_bf16 v[4:7], v[218:221], v[204:207], v[4:7]
	v_mfma_f32_16x16x32_bf16 v[0:3], v[226:229], v[204:207], v[0:3]
	v_mfma_f32_16x16x32_bf16 v[46:49], v[222:225], v[184:187], v[46:49]
	v_mfma_f32_16x16x32_bf16 v[42:45], v[230:233], v[184:187], v[42:45]
	v_mfma_f32_16x16x32_bf16 v[30:33], v[222:225], v[192:195], v[30:33]
	v_mfma_f32_16x16x32_bf16 v[26:29], v[230:233], v[192:195], v[26:29]
	v_mfma_f32_16x16x32_bf16 v[14:17], v[222:225], v[200:203], v[14:17]
	v_mfma_f32_16x16x32_bf16 v[10:13], v[230:233], v[200:203], v[10:13]
	v_mfma_f32_16x16x32_bf16 v[4:7], v[222:225], v[214:217], v[4:7]
	v_mfma_f32_16x16x32_bf16 v[0:3], v[230:233], v[214:217], v[0:3]
	s_setprio 0
	s_movk_i32 s5, 0x100
	s_andn2_b64 vcc, exec, s[16:17]
	s_mov_b64 s[46:47], -1
	s_mov_b64 s[16:17], 0
	s_barrier
	s_cbranch_vccz .LBB0_452
; template <class Epi>
; DEVI void gemm_phase(LAS unsigned char* lds, const Gemm g, const Epi& E) {
;     ...
;                     if constexpr (Epi::PAIR) E.pair8(cur.b, r, cur.pn * HALF + wc * 32 + 8 * fq, acc[ai][0][m][0] * rs, acc[ai][0][m][1] * rs, acc[ai][1][m][0] * rs, acc[ai][1][m][1] * rs);
;                     else
; #pragma unroll
;                     for (int bj = 0; bj < 2; ++bj) {
;                         const int c = col0 + bj * HALF; f32x4 v0 = acc[ai][bj][m][0], v1 = acc[ai][bj][m][1];
;                         if constexpr (Epi::RS) { v0 = v0 * rs; v1 = v1 * rs; }
;                         if constexpr (Epi::PRE) part += E.frag_pre8(cur.b, r, c, v0, v1, pre[mm][bj][0], pre[mm][bj][1]);
;                         else if constexpr (Epi::PERM) E.frag8(cur.b, r, c, v0, v1);
;                         else { E.frag(cur.b, r, c, v0); E.frag(cur.b, r, c + 16, v1); }
;                     }
	s_ashr_i32 s8, s44, 2
	s_ashr_i32 s9, s8, 31
	s_lshl_b64 s[8:9], s[8:9], 21
	s_add_u32 s5, s62, s8
	s_addc_u32 s7, s63, s9
	s_lshl_b32 s8, s44, 9
	v_lshl_add_u32 v142, s66, 8, v138
	s_and_b32 s8, s8, 0x600
	s_add_u32 s8, s5, s8
	v_ashrrev_i32_e32 v143, 31, v142
	s_addc_u32 s9, s7, 0
	v_lshlrev_b64 v[144:145], 11, v[142:143]
	v_cvt_pk_bf16_f32 v110, v110, v111
	v_cvt_pk_bf16_f32 v111, v112, v113
	v_cvt_pk_bf16_f32 v112, v106, v107
	v_or_b32_e32 v106, 16, v142
	v_lshl_add_u64 v[144:145], s[8:9], 0, v[144:145]
	v_ashrrev_i32_e32 v107, 31, v106
	v_cvt_pk_bf16_f32 v126, v126, v127
	v_cvt_pk_bf16_f32 v127, v128, v129
	v_cvt_pk_bf16_f32 v128, v122, v123
	v_lshl_add_u64 v[122:123], v[144:145], 0, v[8:9]
	v_cvt_pk_bf16_f32 v113, v108, v109
	v_lshlrev_b64 v[106:107], 11, v[106:107]
	v_cvt_pk_bf16_f32 v94, v94, v95
	v_cvt_pk_bf16_f32 v95, v96, v97
	v_cvt_pk_bf16_f32 v96, v90, v91
	v_or_b32_e32 v90, 32, v142
	global_store_dwordx4 v[122:123], v[110:113], off offset:256
	v_ashrrev_i32_e32 v91, 31, v90
	v_cvt_pk_bf16_f32 v97, v92, v93
	v_lshl_add_u64 v[110:111], s[8:9], 0, v[106:107]
	v_lshl_add_u64 v[110:111], v[110:111], 0, v[8:9]
	v_lshlrev_b64 v[90:91], 11, v[90:91]
	v_cvt_pk_bf16_f32 v78, v78, v79
	v_cvt_pk_bf16_f32 v79, v80, v81
	v_cvt_pk_bf16_f32 v80, v74, v75
	v_or_b32_e32 v74, 48, v142
	global_store_dwordx4 v[110:111], v[94:97], off offset:256
	v_ashrrev_i32_e32 v75, 31, v74
	v_cvt_pk_bf16_f32 v81, v76, v77
	v_lshl_add_u64 v[94:95], s[8:9], 0, v[90:91]
	v_lshl_add_u64 v[94:95], v[94:95], 0, v[8:9]
	v_lshlrev_b64 v[74:75], 11, v[74:75]
	s_mov_b32 s5, 0x40000
	global_store_dwordx4 v[94:95], v[78:81], off offset:256
	v_cvt_pk_bf16_f32 v62, v62, v63
	v_cvt_pk_bf16_f32 v63, v64, v65
	v_lshl_add_u64 v[78:79], s[8:9], 0, v[74:75]
	v_cvt_pk_bf16_f32 v65, v60, v61
	s_mov_b64 s[8:9], 0x40000
	v_add_co_u32_e32 v60, vcc, s5, v122
	v_cvt_pk_bf16_f32 v64, v58, v59
	v_lshl_add_u64 v[58:59], v[122:123], 0, s[8:9]
	v_addc_co_u32_e32 v61, vcc, 0, v123, vcc
	v_cvt_pk_bf16_f32 v46, v46, v47
	v_cvt_pk_bf16_f32 v47, v48, v49
	v_cvt_pk_bf16_f32 v48, v42, v43
	v_cvt_pk_bf16_f32 v49, v44, v45
	s_mov_b32 s5, 0x48000
	global_store_dwordx4 v[58:59], v[46:49], off offset:256
	s_mov_b64 s[8:9], 0x48000
	v_cvt_pk_bf16_f32 v30, v30, v31
	v_add_co_u32_e32 v48, vcc, s5, v122
	v_lshl_add_u64 v[46:47], v[122:123], 0, s[8:9]
	s_nop 0
	v_addc_co_u32_e32 v49, vcc, 0, v123, vcc
	v_cvt_pk_bf16_f32 v31, v32, v33
	v_cvt_pk_bf16_f32 v32, v26, v27
	v_cvt_pk_bf16_f32 v33, v28, v29
	s_mov_b32 s5, 0x50000
	global_store_dwordx4 v[46:47], v[30:33], off offset:256
	s_mov_b64 s[8:9], 0x50000
	v_cvt_pk_bf16_f32 v14, v14, v15
	v_add_co_u32_e32 v32, vcc, s5, v122
	v_lshl_add_u64 v[30:31], v[122:123], 0, s[8:9]
	s_nop 0
	v_addc_co_u32_e32 v33, vcc, 0, v123, vcc
	v_cvt_pk_bf16_f32 v15, v16, v17
	v_cvt_pk_bf16_f32 v16, v10, v11
	v_cvt_pk_bf16_f32 v17, v12, v13
	s_mov_b32 s5, 0x58000
	global_store_dwordx4 v[30:31], v[14:17], off offset:256
	s_mov_b64 s[8:9], 0x58000
	v_cvt_pk_bf16_f32 v129, v124, v125
	v_add_co_u32_e32 v16, vcc, s5, v122
	v_cvt_pk_bf16_f32 v106, v118, v119
	s_nop 0
	v_addc_co_u32_e32 v17, vcc, 0, v123, vcc
	v_cvt_pk_bf16_f32 v107, v120, v121
	v_cvt_pk_bf16_f32 v108, v114, v115
	v_cvt_pk_bf16_f32 v109, v116, v117
	v_cvt_pk_bf16_f32 v90, v102, v103
	v_cvt_pk_bf16_f32 v91, v104, v105
	v_cvt_pk_bf16_f32 v92, v98, v99
	v_cvt_pk_bf16_f32 v93, v100, v101
	v_cvt_pk_bf16_f32 v74, v86, v87
	v_cvt_pk_bf16_f32 v75, v88, v89
	v_cvt_pk_bf16_f32 v76, v82, v83
	v_cvt_pk_bf16_f32 v77, v84, v85
	v_lshl_add_u64 v[78:79], v[78:79], 0, v[8:9]
	v_cvt_pk_bf16_f32 v70, v70, v71
	v_cvt_pk_bf16_f32 v71, v72, v73
	v_cvt_pk_bf16_f32 v72, v66, v67
	v_cvt_pk_bf16_f32 v73, v68, v69
	v_cvt_pk_bf16_f32 v42, v54, v55
	v_cvt_pk_bf16_f32 v43, v56, v57
	v_cvt_pk_bf16_f32 v44, v50, v51
	v_cvt_pk_bf16_f32 v45, v52, v53
	v_cvt_pk_bf16_f32 v26, v38, v39
	v_cvt_pk_bf16_f32 v27, v40, v41
	v_cvt_pk_bf16_f32 v28, v34, v35
	v_cvt_pk_bf16_f32 v29, v36, v37
	v_cvt_pk_bf16_f32 v10, v22, v23
	v_cvt_pk_bf16_f32 v11, v24, v25
	v_cvt_pk_bf16_f32 v12, v18, v19
	v_cvt_pk_bf16_f32 v13, v20, v21
	v_lshl_add_u64 v[14:15], v[122:123], 0, s[8:9]
	v_cvt_pk_bf16_f32 v4, v4, v5
	v_cvt_pk_bf16_f32 v5, v6, v7
	v_cvt_pk_bf16_f32 v6, v0, v1
	v_cvt_pk_bf16_f32 v7, v2, v3
	s_and_b64 vcc, exec, s[12:13]
	s_mov_b32 s44, s4
	s_mov_b32 s66, s6
	s_mov_b64 s[10:11], s[2:3]
	s_mov_b64 s[8:9], s[14:15]
	v_readlane_b32 s55, v254, 0
	s_movk_i32 s49, 0x2000
	s_movk_i32 s50, 0x1000
	s_movk_i32 s51, 0x800
	s_movk_i32 s52, 0x110
	s_movk_i32 s53, 0x3000
	global_store_dwordx4 v[122:123], v[126:129], off
	global_store_dwordx4 v[110:111], v[106:109], off
	global_store_dwordx4 v[94:95], v[90:93], off
	global_store_dwordx4 v[78:79], v[74:77], off
	global_store_dwordx4 v[78:79], v[70:73], off offset:256
	global_store_dwordx4 v[60:61], v[62:65], off
	global_store_dwordx4 v[48:49], v[42:45], off
	global_store_dwordx4 v[32:33], v[26:29], off
	global_store_dwordx4 v[16:17], v[10:13], off
	global_store_dwordx4 v[14:15], v[4:7], off offset:256
	s_cbranch_vccz .LBB0_445
	s_waitcnt vmcnt(0)
	s_cmpk_gt_u32 s0, 0xff
	v_readlane_b32 s40, v254, 1
	s_cbranch_scc1 .LBB0_456
	s_barrier

; #define PG8_STAGE(bufoff, gbase, voff) do { _Pragma("unroll") for (int _i = 0; _i < 2; ++_i) \
;         __builtin_amdgcn_global_load_lds((const unsigned*)((const char*)(gbase) + (voff)[_i]), (LAS unsigned*)(lds + (bufoff) + ldsw + _i * 8192), 16, 0, 0); } while (0)
; #define PG8_LDA(dst, b, h) do { _Pragma("unroll") for (int m = 0; m < 4; ++m) _Pragma("unroll") for (int k = 0; k < 2; ++k) dst[m][k] = *(const LAS bf16x8*)(lds + PG8_SA(b, h) + aoff + m * 2048 + k * 1024); } while (0)
; #define PG8_LDB(dst, b, h) do { _Pragma("unroll") for (int n = 0; n < 2; ++n) _Pragma("unroll") for (int k = 0; k < 2; ++k) dst[n][k] = *(const LAS bf16x8*)(lds + PG8_SB(b, h) + boff + n * 2048 + k * 1024); } while (0)
; #define PG8_MMA(ai, bj, At, Bt) do { __builtin_amdgcn_s_setprio(1); _Pragma("unroll") for (int m = 0; m < 4; ++m) _Pragma("unroll") for (int n = 0; n < 2; ++n) _Pragma("unroll") for (int k = 0; k < 2; ++k) \
;         acc[ai][bj][m][n] = __builtin_amdgcn_mfma_f32_16x16x32_bf16(Bt[n][k], At[m][k], acc[ai][bj][m][n], 0, 0, 0); __builtin_amdgcn_s_setprio(0); } while (0)
; #define PG8_WAIT_V(n) asm volatile("s_waitcnt vmcnt(" #n ")" ::: "memory")
; #define PG8_WAIT_L(n) asm volatile("s_waitcnt lgkmcnt(" #n ")" ::: "memory")
; #define PG8_BAR __builtin_amdgcn_s_barrier()
; #define PG8_SCHED __builtin_amdgcn_sched_barrier(0)
; template <class Epi>
; DEVI void gemm_phase(LAS unsigned char* lds, const Gemm g, const Epi& E) {
;     ...
;             PG8_LDB(B0, 0, 0); PG8_SCHED; PG8_LDA(At, 0, 0); PG8_STAGE(PG8_SA(1, 1), a1 + hstepA, voffA);
;             PG8_WAIT_L(8); PG8_BAR; PG8_WAIT_L(0); PG8_MMA(0, 0, At, B0); PG8_BAR; PG8_SCHED;
;             PG8_LDB(B1, 0, 1); PG8_STAGE(PG8_SB(0, 0), b2, voffB);
;             PG8_BAR; PG8_WAIT_L(0); PG8_MMA(0, 1, At, B1); PG8_BAR;
;             PG8_LDA(At, 0, 1); PG8_STAGE(PG8_SA(0, 0), a2, voffA);
;             PG8_BAR; PG8_WAIT_L(0); PG8_MMA(1, 0, At, B0); PG8_BAR; PG8_SCHED;
;             PG8_STAGE(PG8_SB(0, 1), b2 + hstepB, voffB);
;             PG8_WAIT_V(6); PG8_BAR; PG8_MMA(1, 1, At, B1); PG8_BAR;
;             PG8_LDB(B0, 1, 0); PG8_SCHED; PG8_LDA(At, 1, 0); PG8_STAGE(PG8_SA(0, 1), a2 + hstepA, voffA);
;             PG8_WAIT_L(8); PG8_BAR; PG8_WAIT_L(0); PG8_MMA(0, 0, At, B0); PG8_BAR; PG8_SCHED;
.LBB0_968:
	s_add_u32 s26, s68, 0xfffc0080
	s_addc_u32 s27, s69, -1
	s_add_i32 s38, 0, 0x10000
	v_add_u32_e32 v142, s38, v193
	ds_read_b128 v[130:133], v142
	ds_read_b128 v[134:137], v142 offset:1024
	ds_read_b128 v[138:141], v142 offset:2048
	ds_read_b128 v[142:145], v142 offset:3072
	s_cmp_eq_u32 s19, 12
	s_cselect_b32 s83, s0, s27
	s_cselect_b32 s82, s1, s26
	s_cselect_b32 s81, s9, s18
	s_cselect_b32 s80, s13, s15
	v_lshl_add_u64 v[162:163], s[68:69], 0, v[178:179]
	s_add_i32 m0, s85, 0xc000
	ds_read_b128 v[146:149], v198
	ds_read_b128 v[182:185], v198 offset:1024
	ds_read_b128 v[186:189], v198 offset:2048
	ds_read_b128 v[200:203], v198 offset:3072
	ds_read_b128 v[204:207], v198 offset:4096
	ds_read_b128 v[214:217], v198 offset:5120
	ds_read_b128 v[218:221], v198 offset:6144
	ds_read_b128 v[222:225], v198 offset:7168
	global_load_lds_dwordx4 v[162:163], off
	v_lshl_add_u64 v[162:163], s[68:69], 0, v[180:181]
	s_add_i32 m0, s85, 0xe000
	s_nop 0
	global_load_lds_dwordx4 v[162:163], off
	s_waitcnt lgkmcnt(8)
	s_barrier
	s_waitcnt lgkmcnt(0)
	s_setprio 1
	v_mfma_f32_16x16x32_bf16 v[126:129], v[130:133], v[146:149], v[126:129]
	v_mfma_f32_16x16x32_bf16 v[122:125], v[138:141], v[146:149], v[122:125]
	v_mfma_f32_16x16x32_bf16 v[110:113], v[130:133], v[186:189], v[110:113]
	v_mfma_f32_16x16x32_bf16 v[106:109], v[138:141], v[186:189], v[106:109]
	v_mfma_f32_16x16x32_bf16 v[94:97], v[130:133], v[204:207], v[94:97]
	v_mfma_f32_16x16x32_bf16 v[90:93], v[138:141], v[204:207], v[90:93]
	v_mfma_f32_16x16x32_bf16 v[78:81], v[130:133], v[218:221], v[78:81]
	v_mfma_f32_16x16x32_bf16 v[74:77], v[138:141], v[218:221], v[74:77]
	v_mfma_f32_16x16x32_bf16 v[126:129], v[134:137], v[182:185], v[126:129]
	v_mfma_f32_16x16x32_bf16 v[122:125], v[142:145], v[182:185], v[122:125]
	v_mfma_f32_16x16x32_bf16 v[110:113], v[134:137], v[200:203], v[110:113]
	v_mfma_f32_16x16x32_bf16 v[106:109], v[142:145], v[200:203], v[106:109]
	v_mfma_f32_16x16x32_bf16 v[94:97], v[134:137], v[214:217], v[94:97]
	v_mfma_f32_16x16x32_bf16 v[90:93], v[142:145], v[214:217], v[90:93]
	v_mfma_f32_16x16x32_bf16 v[78:81], v[134:137], v[222:225], v[78:81]
	v_mfma_f32_16x16x32_bf16 v[74:77], v[142:145], v[222:225], v[74:77]
	s_setprio 0
	s_barrier
	s_add_i32 s39, 0, 0x14000
	v_add_u32_e32 v162, s39, v193
	s_add_i32 s26, s38, s84
	ds_read_b128 v[226:229], v162
	ds_read_b128 v[230:233], v162 offset:1024
	ds_read_b128 v[234:237], v162 offset:2048
	ds_read_b128 v[238:241], v162 offset:3072
	v_lshl_add_u64 v[162:163], s[80:81], 0, v[8:9]
	s_mov_b32 m0, s26
	v_lshl_add_u64 v[164:165], s[80:81], 0, v[176:177]
	global_load_lds_dwordx4 v[162:163], off
	s_add_i32 m0, s26, 0x2000
	s_nop 0
	global_load_lds_dwordx4 v[164:165], off
	s_barrier
	s_waitcnt lgkmcnt(0)
	s_setprio 1
	v_mfma_f32_16x16x32_bf16 v[118:121], v[226:229], v[146:149], v[118:121]
	v_mfma_f32_16x16x32_bf16 v[114:117], v[234:237], v[146:149], v[114:117]
	v_mfma_f32_16x16x32_bf16 v[102:105], v[226:229], v[186:189], v[102:105]
	v_mfma_f32_16x16x32_bf16 v[98:101], v[234:237], v[186:189], v[98:101]
	v_mfma_f32_16x16x32_bf16 v[86:89], v[226:229], v[204:207], v[86:89]
	v_mfma_f32_16x16x32_bf16 v[82:85], v[234:237], v[204:207], v[82:85]
	v_mfma_f32_16x16x32_bf16 v[70:73], v[226:229], v[218:221], v[70:73]
	v_mfma_f32_16x16x32_bf16 v[66:69], v[234:237], v[218:221], v[66:69]
	v_mfma_f32_16x16x32_bf16 v[118:121], v[230:233], v[182:185], v[118:121]
	v_mfma_f32_16x16x32_bf16 v[114:117], v[238:241], v[182:185], v[114:117]
	v_mfma_f32_16x16x32_bf16 v[102:105], v[230:233], v[200:203], v[102:105]
	v_mfma_f32_16x16x32_bf16 v[98:101], v[238:241], v[200:203], v[98:101]
	v_mfma_f32_16x16x32_bf16 v[86:89], v[230:233], v[214:217], v[86:89]
	v_mfma_f32_16x16x32_bf16 v[82:85], v[238:241], v[214:217], v[82:85]
	v_mfma_f32_16x16x32_bf16 v[70:73], v[230:233], v[222:225], v[70:73]
	v_mfma_f32_16x16x32_bf16 v[66:69], v[238:241], v[222:225], v[66:69]
	s_setprio 0
	s_mov_b32 m0, s85
	v_lshl_add_u64 v[190:191], s[82:83], 0, v[150:151]
	s_barrier
	ds_read_b128 v[146:149], v198 offset:16384
	ds_read_b128 v[182:185], v198 offset:17408
	ds_read_b128 v[186:189], v198 offset:18432
	ds_read_b128 v[200:203], v198 offset:19456
	ds_read_b128 v[204:207], v198 offset:20480
	ds_read_b128 v[214:217], v198 offset:21504
	ds_read_b128 v[218:221], v198 offset:22528
	ds_read_b128 v[222:225], v198 offset:23552
	global_load_lds_dwordx4 v[190:191], off
	v_lshl_add_u64 v[208:209], s[82:83], 0, v[152:153]
	s_mov_b32 m0, s86
	s_nop 0
	global_load_lds_dwordx4 v[208:209], off
	s_barrier
	s_waitcnt lgkmcnt(0)
	s_setprio 1
	v_mfma_f32_16x16x32_bf16 v[62:65], v[130:133], v[146:149], v[62:65]
	v_mfma_f32_16x16x32_bf16 v[58:61], v[138:141], v[146:149], v[58:61]
	v_mfma_f32_16x16x32_bf16 v[46:49], v[130:133], v[186:189], v[46:49]
	v_mfma_f32_16x16x32_bf16 v[42:45], v[138:141], v[186:189], v[42:45]
	v_mfma_f32_16x16x32_bf16 v[30:33], v[130:133], v[204:207], v[30:33]
	v_mfma_f32_16x16x32_bf16 v[26:29], v[138:141], v[204:207], v[26:29]
	v_mfma_f32_16x16x32_bf16 v[14:17], v[130:133], v[218:221], v[14:17]
	v_mfma_f32_16x16x32_bf16 v[10:13], v[138:141], v[218:221], v[10:13]
	v_mfma_f32_16x16x32_bf16 v[62:65], v[134:137], v[182:185], v[62:65]
	v_mfma_f32_16x16x32_bf16 v[58:61], v[142:145], v[182:185], v[58:61]
	v_mfma_f32_16x16x32_bf16 v[46:49], v[134:137], v[200:203], v[46:49]
	v_mfma_f32_16x16x32_bf16 v[42:45], v[142:145], v[200:203], v[42:45]
	v_mfma_f32_16x16x32_bf16 v[30:33], v[134:137], v[214:217], v[30:33]
	v_mfma_f32_16x16x32_bf16 v[26:29], v[142:145], v[214:217], v[26:29]
	v_mfma_f32_16x16x32_bf16 v[14:17], v[134:137], v[222:225], v[14:17]
	v_mfma_f32_16x16x32_bf16 v[10:13], v[142:145], v[222:225], v[10:13]
	s_setprio 0
	s_barrier
; #define PG8_STAGE(bufoff, gbase, voff) do { _Pragma("unroll") for (int _i = 0; _i < 2; ++_i) \
;         __builtin_amdgcn_global_load_lds((const unsigned*)((const char*)(gbase) + (voff)[_i]), (LAS unsigned*)(lds + (bufoff) + ldsw + _i * 8192), 16, 0, 0); } while (0)
; #define PG8_LDA(dst, b, h) do { _Pragma("unroll") for (int m = 0; m < 4; ++m) _Pragma("unroll") for (int k = 0; k < 2; ++k) dst[m][k] = *(const LAS bf16x8*)(lds + PG8_SA(b, h) + aoff + m * 2048 + k * 1024); } while (0)
; #define PG8_LDB(dst, b, h) do { _Pragma("unroll") for (int n = 0; n < 2; ++n) _Pragma("unroll") for (int k = 0; k < 2; ++k) dst[n][k] = *(const LAS bf16x8*)(lds + PG8_SB(b, h) + boff + n * 2048 + k * 1024); } while (0)
; #define PG8_MMA(ai, bj, At, Bt) do { __builtin_amdgcn_s_setprio(1); _Pragma("unroll") for (int m = 0; m < 4; ++m) _Pragma("unroll") for (int n = 0; n < 2; ++n) _Pragma("unroll") for (int k = 0; k < 2; ++k) \
;         acc[ai][bj][m][n] = __builtin_amdgcn_mfma_f32_16x16x32_bf16(Bt[n][k], At[m][k], acc[ai][bj][m][n], 0, 0, 0); __builtin_amdgcn_s_setprio(0); } while (0)
; #define PG8_WAIT_V(n) asm volatile("s_waitcnt vmcnt(" #n ")" ::: "memory")
; #define PG8_WAIT_L(n) asm volatile("s_waitcnt lgkmcnt(" #n ")" ::: "memory")
; #define PG8_BAR __builtin_amdgcn_s_barrier()
; #define PG8_SCHED __builtin_amdgcn_sched_barrier(0)
; template <class Epi>
; DEVI void gemm_phase(LAS unsigned char* lds, const Gemm g, const Epi& E) {
;     ...
;             PG8_STAGE(PG8_SB(0, 1), b2 + hstepB, voffB);
;             PG8_WAIT_V(6); PG8_BAR; PG8_MMA(1, 1, At, B1); PG8_BAR;
;             PG8_LDB(B0, 1, 0); PG8_SCHED; PG8_LDA(At, 1, 0); PG8_STAGE(PG8_SA(0, 1), a2 + hstepA, voffA);
;             PG8_WAIT_L(8); PG8_BAR; PG8_WAIT_L(0); PG8_MMA(0, 0, At, B0); PG8_BAR; PG8_SCHED;
;             PG8_LDB(B1, 1, 1); PG8_STAGE(PG8_SB(1, 0), b3, voffB);
;             PG8_BAR; PG8_WAIT_L(0); PG8_MMA(0, 1, At, B1); PG8_BAR;
;             PG8_LDA(At, 1, 1); PG8_STAGE(PG8_SA(1, 0), a3, voffA);
;             PG8_BAR; PG8_WAIT_L(0); PG8_MMA(1, 0, At, B0); PG8_BAR; PG8_SCHED;
	s_add_u32 s26, s80, 0x40000
	s_addc_u32 s27, s81, 0
	s_add_i32 s38, s39, s84
	v_lshl_add_u64 v[130:131], s[26:27], 0, v[8:9]
	s_mov_b32 m0, s38
	s_nop 0
	global_load_lds_dwordx4 v[130:131], off
	v_lshl_add_u64 v[130:131], s[26:27], 0, v[176:177]
	s_add_i32 m0, s38, 0x2000
	s_nop 0
	global_load_lds_dwordx4 v[130:131], off
	s_waitcnt vmcnt(6)
	s_barrier
	s_setprio 1
	v_mfma_f32_16x16x32_bf16 v[54:57], v[226:229], v[146:149], v[54:57]
	v_mfma_f32_16x16x32_bf16 v[50:53], v[234:237], v[146:149], v[50:53]
	v_mfma_f32_16x16x32_bf16 v[38:41], v[226:229], v[186:189], v[38:41]
	v_mfma_f32_16x16x32_bf16 v[34:37], v[234:237], v[186:189], v[34:37]
	v_mfma_f32_16x16x32_bf16 v[22:25], v[226:229], v[204:207], v[22:25]
	v_mfma_f32_16x16x32_bf16 v[18:21], v[234:237], v[204:207], v[18:21]
	v_mfma_f32_16x16x32_bf16 v[4:7], v[226:229], v[218:221], v[4:7]
	v_mfma_f32_16x16x32_bf16 v[0:3], v[234:237], v[218:221], v[0:3]
	v_mfma_f32_16x16x32_bf16 v[54:57], v[230:233], v[182:185], v[54:57]
	v_mfma_f32_16x16x32_bf16 v[50:53], v[238:241], v[182:185], v[50:53]
	v_mfma_f32_16x16x32_bf16 v[38:41], v[230:233], v[200:203], v[38:41]
	v_mfma_f32_16x16x32_bf16 v[34:37], v[238:241], v[200:203], v[34:37]
	v_mfma_f32_16x16x32_bf16 v[22:25], v[230:233], v[214:217], v[22:25]
	v_mfma_f32_16x16x32_bf16 v[18:21], v[238:241], v[214:217], v[18:21]
	v_mfma_f32_16x16x32_bf16 v[4:7], v[230:233], v[222:225], v[4:7]
	v_mfma_f32_16x16x32_bf16 v[0:3], v[238:241], v[222:225], v[0:3]
	s_setprio 0
	s_add_i32 s38, 0, 0x18000
	v_add_u32_e32 v142, s38, v193
	s_barrier
	ds_read_b128 v[130:133], v142
	ds_read_b128 v[134:137], v142 offset:1024
	ds_read_b128 v[138:141], v142 offset:2048
	ds_read_b128 v[142:145], v142 offset:3072
	s_add_u32 s26, s82, 0x40000
	s_addc_u32 s27, s83, 0
	s_mov_b32 m0, s87
	v_lshl_add_u64 v[226:227], s[26:27], 0, v[150:151]
	ds_read_b128 v[146:149], v198 offset:32768
	ds_read_b128 v[182:185], v198 offset:33792
	ds_read_b128 v[186:189], v198 offset:34816
	ds_read_b128 v[200:203], v198 offset:35840
	ds_read_b128 v[204:207], v198 offset:36864
	ds_read_b128 v[214:217], v198 offset:37888
	ds_read_b128 v[218:221], v198 offset:38912
	ds_read_b128 v[222:225], v198 offset:39936
	global_load_lds_dwordx4 v[226:227], off
	v_lshl_add_u64 v[226:227], s[26:27], 0, v[152:153]
	s_mov_b32 m0, s88
	s_nop 0
	global_load_lds_dwordx4 v[226:227], off
	s_waitcnt lgkmcnt(8)
	s_barrier
	s_waitcnt lgkmcnt(0)
	s_setprio 1
	v_mfma_f32_16x16x32_bf16 v[126:129], v[130:133], v[146:149], v[126:129]
	v_mfma_f32_16x16x32_bf16 v[122:125], v[138:141], v[146:149], v[122:125]
	v_mfma_f32_16x16x32_bf16 v[110:113], v[130:133], v[186:189], v[110:113]
	v_mfma_f32_16x16x32_bf16 v[106:109], v[138:141], v[186:189], v[106:109]
	v_mfma_f32_16x16x32_bf16 v[94:97], v[130:133], v[204:207], v[94:97]
	v_mfma_f32_16x16x32_bf16 v[90:93], v[138:141], v[204:207], v[90:93]
	v_mfma_f32_16x16x32_bf16 v[78:81], v[130:133], v[218:221], v[78:81]
	v_mfma_f32_16x16x32_bf16 v[74:77], v[138:141], v[218:221], v[74:77]
	v_mfma_f32_16x16x32_bf16 v[126:129], v[134:137], v[182:185], v[126:129]
	v_mfma_f32_16x16x32_bf16 v[122:125], v[142:145], v[182:185], v[122:125]
	v_mfma_f32_16x16x32_bf16 v[110:113], v[134:137], v[200:203], v[110:113]
	v_mfma_f32_16x16x32_bf16 v[106:109], v[142:145], v[200:203], v[106:109]
	v_mfma_f32_16x16x32_bf16 v[94:97], v[134:137], v[214:217], v[94:97]
	v_mfma_f32_16x16x32_bf16 v[90:93], v[142:145], v[214:217], v[90:93]
	v_mfma_f32_16x16x32_bf16 v[78:81], v[134:137], v[222:225], v[78:81]
	v_mfma_f32_16x16x32_bf16 v[74:77], v[142:145], v[222:225], v[74:77]
	s_setprio 0
	s_barrier
	s_add_i32 s39, 0, 0x1c000
	s_add_i32 s26, s38, s84
	v_add_u32_e32 v199, s39, v193
	v_lshl_add_u64 v[162:163], v[162:163], 0, s[70:71]
	s_mov_b32 m0, s26
	ds_read_b128 v[226:229], v199
	ds_read_b128 v[230:233], v199 offset:1024
	ds_read_b128 v[234:237], v199 offset:2048
	ds_read_b128 v[238:241], v199 offset:3072
	global_load_lds_dwordx4 v[162:163], off
	v_lshl_add_u64 v[162:163], v[164:165], 0, s[70:71]
	s_add_i32 m0, s26, 0x2000
	s_nop 0
	global_load_lds_dwordx4 v[162:163], off
	s_barrier
	s_waitcnt lgkmcnt(0)
	s_setprio 1
	v_mfma_f32_16x16x32_bf16 v[118:121], v[226:229], v[146:149], v[118:121]
	v_mfma_f32_16x16x32_bf16 v[114:117], v[234:237], v[146:149], v[114:117]
	v_mfma_f32_16x16x32_bf16 v[102:105], v[226:229], v[186:189], v[102:105]
	v_mfma_f32_16x16x32_bf16 v[98:101], v[234:237], v[186:189], v[98:101]
	v_mfma_f32_16x16x32_bf16 v[86:89], v[226:229], v[204:207], v[86:89]
	v_mfma_f32_16x16x32_bf16 v[82:85], v[234:237], v[204:207], v[82:85]
	v_mfma_f32_16x16x32_bf16 v[70:73], v[226:229], v[218:221], v[70:73]
	v_mfma_f32_16x16x32_bf16 v[66:69], v[234:237], v[218:221], v[66:69]
	v_mfma_f32_16x16x32_bf16 v[118:121], v[230:233], v[182:185], v[118:121]
	v_mfma_f32_16x16x32_bf16 v[114:117], v[238:241], v[182:185], v[114:117]
	v_mfma_f32_16x16x32_bf16 v[102:105], v[230:233], v[200:203], v[102:105]
	v_mfma_f32_16x16x32_bf16 v[98:101], v[238:241], v[200:203], v[98:101]
	v_mfma_f32_16x16x32_bf16 v[86:89], v[230:233], v[214:217], v[86:89]
	v_mfma_f32_16x16x32_bf16 v[82:85], v[238:241], v[214:217], v[82:85]
	v_mfma_f32_16x16x32_bf16 v[70:73], v[230:233], v[222:225], v[70:73]
	v_mfma_f32_16x16x32_bf16 v[66:69], v[238:241], v[222:225], v[66:69]
	s_setprio 0
	s_mov_b32 m0, s89
	v_lshl_add_u64 v[162:163], v[190:191], 0, s[70:71]
	s_barrier
	ds_read_b128 v[146:149], v198 offset:49152
	ds_read_b128 v[182:185], v198 offset:50176
	ds_read_b128 v[186:189], v198 offset:51200
	ds_read_b128 v[200:203], v198 offset:52224
	ds_read_b128 v[204:207], v198 offset:53248
	ds_read_b128 v[214:217], v198 offset:54272
	ds_read_b128 v[218:221], v198 offset:55296
	ds_read_b128 v[222:225], v198 offset:56320
	global_load_lds_dwordx4 v[162:163], off
	v_lshl_add_u64 v[162:163], v[208:209], 0, s[70:71]
	s_mov_b32 m0, s90
	s_nop 0
	global_load_lds_dwordx4 v[162:163], off
	s_barrier
; #define PG8_WAIT_V(n) asm volatile("s_waitcnt vmcnt(" #n ")" ::: "memory")
; #define PG8_WAIT_L(n) asm volatile("s_waitcnt lgkmcnt(" #n ")" ::: "memory")
; template <class Epi>
; DEVI void gemm_phase(LAS unsigned char* lds, const Gemm g, const Epi& E) {
;     ...
;             PG8_WAIT_V(6); PG8_BAR; PG8_MMA(1, 1, At, B1); PG8_BAR;
;             PG8_LDB(B0, 1, 0); PG8_SCHED; PG8_LDA(At, 1, 0); PG8_STAGE(PG8_SA(0, 1), a2 + hstepA, voffA);
;             PG8_WAIT_L(8); PG8_BAR; PG8_WAIT_L(0); PG8_MMA(0, 0, At, B0); PG8_BAR; PG8_SCHED;
;             PG8_LDB(B1, 1, 1); PG8_STAGE(PG8_SB(1, 0), b3, voffB);
;             PG8_BAR; PG8_WAIT_L(0); PG8_MMA(0, 1, At, B1); PG8_BAR;
;             PG8_LDA(At, 1, 1); PG8_STAGE(PG8_SA(1, 0), a3, voffA);
;             PG8_BAR; PG8_WAIT_L(0); PG8_MMA(1, 0, At, B0); PG8_BAR; PG8_SCHED;
;             PG8_STAGE(PG8_SB(1, 1), b3 + hstepB, voffB);
;             PG8_WAIT_V(6); PG8_BAR; PG8_MMA(1, 1, At, B1); PG8_BAR;
;     ...
;                 if constexpr (Epi::PRE) {
; #pragma unroll
;                     for (int m = 0; m < 2; ++m)
; #pragma unroll
;                         for (int bj = 0; bj < 2; ++bj)
; #pragma unroll
;                             for (int n = 0; n < 2; ++n) pre[m][bj][n] = E.load(row0 + ai * HALF + (m0 + m) * 16, col0 + bj * HALF + n * NST);
;                 }
; #pragma unroll
;                 for (int mm = 0; mm < 2; ++mm) {
;                     const int m = m0 + mm;
;                     const int r = row0 + ai * HALF + m * 16; float rs = 1.f, part = 0.f;
;                     if constexpr (Epi::RS) rs = rsv[ai * 4 + m];
;                     if constexpr (Epi::PAIR) E.pair8(cur.b, r, cur.pn * HALF + wc * 32 + 8 * fq, acc[ai][0][m][0] * rs, acc[ai][0][m][1] * rs, acc[ai][1][m][0] * rs, acc[ai][1][m][1] * rs);
;                     else
; #pragma unroll
;                     for (int bj = 0; bj < 2; ++bj) {
;                         const int c = col0 + bj * HALF; f32x4 v0 = acc[ai][bj][m][0], v1 = acc[ai][bj][m][1];
;                         if constexpr (Epi::RS) { v0 = v0 * rs; v1 = v1 * rs; }
;                         if constexpr (Epi::PRE) part += E.frag_pre8(cur.b, r, c, v0, v1, pre[mm][bj][0], pre[mm][bj][1]);
;                         else if constexpr (Epi::PERM) E.frag8(cur.b, r, c, v0, v1);
;                         else { E.frag(cur.b, r, c, v0); E.frag(cur.b, r, c + 16, v1); }
;                     }
	s_waitcnt lgkmcnt(0)
	s_setprio 1
	v_mfma_f32_16x16x32_bf16 v[62:65], v[130:133], v[146:149], v[62:65]
	v_mfma_f32_16x16x32_bf16 v[58:61], v[138:141], v[146:149], v[58:61]
	v_mfma_f32_16x16x32_bf16 v[46:49], v[130:133], v[186:189], v[46:49]
	v_mfma_f32_16x16x32_bf16 v[42:45], v[138:141], v[186:189], v[42:45]
	v_mfma_f32_16x16x32_bf16 v[30:33], v[130:133], v[204:207], v[30:33]
	v_mfma_f32_16x16x32_bf16 v[26:29], v[138:141], v[204:207], v[26:29]
	v_mfma_f32_16x16x32_bf16 v[14:17], v[130:133], v[218:221], v[14:17]
	v_mfma_f32_16x16x32_bf16 v[10:13], v[138:141], v[218:221], v[10:13]
	v_mfma_f32_16x16x32_bf16 v[62:65], v[134:137], v[182:185], v[62:65]
	v_mfma_f32_16x16x32_bf16 v[58:61], v[142:145], v[182:185], v[58:61]
	v_mfma_f32_16x16x32_bf16 v[46:49], v[134:137], v[200:203], v[46:49]
	v_mfma_f32_16x16x32_bf16 v[42:45], v[142:145], v[200:203], v[42:45]
	v_mfma_f32_16x16x32_bf16 v[30:33], v[134:137], v[214:217], v[30:33]
	v_mfma_f32_16x16x32_bf16 v[26:29], v[142:145], v[214:217], v[26:29]
	v_mfma_f32_16x16x32_bf16 v[14:17], v[134:137], v[222:225], v[14:17]
	v_mfma_f32_16x16x32_bf16 v[10:13], v[142:145], v[222:225], v[10:13]
	s_setprio 0
	s_barrier
	s_add_u32 s26, s80, 0x40080
	s_addc_u32 s27, s81, 0
	s_add_i32 s38, s39, s84
	v_lshl_add_u64 v[130:131], s[26:27], 0, v[8:9]
	s_mov_b32 m0, s38
	s_nop 0
	global_load_lds_dwordx4 v[130:131], off
	v_lshl_add_u64 v[130:131], s[26:27], 0, v[176:177]
	s_add_i32 m0, s38, 0x2000
	s_nop 0
	global_load_lds_dwordx4 v[130:131], off
	s_waitcnt vmcnt(6)
	s_barrier
	s_setprio 1
	v_mfma_f32_16x16x32_bf16 v[54:57], v[226:229], v[146:149], v[54:57]
	v_mfma_f32_16x16x32_bf16 v[50:53], v[234:237], v[146:149], v[50:53]
	v_mfma_f32_16x16x32_bf16 v[38:41], v[226:229], v[186:189], v[38:41]
	v_mfma_f32_16x16x32_bf16 v[34:37], v[234:237], v[186:189], v[34:37]
	v_mfma_f32_16x16x32_bf16 v[22:25], v[226:229], v[204:207], v[22:25]
	v_mfma_f32_16x16x32_bf16 v[18:21], v[234:237], v[204:207], v[18:21]
	v_mfma_f32_16x16x32_bf16 v[4:7], v[226:229], v[218:221], v[4:7]
	v_mfma_f32_16x16x32_bf16 v[0:3], v[234:237], v[218:221], v[0:3]
	v_mfma_f32_16x16x32_bf16 v[54:57], v[230:233], v[182:185], v[54:57]
	v_mfma_f32_16x16x32_bf16 v[50:53], v[238:241], v[182:185], v[50:53]
	v_mfma_f32_16x16x32_bf16 v[38:41], v[230:233], v[200:203], v[38:41]
	v_mfma_f32_16x16x32_bf16 v[34:37], v[238:241], v[200:203], v[34:37]
	v_mfma_f32_16x16x32_bf16 v[22:25], v[230:233], v[214:217], v[22:25]
	v_mfma_f32_16x16x32_bf16 v[18:21], v[238:241], v[214:217], v[18:21]
	v_mfma_f32_16x16x32_bf16 v[4:7], v[230:233], v[222:225], v[4:7]
	v_mfma_f32_16x16x32_bf16 v[0:3], v[238:241], v[222:225], v[0:3]
	s_setprio 0
	s_add_i32 s19, s19, 2
	s_add_u32 s68, s68, 0x100
	s_addc_u32 s69, s69, 0
	s_add_u32 s15, s15, 0x100
	s_addc_u32 s18, s18, 0
	s_cmp_gt_u32 s19, 13
	s_barrier
	s_cbranch_scc0 .LBB0_968
	v_and_b32_e32 v131, 64, v155
	v_xor_b32_e32 v130, 16, v155
	v_add_u32_e32 v131, 64, v131
	v_cmp_lt_i32_e32 vcc, v130, v131
	s_lshl_b32 s9, s46, 8
	v_add_u32_e32 v186, s9, v192
	v_cndmask_b32_e32 v130, v155, v130, vcc
	v_lshlrev_b32_e32 v200, 2, v130
	v_xor_b32_e32 v130, 32, v155
	v_cmp_lt_i32_e32 vcc, v130, v131
	v_lshl_or_b32 v184, s8, 8, v197
	v_ashrrev_i32_e32 v187, 31, v186
	v_cndmask_b32_e32 v130, v155, v130, vcc
	v_lshlrev_b32_e32 v199, 2, v130
	v_lshlrev_b64 v[130:131], 12, v[186:187]
	v_ashrrev_i32_e32 v185, 31, v184
	v_lshl_add_u64 v[130:131], s[78:79], 0, v[130:131]
	v_lshlrev_b64 v[188:189], 2, v[184:185]
	v_lshl_add_u64 v[130:131], v[130:131], 0, v[188:189]
	global_load_dwordx4 v[202:205], v[130:131], off offset:16
	global_load_dwordx4 v[206:209], v[130:131], off
	global_load_dwordx4 v[146:149], v[130:131], off offset:528
	global_load_dwordx4 v[214:217], v[130:131], off offset:512
	v_or_b32_e32 v190, 16, v186
	v_ashrrev_i32_e32 v191, 31, v190
	v_lshlrev_b64 v[130:131], 12, v[190:191]
	v_lshl_add_u64 v[130:131], s[78:79], 0, v[130:131]
	v_lshl_add_u64 v[134:135], v[130:131], 0, v[188:189]
	global_load_dwordx4 v[138:141], v[134:135], off offset:16
	global_load_dwordx4 v[142:145], v[134:135], off
	global_load_dwordx4 v[130:133], v[134:135], off offset:528
	s_nop 0
	global_load_dwordx4 v[134:137], v[134:135], off offset:512
	v_lshlrev_b64 v[162:163], 10, v[186:187]
	v_lshl_add_u64 v[164:165], v[162:163], 0, v[184:185]
	v_or_b32_e32 v182, 0x80, v184
	v_ashrrev_i32_e32 v183, 31, v182
	s_waitcnt vmcnt(0)
	v_pk_add_f32 v[122:123], v[122:123], v[202:203]
	v_pk_add_f32 v[128:129], v[128:129], v[208:209]
	v_pk_add_f32 v[126:127], v[126:127], v[206:207]
	v_lshl_add_u64 v[206:207], v[164:165], 2, s[30:31]
	v_pk_add_f32 v[124:125], v[124:125], v[204:205]
	global_store_dwordx4 v[206:207], v[126:129], off
	global_store_dwordx4 v[206:207], v[122:125], off offset:16
	v_cvt_pk_bf16_f32 v202, v126, v127
	v_cvt_pk_bf16_f32 v204, v122, v123
	v_mul_f32_e32 v127, v127, v127
	v_mul_f32_e32 v123, v123, v123
	v_fmac_f32_e32 v127, v126, v126
	v_mul_f32_e32 v126, v129, v129
	v_fmac_f32_e32 v123, v122, v122
	v_mul_f32_e32 v122, v125, v125
	v_fmac_f32_e32 v126, v128, v128
	v_fmac_f32_e32 v122, v124, v124
	v_cvt_pk_bf16_f32 v203, v128, v129
	v_cvt_pk_bf16_f32 v205, v124, v125
	v_lshl_add_u64 v[164:165], v[164:165], 1, s[28:29]
	v_add_f32_e32 v126, v127, v126
	v_add_f32_e32 v122, v123, v122
	v_pk_add_f32 v[120:121], v[120:121], v[216:217]
	v_pk_add_f32 v[118:119], v[118:119], v[214:215]
	v_pk_add_f32 v[114:115], v[114:115], v[146:147]
	global_store_dwordx4 v[164:165], v[202:205], off
	v_add_f32_e32 v128, v126, v122
	v_pk_add_f32 v[116:117], v[116:117], v[148:149]
	global_store_dwordx4 v[206:207], v[118:121], off offset:512
	global_store_dwordx4 v[206:207], v[114:117], off offset:528
	v_cvt_pk_bf16_f32 v122, v118, v119
	v_cvt_pk_bf16_f32 v124, v114, v115
	v_mul_f32_e32 v119, v119, v119
	v_mul_f32_e32 v115, v115, v115
	v_fmac_f32_e32 v119, v118, v118
	v_mul_f32_e32 v118, v121, v121
	v_fmac_f32_e32 v115, v114, v114
	v_mul_f32_e32 v114, v117, v117
	v_fmac_f32_e32 v118, v120, v120
	v_fmac_f32_e32 v114, v116, v116
	v_add_f32_e32 v118, v119, v118
	v_add_f32_e32 v114, v115, v114
	v_add_f32_e32 v114, v118, v114
	v_add_f32_e32 v114, v128, v114
	ds_bpermute_b32 v115, v200, v114
	v_lshl_add_u64 v[126:127], v[162:163], 0, v[182:183]
	v_cvt_pk_bf16_f32 v123, v120, v121
	v_cvt_pk_bf16_f32 v125, v116, v117
	v_lshl_add_u64 v[126:127], v[126:127], 1, s[28:29]
	s_waitcnt lgkmcnt(0)
	v_add_f32_e32 v114, v114, v115
	ds_bpermute_b32 v115, v199, v114
	global_store_dwordx4 v[126:127], v[122:125], off
	s_and_saveexec_b64 s[46:47], s[2:3]
	s_cbranch_execz .LBB0_971
	s_waitcnt lgkmcnt(0)
	v_add_f32_e32 v114, v114, v115
	ds_write_b32 v194, v114

; #define PG8_STAGE(bufoff, gbase, voff) do { _Pragma("unroll") for (int _i = 0; _i < 2; ++_i) \
;         __builtin_amdgcn_global_load_lds((const unsigned*)((const char*)(gbase) + (voff)[_i]), (LAS unsigned*)(lds + (bufoff) + ldsw + _i * 8192), 16, 0, 0); } while (0)
; #define PG8_LDA(dst, b, h) do { _Pragma("unroll") for (int m = 0; m < 4; ++m) _Pragma("unroll") for (int k = 0; k < 2; ++k) dst[m][k] = *(const LAS bf16x8*)(lds + PG8_SA(b, h) + aoff + m * 2048 + k * 1024); } while (0)
; #define PG8_LDB(dst, b, h) do { _Pragma("unroll") for (int n = 0; n < 2; ++n) _Pragma("unroll") for (int k = 0; k < 2; ++k) dst[n][k] = *(const LAS bf16x8*)(lds + PG8_SB(b, h) + boff + n * 2048 + k * 1024); } while (0)
; #define PG8_MMA(ai, bj, At, Bt) do { __builtin_amdgcn_s_setprio(1); _Pragma("unroll") for (int m = 0; m < 4; ++m) _Pragma("unroll") for (int n = 0; n < 2; ++n) _Pragma("unroll") for (int k = 0; k < 2; ++k) \
;         acc[ai][bj][m][n] = __builtin_amdgcn_mfma_f32_16x16x32_bf16(Bt[n][k], At[m][k], acc[ai][bj][m][n], 0, 0, 0); __builtin_amdgcn_s_setprio(0); } while (0)
; #define PG8_WAIT_V(n) asm volatile("s_waitcnt vmcnt(" #n ")" ::: "memory")
; #define PG8_WAIT_L(n) asm volatile("s_waitcnt lgkmcnt(" #n ")" ::: "memory")
; #define PG8_BAR __builtin_amdgcn_s_barrier()
; #define PG8_SCHED __builtin_amdgcn_sched_barrier(0)
; template <class Epi>
; DEVI void gemm_phase(LAS unsigned char* lds, const Gemm g, const Epi& E) {
;     ...
;             PG8_LDB(B0, 0, 0); PG8_SCHED; PG8_LDA(At, 0, 0); PG8_STAGE(PG8_SA(1, 1), a1 + hstepA, voffA);
;             PG8_WAIT_L(8); PG8_BAR; PG8_WAIT_L(0); PG8_MMA(0, 0, At, B0); PG8_BAR; PG8_SCHED;
;             PG8_LDB(B1, 0, 1); PG8_STAGE(PG8_SB(0, 0), b2, voffB);
;             PG8_BAR; PG8_WAIT_L(0); PG8_MMA(0, 1, At, B1); PG8_BAR;
;             PG8_LDA(At, 0, 1); PG8_STAGE(PG8_SA(0, 0), a2, voffA);
;             PG8_BAR; PG8_WAIT_L(0); PG8_MMA(1, 0, At, B0); PG8_BAR; PG8_SCHED;
;             PG8_STAGE(PG8_SB(0, 1), b2 + hstepB, voffB);
;             PG8_WAIT_V(6); PG8_BAR; PG8_MMA(1, 1, At, B1); PG8_BAR;
;             PG8_LDB(B0, 1, 0); PG8_SCHED; PG8_LDA(At, 1, 0); PG8_STAGE(PG8_SA(0, 1), a2 + hstepA, voffA);
;             PG8_WAIT_L(8); PG8_BAR; PG8_WAIT_L(0); PG8_MMA(0, 0, At, B0); PG8_BAR; PG8_SCHED;
.LBB0_1007:
	s_add_u32 s16, s14, 0xfffc0080
	s_addc_u32 s17, s15, -1
	s_add_i32 s26, 0, 0x10000
	v_add_u32_e32 v8, s26, v199
	ds_read_b128 v[130:133], v8
	ds_read_b128 v[134:137], v8 offset:1024
	ds_read_b128 v[138:141], v8 offset:2048
	ds_read_b128 v[142:145], v8 offset:3072
	s_cmp_eq_u32 s19, 12
	s_cselect_b32 s37, s0, s17
	s_cselect_b32 s36, s1, s16
	s_cselect_b32 s17, s5, s18
	s_cselect_b32 s16, s7, s9
	v_lshl_add_u64 v[162:163], s[14:15], 0, v[180:181]
	s_add_i32 m0, s66, 0xc000
	ds_read_b128 v[184:187], v204
	ds_read_b128 v[188:191], v204 offset:1024
	ds_read_b128 v[192:195], v204 offset:2048
	ds_read_b128 v[206:209], v204 offset:3072
	ds_read_b128 v[214:217], v204 offset:4096
	ds_read_b128 v[218:221], v204 offset:5120
	ds_read_b128 v[222:225], v204 offset:6144
	ds_read_b128 v[226:229], v204 offset:7168
	global_load_lds_dwordx4 v[162:163], off
	v_lshl_add_u64 v[162:163], s[14:15], 0, v[182:183]
	s_add_i32 m0, s66, 0xe000
	s_nop 0
	global_load_lds_dwordx4 v[162:163], off
	s_waitcnt lgkmcnt(8)
	s_barrier
	s_waitcnt lgkmcnt(0)
	s_setprio 1
	v_mfma_f32_16x16x32_bf16 v[126:129], v[130:133], v[184:187], v[126:129]
	v_mfma_f32_16x16x32_bf16 v[122:125], v[138:141], v[184:187], v[122:125]
	v_mfma_f32_16x16x32_bf16 v[114:117], v[130:133], v[192:195], v[114:117]
	v_mfma_f32_16x16x32_bf16 v[106:109], v[138:141], v[192:195], v[106:109]
	v_mfma_f32_16x16x32_bf16 v[102:105], v[130:133], v[214:217], v[102:105]
	v_mfma_f32_16x16x32_bf16 v[94:97], v[138:141], v[214:217], v[94:97]
	v_mfma_f32_16x16x32_bf16 v[82:85], v[130:133], v[222:225], v[82:85]
	v_mfma_f32_16x16x32_bf16 v[74:77], v[138:141], v[222:225], v[74:77]
	v_mfma_f32_16x16x32_bf16 v[126:129], v[134:137], v[188:191], v[126:129]
	v_mfma_f32_16x16x32_bf16 v[122:125], v[142:145], v[188:191], v[122:125]
	v_mfma_f32_16x16x32_bf16 v[114:117], v[134:137], v[206:209], v[114:117]
	v_mfma_f32_16x16x32_bf16 v[106:109], v[142:145], v[206:209], v[106:109]
	v_mfma_f32_16x16x32_bf16 v[102:105], v[134:137], v[218:221], v[102:105]
	v_mfma_f32_16x16x32_bf16 v[94:97], v[142:145], v[218:221], v[94:97]
	v_mfma_f32_16x16x32_bf16 v[82:85], v[134:137], v[226:229], v[82:85]
	v_mfma_f32_16x16x32_bf16 v[74:77], v[142:145], v[226:229], v[74:77]
	s_setprio 0
	s_barrier
	s_add_i32 s38, 0, 0x14000
	s_add_i32 s26, s26, s47
	v_add_u32_e32 v8, s38, v199
	v_lshl_add_u64 v[162:163], s[16:17], 0, v[148:149]
	s_mov_b32 m0, s26
	ds_read_b128 v[230:233], v8
	ds_read_b128 v[234:237], v8 offset:1024
	ds_read_b128 v[238:241], v8 offset:2048
	ds_read_b128 v[242:245], v8 offset:3072
	global_load_lds_dwordx4 v[162:163], off
	v_lshl_add_u64 v[164:165], s[16:17], 0, v[152:153]
	s_add_i32 m0, s26, 0x2000
	s_nop 0
	global_load_lds_dwordx4 v[164:165], off
	s_barrier
	s_waitcnt lgkmcnt(0)
	s_setprio 1
	v_mfma_f32_16x16x32_bf16 v[118:121], v[230:233], v[184:187], v[118:121]
	v_mfma_f32_16x16x32_bf16 v[110:113], v[238:241], v[184:187], v[110:113]
	v_mfma_f32_16x16x32_bf16 v[98:101], v[230:233], v[192:195], v[98:101]
	v_mfma_f32_16x16x32_bf16 v[90:93], v[238:241], v[192:195], v[90:93]
	v_mfma_f32_16x16x32_bf16 v[86:89], v[230:233], v[214:217], v[86:89]
	v_mfma_f32_16x16x32_bf16 v[78:81], v[238:241], v[214:217], v[78:81]
	v_mfma_f32_16x16x32_bf16 v[54:57], v[230:233], v[222:225], v[54:57]
	v_mfma_f32_16x16x32_bf16 v[34:37], v[238:241], v[222:225], v[34:37]
	v_mfma_f32_16x16x32_bf16 v[118:121], v[234:237], v[188:191], v[118:121]
	v_mfma_f32_16x16x32_bf16 v[110:113], v[242:245], v[188:191], v[110:113]
	v_mfma_f32_16x16x32_bf16 v[98:101], v[234:237], v[206:209], v[98:101]
	v_mfma_f32_16x16x32_bf16 v[90:93], v[242:245], v[206:209], v[90:93]
	v_mfma_f32_16x16x32_bf16 v[86:89], v[234:237], v[218:221], v[86:89]
	v_mfma_f32_16x16x32_bf16 v[78:81], v[242:245], v[218:221], v[78:81]
	v_mfma_f32_16x16x32_bf16 v[54:57], v[234:237], v[226:229], v[54:57]
	v_mfma_f32_16x16x32_bf16 v[34:37], v[242:245], v[226:229], v[34:37]
	s_setprio 0
	s_mov_b32 m0, s66
	v_lshl_add_u64 v[202:203], s[36:37], 0, v[146:147]
	s_barrier
	ds_read_b128 v[184:187], v204 offset:16384
	ds_read_b128 v[188:191], v204 offset:17408
	ds_read_b128 v[192:195], v204 offset:18432
	ds_read_b128 v[206:209], v204 offset:19456
	ds_read_b128 v[214:217], v204 offset:20480
	ds_read_b128 v[218:221], v204 offset:21504
	ds_read_b128 v[222:225], v204 offset:22528
	ds_read_b128 v[226:229], v204 offset:23552
	global_load_lds_dwordx4 v[202:203], off
	v_lshl_add_u64 v[246:247], s[36:37], 0, v[150:151]
	s_mov_b32 m0, s68
	s_nop 0
	global_load_lds_dwordx4 v[246:247], off
	s_barrier
	s_waitcnt lgkmcnt(0)
	s_setprio 1
	v_mfma_f32_16x16x32_bf16 v[58:61], v[130:133], v[184:187], v[58:61]
	v_mfma_f32_16x16x32_bf16 v[62:65], v[138:141], v[184:187], v[62:65]
	v_mfma_f32_16x16x32_bf16 v[38:41], v[130:133], v[192:195], v[38:41]
	v_mfma_f32_16x16x32_bf16 v[42:45], v[138:141], v[192:195], v[42:45]
	v_mfma_f32_16x16x32_bf16 v[18:21], v[130:133], v[214:217], v[18:21]
	v_mfma_f32_16x16x32_bf16 v[22:25], v[138:141], v[214:217], v[22:25]
	v_mfma_f32_16x16x32_bf16 v[0:3], v[130:133], v[222:225], v[0:3]
	v_mfma_f32_16x16x32_bf16 v[4:7], v[138:141], v[222:225], v[4:7]
	v_mfma_f32_16x16x32_bf16 v[58:61], v[134:137], v[188:191], v[58:61]
	v_mfma_f32_16x16x32_bf16 v[62:65], v[142:145], v[188:191], v[62:65]
	v_mfma_f32_16x16x32_bf16 v[38:41], v[134:137], v[206:209], v[38:41]
	v_mfma_f32_16x16x32_bf16 v[42:45], v[142:145], v[206:209], v[42:45]
	v_mfma_f32_16x16x32_bf16 v[18:21], v[134:137], v[218:221], v[18:21]
	v_mfma_f32_16x16x32_bf16 v[22:25], v[142:145], v[218:221], v[22:25]
	v_mfma_f32_16x16x32_bf16 v[0:3], v[134:137], v[226:229], v[0:3]
	v_mfma_f32_16x16x32_bf16 v[4:7], v[142:145], v[226:229], v[4:7]
	s_setprio 0
	s_barrier
; #define PG8_STAGE(bufoff, gbase, voff) do { _Pragma("unroll") for (int _i = 0; _i < 2; ++_i) \
;         __builtin_amdgcn_global_load_lds((const unsigned*)((const char*)(gbase) + (voff)[_i]), (LAS unsigned*)(lds + (bufoff) + ldsw + _i * 8192), 16, 0, 0); } while (0)
; #define PG8_LDA(dst, b, h) do { _Pragma("unroll") for (int m = 0; m < 4; ++m) _Pragma("unroll") for (int k = 0; k < 2; ++k) dst[m][k] = *(const LAS bf16x8*)(lds + PG8_SA(b, h) + aoff + m * 2048 + k * 1024); } while (0)
; #define PG8_LDB(dst, b, h) do { _Pragma("unroll") for (int n = 0; n < 2; ++n) _Pragma("unroll") for (int k = 0; k < 2; ++k) dst[n][k] = *(const LAS bf16x8*)(lds + PG8_SB(b, h) + boff + n * 2048 + k * 1024); } while (0)
; #define PG8_MMA(ai, bj, At, Bt) do { __builtin_amdgcn_s_setprio(1); _Pragma("unroll") for (int m = 0; m < 4; ++m) _Pragma("unroll") for (int n = 0; n < 2; ++n) _Pragma("unroll") for (int k = 0; k < 2; ++k) \
;         acc[ai][bj][m][n] = __builtin_amdgcn_mfma_f32_16x16x32_bf16(Bt[n][k], At[m][k], acc[ai][bj][m][n], 0, 0, 0); __builtin_amdgcn_s_setprio(0); } while (0)
; #define PG8_WAIT_V(n) asm volatile("s_waitcnt vmcnt(" #n ")" ::: "memory")
; #define PG8_WAIT_L(n) asm volatile("s_waitcnt lgkmcnt(" #n ")" ::: "memory")
; #define PG8_BAR __builtin_amdgcn_s_barrier()
; #define PG8_SCHED __builtin_amdgcn_sched_barrier(0)
; template <class Epi>
; DEVI void gemm_phase(LAS unsigned char* lds, const Gemm g, const Epi& E) {
;     ...
;             PG8_STAGE(PG8_SB(0, 1), b2 + hstepB, voffB);
;             PG8_WAIT_V(6); PG8_BAR; PG8_MMA(1, 1, At, B1); PG8_BAR;
;             PG8_LDB(B0, 1, 0); PG8_SCHED; PG8_LDA(At, 1, 0); PG8_STAGE(PG8_SA(0, 1), a2 + hstepA, voffA);
;             PG8_WAIT_L(8); PG8_BAR; PG8_WAIT_L(0); PG8_MMA(0, 0, At, B0); PG8_BAR; PG8_SCHED;
;             PG8_LDB(B1, 1, 1); PG8_STAGE(PG8_SB(1, 0), b3, voffB);
;             PG8_BAR; PG8_WAIT_L(0); PG8_MMA(0, 1, At, B1); PG8_BAR;
;             PG8_LDA(At, 1, 1); PG8_STAGE(PG8_SA(1, 0), a3, voffA);
;             PG8_BAR; PG8_WAIT_L(0); PG8_MMA(1, 0, At, B0); PG8_BAR; PG8_SCHED;
	s_add_u32 s26, s16, 0x40000
	s_addc_u32 s27, s17, 0
	s_add_i32 s38, s38, s47
	v_lshl_add_u64 v[130:131], s[26:27], 0, v[148:149]
	s_mov_b32 m0, s38
	s_nop 0
	global_load_lds_dwordx4 v[130:131], off
	v_lshl_add_u64 v[130:131], s[26:27], 0, v[152:153]
	s_add_i32 m0, s38, 0x2000
	s_nop 0
	global_load_lds_dwordx4 v[130:131], off
	s_waitcnt vmcnt(6)
	s_barrier
	s_setprio 1
	v_mfma_f32_16x16x32_bf16 v[66:69], v[230:233], v[184:187], v[66:69]
	v_mfma_f32_16x16x32_bf16 v[70:73], v[238:241], v[184:187], v[70:73]
	v_mfma_f32_16x16x32_bf16 v[46:49], v[230:233], v[192:195], v[46:49]
	v_mfma_f32_16x16x32_bf16 v[50:53], v[238:241], v[192:195], v[50:53]
	v_mfma_f32_16x16x32_bf16 v[26:29], v[230:233], v[214:217], v[26:29]
	v_mfma_f32_16x16x32_bf16 v[30:33], v[238:241], v[214:217], v[30:33]
	v_mfma_f32_16x16x32_bf16 v[10:13], v[230:233], v[222:225], v[10:13]
	v_mfma_f32_16x16x32_bf16 v[14:17], v[238:241], v[222:225], v[14:17]
	v_mfma_f32_16x16x32_bf16 v[66:69], v[234:237], v[188:191], v[66:69]
	v_mfma_f32_16x16x32_bf16 v[70:73], v[242:245], v[188:191], v[70:73]
	v_mfma_f32_16x16x32_bf16 v[46:49], v[234:237], v[206:209], v[46:49]
	v_mfma_f32_16x16x32_bf16 v[50:53], v[242:245], v[206:209], v[50:53]
	v_mfma_f32_16x16x32_bf16 v[26:29], v[234:237], v[218:221], v[26:29]
	v_mfma_f32_16x16x32_bf16 v[30:33], v[242:245], v[218:221], v[30:33]
	v_mfma_f32_16x16x32_bf16 v[10:13], v[234:237], v[226:229], v[10:13]
	v_mfma_f32_16x16x32_bf16 v[14:17], v[242:245], v[226:229], v[14:17]
	s_setprio 0
	s_add_i32 s38, 0, 0x18000
	v_add_u32_e32 v8, s38, v199
	s_barrier
	ds_read_b128 v[130:133], v8
	ds_read_b128 v[134:137], v8 offset:1024
	ds_read_b128 v[138:141], v8 offset:2048
	ds_read_b128 v[142:145], v8 offset:3072
	s_add_u32 s26, s36, 0x40000
	s_addc_u32 s27, s37, 0
	s_mov_b32 m0, s69
	v_lshl_add_u64 v[230:231], s[26:27], 0, v[146:147]
	ds_read_b128 v[184:187], v204 offset:32768
	ds_read_b128 v[188:191], v204 offset:33792
	ds_read_b128 v[192:195], v204 offset:34816
	ds_read_b128 v[206:209], v204 offset:35840
	ds_read_b128 v[214:217], v204 offset:36864
	ds_read_b128 v[218:221], v204 offset:37888
	ds_read_b128 v[222:225], v204 offset:38912
	ds_read_b128 v[226:229], v204 offset:39936
	global_load_lds_dwordx4 v[230:231], off
	v_lshl_add_u64 v[230:231], s[26:27], 0, v[150:151]
	s_mov_b32 m0, s80
	s_nop 0
	global_load_lds_dwordx4 v[230:231], off
	s_waitcnt lgkmcnt(8)
	s_barrier
	s_waitcnt lgkmcnt(0)
	s_setprio 1
	v_mfma_f32_16x16x32_bf16 v[126:129], v[130:133], v[184:187], v[126:129]
	v_mfma_f32_16x16x32_bf16 v[122:125], v[138:141], v[184:187], v[122:125]
	v_mfma_f32_16x16x32_bf16 v[114:117], v[130:133], v[192:195], v[114:117]
	v_mfma_f32_16x16x32_bf16 v[106:109], v[138:141], v[192:195], v[106:109]
	v_mfma_f32_16x16x32_bf16 v[102:105], v[130:133], v[214:217], v[102:105]
	v_mfma_f32_16x16x32_bf16 v[94:97], v[138:141], v[214:217], v[94:97]
	v_mfma_f32_16x16x32_bf16 v[82:85], v[130:133], v[222:225], v[82:85]
	v_mfma_f32_16x16x32_bf16 v[74:77], v[138:141], v[222:225], v[74:77]
	v_mfma_f32_16x16x32_bf16 v[126:129], v[134:137], v[188:191], v[126:129]
	v_mfma_f32_16x16x32_bf16 v[122:125], v[142:145], v[188:191], v[122:125]
	v_mfma_f32_16x16x32_bf16 v[114:117], v[134:137], v[206:209], v[114:117]
	v_mfma_f32_16x16x32_bf16 v[106:109], v[142:145], v[206:209], v[106:109]
	v_mfma_f32_16x16x32_bf16 v[102:105], v[134:137], v[218:221], v[102:105]
	v_mfma_f32_16x16x32_bf16 v[94:97], v[142:145], v[218:221], v[94:97]
	v_mfma_f32_16x16x32_bf16 v[82:85], v[134:137], v[226:229], v[82:85]
	v_mfma_f32_16x16x32_bf16 v[74:77], v[142:145], v[226:229], v[74:77]
	s_setprio 0
	s_barrier
	s_add_i32 s26, 0, 0x1c000
	s_add_i32 s27, s38, s47
	v_add_u32_e32 v8, s26, v199
	v_lshl_add_u64 v[162:163], v[162:163], 0, s[70:71]
	s_mov_b32 m0, s27
	ds_read_b128 v[230:233], v8
	ds_read_b128 v[234:237], v8 offset:1024
	ds_read_b128 v[238:241], v8 offset:2048
	ds_read_b128 v[242:245], v8 offset:3072
	global_load_lds_dwordx4 v[162:163], off
	v_lshl_add_u64 v[162:163], v[164:165], 0, s[70:71]
	s_add_i32 m0, s27, 0x2000
	s_nop 0
	global_load_lds_dwordx4 v[162:163], off
	s_barrier
	s_waitcnt lgkmcnt(0)
	s_setprio 1
	v_mfma_f32_16x16x32_bf16 v[118:121], v[230:233], v[184:187], v[118:121]
	v_mfma_f32_16x16x32_bf16 v[110:113], v[238:241], v[184:187], v[110:113]
	v_mfma_f32_16x16x32_bf16 v[98:101], v[230:233], v[192:195], v[98:101]
	v_mfma_f32_16x16x32_bf16 v[90:93], v[238:241], v[192:195], v[90:93]
	v_mfma_f32_16x16x32_bf16 v[86:89], v[230:233], v[214:217], v[86:89]
	v_mfma_f32_16x16x32_bf16 v[78:81], v[238:241], v[214:217], v[78:81]
	v_mfma_f32_16x16x32_bf16 v[54:57], v[230:233], v[222:225], v[54:57]
	v_mfma_f32_16x16x32_bf16 v[34:37], v[238:241], v[222:225], v[34:37]
	v_mfma_f32_16x16x32_bf16 v[118:121], v[234:237], v[188:191], v[118:121]
	v_mfma_f32_16x16x32_bf16 v[110:113], v[242:245], v[188:191], v[110:113]
	v_mfma_f32_16x16x32_bf16 v[98:101], v[234:237], v[206:209], v[98:101]
	v_mfma_f32_16x16x32_bf16 v[90:93], v[242:245], v[206:209], v[90:93]
	v_mfma_f32_16x16x32_bf16 v[86:89], v[234:237], v[218:221], v[86:89]
	v_mfma_f32_16x16x32_bf16 v[78:81], v[242:245], v[218:221], v[78:81]
	v_mfma_f32_16x16x32_bf16 v[54:57], v[234:237], v[226:229], v[54:57]
	v_mfma_f32_16x16x32_bf16 v[34:37], v[242:245], v[226:229], v[34:37]
	s_setprio 0
	s_mov_b32 m0, s81
	v_lshl_add_u64 v[162:163], v[202:203], 0, s[70:71]
	s_barrier
	ds_read_b128 v[184:187], v204 offset:49152
	ds_read_b128 v[188:191], v204 offset:50176
	ds_read_b128 v[192:195], v204 offset:51200
	ds_read_b128 v[206:209], v204 offset:52224
	ds_read_b128 v[214:217], v204 offset:53248
	ds_read_b128 v[218:221], v204 offset:54272
	ds_read_b128 v[222:225], v204 offset:55296
	ds_read_b128 v[226:229], v204 offset:56320
	global_load_lds_dwordx4 v[162:163], off
	v_lshl_add_u64 v[162:163], v[246:247], 0, s[70:71]
	s_mov_b32 m0, s82
	s_nop 0
	global_load_lds_dwordx4 v[162:163], off
	s_barrier
; #define PG8_STAGE(bufoff, gbase, voff) do { _Pragma("unroll") for (int _i = 0; _i < 2; ++_i) \
;         __builtin_amdgcn_global_load_lds((const unsigned*)((const char*)(gbase) + (voff)[_i]), (LAS unsigned*)(lds + (bufoff) + ldsw + _i * 8192), 16, 0, 0); } while (0)
; #define PG8_LDA(dst, b, h) do { _Pragma("unroll") for (int m = 0; m < 4; ++m) _Pragma("unroll") for (int k = 0; k < 2; ++k) dst[m][k] = *(const LAS bf16x8*)(lds + PG8_SA(b, h) + aoff + m * 2048 + k * 1024); } while (0)
; #define PG8_LDB(dst, b, h) do { _Pragma("unroll") for (int n = 0; n < 2; ++n) _Pragma("unroll") for (int k = 0; k < 2; ++k) dst[n][k] = *(const LAS bf16x8*)(lds + PG8_SB(b, h) + boff + n * 2048 + k * 1024); } while (0)
; #define PG8_WAIT_V(n) asm volatile("s_waitcnt vmcnt(" #n ")" ::: "memory")
; #define PG8_WAIT_L(n) asm volatile("s_waitcnt lgkmcnt(" #n ")" ::: "memory")
; #define PG8_BAR __builtin_amdgcn_s_barrier()
; #define PG8_SCHED __builtin_amdgcn_sched_barrier(0)
; template <class Epi>
; DEVI void gemm_phase(LAS unsigned char* lds, const Gemm g, const Epi& E) {
;     ...
;             PG8_WAIT_V(6); PG8_BAR; PG8_MMA(1, 1, At, B1); PG8_BAR;
;             PG8_LDB(B0, 1, 0); PG8_SCHED; PG8_LDA(At, 1, 0); PG8_STAGE(PG8_SA(0, 1), a2 + hstepA, voffA);
;             PG8_WAIT_L(8); PG8_BAR; PG8_WAIT_L(0); PG8_MMA(0, 0, At, B0); PG8_BAR; PG8_SCHED;
;             PG8_LDB(B1, 1, 1); PG8_STAGE(PG8_SB(1, 0), b3, voffB);
;             PG8_BAR; PG8_WAIT_L(0); PG8_MMA(0, 1, At, B1); PG8_BAR;
;             PG8_LDA(At, 1, 1); PG8_STAGE(PG8_SA(1, 0), a3, voffA);
;             PG8_BAR; PG8_WAIT_L(0); PG8_MMA(1, 0, At, B0); PG8_BAR; PG8_SCHED;
;             PG8_STAGE(PG8_SB(1, 1), b3 + hstepB, voffB);
;             PG8_WAIT_V(6); PG8_BAR; PG8_MMA(1, 1, At, B1); PG8_BAR;
;         }
;         {
;             const int row0 = cur.pm * BM + wr * 64 + fr, col0 = cur.pn * BM + wc * 32 + (Epi::PERM ? 8 : 4) * fq; constexpr int NST = Epi::PERM ? 4 : 16;
;             float rsv[8];
;             if constexpr (Epi::RS) { f32x4 q4[8];
; #pragma unroll
;                 for (int i = 0; i < 8; ++i) q4[i] = *(const f32x4*)(E.ssq_in + (size_t)(row0 + (i >> 2) * HALF + (i & 3) * 16) * 4);
; #pragma unroll
;                 for (int i = 0; i < 8; ++i) rsv[i] = rsqrtf((((q4[i][0] + q4[i][1]) + q4[i][2]) + q4[i][3]) * (1.f / DM) + 1e-6f); }
	s_waitcnt lgkmcnt(0)
	s_setprio 1
	v_mfma_f32_16x16x32_bf16 v[58:61], v[130:133], v[184:187], v[58:61]
	v_mfma_f32_16x16x32_bf16 v[62:65], v[138:141], v[184:187], v[62:65]
	v_mfma_f32_16x16x32_bf16 v[38:41], v[130:133], v[192:195], v[38:41]
	v_mfma_f32_16x16x32_bf16 v[42:45], v[138:141], v[192:195], v[42:45]
	v_mfma_f32_16x16x32_bf16 v[18:21], v[130:133], v[214:217], v[18:21]
	v_mfma_f32_16x16x32_bf16 v[22:25], v[138:141], v[214:217], v[22:25]
	v_mfma_f32_16x16x32_bf16 v[0:3], v[130:133], v[222:225], v[0:3]
	v_mfma_f32_16x16x32_bf16 v[4:7], v[138:141], v[222:225], v[4:7]
	v_mfma_f32_16x16x32_bf16 v[58:61], v[134:137], v[188:191], v[58:61]
	v_mfma_f32_16x16x32_bf16 v[62:65], v[142:145], v[188:191], v[62:65]
	v_mfma_f32_16x16x32_bf16 v[38:41], v[134:137], v[206:209], v[38:41]
	v_mfma_f32_16x16x32_bf16 v[42:45], v[142:145], v[206:209], v[42:45]
	v_mfma_f32_16x16x32_bf16 v[18:21], v[134:137], v[218:221], v[18:21]
	v_mfma_f32_16x16x32_bf16 v[22:25], v[142:145], v[218:221], v[22:25]
	v_mfma_f32_16x16x32_bf16 v[0:3], v[134:137], v[226:229], v[0:3]
	v_mfma_f32_16x16x32_bf16 v[4:7], v[142:145], v[226:229], v[4:7]
	s_setprio 0
	s_barrier
	s_add_u32 s16, s16, 0x40080
	s_addc_u32 s17, s17, 0
	s_add_i32 s26, s26, s47
	v_lshl_add_u64 v[130:131], s[16:17], 0, v[148:149]
	s_mov_b32 m0, s26
	s_nop 0
	global_load_lds_dwordx4 v[130:131], off
	v_lshl_add_u64 v[130:131], s[16:17], 0, v[152:153]
	s_add_i32 m0, s26, 0x2000
	s_nop 0
	global_load_lds_dwordx4 v[130:131], off
	s_waitcnt vmcnt(6)
	s_barrier
	s_setprio 1
	v_mfma_f32_16x16x32_bf16 v[66:69], v[230:233], v[184:187], v[66:69]
	v_mfma_f32_16x16x32_bf16 v[70:73], v[238:241], v[184:187], v[70:73]
	v_mfma_f32_16x16x32_bf16 v[46:49], v[230:233], v[192:195], v[46:49]
	v_mfma_f32_16x16x32_bf16 v[50:53], v[238:241], v[192:195], v[50:53]
	v_mfma_f32_16x16x32_bf16 v[26:29], v[230:233], v[214:217], v[26:29]
	v_mfma_f32_16x16x32_bf16 v[30:33], v[238:241], v[214:217], v[30:33]
	v_mfma_f32_16x16x32_bf16 v[10:13], v[230:233], v[222:225], v[10:13]
	v_mfma_f32_16x16x32_bf16 v[14:17], v[238:241], v[222:225], v[14:17]
	v_mfma_f32_16x16x32_bf16 v[66:69], v[234:237], v[188:191], v[66:69]
	v_mfma_f32_16x16x32_bf16 v[70:73], v[242:245], v[188:191], v[70:73]
	v_mfma_f32_16x16x32_bf16 v[46:49], v[234:237], v[206:209], v[46:49]
	v_mfma_f32_16x16x32_bf16 v[50:53], v[242:245], v[206:209], v[50:53]
	v_mfma_f32_16x16x32_bf16 v[26:29], v[234:237], v[218:221], v[26:29]
	v_mfma_f32_16x16x32_bf16 v[30:33], v[242:245], v[218:221], v[30:33]
	v_mfma_f32_16x16x32_bf16 v[10:13], v[234:237], v[226:229], v[10:13]
	v_mfma_f32_16x16x32_bf16 v[14:17], v[242:245], v[226:229], v[14:17]
	s_setprio 0
	s_add_i32 s19, s19, 2
	s_add_u32 s14, s14, 0x100
	s_addc_u32 s15, s15, 0
	s_add_u32 s9, s9, 0x100
	s_addc_u32 s18, s18, 0
	s_cmp_gt_u32 s19, 13
	s_barrier
	s_cbranch_scc0 .LBB0_1007
	v_lshl_add_u32 v194, s4, 8, v197
	v_add_u32_e32 v184, 0xb0, v194
	v_ashrrev_i32_e32 v195, 31, v194
	v_ashrrev_i32_e32 v185, 31, v184
	v_lshl_add_u64 v[130:131], v[194:195], 4, s[76:77]
	v_lshl_add_u64 v[134:135], v[184:185], 4, s[76:77]
	global_load_dwordx4 v[206:209], v[130:131], off
	v_or_b32_e32 v192, 48, v194
	global_load_dwordx4 v[134:137], v[134:135], off
	v_or_b32_e32 v130, 16, v194
	v_ashrrev_i32_e32 v131, 31, v130
	v_lshl_add_u64 v[130:131], v[130:131], 4, s[76:77]
	global_load_dwordx4 v[214:217], v[130:131], off
	v_or_b32_e32 v130, 32, v194
	v_ashrrev_i32_e32 v131, 31, v130
	v_lshl_add_u64 v[130:131], v[130:131], 4, s[76:77]
	v_ashrrev_i32_e32 v193, 31, v192
	global_load_dwordx4 v[218:221], v[130:131], off
	v_lshl_add_u64 v[130:131], v[192:193], 4, s[76:77]
	global_load_dwordx4 v[222:225], v[130:131], off
	v_add_u32_e32 v190, 0x80, v194
	v_ashrrev_i32_e32 v191, 31, v190
	v_add_u32_e32 v188, 0x90, v194
	v_lshl_add_u64 v[130:131], v[190:191], 4, s[76:77]
	v_ashrrev_i32_e32 v189, 31, v188
	global_load_dwordx4 v[138:141], v[130:131], off
	v_lshl_add_u64 v[130:131], v[188:189], 4, s[76:77]
	global_load_dwordx4 v[142:145], v[130:131], off
	v_add_u32_e32 v186, 0xa0, v194
	v_ashrrev_i32_e32 v187, 31, v186
	v_lshl_add_u64 v[130:131], v[186:187], 4, s[76:77]
	global_load_dwordx4 v[130:133], v[130:131], off
	s_mov_b32 s0, 0x358637bd
	v_mov_b64_e32 v[202:203], s[0:1]
	s_mov_b64 s[16:17], s[12:13]
	s_mov_b64 s[14:15], s[10:11]
	s_waitcnt vmcnt(0)
; template <class Epi>
; DEVI void gemm_phase(LAS unsigned char* lds, const Gemm g, const Epi& E) {
;     ...
;                 for (int i = 0; i < 8; ++i) rsv[i] = rsqrtf((((q4[i][0] + q4[i][1]) + q4[i][2]) + q4[i][3]) * (1.f / DM) + 1e-6f); }
;             if constexpr (Epi::SOFTMAX) {
;                 LAS float* red = (LAS float*)(lds + 131072);
; #pragma unroll
;                 for (int ai = 0; ai < 2; ++ai)
; #pragma unroll
;                     for (int m = 0; m < 4; ++m) { const float sc = rsv[ai * 4 + m] * 0.0625f; float part = 0.f;
; #pragma unroll
;                         for (int bj = 0; bj < 2; ++bj)
; #pragma unroll
;                             for (int n = 0; n < 2; ++n)
; #pragma unroll
;                                 for (int j = 0; j < 4; ++j) { const float e = __expf(fmaxf(fminf(acc[ai][bj][m][n][j] * sc, 80.f), -80.f)); acc[ai][bj][m][n][j] = e; part += e; }
;                         part += __shfl_xor(part, 16); part += __shfl_xor(part, 32);
;                         if (fq == 0) red[(wr * 4 + wc) * 128 + ai * 64 + m * 16 + fr] = part; }
;                 PG8_WAIT_L(0); PG8_BAR;
; #pragma unroll
;                 for (int ai = 0; ai < 2; ++ai)
; #pragma unroll
;                     for (int m = 0; m < 4; ++m) { const LAS float* rr = red + wr * 512 + ai * 64 + m * 16 + fr;
;                         const float inv = __builtin_amdgcn_rcpf(((rr[0] + rr[128]) + rr[256]) + rr[384]); const int r = row0 + ai * HALF + m * 16;
; #pragma unroll
;                         for (int bj = 0; bj < 2; ++bj) *(u32x4*)(E.P + (size_t)r * DM + col0 + bj * HALF) = pk8(acc[ai][bj][m][0] * inv, acc[ai][bj][m][1] * inv); }
;             } else
; #pragma unroll
;             for (int am = 0; am < 4; ++am) {
;                 const int ai = am >> 1, m0 = (am & 1) * 2;
;                 f32x4 pre[2][2][2];
;                 if constexpr (Epi::PRE) {
; #pragma unroll
;                     for (int m = 0; m < 2; ++m)
; #pragma unroll
;                         for (int bj = 0; bj < 2; ++bj)
; #pragma unroll
;                             for (int n = 0; n < 2; ++n) pre[m][bj][n] = E.load(row0 + ai * HALF + (m0 + m) * 16, col0 + bj * HALF + n * NST);
;                 }
; #pragma unroll
;                 for (int mm = 0; mm < 2; ++mm) {
;                     const int m = m0 + mm;
;                     const int r = row0 + ai * HALF + m * 16; float rs = 1.f, part = 0.f;
	v_mov_b32_e32 v163, v206
	v_mov_b32_e32 v165, v208
	v_mov_b32_e32 v162, v214
	v_mov_b32_e32 v206, v215
	v_pk_add_f32 v[162:163], v[162:163], v[206:207]
	v_mov_b32_e32 v164, v216
	v_pk_add_f32 v[162:163], v[164:165], v[162:163]
	v_mov_b32_e32 v208, v217
	v_pk_add_f32 v[162:163], v[208:209], v[162:163]
	v_mov_b32_e32 v164, v224
	v_pk_fma_f32 v[162:163], v[162:163], s[72:73], v[202:203] op_sel_hi:[1,0,0]
	v_mov_b32_e32 v165, v220
	v_mul_f32_e32 v8, 0x4b800000, v163
	v_cmp_gt_f32_e64 s[4:5], s94, v163
	v_cmp_gt_f32_e32 vcc, s94, v162
	v_mov_b32_e32 v220, v225
	v_cndmask_b32_e64 v8, v163, v8, s[4:5]
	v_rsq_f32_e32 v8, v8
	s_nop 0
	v_mul_f32_e32 v163, 0x45800000, v8
	v_cndmask_b32_e64 v198, v8, v163, s[4:5]
	v_mul_f32_e32 v8, 0x4b800000, v162
	v_cndmask_b32_e32 v8, v162, v8, vcc
	v_rsq_f32_e32 v8, v8
	v_mov_b32_e32 v163, v218
	v_mov_b32_e32 v218, v223
	v_pk_mul_f32 v[128:129], v[128:129], v[198:199] op_sel_hi:[1,0]
	v_mul_f32_e32 v162, 0x45800000, v8
	v_cndmask_b32_e32 v8, v8, v162, vcc
	v_mov_b32_e32 v162, v222
	v_pk_add_f32 v[162:163], v[162:163], v[218:219]
	v_pk_mul_f32 v[126:127], v[126:127], v[198:199] op_sel_hi:[1,0]
	v_pk_add_f32 v[162:163], v[164:165], v[162:163]
	v_pk_mul_f32 v[122:123], v[122:123], v[198:199] op_sel_hi:[1,0]
	v_pk_add_f32 v[162:163], v[220:221], v[162:163]
	v_pk_mul_f32 v[120:121], v[120:121], v[198:199] op_sel_hi:[1,0]
	v_pk_fma_f32 v[162:163], v[162:163], s[72:73], v[202:203] op_sel_hi:[1,0,0]
	v_pk_mul_f32 v[118:119], v[118:119], v[198:199] op_sel_hi:[1,0]
	v_mul_f32_e32 v164, 0x4b800000, v163
	v_cmp_gt_f32_e64 s[4:5], s94, v163
	v_cmp_gt_f32_e32 vcc, s94, v162
	v_pk_mul_f32 v[110:111], v[110:111], v[198:199] op_sel_hi:[1,0]
	v_cndmask_b32_e64 v163, v163, v164, s[4:5]
	v_rsq_f32_e32 v163, v163
	v_cvt_pk_bf16_f32 v118, v118, v119
	v_cvt_pk_bf16_f32 v119, v120, v121
	v_cvt_pk_bf16_f32 v120, v110, v111
	v_mul_f32_e32 v164, 0x45800000, v163
	v_cndmask_b32_e64 v200, v163, v164, s[4:5]
	v_mul_f32_e32 v163, 0x4b800000, v162
	v_cndmask_b32_e32 v162, v162, v163, vcc
	v_rsq_f32_e32 v162, v162
	v_pk_mul_f32 v[112:113], v[112:113], v[198:199] op_sel_hi:[1,0]
	v_pk_mul_f32 v[114:115], v[114:115], v[8:9] op_sel_hi:[1,0]
	v_cvt_pk_bf16_f32 v121, v112, v113
	v_mul_f32_e32 v163, 0x45800000, v162
	v_cndmask_b32_e32 v196, v162, v163, vcc
	v_mov_b32_e32 v162, v142
	v_mov_b32_e32 v163, v138
	v_mov_b32_e32 v138, v143
	v_pk_add_f32 v[138:139], v[162:163], v[138:139]
	v_mov_b32_e32 v142, v144
	v_mov_b32_e32 v143, v140
	v_pk_add_f32 v[138:139], v[142:143], v[138:139]
	v_mov_b32_e32 v140, v145
	v_pk_add_f32 v[138:139], v[140:141], v[138:139]
	v_mov_b32_e32 v142, v134
	v_pk_fma_f32 v[140:141], v[138:139], s[72:73], v[202:203] op_sel_hi:[1,0,0]
	v_mov_b32_e32 v143, v130
	v_mul_f32_e32 v138, 0x4b800000, v141
	v_cmp_gt_f32_e64 s[4:5], s94, v141
	v_mov_b32_e32 v130, v135
	v_pk_add_f32 v[130:131], v[142:143], v[130:131]
	v_cndmask_b32_e64 v138, v141, v138, s[4:5]
	v_rsq_f32_e32 v138, v138
	v_mov_b32_e32 v134, v136
	v_mov_b32_e32 v135, v132
	v_pk_add_f32 v[130:131], v[134:135], v[130:131]
	v_mov_b32_e32 v132, v137
	v_pk_add_f32 v[130:131], v[132:133], v[130:131]
	v_mul_f32_e32 v139, 0x45800000, v138
	v_pk_fma_f32 v[130:131], v[130:131], s[72:73], v[202:203] op_sel_hi:[1,0,0]
	v_cmp_gt_f32_e32 vcc, s94, v140
	v_cndmask_b32_e64 v138, v138, v139, s[4:5]
	v_mul_f32_e32 v139, 0x4b800000, v140
	v_mul_f32_e32 v132, 0x4b800000, v131
	v_cmp_gt_f32_e64 s[4:5], s94, v131
	v_cndmask_b32_e32 v139, v140, v139, vcc
	v_rsq_f32_e32 v139, v139
	v_cndmask_b32_e64 v131, v131, v132, s[4:5]
	v_rsq_f32_e32 v131, v131
	v_pk_mul_f32 v[136:137], v[124:125], v[198:199] op_sel_hi:[1,0]
	v_mul_f32_e32 v140, 0x45800000, v139
	v_cndmask_b32_e32 v140, v139, v140, vcc
	v_mul_f32_e32 v132, 0x45800000, v131
	v_cmp_gt_f32_e32 vcc, s94, v130
	v_cndmask_b32_e64 v132, v131, v132, s[4:5]
	v_mul_f32_e32 v131, 0x4b800000, v130
	v_cndmask_b32_e32 v130, v130, v131, vcc
	v_rsq_f32_e32 v130, v130
	v_cvt_pk_bf16_f32 v125, v128, v129
	v_ashrrev_i32_e32 v134, 5, v194
	v_ashrrev_i32_e32 v135, 31, v134
	v_mul_f32_e32 v131, 0x45800000, v130
	v_cndmask_b32_e32 v130, v130, v131, vcc
	v_lshl_or_b32 v131, s84, 8, v201
	v_ashrrev_i32_e32 v128, 4, v131
	v_ashrrev_i32_e32 v129, 31, v128
	v_cvt_pk_bf16_f32 v124, v126, v127
	v_cvt_pk_bf16_f32 v126, v122, v123
	v_lshlrev_b64 v[122:123], 10, v[128:129]
	v_or_b32_e32 v110, 8, v128
	v_cvt_pk_bf16_f32 v127, v136, v137
	v_lshl_add_u64 v[136:137], v[122:123], 0, v[134:135]
	v_ashrrev_i32_e32 v111, 31, v110
	v_mad_u64_u32 v[142:143], s[0:1], v136, s34, v[178:179]
	v_lshlrev_b64 v[110:111], 10, v[110:111]
	v_mad_i32_i24 v143, v137, s34, v143
	v_lshl_add_u64 v[112:113], v[110:111], 0, v[134:135]
	global_store_dwordx4 v[142:143], v[124:127], off
	v_pk_mul_f32 v[100:101], v[100:101], v[8:9] op_sel_hi:[1,0]
	v_pk_mul_f32 v[98:99], v[98:99], v[8:9] op_sel_hi:[1,0]
	v_mad_u64_u32 v[124:125], s[0:1], v112, s34, v[178:179]
	v_mad_i32_i24 v125, v113, s34, v125
	v_pk_mul_f32 v[112:113], v[116:117], v[8:9] op_sel_hi:[1,0]
	v_pk_mul_f32 v[116:117], v[108:109], v[8:9] op_sel_hi:[1,0]
	v_pk_mul_f32 v[108:109], v[106:107], v[8:9] op_sel_hi:[1,0]
	v_cvt_pk_bf16_f32 v106, v114, v115
	v_cvt_pk_bf16_f32 v107, v112, v113
	v_cvt_pk_bf16_f32 v108, v108, v109
	v_cvt_pk_bf16_f32 v109, v116, v117
	global_store_dwordx4 v[142:143], v[106:109], off offset:512
	v_pk_mul_f32 v[94:95], v[94:95], v[200:201] op_sel_hi:[1,0]
	v_pk_mul_f32 v[96:97], v[96:97], v[200:201] op_sel_hi:[1,0]
	v_pk_mul_f32 v[106:107], v[92:93], v[8:9] op_sel_hi:[1,0]
	v_pk_mul_f32 v[92:93], v[90:91], v[8:9] op_sel_hi:[1,0]
	v_cvt_pk_bf16_f32 v90, v98, v99
	v_cvt_pk_bf16_f32 v91, v100, v101
	v_cvt_pk_bf16_f32 v92, v92, v93
; template <class Epi>
; DEVI void gemm_phase(LAS unsigned char* lds, const Gemm g, const Epi& E) {
;     ...
;                 for (int mm = 0; mm < 2; ++mm) {
;                     const int m = m0 + mm;
;                     const int r = row0 + ai * HALF + m * 16; float rs = 1.f, part = 0.f;
;                     if constexpr (Epi::RS) rs = rsv[ai * 4 + m];
;                     if constexpr (Epi::PAIR) E.pair8(cur.b, r, cur.pn * HALF + wc * 32 + 8 * fq, acc[ai][0][m][0] * rs, acc[ai][0][m][1] * rs, acc[ai][1][m][0] * rs, acc[ai][1][m][1] * rs);
;                     else
; #pragma unroll
;                     for (int bj = 0; bj < 2; ++bj) {
;                         const int c = col0 + bj * HALF; f32x4 v0 = acc[ai][bj][m][0], v1 = acc[ai][bj][m][1];
;                         if constexpr (Epi::RS) { v0 = v0 * rs; v1 = v1 * rs; }
;                         if constexpr (Epi::PRE) part += E.frag_pre8(cur.b, r, c, v0, v1, pre[mm][bj][0], pre[mm][bj][1]);
;                         else if constexpr (Epi::PERM) E.frag8(cur.b, r, c, v0, v1);
;                         else { E.frag(cur.b, r, c, v0); E.frag(cur.b, r, c + 16, v1); }
;                     }
	v_cvt_pk_bf16_f32 v93, v106, v107
	v_or_b32_e32 v98, 1, v134
	global_store_dwordx4 v[124:125], v[90:93], off offset:512
	v_ashrrev_i32_e32 v99, 31, v98
	v_pk_mul_f32 v[86:87], v[86:87], v[200:201] op_sel_hi:[1,0]
	v_pk_mul_f32 v[92:93], v[104:105], v[200:201] op_sel_hi:[1,0]
	v_pk_mul_f32 v[90:91], v[102:103], v[200:201] op_sel_hi:[1,0]
	v_pk_mul_f32 v[88:89], v[88:89], v[200:201] op_sel_hi:[1,0]
	v_cvt_pk_bf16_f32 v90, v90, v91
	v_cvt_pk_bf16_f32 v91, v92, v93
	v_cvt_pk_bf16_f32 v92, v94, v95
	v_lshl_add_u64 v[94:95], v[122:123], 0, v[98:99]
	v_cvt_pk_bf16_f32 v93, v96, v97
	v_mad_u64_u32 v[96:97], s[0:1], v94, s34, v[178:179]
	v_mad_i32_i24 v97, v95, s34, v97
	global_store_dwordx4 v[96:97], v[90:93], off
	v_lshlrev_b32_e32 v8, 5, v192
	v_and_b32_e32 v8, 0x3e0, v8
	v_pk_mul_f32 v[90:91], v[80:81], v[200:201] op_sel_hi:[1,0]
	v_pk_mul_f32 v[80:81], v[78:79], v[200:201] op_sel_hi:[1,0]
	v_cvt_pk_bf16_f32 v78, v86, v87
	v_lshl_add_u64 v[86:87], v[110:111], 0, v[98:99]
	v_cvt_pk_bf16_f32 v79, v88, v89
	v_mad_u64_u32 v[88:89], s[0:1], v86, s34, v[178:179]
	v_cvt_pk_bf16_f32 v80, v80, v81
	v_cvt_pk_bf16_f32 v81, v90, v91
	v_mad_i32_i24 v89, v87, s34, v89
	global_store_dwordx4 v[88:89], v[78:81], off
	v_pk_mul_f32 v[82:83], v[82:83], v[196:197] op_sel_hi:[1,0]
	v_pk_mul_f32 v[84:85], v[84:85], v[196:197] op_sel_hi:[1,0]
	v_ashrrev_i32_e32 v78, 5, v192
	v_ashrrev_i32_e32 v79, 31, v78
	v_lshl_add_u64 v[80:81], v[176:177], 0, v[8:9]
	v_pk_mul_f32 v[86:87], v[76:77], v[196:197] op_sel_hi:[1,0]
	v_pk_mul_f32 v[76:77], v[74:75], v[196:197] op_sel_hi:[1,0]
	v_cvt_pk_bf16_f32 v74, v82, v83
	v_lshl_add_u64 v[82:83], v[122:123], 0, v[78:79]
	v_cvt_pk_bf16_f32 v75, v84, v85
	v_mad_u64_u32 v[84:85], s[0:1], v82, s34, v[80:81]
	v_cvt_pk_bf16_f32 v76, v76, v77
	v_cvt_pk_bf16_f32 v77, v86, v87
	v_mad_i32_i24 v85, v83, s34, v85
	v_pk_mul_f32 v[54:55], v[54:55], v[196:197] op_sel_hi:[1,0]
	global_store_dwordx4 v[124:125], v[118:121], off
	global_store_dwordx4 v[84:85], v[74:77], off
	v_pk_mul_f32 v[56:57], v[56:57], v[196:197] op_sel_hi:[1,0]
	v_lshlrev_b32_e32 v8, 5, v188
	v_pk_mul_f32 v[74:75], v[36:37], v[196:197] op_sel_hi:[1,0]
	v_pk_mul_f32 v[36:37], v[34:35], v[196:197] op_sel_hi:[1,0]
	v_cvt_pk_bf16_f32 v34, v54, v55
	v_lshl_add_u64 v[54:55], v[110:111], 0, v[78:79]
	v_cvt_pk_bf16_f32 v35, v56, v57
	v_mad_u64_u32 v[56:57], s[0:1], v54, s34, v[80:81]
	v_cvt_pk_bf16_f32 v36, v36, v37
	v_cvt_pk_bf16_f32 v37, v74, v75
	v_mad_i32_i24 v57, v55, s34, v57
	v_ashrrev_i32_e32 v54, 5, v190
	global_store_dwordx4 v[56:57], v[34:37], off
	v_ashrrev_i32_e32 v55, 31, v54
	v_pk_mul_f32 v[56:57], v[64:65], v[138:139] op_sel_hi:[1,0]
	v_pk_mul_f32 v[36:37], v[60:61], v[138:139] op_sel_hi:[1,0]
	v_pk_mul_f32 v[34:35], v[58:59], v[138:139] op_sel_hi:[1,0]
	v_pk_mul_f32 v[58:59], v[62:63], v[138:139] op_sel_hi:[1,0]
	v_cvt_pk_bf16_f32 v34, v34, v35
	v_cvt_pk_bf16_f32 v35, v36, v37
	v_cvt_pk_bf16_f32 v37, v56, v57
	v_lshl_add_u64 v[56:57], v[122:123], 0, v[54:55]
	v_cvt_pk_bf16_f32 v36, v58, v59
	v_mad_u64_u32 v[58:59], s[0:1], v56, s34, v[178:179]
	v_mad_i32_i24 v59, v57, s34, v59
	global_store_dwordx4 v[58:59], v[34:37], off
	v_pk_mul_f32 v[56:57], v[72:73], v[138:139] op_sel_hi:[1,0]
	v_lshl_add_u64 v[54:55], v[110:111], 0, v[54:55]
	v_pk_mul_f32 v[36:37], v[68:69], v[138:139] op_sel_hi:[1,0]
	v_pk_mul_f32 v[34:35], v[66:67], v[138:139] op_sel_hi:[1,0]
	v_pk_mul_f32 v[58:59], v[70:71], v[138:139] op_sel_hi:[1,0]
	v_cvt_pk_bf16_f32 v34, v34, v35
	v_cvt_pk_bf16_f32 v35, v36, v37
	v_cvt_pk_bf16_f32 v37, v56, v57
	v_mad_u64_u32 v[56:57], s[0:1], v54, s34, v[178:179]
	v_cvt_pk_bf16_f32 v36, v58, v59
	v_mad_i32_i24 v57, v55, s34, v57
	v_ashrrev_i32_e32 v54, 5, v188
	global_store_dwordx4 v[56:57], v[34:37], off
	v_ashrrev_i32_e32 v55, 31, v54
; template <class Epi>
; DEVI void gemm_phase(LAS unsigned char* lds, const Gemm g, const Epi& E) {
;     ...
;                 for (int mm = 0; mm < 2; ++mm) {
;                     const int m = m0 + mm;
;                     const int r = row0 + ai * HALF + m * 16; float rs = 1.f, part = 0.f;
;                     if constexpr (Epi::RS) rs = rsv[ai * 4 + m];
;                     if constexpr (Epi::PAIR) E.pair8(cur.b, r, cur.pn * HALF + wc * 32 + 8 * fq, acc[ai][0][m][0] * rs, acc[ai][0][m][1] * rs, acc[ai][1][m][0] * rs, acc[ai][1][m][1] * rs);
;                     else
; #pragma unroll
;                     for (int bj = 0; bj < 2; ++bj) {
;                         const int c = col0 + bj * HALF; f32x4 v0 = acc[ai][bj][m][0], v1 = acc[ai][bj][m][1];
;                         if constexpr (Epi::RS) { v0 = v0 * rs; v1 = v1 * rs; }
;                         if constexpr (Epi::PRE) part += E.frag_pre8(cur.b, r, c, v0, v1, pre[mm][bj][0], pre[mm][bj][1]);
;                         else if constexpr (Epi::PERM) E.frag8(cur.b, r, c, v0, v1);
;                         else { E.frag(cur.b, r, c, v0); E.frag(cur.b, r, c + 16, v1); }
;                     }
	v_and_b32_e32 v8, 0x3e0, v8
	v_pk_mul_f32 v[36:37], v[40:41], v[140:141] op_sel_hi:[1,0]
	v_pk_mul_f32 v[34:35], v[38:39], v[140:141] op_sel_hi:[1,0]
	v_pk_mul_f32 v[38:39], v[44:45], v[140:141] op_sel_hi:[1,0]
	v_lshl_add_u64 v[56:57], v[176:177], 0, v[8:9]
	v_pk_mul_f32 v[40:41], v[42:43], v[140:141] op_sel_hi:[1,0]
	v_cvt_pk_bf16_f32 v34, v34, v35
	v_cvt_pk_bf16_f32 v35, v36, v37
	v_cvt_pk_bf16_f32 v37, v38, v39
	v_lshl_add_u64 v[38:39], v[122:123], 0, v[54:55]
	v_cvt_pk_bf16_f32 v36, v40, v41
	v_mad_u64_u32 v[40:41], s[0:1], v38, s34, v[56:57]
	v_mad_i32_i24 v41, v39, s34, v41
	global_store_dwordx4 v[40:41], v[34:37], off
	v_pk_mul_f32 v[38:39], v[52:53], v[140:141] op_sel_hi:[1,0]
	v_pk_mul_f32 v[40:41], v[50:51], v[140:141] op_sel_hi:[1,0]
	v_pk_mul_f32 v[36:37], v[48:49], v[140:141] op_sel_hi:[1,0]
	v_pk_mul_f32 v[34:35], v[46:47], v[140:141] op_sel_hi:[1,0]
	v_pk_mul_f32 v[20:21], v[20:21], v[132:133] op_sel_hi:[1,0]
	v_cvt_pk_bf16_f32 v34, v34, v35
	v_cvt_pk_bf16_f32 v35, v36, v37
	v_cvt_pk_bf16_f32 v37, v38, v39
	v_lshl_add_u64 v[38:39], v[110:111], 0, v[54:55]
	v_cvt_pk_bf16_f32 v36, v40, v41
	v_mad_u64_u32 v[40:41], s[0:1], v38, s34, v[56:57]
	v_mad_i32_i24 v41, v39, s34, v41
	global_store_dwordx4 v[40:41], v[34:37], off
	v_pk_mul_f32 v[18:19], v[18:19], v[132:133] op_sel_hi:[1,0]
	v_pk_mul_f32 v[22:23], v[22:23], v[132:133] op_sel_hi:[1,0]
	v_ashrrev_i32_e32 v34, 5, v186
	v_ashrrev_i32_e32 v35, 31, v34
	v_pk_mul_f32 v[24:25], v[24:25], v[132:133] op_sel_hi:[1,0]
	v_cvt_pk_bf16_f32 v18, v18, v19
	v_cvt_pk_bf16_f32 v19, v20, v21
	v_cvt_pk_bf16_f32 v20, v22, v23
	v_lshl_add_u64 v[22:23], v[122:123], 0, v[34:35]
	v_cvt_pk_bf16_f32 v21, v24, v25
	v_mad_u64_u32 v[24:25], s[0:1], v22, s34, v[178:179]
	v_mad_i32_i24 v25, v23, s34, v25
	global_store_dwordx4 v[24:25], v[18:21], off
	v_pk_mul_f32 v[22:23], v[32:33], v[132:133] op_sel_hi:[1,0]
	v_pk_mul_f32 v[24:25], v[30:31], v[132:133] op_sel_hi:[1,0]
	v_pk_mul_f32 v[20:21], v[28:29], v[132:133] op_sel_hi:[1,0]
	v_pk_mul_f32 v[18:19], v[26:27], v[132:133] op_sel_hi:[1,0]
	v_lshlrev_b32_e32 v8, 5, v184
	v_cvt_pk_bf16_f32 v18, v18, v19
	v_cvt_pk_bf16_f32 v19, v20, v21
	v_cvt_pk_bf16_f32 v21, v22, v23
	v_lshl_add_u64 v[22:23], v[110:111], 0, v[34:35]
	v_cvt_pk_bf16_f32 v20, v24, v25
	v_mad_u64_u32 v[24:25], s[0:1], v22, s34, v[178:179]
	v_mad_i32_i24 v25, v23, s34, v25
	global_store_dwordx4 v[24:25], v[18:21], off
	v_and_b32_e32 v8, 0x3e0, v8
	v_pk_mul_f32 v[2:3], v[2:3], v[130:131] op_sel_hi:[1,0]
	v_ashrrev_i32_e32 v18, 5, v184
	v_ashrrev_i32_e32 v19, 31, v18
	v_pk_mul_f32 v[0:1], v[0:1], v[130:131] op_sel_hi:[1,0]
	v_pk_mul_f32 v[4:5], v[4:5], v[130:131] op_sel_hi:[1,0]
	v_lshl_add_u64 v[20:21], v[176:177], 0, v[8:9]
	v_pk_mul_f32 v[6:7], v[6:7], v[130:131] op_sel_hi:[1,0]
	v_cvt_pk_bf16_f32 v0, v0, v1
	v_cvt_pk_bf16_f32 v1, v2, v3
	v_cvt_pk_bf16_f32 v2, v4, v5
	v_lshl_add_u64 v[4:5], v[122:123], 0, v[18:19]
	v_cvt_pk_bf16_f32 v3, v6, v7
	v_mad_u64_u32 v[6:7], s[0:1], v4, s34, v[20:21]
	v_mad_i32_i24 v7, v5, s34, v7
	global_store_dwordx4 v[6:7], v[0:3], off
	v_pk_mul_f32 v[4:5], v[16:17], v[130:131] op_sel_hi:[1,0]
	v_pk_mul_f32 v[6:7], v[14:15], v[130:131] op_sel_hi:[1,0]
	v_pk_mul_f32 v[2:3], v[12:13], v[130:131] op_sel_hi:[1,0]
	v_pk_mul_f32 v[0:1], v[10:11], v[130:131] op_sel_hi:[1,0]
	s_and_b64 vcc, exec, s[2:3]
	v_cvt_pk_bf16_f32 v0, v0, v1
	v_cvt_pk_bf16_f32 v1, v2, v3
	v_cvt_pk_bf16_f32 v3, v4, v5
	v_lshl_add_u64 v[4:5], v[110:111], 0, v[18:19]
	v_cvt_pk_bf16_f32 v2, v6, v7
	v_mad_u64_u32 v[6:7], s[0:1], v4, s34, v[20:21]
	v_mad_i32_i24 v7, v5, s34, v7
	s_mov_b32 s84, s8
	s_mov_b32 s4, s6
	global_store_dwordx4 v[6:7], v[0:3], off
	s_cbranch_vccz .LBB0_1000
	s_waitcnt vmcnt(0)
	s_cmpk_gt_u32 s46, 0xff
	s_cbranch_scc1 .LBB0_1011
	s_barrier

; #define PG8_STAGE(bufoff, gbase, voff) do { _Pragma("unroll") for (int _i = 0; _i < 2; ++_i) \
;         __builtin_amdgcn_global_load_lds((const unsigned*)((const char*)(gbase) + (voff)[_i]), (LAS unsigned*)(lds + (bufoff) + ldsw + _i * 8192), 16, 0, 0); } while (0)
; #define PG8_LDA(dst, b, h) do { _Pragma("unroll") for (int m = 0; m < 4; ++m) _Pragma("unroll") for (int k = 0; k < 2; ++k) dst[m][k] = *(const LAS bf16x8*)(lds + PG8_SA(b, h) + aoff + m * 2048 + k * 1024); } while (0)
; #define PG8_LDB(dst, b, h) do { _Pragma("unroll") for (int n = 0; n < 2; ++n) _Pragma("unroll") for (int k = 0; k < 2; ++k) dst[n][k] = *(const LAS bf16x8*)(lds + PG8_SB(b, h) + boff + n * 2048 + k * 1024); } while (0)
; #define PG8_MMA(ai, bj, At, Bt) do { __builtin_amdgcn_s_setprio(1); _Pragma("unroll") for (int m = 0; m < 4; ++m) _Pragma("unroll") for (int n = 0; n < 2; ++n) _Pragma("unroll") for (int k = 0; k < 2; ++k) \
;         acc[ai][bj][m][n] = __builtin_amdgcn_mfma_f32_16x16x32_bf16(Bt[n][k], At[m][k], acc[ai][bj][m][n], 0, 0, 0); __builtin_amdgcn_s_setprio(0); } while (0)
; #define PG8_WAIT_V(n) asm volatile("s_waitcnt vmcnt(" #n ")" ::: "memory")
; #define PG8_WAIT_L(n) asm volatile("s_waitcnt lgkmcnt(" #n ")" ::: "memory")
; #define PG8_BAR __builtin_amdgcn_s_barrier()
; #define PG8_SCHED __builtin_amdgcn_sched_barrier(0)
; template <class Epi>
; DEVI void gemm_phase(LAS unsigned char* lds, const Gemm g, const Epi& E) {
;     ...
;             PG8_LDB(B0, 0, 0); PG8_SCHED; PG8_LDA(At, 0, 0); PG8_STAGE(PG8_SA(1, 1), a1 + hstepA, voffA);
;             PG8_WAIT_L(8); PG8_BAR; PG8_WAIT_L(0); PG8_MMA(0, 0, At, B0); PG8_BAR; PG8_SCHED;
;             PG8_LDB(B1, 0, 1); PG8_STAGE(PG8_SB(0, 0), b2, voffB);
;             PG8_BAR; PG8_WAIT_L(0); PG8_MMA(0, 1, At, B1); PG8_BAR;
;             PG8_LDA(At, 0, 1); PG8_STAGE(PG8_SA(0, 0), a2, voffA);
;             PG8_BAR; PG8_WAIT_L(0); PG8_MMA(1, 0, At, B0); PG8_BAR; PG8_SCHED;
;             PG8_STAGE(PG8_SB(0, 1), b2 + hstepB, voffB);
;             PG8_WAIT_V(6); PG8_BAR; PG8_MMA(1, 1, At, B1); PG8_BAR;
;             PG8_LDB(B0, 1, 0); PG8_SCHED; PG8_LDA(At, 1, 0); PG8_STAGE(PG8_SA(0, 1), a2 + hstepA, voffA);
;             PG8_WAIT_L(8); PG8_BAR; PG8_WAIT_L(0); PG8_MMA(0, 0, At, B0); PG8_BAR; PG8_SCHED;
.LBB0_1127:
	s_add_u32 s14, s12, 0x100
	s_addc_u32 s15, s13, 0
	s_add_i32 s48, 0, 0x10000
	v_add_u32_e32 v81, s48, v79
	ds_read_b128 v[82:85], v81
	ds_read_b128 v[86:89], v81 offset:1024
	ds_read_b128 v[90:93], v81 offset:2048
	ds_read_b128 v[94:97], v81 offset:3072
	s_cmp_eq_u32 s47, 4
	s_cselect_b32 s37, s9, s15
	s_cselect_b32 s36, s8, s14
	s_cselect_b32 s17, s11, s7
	s_cselect_b32 s16, s10, s5
	v_lshl_add_u64 v[130:131], s[12:13], 0, v[74:75]
	s_add_i32 m0, s18, 0xc000
	ds_read_b128 v[98:101], v80
	ds_read_b128 v[102:105], v80 offset:1024
	ds_read_b128 v[106:109], v80 offset:2048
	ds_read_b128 v[110:113], v80 offset:3072
	ds_read_b128 v[114:117], v80 offset:4096
	ds_read_b128 v[118:121], v80 offset:5120
	ds_read_b128 v[122:125], v80 offset:6144
	ds_read_b128 v[126:129], v80 offset:7168
	global_load_lds_dwordx4 v[130:131], off
	v_lshl_add_u64 v[130:131], s[12:13], 0, v[76:77]
	s_add_i32 m0, s18, 0xe000
	s_nop 0
	global_load_lds_dwordx4 v[130:131], off
	s_waitcnt lgkmcnt(8)
	s_barrier
	s_waitcnt lgkmcnt(0)
	s_setprio 1
	v_mfma_f32_16x16x32_bf16 v[62:65], v[82:85], v[98:101], v[62:65]
	v_mfma_f32_16x16x32_bf16 v[58:61], v[90:93], v[98:101], v[58:61]
	v_mfma_f32_16x16x32_bf16 v[54:57], v[82:85], v[106:109], v[54:57]
	v_mfma_f32_16x16x32_bf16 v[50:53], v[90:93], v[106:109], v[50:53]
	v_mfma_f32_16x16x32_bf16 v[46:49], v[82:85], v[114:117], v[46:49]
	v_mfma_f32_16x16x32_bf16 v[42:45], v[90:93], v[114:117], v[42:45]
	v_mfma_f32_16x16x32_bf16 v[38:41], v[82:85], v[122:125], v[38:41]
	v_mfma_f32_16x16x32_bf16 v[34:37], v[90:93], v[122:125], v[34:37]
	v_mfma_f32_16x16x32_bf16 v[62:65], v[86:89], v[102:105], v[62:65]
	v_mfma_f32_16x16x32_bf16 v[58:61], v[94:97], v[102:105], v[58:61]
	v_mfma_f32_16x16x32_bf16 v[54:57], v[86:89], v[110:113], v[54:57]
	v_mfma_f32_16x16x32_bf16 v[50:53], v[94:97], v[110:113], v[50:53]
	v_mfma_f32_16x16x32_bf16 v[46:49], v[86:89], v[118:121], v[46:49]
	v_mfma_f32_16x16x32_bf16 v[42:45], v[94:97], v[118:121], v[42:45]
	v_mfma_f32_16x16x32_bf16 v[38:41], v[86:89], v[126:129], v[38:41]
	v_mfma_f32_16x16x32_bf16 v[34:37], v[94:97], v[126:129], v[34:37]
	s_setprio 0
	s_barrier
	s_add_i32 s12, s48, s1
	v_lshl_add_u64 v[130:131], s[16:17], 0, v[70:71]
	s_mov_b32 m0, s12
	v_lshl_add_u64 v[132:133], s[16:17], 0, v[66:67]
	global_load_lds_dwordx4 v[130:131], off
	s_add_i32 m0, s12, 0x2000
	s_nop 0
	global_load_lds_dwordx4 v[132:133], off
	s_barrier
	s_waitcnt lgkmcnt(0)
	s_setprio 1
	s_setprio 0
	s_mov_b32 m0, s18
	v_lshl_add_u64 v[134:135], s[36:37], 0, v[72:73]
	s_barrier
	ds_read_b128 v[98:101], v80 offset:16384
	ds_read_b128 v[102:105], v80 offset:17408
	ds_read_b128 v[106:109], v80 offset:18432
	ds_read_b128 v[110:113], v80 offset:19456
	ds_read_b128 v[114:117], v80 offset:20480
	ds_read_b128 v[118:121], v80 offset:21504
	ds_read_b128 v[122:125], v80 offset:22528
	ds_read_b128 v[126:129], v80 offset:23552
	global_load_lds_dwordx4 v[134:135], off
	v_lshl_add_u64 v[136:137], s[36:37], 0, v[68:69]
	s_mov_b32 m0, s19
	s_nop 0
	global_load_lds_dwordx4 v[136:137], off
	s_barrier
	s_waitcnt lgkmcnt(0)
	s_setprio 1
	v_mfma_f32_16x16x32_bf16 v[30:33], v[82:85], v[98:101], v[30:33]
	v_mfma_f32_16x16x32_bf16 v[26:29], v[90:93], v[98:101], v[26:29]
	v_mfma_f32_16x16x32_bf16 v[22:25], v[82:85], v[106:109], v[22:25]
	v_mfma_f32_16x16x32_bf16 v[18:21], v[90:93], v[106:109], v[18:21]
	v_mfma_f32_16x16x32_bf16 v[14:17], v[82:85], v[114:117], v[14:17]
	v_mfma_f32_16x16x32_bf16 v[10:13], v[90:93], v[114:117], v[10:13]
	v_mfma_f32_16x16x32_bf16 v[4:7], v[82:85], v[122:125], v[4:7]
	v_mfma_f32_16x16x32_bf16 v[0:3], v[90:93], v[122:125], v[0:3]
	v_mfma_f32_16x16x32_bf16 v[30:33], v[86:89], v[102:105], v[30:33]
	v_mfma_f32_16x16x32_bf16 v[26:29], v[94:97], v[102:105], v[26:29]
	v_mfma_f32_16x16x32_bf16 v[22:25], v[86:89], v[110:113], v[22:25]
	v_mfma_f32_16x16x32_bf16 v[18:21], v[94:97], v[110:113], v[18:21]
	v_mfma_f32_16x16x32_bf16 v[14:17], v[86:89], v[118:121], v[14:17]
	v_mfma_f32_16x16x32_bf16 v[10:13], v[94:97], v[118:121], v[10:13]
	v_mfma_f32_16x16x32_bf16 v[4:7], v[86:89], v[126:129], v[4:7]
	v_mfma_f32_16x16x32_bf16 v[0:3], v[94:97], v[126:129], v[0:3]
	s_setprio 0
	s_barrier
	s_add_u32 s12, s16, 0x20000
	s_addc_u32 s13, s17, 0
	s_mov_b32 m0, s26
	v_lshl_add_u64 v[82:83], s[12:13], 0, v[70:71]
	global_load_lds_dwordx4 v[82:83], off
	v_lshl_add_u64 v[82:83], s[12:13], 0, v[66:67]
	s_mov_b32 m0, s27
	s_nop 0
	global_load_lds_dwordx4 v[82:83], off
	s_waitcnt vmcnt(6)
	s_barrier
	s_setprio 1
	s_setprio 0
	s_add_i32 s48, 0, 0x18000
	v_add_u32_e32 v81, s48, v79
	s_barrier
	ds_read_b128 v[82:85], v81
	ds_read_b128 v[86:89], v81 offset:1024
	ds_read_b128 v[90:93], v81 offset:2048
	ds_read_b128 v[94:97], v81 offset:3072
	s_add_u32 s12, s36, 0x28000
	s_addc_u32 s13, s37, 0
	s_mov_b32 m0, s38
	v_lshl_add_u64 v[138:139], s[12:13], 0, v[72:73]
	ds_read_b128 v[98:101], v80 offset:32768
	ds_read_b128 v[102:105], v80 offset:33792
	ds_read_b128 v[106:109], v80 offset:34816
	ds_read_b128 v[110:113], v80 offset:35840
	ds_read_b128 v[114:117], v80 offset:36864
	ds_read_b128 v[118:121], v80 offset:37888
	ds_read_b128 v[122:125], v80 offset:38912
	ds_read_b128 v[126:129], v80 offset:39936
	global_load_lds_dwordx4 v[138:139], off
	v_lshl_add_u64 v[138:139], s[12:13], 0, v[68:69]
	s_mov_b32 m0, s39
	s_nop 0
	global_load_lds_dwordx4 v[138:139], off
	s_waitcnt lgkmcnt(8)
	s_barrier
; #define PG8_STAGE(bufoff, gbase, voff) do { _Pragma("unroll") for (int _i = 0; _i < 2; ++_i) \
;         __builtin_amdgcn_global_load_lds((const unsigned*)((const char*)(gbase) + (voff)[_i]), (LAS unsigned*)(lds + (bufoff) + ldsw + _i * 8192), 16, 0, 0); } while (0)
; #define PG8_LDA(dst, b, h) do { _Pragma("unroll") for (int m = 0; m < 4; ++m) _Pragma("unroll") for (int k = 0; k < 2; ++k) dst[m][k] = *(const LAS bf16x8*)(lds + PG8_SA(b, h) + aoff + m * 2048 + k * 1024); } while (0)
; #define PG8_LDB(dst, b, h) do { _Pragma("unroll") for (int n = 0; n < 2; ++n) _Pragma("unroll") for (int k = 0; k < 2; ++k) dst[n][k] = *(const LAS bf16x8*)(lds + PG8_SB(b, h) + boff + n * 2048 + k * 1024); } while (0)
; #define PG8_MMA(ai, bj, At, Bt) do { __builtin_amdgcn_s_setprio(1); _Pragma("unroll") for (int m = 0; m < 4; ++m) _Pragma("unroll") for (int n = 0; n < 2; ++n) _Pragma("unroll") for (int k = 0; k < 2; ++k) \
;         acc[ai][bj][m][n] = __builtin_amdgcn_mfma_f32_16x16x32_bf16(Bt[n][k], At[m][k], acc[ai][bj][m][n], 0, 0, 0); __builtin_amdgcn_s_setprio(0); } while (0)
; template <class Epi>
; DEVI void gemm_phase(LAS unsigned char* lds, const Gemm g, const Epi& E) {
;     ...
;             PG8_LDB(B0, 1, 0); PG8_SCHED; PG8_LDA(At, 1, 0); PG8_STAGE(PG8_SA(0, 1), a2 + hstepA, voffA);
;             PG8_WAIT_L(8); PG8_BAR; PG8_WAIT_L(0); PG8_MMA(0, 0, At, B0); PG8_BAR; PG8_SCHED;
;             PG8_LDB(B1, 1, 1); PG8_STAGE(PG8_SB(1, 0), b3, voffB);
;             PG8_BAR; PG8_WAIT_L(0); PG8_MMA(0, 1, At, B1); PG8_BAR;
;             PG8_LDA(At, 1, 1); PG8_STAGE(PG8_SA(1, 0), a3, voffA);
;             PG8_BAR; PG8_WAIT_L(0); PG8_MMA(1, 0, At, B0); PG8_BAR; PG8_SCHED;
;             PG8_STAGE(PG8_SB(1, 1), b3 + hstepB, voffB);
;             PG8_WAIT_V(6); PG8_BAR; PG8_MMA(1, 1, At, B1); PG8_BAR;
;         }
;     ...
;                     for (int bj = 0; bj < 2; ++bj) {
;                         const int c = col0 + bj * HALF; f32x4 v0 = acc[ai][bj][m][0], v1 = acc[ai][bj][m][1];
;                         if constexpr (Epi::RS) { v0 = v0 * rs; v1 = v1 * rs; }
;                         if constexpr (Epi::PRE) part += E.frag_pre8(cur.b, r, c, v0, v1, pre[mm][bj][0], pre[mm][bj][1]);
;                         else if constexpr (Epi::PERM) E.frag8(cur.b, r, c, v0, v1);
;                         else { E.frag(cur.b, r, c, v0); E.frag(cur.b, r, c + 16, v1); }
	s_waitcnt lgkmcnt(0)
	s_setprio 1
	v_mfma_f32_16x16x32_bf16 v[62:65], v[82:85], v[98:101], v[62:65]
	v_mfma_f32_16x16x32_bf16 v[58:61], v[90:93], v[98:101], v[58:61]
	v_mfma_f32_16x16x32_bf16 v[54:57], v[82:85], v[106:109], v[54:57]
	v_mfma_f32_16x16x32_bf16 v[50:53], v[90:93], v[106:109], v[50:53]
	v_mfma_f32_16x16x32_bf16 v[46:49], v[82:85], v[114:117], v[46:49]
	v_mfma_f32_16x16x32_bf16 v[42:45], v[90:93], v[114:117], v[42:45]
	v_mfma_f32_16x16x32_bf16 v[38:41], v[82:85], v[122:125], v[38:41]
	v_mfma_f32_16x16x32_bf16 v[34:37], v[90:93], v[122:125], v[34:37]
	v_mfma_f32_16x16x32_bf16 v[62:65], v[86:89], v[102:105], v[62:65]
	v_mfma_f32_16x16x32_bf16 v[58:61], v[94:97], v[102:105], v[58:61]
	v_mfma_f32_16x16x32_bf16 v[54:57], v[86:89], v[110:113], v[54:57]
	v_mfma_f32_16x16x32_bf16 v[50:53], v[94:97], v[110:113], v[50:53]
	v_mfma_f32_16x16x32_bf16 v[46:49], v[86:89], v[118:121], v[46:49]
	v_mfma_f32_16x16x32_bf16 v[42:45], v[94:97], v[118:121], v[42:45]
	v_mfma_f32_16x16x32_bf16 v[38:41], v[86:89], v[126:129], v[38:41]
	v_mfma_f32_16x16x32_bf16 v[34:37], v[94:97], v[126:129], v[34:37]
	s_setprio 0
	s_barrier
	s_add_i32 s12, s48, s1
	v_lshl_add_u64 v[98:99], v[130:131], 0, s[70:71]
	s_mov_b32 m0, s12
	s_nop 0
	global_load_lds_dwordx4 v[98:99], off
	v_lshl_add_u64 v[98:99], v[132:133], 0, s[70:71]
	s_add_i32 m0, s12, 0x2000
	s_nop 0
	global_load_lds_dwordx4 v[98:99], off
	s_barrier
	s_waitcnt lgkmcnt(0)
	s_setprio 1
	s_setprio 0
	s_mov_b32 m0, s41
	v_lshl_add_u64 v[130:131], v[134:135], 0, s[70:71]
	s_barrier
	ds_read_b128 v[98:101], v80 offset:49152
	ds_read_b128 v[102:105], v80 offset:50176
	ds_read_b128 v[106:109], v80 offset:51200
	ds_read_b128 v[110:113], v80 offset:52224
	ds_read_b128 v[114:117], v80 offset:53248
	ds_read_b128 v[118:121], v80 offset:54272
	ds_read_b128 v[122:125], v80 offset:55296
	ds_read_b128 v[126:129], v80 offset:56320
	global_load_lds_dwordx4 v[130:131], off
	v_lshl_add_u64 v[130:131], v[136:137], 0, s[70:71]
	s_mov_b32 m0, s42
	s_nop 0
	global_load_lds_dwordx4 v[130:131], off
	s_barrier
	s_waitcnt lgkmcnt(0)
	s_setprio 1
	v_mfma_f32_16x16x32_bf16 v[30:33], v[82:85], v[98:101], v[30:33]
	v_mfma_f32_16x16x32_bf16 v[26:29], v[90:93], v[98:101], v[26:29]
	v_mfma_f32_16x16x32_bf16 v[22:25], v[82:85], v[106:109], v[22:25]
	v_mfma_f32_16x16x32_bf16 v[18:21], v[90:93], v[106:109], v[18:21]
	v_mfma_f32_16x16x32_bf16 v[14:17], v[82:85], v[114:117], v[14:17]
	v_mfma_f32_16x16x32_bf16 v[10:13], v[90:93], v[114:117], v[10:13]
	v_mfma_f32_16x16x32_bf16 v[4:7], v[82:85], v[122:125], v[4:7]
	v_mfma_f32_16x16x32_bf16 v[0:3], v[90:93], v[122:125], v[0:3]
	v_mfma_f32_16x16x32_bf16 v[30:33], v[86:89], v[102:105], v[30:33]
	v_mfma_f32_16x16x32_bf16 v[26:29], v[94:97], v[102:105], v[26:29]
	v_mfma_f32_16x16x32_bf16 v[22:25], v[86:89], v[110:113], v[22:25]
	v_mfma_f32_16x16x32_bf16 v[18:21], v[94:97], v[110:113], v[18:21]
	v_mfma_f32_16x16x32_bf16 v[14:17], v[86:89], v[118:121], v[14:17]
	v_mfma_f32_16x16x32_bf16 v[10:13], v[94:97], v[118:121], v[10:13]
	v_mfma_f32_16x16x32_bf16 v[4:7], v[86:89], v[126:129], v[4:7]
	v_mfma_f32_16x16x32_bf16 v[0:3], v[94:97], v[126:129], v[0:3]
	s_setprio 0
	s_barrier
	s_add_u32 s12, s16, 0x20080
	s_addc_u32 s13, s17, 0
	s_mov_b32 m0, s43
	v_lshl_add_u64 v[82:83], s[12:13], 0, v[70:71]
	global_load_lds_dwordx4 v[82:83], off
	v_lshl_add_u64 v[82:83], s[12:13], 0, v[66:67]
	s_mov_b32 m0, s44
	s_nop 0
	global_load_lds_dwordx4 v[82:83], off
	s_waitcnt vmcnt(6)
	s_barrier
	s_setprio 1
	s_setprio 0
	s_add_i32 s47, s47, 2
	s_add_u32 s5, s5, 0x100
	s_addc_u32 s7, s7, 0
	s_cmp_gt_u32 s47, 5
	s_mov_b64 s[12:13], s[14:15]
	s_barrier
	s_cbranch_scc0 .LBB0_1127
	s_ashr_i32 s5, s4, 31
	v_lshl_add_u32 v82, s40, 8, v78
	s_lshl_b64 s[4:5], s[4:5], 19
	v_readlane_b32 s7, v253, 50
	s_add_u32 s4, s7, s4
	v_readlane_b32 s7, v253, 51
	v_ashrrev_i32_e32 v83, 31, v82
	s_addc_u32 s5, s7, s5
	v_lshlrev_b64 v[84:85], 9, v[82:83]
	v_lshl_add_u64 v[84:85], s[4:5], 0, v[84:85]
	v_lshl_add_u64 v[84:85], v[84:85], 0, v[8:9]
	global_store_dwordx4 v[84:85], v[62:65], off
	global_store_dwordx4 v[84:85], v[58:61], off offset:64
	s_mov_b32 s40, s46
	s_mov_b64 s[14:15], s[10:11]
	v_or_b32_e32 v58, 16, v82
	v_ashrrev_i32_e32 v59, 31, v58
	v_lshlrev_b64 v[58:59], 9, v[58:59]
	v_lshl_add_u64 v[58:59], s[4:5], 0, v[58:59]
	v_lshl_add_u64 v[58:59], v[58:59], 0, v[8:9]
	global_store_dwordx4 v[58:59], v[54:57], off
	global_store_dwordx4 v[58:59], v[50:53], off offset:64
	s_mov_b64 s[12:13], s[8:9]
	s_nop 0
	v_or_b32_e32 v50, 32, v82
	v_ashrrev_i32_e32 v51, 31, v50
	v_lshlrev_b64 v[50:51], 9, v[50:51]
	v_lshl_add_u64 v[50:51], s[4:5], 0, v[50:51]
	v_lshl_add_u64 v[50:51], v[50:51], 0, v[8:9]
	global_store_dwordx4 v[50:51], v[46:49], off
	global_store_dwordx4 v[50:51], v[42:45], off offset:64
	s_nop 1
	v_or_b32_e32 v42, 48, v82
	v_ashrrev_i32_e32 v43, 31, v42
	v_lshlrev_b64 v[42:43], 9, v[42:43]
	v_lshl_add_u64 v[42:43], s[4:5], 0, v[42:43]
	v_lshl_add_u64 v[42:43], v[42:43], 0, v[8:9]
	s_mov_b64 s[4:5], 0x10000
	global_store_dwordx4 v[42:43], v[38:41], off
	global_store_dwordx4 v[42:43], v[34:37], off offset:64
	s_nop 1
	v_lshl_add_u64 v[34:35], v[84:85], 0, s[4:5]
	s_mov_b32 s4, 0x10000
	v_add_co_u32_e32 v36, vcc, s4, v84
	s_mov_b64 s[4:5], 0x12000
	s_nop 0
	v_addc_co_u32_e32 v37, vcc, 0, v85, vcc
	global_store_dwordx4 v[36:37], v[30:33], off
	global_store_dwordx4 v[34:35], v[26:29], off offset:64
	s_nop 1
	v_lshl_add_u64 v[26:27], v[84:85], 0, s[4:5]
	s_mov_b32 s4, 0x12000
	v_add_co_u32_e32 v28, vcc, s4, v84
	s_mov_b64 s[4:5], 0x14000
	s_nop 0
	v_addc_co_u32_e32 v29, vcc, 0, v85, vcc
	global_store_dwordx4 v[28:29], v[22:25], off
	global_store_dwordx4 v[26:27], v[18:21], off offset:64
	s_nop 1
	v_add_co_u32_e32 v20, vcc, 0x14000, v84
	v_lshl_add_u64 v[18:19], v[84:85], 0, s[4:5]
	s_nop 0
	v_addc_co_u32_e32 v21, vcc, 0, v85, vcc
	global_store_dwordx4 v[20:21], v[14:17], off
	global_store_dwordx4 v[18:19], v[10:13], off offset:64
	s_mov_b64 s[4:5], 0x16000
	s_nop 0
	v_add_co_u32_e32 v12, vcc, 0x16000, v84
	v_lshl_add_u64 v[10:11], v[84:85], 0, s[4:5]
	s_nop 0
	v_addc_co_u32_e32 v13, vcc, 0, v85, vcc
	s_and_b64 vcc, exec, s[2:3]
	s_mov_b32 s4, s6
	global_store_dwordx4 v[12:13], v[4:7], off
	global_store_dwordx4 v[10:11], v[0:3], off offset:64
	s_cbranch_vccz .LBB0_1122
	s_branch .LBB0_1131

; #define PG8_STAGE(bufoff, gbase, voff) do { _Pragma("unroll") for (int _i = 0; _i < 2; ++_i) \
;         __builtin_amdgcn_global_load_lds((const unsigned*)((const char*)(gbase) + (voff)[_i]), (LAS unsigned*)(lds + (bufoff) + ldsw + _i * 8192), 16, 0, 0); } while (0)
; #define PG8_LDA(dst, b, h) do { _Pragma("unroll") for (int m = 0; m < 4; ++m) _Pragma("unroll") for (int k = 0; k < 2; ++k) dst[m][k] = *(const LAS bf16x8*)(lds + PG8_SA(b, h) + aoff + m * 2048 + k * 1024); } while (0)
; #define PG8_LDB(dst, b, h) do { _Pragma("unroll") for (int n = 0; n < 2; ++n) _Pragma("unroll") for (int k = 0; k < 2; ++k) dst[n][k] = *(const LAS bf16x8*)(lds + PG8_SB(b, h) + boff + n * 2048 + k * 1024); } while (0)
; #define PG8_MMA(ai, bj, At, Bt) do { __builtin_amdgcn_s_setprio(1); _Pragma("unroll") for (int m = 0; m < 4; ++m) _Pragma("unroll") for (int n = 0; n < 2; ++n) _Pragma("unroll") for (int k = 0; k < 2; ++k) \
;         acc[ai][bj][m][n] = __builtin_amdgcn_mfma_f32_16x16x32_bf16(Bt[n][k], At[m][k], acc[ai][bj][m][n], 0, 0, 0); __builtin_amdgcn_s_setprio(0); } while (0)
; #define PG8_WAIT_V(n) asm volatile("s_waitcnt vmcnt(" #n ")" ::: "memory")
; #define PG8_WAIT_L(n) asm volatile("s_waitcnt lgkmcnt(" #n ")" ::: "memory")
; #define PG8_BAR __builtin_amdgcn_s_barrier()
; #define PG8_SCHED __builtin_amdgcn_sched_barrier(0)
; template <class Epi>
; DEVI void gemm_phase(LAS unsigned char* lds, const Gemm g, const Epi& E) {
;     ...
;             PG8_LDB(B0, 0, 0); PG8_SCHED; PG8_LDA(At, 0, 0); PG8_STAGE(PG8_SA(1, 1), a1 + hstepA, voffA);
;             PG8_WAIT_L(8); PG8_BAR; PG8_WAIT_L(0); PG8_MMA(0, 0, At, B0); PG8_BAR; PG8_SCHED;
;             PG8_LDB(B1, 0, 1); PG8_STAGE(PG8_SB(0, 0), b2, voffB);
;             PG8_BAR; PG8_WAIT_L(0); PG8_MMA(0, 1, At, B1); PG8_BAR;
;             PG8_LDA(At, 0, 1); PG8_STAGE(PG8_SA(0, 0), a2, voffA);
;             PG8_BAR; PG8_WAIT_L(0); PG8_MMA(1, 0, At, B0); PG8_BAR; PG8_SCHED;
;             PG8_STAGE(PG8_SB(0, 1), b2 + hstepB, voffB);
;             PG8_WAIT_V(6); PG8_BAR; PG8_MMA(1, 1, At, B1); PG8_BAR;
;             PG8_LDB(B0, 1, 0); PG8_SCHED; PG8_LDA(At, 1, 0); PG8_STAGE(PG8_SA(0, 1), a2 + hstepA, voffA);
;             PG8_WAIT_L(8); PG8_BAR; PG8_WAIT_L(0); PG8_MMA(0, 0, At, B0); PG8_BAR; PG8_SCHED;
.LBB0_1198:
	s_add_u32 s11, s6, s5
	s_addc_u32 s13, s7, 0
	s_add_u32 s49, s11, 0x100
	s_addc_u32 s52, s13, 0
	s_and_b64 s[50:51], s[46:47], exec
	s_cselect_b32 s83, s17, s52
	s_cselect_b32 s82, s16, s49
	s_add_u32 s5, s8, s5
	s_addc_u32 s49, s9, 0
	s_add_u32 s5, s5, 0x100
	s_addc_u32 s49, s49, 0
	s_add_i32 s50, 0, 0x10000
	s_and_b64 s[46:47], s[46:47], exec
	s_cselect_b32 s85, s3, s49
	s_cselect_b32 s84, s2, s5
	s_add_u32 s86, s11, 0x40080
	s_addc_u32 s87, s13, 0
	s_add_i32 s53, s50, s38
	s_add_i32 m0, s39, 0xc000
	s_add_i32 s54, s39, 0xe000
	s_add_i32 s52, 0, 0x14000
	s_add_i32 s51, s53, 0x2000
	s_add_u32 s80, s84, 0x40000
	v_add_u32_e32 v162, s50, v152
	s_addc_u32 s81, s85, 0
	s_add_i32 s88, s52, s38
	ds_read_b128 v[178:181], v162
	ds_read_b128 v[182:185], v162 offset:1024
	ds_read_b128 v[186:189], v162 offset:2048
	ds_read_b128 v[190:193], v162 offset:3072
	s_add_i32 s66, s88, 0x2000
	s_add_i32 s49, 0, 0x18000
	s_add_u32 s68, s82, 0x40000
	s_addc_u32 s69, s83, 0
	s_add_i32 s13, s49, s38
	s_add_i32 s11, 0, 0x1c000
	s_add_i32 s5, s13, 0x2000
	s_add_u32 s46, s84, 0x40080
	s_addc_u32 s47, s85, 0
	s_add_i32 s50, s11, s38
	s_add_i32 s89, s50, 0x2000
	v_lshl_add_u64 v[162:163], s[86:87], 0, v[134:135]
	ds_read_b128 v[194:197], v176
	ds_read_b128 v[198:201], v176 offset:1024
	ds_read_b128 v[202:205], v176 offset:2048
	ds_read_b128 v[206:209], v176 offset:3072
	ds_read_b128 v[214:217], v176 offset:4096
	ds_read_b128 v[218:221], v176 offset:5120
	ds_read_b128 v[222:225], v176 offset:6144
	ds_read_b128 v[226:229], v176 offset:7168
	global_load_lds_dwordx4 v[162:163], off
	v_lshl_add_u64 v[162:163], s[86:87], 0, v[132:133]
	s_mov_b32 m0, s54
	s_nop 0
	global_load_lds_dwordx4 v[162:163], off
	s_waitcnt lgkmcnt(8)
	s_barrier
	s_waitcnt lgkmcnt(0)
	s_setprio 1
	v_mfma_f32_16x16x32_bf16 v[126:129], v[178:181], v[194:197], v[126:129]
	v_mfma_f32_16x16x32_bf16 v[122:125], v[186:189], v[194:197], v[122:125]
	v_mfma_f32_16x16x32_bf16 v[118:121], v[178:181], v[202:205], v[118:121]
	v_mfma_f32_16x16x32_bf16 v[114:117], v[186:189], v[202:205], v[114:117]
	v_mfma_f32_16x16x32_bf16 v[102:105], v[178:181], v[214:217], v[102:105]
	v_mfma_f32_16x16x32_bf16 v[98:101], v[186:189], v[214:217], v[98:101]
	v_mfma_f32_16x16x32_bf16 v[86:89], v[178:181], v[222:225], v[86:89]
	v_mfma_f32_16x16x32_bf16 v[82:85], v[186:189], v[222:225], v[82:85]
	v_mfma_f32_16x16x32_bf16 v[126:129], v[182:185], v[198:201], v[126:129]
	v_mfma_f32_16x16x32_bf16 v[122:125], v[190:193], v[198:201], v[122:125]
	v_mfma_f32_16x16x32_bf16 v[118:121], v[182:185], v[206:209], v[118:121]
	v_mfma_f32_16x16x32_bf16 v[114:117], v[190:193], v[206:209], v[114:117]
	v_mfma_f32_16x16x32_bf16 v[102:105], v[182:185], v[218:221], v[102:105]
	v_mfma_f32_16x16x32_bf16 v[98:101], v[190:193], v[218:221], v[98:101]
	v_mfma_f32_16x16x32_bf16 v[86:89], v[182:185], v[226:229], v[86:89]
	v_mfma_f32_16x16x32_bf16 v[82:85], v[190:193], v[226:229], v[82:85]
	s_setprio 0
	s_barrier
	v_add_u32_e32 v162, s52, v152
	s_mov_b32 m0, s53
	ds_read_b128 v[230:233], v162
	ds_read_b128 v[234:237], v162 offset:1024
	ds_read_b128 v[238:241], v162 offset:2048
	ds_read_b128 v[242:245], v162 offset:3072
	v_lshl_add_u64 v[162:163], s[84:85], 0, v[8:9]
	global_load_lds_dwordx4 v[162:163], off
	v_lshl_add_u64 v[164:165], s[84:85], 0, v[130:131]
	s_mov_b32 m0, s51
	s_nop 0
	global_load_lds_dwordx4 v[164:165], off
	s_barrier
	s_waitcnt lgkmcnt(0)
	s_setprio 1
	v_mfma_f32_16x16x32_bf16 v[110:113], v[230:233], v[194:197], v[110:113]
	v_mfma_f32_16x16x32_bf16 v[106:109], v[238:241], v[194:197], v[106:109]
	v_mfma_f32_16x16x32_bf16 v[94:97], v[230:233], v[202:205], v[94:97]
	v_mfma_f32_16x16x32_bf16 v[90:93], v[238:241], v[202:205], v[90:93]
	v_mfma_f32_16x16x32_bf16 v[78:81], v[230:233], v[214:217], v[78:81]
	v_mfma_f32_16x16x32_bf16 v[74:77], v[238:241], v[214:217], v[74:77]
	v_mfma_f32_16x16x32_bf16 v[70:73], v[230:233], v[222:225], v[70:73]
	v_mfma_f32_16x16x32_bf16 v[66:69], v[238:241], v[222:225], v[66:69]
	v_mfma_f32_16x16x32_bf16 v[110:113], v[234:237], v[198:201], v[110:113]
	v_mfma_f32_16x16x32_bf16 v[106:109], v[242:245], v[198:201], v[106:109]
	v_mfma_f32_16x16x32_bf16 v[94:97], v[234:237], v[206:209], v[94:97]
	v_mfma_f32_16x16x32_bf16 v[90:93], v[242:245], v[206:209], v[90:93]
	v_mfma_f32_16x16x32_bf16 v[78:81], v[234:237], v[218:221], v[78:81]
	v_mfma_f32_16x16x32_bf16 v[74:77], v[242:245], v[218:221], v[74:77]
	v_mfma_f32_16x16x32_bf16 v[70:73], v[234:237], v[226:229], v[70:73]
	v_mfma_f32_16x16x32_bf16 v[66:69], v[242:245], v[226:229], v[66:69]
	s_setprio 0
	s_mov_b32 m0, s39
	v_lshl_add_u64 v[246:247], s[82:83], 0, v[134:135]
	s_barrier
	ds_read_b128 v[194:197], v176 offset:16384
	ds_read_b128 v[198:201], v176 offset:17408
	ds_read_b128 v[202:205], v176 offset:18432
	ds_read_b128 v[206:209], v176 offset:19456
	ds_read_b128 v[214:217], v176 offset:20480
	ds_read_b128 v[218:221], v176 offset:21504
	ds_read_b128 v[222:225], v176 offset:22528
	ds_read_b128 v[226:229], v176 offset:23552
	global_load_lds_dwordx4 v[246:247], off
	v_lshl_add_u64 v[248:249], s[82:83], 0, v[132:133]
	s_mov_b32 m0, s40
	s_nop 0
	global_load_lds_dwordx4 v[248:249], off
	s_barrier
; #define PG8_STAGE(bufoff, gbase, voff) do { _Pragma("unroll") for (int _i = 0; _i < 2; ++_i) \
;         __builtin_amdgcn_global_load_lds((const unsigned*)((const char*)(gbase) + (voff)[_i]), (LAS unsigned*)(lds + (bufoff) + ldsw + _i * 8192), 16, 0, 0); } while (0)
; #define PG8_LDA(dst, b, h) do { _Pragma("unroll") for (int m = 0; m < 4; ++m) _Pragma("unroll") for (int k = 0; k < 2; ++k) dst[m][k] = *(const LAS bf16x8*)(lds + PG8_SA(b, h) + aoff + m * 2048 + k * 1024); } while (0)
; #define PG8_LDB(dst, b, h) do { _Pragma("unroll") for (int n = 0; n < 2; ++n) _Pragma("unroll") for (int k = 0; k < 2; ++k) dst[n][k] = *(const LAS bf16x8*)(lds + PG8_SB(b, h) + boff + n * 2048 + k * 1024); } while (0)
; #define PG8_MMA(ai, bj, At, Bt) do { __builtin_amdgcn_s_setprio(1); _Pragma("unroll") for (int m = 0; m < 4; ++m) _Pragma("unroll") for (int n = 0; n < 2; ++n) _Pragma("unroll") for (int k = 0; k < 2; ++k) \
;         acc[ai][bj][m][n] = __builtin_amdgcn_mfma_f32_16x16x32_bf16(Bt[n][k], At[m][k], acc[ai][bj][m][n], 0, 0, 0); __builtin_amdgcn_s_setprio(0); } while (0)
; #define PG8_WAIT_V(n) asm volatile("s_waitcnt vmcnt(" #n ")" ::: "memory")
; #define PG8_WAIT_L(n) asm volatile("s_waitcnt lgkmcnt(" #n ")" ::: "memory")
; #define PG8_BAR __builtin_amdgcn_s_barrier()
; #define PG8_SCHED __builtin_amdgcn_sched_barrier(0)
; template <class Epi>
; DEVI void gemm_phase(LAS unsigned char* lds, const Gemm g, const Epi& E) {
;     ...
;             PG8_BAR; PG8_WAIT_L(0); PG8_MMA(1, 0, At, B0); PG8_BAR; PG8_SCHED;
;             PG8_STAGE(PG8_SB(0, 1), b2 + hstepB, voffB);
;             PG8_WAIT_V(6); PG8_BAR; PG8_MMA(1, 1, At, B1); PG8_BAR;
;             PG8_LDB(B0, 1, 0); PG8_SCHED; PG8_LDA(At, 1, 0); PG8_STAGE(PG8_SA(0, 1), a2 + hstepA, voffA);
;             PG8_WAIT_L(8); PG8_BAR; PG8_WAIT_L(0); PG8_MMA(0, 0, At, B0); PG8_BAR; PG8_SCHED;
;             PG8_LDB(B1, 1, 1); PG8_STAGE(PG8_SB(1, 0), b3, voffB);
;             PG8_BAR; PG8_WAIT_L(0); PG8_MMA(0, 1, At, B1); PG8_BAR;
;             PG8_LDA(At, 1, 1); PG8_STAGE(PG8_SA(1, 0), a3, voffA);
;             PG8_BAR; PG8_WAIT_L(0); PG8_MMA(1, 0, At, B0); PG8_BAR; PG8_SCHED;
	s_waitcnt lgkmcnt(0)
	s_setprio 1
	v_mfma_f32_16x16x32_bf16 v[62:65], v[178:181], v[194:197], v[62:65]
	v_mfma_f32_16x16x32_bf16 v[58:61], v[186:189], v[194:197], v[58:61]
	v_mfma_f32_16x16x32_bf16 v[54:57], v[178:181], v[202:205], v[54:57]
	v_mfma_f32_16x16x32_bf16 v[50:53], v[186:189], v[202:205], v[50:53]
	v_mfma_f32_16x16x32_bf16 v[38:41], v[178:181], v[214:217], v[38:41]
	v_mfma_f32_16x16x32_bf16 v[34:37], v[186:189], v[214:217], v[34:37]
	v_mfma_f32_16x16x32_bf16 v[22:25], v[178:181], v[222:225], v[22:25]
	v_mfma_f32_16x16x32_bf16 v[18:21], v[186:189], v[222:225], v[18:21]
	v_mfma_f32_16x16x32_bf16 v[62:65], v[182:185], v[198:201], v[62:65]
	v_mfma_f32_16x16x32_bf16 v[58:61], v[190:193], v[198:201], v[58:61]
	v_mfma_f32_16x16x32_bf16 v[54:57], v[182:185], v[206:209], v[54:57]
	v_mfma_f32_16x16x32_bf16 v[50:53], v[190:193], v[206:209], v[50:53]
	v_mfma_f32_16x16x32_bf16 v[38:41], v[182:185], v[218:221], v[38:41]
	v_mfma_f32_16x16x32_bf16 v[34:37], v[190:193], v[218:221], v[34:37]
	v_mfma_f32_16x16x32_bf16 v[22:25], v[182:185], v[226:229], v[22:25]
	v_mfma_f32_16x16x32_bf16 v[18:21], v[190:193], v[226:229], v[18:21]
	s_setprio 0
	s_barrier
	s_mov_b32 m0, s88
	v_lshl_add_u64 v[178:179], s[80:81], 0, v[8:9]
	global_load_lds_dwordx4 v[178:179], off
	v_lshl_add_u64 v[178:179], s[80:81], 0, v[130:131]
	s_mov_b32 m0, s66
	s_nop 0
	global_load_lds_dwordx4 v[178:179], off
	s_waitcnt vmcnt(6)
	s_barrier
	s_setprio 1
	v_mfma_f32_16x16x32_bf16 v[46:49], v[230:233], v[194:197], v[46:49]
	v_mfma_f32_16x16x32_bf16 v[42:45], v[238:241], v[194:197], v[42:45]
	v_mfma_f32_16x16x32_bf16 v[30:33], v[230:233], v[202:205], v[30:33]
	v_mfma_f32_16x16x32_bf16 v[26:29], v[238:241], v[202:205], v[26:29]
	v_mfma_f32_16x16x32_bf16 v[14:17], v[230:233], v[214:217], v[14:17]
	v_mfma_f32_16x16x32_bf16 v[10:13], v[238:241], v[214:217], v[10:13]
	v_mfma_f32_16x16x32_bf16 v[4:7], v[230:233], v[222:225], v[4:7]
	v_mfma_f32_16x16x32_bf16 v[0:3], v[238:241], v[222:225], v[0:3]
	v_mfma_f32_16x16x32_bf16 v[46:49], v[234:237], v[198:201], v[46:49]
	v_mfma_f32_16x16x32_bf16 v[42:45], v[242:245], v[198:201], v[42:45]
	v_mfma_f32_16x16x32_bf16 v[30:33], v[234:237], v[206:209], v[30:33]
	v_mfma_f32_16x16x32_bf16 v[26:29], v[242:245], v[206:209], v[26:29]
	v_mfma_f32_16x16x32_bf16 v[14:17], v[234:237], v[218:221], v[14:17]
	v_mfma_f32_16x16x32_bf16 v[10:13], v[242:245], v[218:221], v[10:13]
	v_mfma_f32_16x16x32_bf16 v[4:7], v[234:237], v[226:229], v[4:7]
	v_mfma_f32_16x16x32_bf16 v[0:3], v[242:245], v[226:229], v[0:3]
	s_setprio 0
	v_add_u32_e32 v177, s49, v152
	s_barrier
	ds_read_b128 v[178:181], v177
	ds_read_b128 v[182:185], v177 offset:1024
	ds_read_b128 v[186:189], v177 offset:2048
	ds_read_b128 v[190:193], v177 offset:3072
	s_mov_b32 m0, s41
	v_lshl_add_u64 v[230:231], s[68:69], 0, v[134:135]
	ds_read_b128 v[194:197], v176 offset:32768
	ds_read_b128 v[198:201], v176 offset:33792
	ds_read_b128 v[202:205], v176 offset:34816
	ds_read_b128 v[206:209], v176 offset:35840
	ds_read_b128 v[214:217], v176 offset:36864
	ds_read_b128 v[218:221], v176 offset:37888
	ds_read_b128 v[222:225], v176 offset:38912
	ds_read_b128 v[226:229], v176 offset:39936
	global_load_lds_dwordx4 v[230:231], off
	v_lshl_add_u64 v[230:231], s[68:69], 0, v[132:133]
	s_mov_b32 m0, s42
	s_nop 0
	global_load_lds_dwordx4 v[230:231], off
	s_waitcnt lgkmcnt(8)
	s_barrier
	s_waitcnt lgkmcnt(0)
	s_setprio 1
	v_mfma_f32_16x16x32_bf16 v[126:129], v[178:181], v[194:197], v[126:129]
	v_mfma_f32_16x16x32_bf16 v[122:125], v[186:189], v[194:197], v[122:125]
	v_mfma_f32_16x16x32_bf16 v[118:121], v[178:181], v[202:205], v[118:121]
	v_mfma_f32_16x16x32_bf16 v[114:117], v[186:189], v[202:205], v[114:117]
	v_mfma_f32_16x16x32_bf16 v[102:105], v[178:181], v[214:217], v[102:105]
	v_mfma_f32_16x16x32_bf16 v[98:101], v[186:189], v[214:217], v[98:101]
	v_mfma_f32_16x16x32_bf16 v[86:89], v[178:181], v[222:225], v[86:89]
	v_mfma_f32_16x16x32_bf16 v[82:85], v[186:189], v[222:225], v[82:85]
	v_mfma_f32_16x16x32_bf16 v[126:129], v[182:185], v[198:201], v[126:129]
	v_mfma_f32_16x16x32_bf16 v[122:125], v[190:193], v[198:201], v[122:125]
	v_mfma_f32_16x16x32_bf16 v[118:121], v[182:185], v[206:209], v[118:121]
	v_mfma_f32_16x16x32_bf16 v[114:117], v[190:193], v[206:209], v[114:117]
	v_mfma_f32_16x16x32_bf16 v[102:105], v[182:185], v[218:221], v[102:105]
	v_mfma_f32_16x16x32_bf16 v[98:101], v[190:193], v[218:221], v[98:101]
	v_mfma_f32_16x16x32_bf16 v[86:89], v[182:185], v[226:229], v[86:89]
	v_mfma_f32_16x16x32_bf16 v[82:85], v[190:193], v[226:229], v[82:85]
	s_setprio 0
	s_barrier
	s_mov_b32 m0, s13
	v_add_u32_e32 v177, s11, v152
	v_lshl_add_u64 v[162:163], v[162:163], 0, s[70:71]
	ds_read_b128 v[230:233], v177
	ds_read_b128 v[234:237], v177 offset:1024
	ds_read_b128 v[238:241], v177 offset:2048
	ds_read_b128 v[242:245], v177 offset:3072
	global_load_lds_dwordx4 v[162:163], off
	v_lshl_add_u64 v[162:163], v[164:165], 0, s[70:71]
	s_mov_b32 m0, s5
	s_nop 0
	global_load_lds_dwordx4 v[162:163], off
	s_barrier
	s_waitcnt lgkmcnt(0)
	s_setprio 1
	v_mfma_f32_16x16x32_bf16 v[110:113], v[230:233], v[194:197], v[110:113]
	v_mfma_f32_16x16x32_bf16 v[106:109], v[238:241], v[194:197], v[106:109]
	v_mfma_f32_16x16x32_bf16 v[94:97], v[230:233], v[202:205], v[94:97]
	v_mfma_f32_16x16x32_bf16 v[90:93], v[238:241], v[202:205], v[90:93]
	v_mfma_f32_16x16x32_bf16 v[78:81], v[230:233], v[214:217], v[78:81]
	v_mfma_f32_16x16x32_bf16 v[74:77], v[238:241], v[214:217], v[74:77]
	v_mfma_f32_16x16x32_bf16 v[70:73], v[230:233], v[222:225], v[70:73]
	v_mfma_f32_16x16x32_bf16 v[66:69], v[238:241], v[222:225], v[66:69]
	v_mfma_f32_16x16x32_bf16 v[110:113], v[234:237], v[198:201], v[110:113]
	v_mfma_f32_16x16x32_bf16 v[106:109], v[242:245], v[198:201], v[106:109]
	v_mfma_f32_16x16x32_bf16 v[94:97], v[234:237], v[206:209], v[94:97]
	v_mfma_f32_16x16x32_bf16 v[90:93], v[242:245], v[206:209], v[90:93]
	v_mfma_f32_16x16x32_bf16 v[78:81], v[234:237], v[218:221], v[78:81]
	v_mfma_f32_16x16x32_bf16 v[74:77], v[242:245], v[218:221], v[74:77]
	v_mfma_f32_16x16x32_bf16 v[70:73], v[234:237], v[226:229], v[70:73]
	v_mfma_f32_16x16x32_bf16 v[66:69], v[242:245], v[226:229], v[66:69]
	s_setprio 0
	s_mov_b32 m0, s43
	v_lshl_add_u64 v[162:163], v[246:247], 0, s[70:71]
	s_barrier
; #define PG8_STAGE(bufoff, gbase, voff) do { _Pragma("unroll") for (int _i = 0; _i < 2; ++_i) \
;         __builtin_amdgcn_global_load_lds((const unsigned*)((const char*)(gbase) + (voff)[_i]), (LAS unsigned*)(lds + (bufoff) + ldsw + _i * 8192), 16, 0, 0); } while (0)
; #define PG8_LDA(dst, b, h) do { _Pragma("unroll") for (int m = 0; m < 4; ++m) _Pragma("unroll") for (int k = 0; k < 2; ++k) dst[m][k] = *(const LAS bf16x8*)(lds + PG8_SA(b, h) + aoff + m * 2048 + k * 1024); } while (0)
; #define PG8_LDB(dst, b, h) do { _Pragma("unroll") for (int n = 0; n < 2; ++n) _Pragma("unroll") for (int k = 0; k < 2; ++k) dst[n][k] = *(const LAS bf16x8*)(lds + PG8_SB(b, h) + boff + n * 2048 + k * 1024); } while (0)
; #define PG8_MMA(ai, bj, At, Bt) do { __builtin_amdgcn_s_setprio(1); _Pragma("unroll") for (int m = 0; m < 4; ++m) _Pragma("unroll") for (int n = 0; n < 2; ++n) _Pragma("unroll") for (int k = 0; k < 2; ++k) \
;         acc[ai][bj][m][n] = __builtin_amdgcn_mfma_f32_16x16x32_bf16(Bt[n][k], At[m][k], acc[ai][bj][m][n], 0, 0, 0); __builtin_amdgcn_s_setprio(0); } while (0)
; #define PG8_WAIT_V(n) asm volatile("s_waitcnt vmcnt(" #n ")" ::: "memory")
; #define PG8_WAIT_L(n) asm volatile("s_waitcnt lgkmcnt(" #n ")" ::: "memory")
; #define PG8_BAR __builtin_amdgcn_s_barrier()
; #define PG8_SCHED __builtin_amdgcn_sched_barrier(0)
; template <class Epi>
; DEVI void gemm_phase(LAS unsigned char* lds, const Gemm g, const Epi& E) {
;     ...
;             PG8_LDB(B0, 1, 0); PG8_SCHED; PG8_LDA(At, 1, 0); PG8_STAGE(PG8_SA(0, 1), a2 + hstepA, voffA);
;             PG8_WAIT_L(8); PG8_BAR; PG8_WAIT_L(0); PG8_MMA(0, 0, At, B0); PG8_BAR; PG8_SCHED;
;             PG8_LDB(B1, 1, 1); PG8_STAGE(PG8_SB(1, 0), b3, voffB);
;             PG8_BAR; PG8_WAIT_L(0); PG8_MMA(0, 1, At, B1); PG8_BAR;
;             PG8_LDA(At, 1, 1); PG8_STAGE(PG8_SA(1, 0), a3, voffA);
;             PG8_BAR; PG8_WAIT_L(0); PG8_MMA(1, 0, At, B0); PG8_BAR; PG8_SCHED;
;             PG8_STAGE(PG8_SB(1, 1), b3 + hstepB, voffB);
;             PG8_WAIT_V(6); PG8_BAR; PG8_MMA(1, 1, At, B1); PG8_BAR;
;         }
	ds_read_b128 v[194:197], v176 offset:49152
	ds_read_b128 v[198:201], v176 offset:50176
	ds_read_b128 v[202:205], v176 offset:51200
	ds_read_b128 v[206:209], v176 offset:52224
	ds_read_b128 v[214:217], v176 offset:53248
	ds_read_b128 v[218:221], v176 offset:54272
	ds_read_b128 v[222:225], v176 offset:55296
	ds_read_b128 v[226:229], v176 offset:56320
	global_load_lds_dwordx4 v[162:163], off
	v_lshl_add_u64 v[162:163], v[248:249], 0, s[70:71]
	s_mov_b32 m0, s44
	s_nop 0
	global_load_lds_dwordx4 v[162:163], off
	s_barrier
	s_waitcnt lgkmcnt(0)
	s_setprio 1
	v_mfma_f32_16x16x32_bf16 v[62:65], v[178:181], v[194:197], v[62:65]
	v_mfma_f32_16x16x32_bf16 v[58:61], v[186:189], v[194:197], v[58:61]
	v_mfma_f32_16x16x32_bf16 v[54:57], v[178:181], v[202:205], v[54:57]
	v_mfma_f32_16x16x32_bf16 v[50:53], v[186:189], v[202:205], v[50:53]
	v_mfma_f32_16x16x32_bf16 v[38:41], v[178:181], v[214:217], v[38:41]
	v_mfma_f32_16x16x32_bf16 v[34:37], v[186:189], v[214:217], v[34:37]
	v_mfma_f32_16x16x32_bf16 v[22:25], v[178:181], v[222:225], v[22:25]
	v_mfma_f32_16x16x32_bf16 v[18:21], v[186:189], v[222:225], v[18:21]
	v_mfma_f32_16x16x32_bf16 v[62:65], v[182:185], v[198:201], v[62:65]
	v_mfma_f32_16x16x32_bf16 v[58:61], v[190:193], v[198:201], v[58:61]
	v_mfma_f32_16x16x32_bf16 v[54:57], v[182:185], v[206:209], v[54:57]
	v_mfma_f32_16x16x32_bf16 v[50:53], v[190:193], v[206:209], v[50:53]
	v_mfma_f32_16x16x32_bf16 v[38:41], v[182:185], v[218:221], v[38:41]
	v_mfma_f32_16x16x32_bf16 v[34:37], v[190:193], v[218:221], v[34:37]
	v_mfma_f32_16x16x32_bf16 v[22:25], v[182:185], v[226:229], v[22:25]
	v_mfma_f32_16x16x32_bf16 v[18:21], v[190:193], v[226:229], v[18:21]
	s_setprio 0
	s_barrier
	s_mov_b32 m0, s50
	v_lshl_add_u64 v[162:163], s[46:47], 0, v[8:9]
	global_load_lds_dwordx4 v[162:163], off
	v_lshl_add_u64 v[162:163], s[46:47], 0, v[130:131]
	s_mov_b32 m0, s89
	s_nop 0
	global_load_lds_dwordx4 v[162:163], off
	s_waitcnt vmcnt(6)
	s_barrier
	s_setprio 1
	v_mfma_f32_16x16x32_bf16 v[46:49], v[230:233], v[194:197], v[46:49]
	v_mfma_f32_16x16x32_bf16 v[42:45], v[238:241], v[194:197], v[42:45]
	v_mfma_f32_16x16x32_bf16 v[30:33], v[230:233], v[202:205], v[30:33]
	v_mfma_f32_16x16x32_bf16 v[26:29], v[238:241], v[202:205], v[26:29]
	v_mfma_f32_16x16x32_bf16 v[14:17], v[230:233], v[214:217], v[14:17]
	v_mfma_f32_16x16x32_bf16 v[10:13], v[238:241], v[214:217], v[10:13]
	v_mfma_f32_16x16x32_bf16 v[4:7], v[230:233], v[222:225], v[4:7]
	v_mfma_f32_16x16x32_bf16 v[0:3], v[238:241], v[222:225], v[0:3]
	v_mfma_f32_16x16x32_bf16 v[46:49], v[234:237], v[198:201], v[46:49]
	v_mfma_f32_16x16x32_bf16 v[42:45], v[242:245], v[198:201], v[42:45]
	v_mfma_f32_16x16x32_bf16 v[30:33], v[234:237], v[206:209], v[30:33]
	v_mfma_f32_16x16x32_bf16 v[26:29], v[242:245], v[206:209], v[26:29]
	v_mfma_f32_16x16x32_bf16 v[14:17], v[234:237], v[218:221], v[14:17]
	v_mfma_f32_16x16x32_bf16 v[10:13], v[242:245], v[218:221], v[10:13]
	v_mfma_f32_16x16x32_bf16 v[4:7], v[234:237], v[226:229], v[4:7]
	v_mfma_f32_16x16x32_bf16 v[0:3], v[242:245], v[226:229], v[0:3]
	s_setprio 0
	s_movk_i32 s5, 0x100
	s_andn2_b64 vcc, exec, s[36:37]
	s_mov_b64 s[46:47], -1
	s_mov_b64 s[36:37], 0
	s_barrier
	s_cbranch_vccz .LBB0_1198
; template <class Epi>
; DEVI void gemm_phase(LAS unsigned char* lds, const Gemm g, const Epi& E) {
;     ...
;                 for (int mm = 0; mm < 2; ++mm) {
;                     const int m = m0 + mm;
;                     const int r = row0 + ai * HALF + m * 16; float rs = 1.f, part = 0.f;
;                     if constexpr (Epi::RS) rs = rsv[ai * 4 + m];
;                     if constexpr (Epi::PAIR) E.pair8(cur.b, r, cur.pn * HALF + wc * 32 + 8 * fq, acc[ai][0][m][0] * rs, acc[ai][0][m][1] * rs, acc[ai][1][m][0] * rs, acc[ai][1][m][1] * rs);
;                     else
; #pragma unroll
;                     for (int bj = 0; bj < 2; ++bj) {
;                         const int c = col0 + bj * HALF; f32x4 v0 = acc[ai][bj][m][0], v1 = acc[ai][bj][m][1];
;                         if constexpr (Epi::RS) { v0 = v0 * rs; v1 = v1 * rs; }
;                         if constexpr (Epi::PRE) part += E.frag_pre8(cur.b, r, c, v0, v1, pre[mm][bj][0], pre[mm][bj][1]);
;                         else if constexpr (Epi::PERM) E.frag8(cur.b, r, c, v0, v1);
;                         else { E.frag(cur.b, r, c, v0); E.frag(cur.b, r, c + 16, v1); }
;                     }
	v_lshl_or_b32 v162, s4, 8, v153
	s_ashr_i32 s4, s45, 2
	s_ashr_i32 s5, s4, 31
	s_lshl_b32 s6, s45, 8
	s_and_b32 s66, s6, 0x300
	s_lshl_b64 s[4:5], s[4:5], 21
	s_add_u32 s4, s60, s4
	v_lshl_add_u64 v[164:165], v[136:137], 0, s[66:67]
	v_cvt_pk_bf16_f32 v70, v70, v71
	v_cvt_pk_bf16_f32 v71, v72, v73
	v_cvt_pk_bf16_f32 v72, v66, v67
	v_lshl_add_u64 v[66:67], v[144:145], 0, s[66:67]
	s_addc_u32 s5, s61, s5
	v_lshlrev_b64 v[164:165], 11, v[164:165]
	v_ashrrev_i32_e32 v163, 31, v162
	v_lshlrev_b64 v[66:67], 11, v[66:67]
	v_lshl_add_u64 v[164:165], s[4:5], 0, v[164:165]
	v_cvt_pk_bf16_f32 v126, v126, v127
	v_cvt_pk_bf16_f32 v127, v128, v129
	v_cvt_pk_bf16_f32 v128, v122, v123
	v_lshlrev_b64 v[122:123], 1, v[162:163]
	v_cvt_pk_bf16_f32 v110, v110, v111
	v_cvt_pk_bf16_f32 v111, v112, v113
	v_cvt_pk_bf16_f32 v112, v106, v107
	v_lshl_add_u64 v[106:107], v[138:139], 0, s[66:67]
	v_lshl_add_u64 v[66:67], s[4:5], 0, v[66:67]
	v_cvt_pk_bf16_f32 v46, v46, v47
	v_cvt_pk_bf16_f32 v47, v48, v49
	v_cvt_pk_bf16_f32 v48, v42, v43
	v_lshl_add_u64 v[42:43], v[146:147], 0, s[66:67]
	v_cvt_pk_bf16_f32 v129, v124, v125
	v_lshl_add_u64 v[124:125], v[164:165], 0, v[122:123]
	v_cvt_pk_bf16_f32 v113, v108, v109
	v_lshlrev_b64 v[106:107], 11, v[106:107]
	v_cvt_pk_bf16_f32 v62, v62, v63
	v_cvt_pk_bf16_f32 v63, v64, v65
	v_cvt_pk_bf16_f32 v64, v58, v59
	v_lshl_add_u64 v[58:59], v[66:67], 0, v[122:123]
	v_cvt_pk_bf16_f32 v49, v44, v45
	v_lshlrev_b64 v[42:43], 11, v[42:43]
	global_store_dwordx4 v[124:125], v[110:113], off offset:256
	v_cvt_pk_bf16_f32 v94, v94, v95
	v_cvt_pk_bf16_f32 v95, v96, v97
	v_lshl_add_u64 v[110:111], s[4:5], 0, v[106:107]
	v_cvt_pk_bf16_f32 v96, v90, v91
	v_lshl_add_u64 v[90:91], v[140:141], 0, s[66:67]
	global_store_dwordx4 v[58:59], v[46:49], off offset:256
	v_cvt_pk_bf16_f32 v30, v30, v31
	v_cvt_pk_bf16_f32 v31, v32, v33
	v_lshl_add_u64 v[46:47], s[4:5], 0, v[42:43]
	v_cvt_pk_bf16_f32 v32, v26, v27
	v_lshl_add_u64 v[26:27], v[148:149], 0, s[66:67]
	v_lshl_add_u64 v[110:111], v[110:111], 0, v[122:123]
	v_cvt_pk_bf16_f32 v97, v92, v93
	v_lshlrev_b64 v[90:91], 11, v[90:91]
	v_lshl_add_u64 v[46:47], v[46:47], 0, v[122:123]
	v_cvt_pk_bf16_f32 v33, v28, v29
	v_lshlrev_b64 v[26:27], 11, v[26:27]
	global_store_dwordx4 v[110:111], v[94:97], off offset:256
	v_cvt_pk_bf16_f32 v78, v78, v79
	v_cvt_pk_bf16_f32 v79, v80, v81
	v_lshl_add_u64 v[94:95], s[4:5], 0, v[90:91]
	v_cvt_pk_bf16_f32 v80, v74, v75
	v_lshl_add_u64 v[74:75], v[142:143], 0, s[66:67]
	global_store_dwordx4 v[46:47], v[30:33], off offset:256
	v_cvt_pk_bf16_f32 v14, v14, v15
	v_cvt_pk_bf16_f32 v15, v16, v17
	v_lshl_add_u64 v[30:31], s[4:5], 0, v[26:27]
	v_cvt_pk_bf16_f32 v16, v10, v11
	v_lshl_add_u64 v[10:11], v[150:151], 0, s[66:67]
	v_lshl_add_u64 v[94:95], v[94:95], 0, v[122:123]
	v_cvt_pk_bf16_f32 v81, v76, v77
	v_lshlrev_b64 v[74:75], 11, v[74:75]
	v_lshl_add_u64 v[30:31], v[30:31], 0, v[122:123]
	v_cvt_pk_bf16_f32 v17, v12, v13
	v_lshlrev_b64 v[10:11], 11, v[10:11]
	global_store_dwordx4 v[94:95], v[78:81], off offset:256
	global_store_dwordx4 v[30:31], v[14:17], off offset:256
	v_cvt_pk_bf16_f32 v106, v118, v119
	v_lshl_add_u64 v[78:79], s[4:5], 0, v[74:75]
	v_lshl_add_u64 v[14:15], s[4:5], 0, v[10:11]
	v_cvt_pk_bf16_f32 v107, v120, v121
	v_cvt_pk_bf16_f32 v108, v114, v115
	v_cvt_pk_bf16_f32 v109, v116, v117
	v_cvt_pk_bf16_f32 v90, v102, v103
	v_cvt_pk_bf16_f32 v91, v104, v105
	v_cvt_pk_bf16_f32 v92, v98, v99
	v_cvt_pk_bf16_f32 v93, v100, v101
	v_cvt_pk_bf16_f32 v74, v86, v87
	v_cvt_pk_bf16_f32 v75, v88, v89
	v_cvt_pk_bf16_f32 v76, v82, v83
	v_cvt_pk_bf16_f32 v77, v84, v85
	v_lshl_add_u64 v[78:79], v[78:79], 0, v[122:123]
	v_cvt_pk_bf16_f32 v73, v68, v69
	v_cvt_pk_bf16_f32 v65, v60, v61
	v_cvt_pk_bf16_f32 v42, v54, v55
	v_cvt_pk_bf16_f32 v43, v56, v57
	v_cvt_pk_bf16_f32 v44, v50, v51
	v_cvt_pk_bf16_f32 v45, v52, v53
	v_cvt_pk_bf16_f32 v26, v38, v39
	v_cvt_pk_bf16_f32 v27, v40, v41
	v_cvt_pk_bf16_f32 v28, v34, v35
	v_cvt_pk_bf16_f32 v29, v36, v37
	v_cvt_pk_bf16_f32 v10, v22, v23
	v_cvt_pk_bf16_f32 v11, v24, v25
	v_cvt_pk_bf16_f32 v12, v18, v19
	v_cvt_pk_bf16_f32 v13, v20, v21
	v_lshl_add_u64 v[14:15], v[14:15], 0, v[122:123]
	v_cvt_pk_bf16_f32 v4, v4, v5
	v_cvt_pk_bf16_f32 v5, v6, v7
	v_cvt_pk_bf16_f32 v6, v0, v1
	v_cvt_pk_bf16_f32 v7, v2, v3
	s_and_b64 vcc, exec, s[14:15]
	s_mov_b32 s45, s10
	s_mov_b32 s4, s12
	s_mov_b64 s[8:9], s[2:3]
	s_mov_b64 s[6:7], s[16:17]
	s_movk_i32 s52, 0x110
	global_store_dwordx4 v[124:125], v[126:129], off
	global_store_dwordx4 v[110:111], v[106:109], off
	global_store_dwordx4 v[94:95], v[90:93], off
	global_store_dwordx4 v[78:79], v[74:77], off
	global_store_dwordx4 v[78:79], v[70:73], off offset:256
	global_store_dwordx4 v[58:59], v[62:65], off
	global_store_dwordx4 v[46:47], v[42:45], off
	global_store_dwordx4 v[30:31], v[26:29], off
	global_store_dwordx4 v[14:15], v[10:13], off
	global_store_dwordx4 v[14:15], v[4:7], off offset:256
	s_cbranch_vccz .LBB0_1191
	s_waitcnt vmcnt(0)
	s_cmpk_gt_u32 s19, 0xff
	v_readlane_b32 s40, v254, 1
	s_cbranch_scc1 .LBB0_1202
	s_barrier

; #define PG8_STAGE(bufoff, gbase, voff) do { _Pragma("unroll") for (int _i = 0; _i < 2; ++_i) \
;         __builtin_amdgcn_global_load_lds((const unsigned*)((const char*)(gbase) + (voff)[_i]), (LAS unsigned*)(lds + (bufoff) + ldsw + _i * 8192), 16, 0, 0); } while (0)
; #define PG8_LDA(dst, b, h) do { _Pragma("unroll") for (int m = 0; m < 4; ++m) _Pragma("unroll") for (int k = 0; k < 2; ++k) dst[m][k] = *(const LAS bf16x8*)(lds + PG8_SA(b, h) + aoff + m * 2048 + k * 1024); } while (0)
; #define PG8_LDB(dst, b, h) do { _Pragma("unroll") for (int n = 0; n < 2; ++n) _Pragma("unroll") for (int k = 0; k < 2; ++k) dst[n][k] = *(const LAS bf16x8*)(lds + PG8_SB(b, h) + boff + n * 2048 + k * 1024); } while (0)
; #define PG8_MMA(ai, bj, At, Bt) do { __builtin_amdgcn_s_setprio(1); _Pragma("unroll") for (int m = 0; m < 4; ++m) _Pragma("unroll") for (int n = 0; n < 2; ++n) _Pragma("unroll") for (int k = 0; k < 2; ++k) \
;         acc[ai][bj][m][n] = __builtin_amdgcn_mfma_f32_16x16x32_bf16(Bt[n][k], At[m][k], acc[ai][bj][m][n], 0, 0, 0); __builtin_amdgcn_s_setprio(0); } while (0)
; #define PG8_WAIT_V(n) asm volatile("s_waitcnt vmcnt(" #n ")" ::: "memory")
; #define PG8_WAIT_L(n) asm volatile("s_waitcnt lgkmcnt(" #n ")" ::: "memory")
; #define PG8_BAR __builtin_amdgcn_s_barrier()
; #define PG8_SCHED __builtin_amdgcn_sched_barrier(0)
; template <class Epi>
; DEVI void gemm_phase(LAS unsigned char* lds, const Gemm g, const Epi& E) {
;     ...
;             PG8_LDB(B0, 0, 0); PG8_SCHED; PG8_LDA(At, 0, 0); PG8_STAGE(PG8_SA(1, 1), a1 + hstepA, voffA);
;             PG8_WAIT_L(8); PG8_BAR; PG8_WAIT_L(0); PG8_MMA(0, 0, At, B0); PG8_BAR; PG8_SCHED;
;             PG8_LDB(B1, 0, 1); PG8_STAGE(PG8_SB(0, 0), b2, voffB);
;             PG8_BAR; PG8_WAIT_L(0); PG8_MMA(0, 1, At, B1); PG8_BAR;
;             PG8_LDA(At, 0, 1); PG8_STAGE(PG8_SA(0, 0), a2, voffA);
;             PG8_BAR; PG8_WAIT_L(0); PG8_MMA(1, 0, At, B0); PG8_BAR; PG8_SCHED;
;             PG8_STAGE(PG8_SB(0, 1), b2 + hstepB, voffB);
;             PG8_WAIT_V(6); PG8_BAR; PG8_MMA(1, 1, At, B1); PG8_BAR;
;             PG8_LDB(B0, 1, 0); PG8_SCHED; PG8_LDA(At, 1, 0); PG8_STAGE(PG8_SA(0, 1), a2 + hstepA, voffA);
;             PG8_WAIT_L(8); PG8_BAR; PG8_WAIT_L(0); PG8_MMA(0, 0, At, B0); PG8_BAR; PG8_SCHED;
.LBB0_1214:
	s_add_u32 s7, s8, s5
	s_addc_u32 s48, s9, 0
	s_add_u32 s49, s7, 0x100
	s_addc_u32 s50, s48, 0
	s_and_b64 s[46:47], s[36:37], exec
	s_cselect_b32 s81, s15, s50
	s_cselect_b32 s80, s14, s49
	s_add_u32 s5, s10, s5
	s_addc_u32 s46, s11, 0
	s_add_u32 s5, s5, 0x100
	s_addc_u32 s46, s46, 0
	s_add_i32 s50, 0, 0x10000
	s_and_b64 s[36:37], s[36:37], exec
	s_cselect_b32 s83, s3, s46
	s_cselect_b32 s82, s2, s5
	s_add_u32 s84, s7, 0x40080
	s_addc_u32 s85, s48, 0
	s_add_i32 s53, s50, s27
	s_add_i32 m0, s38, 0xc000
	s_add_i32 s54, s38, 0xe000
	s_add_i32 s52, 0, 0x14000
	s_add_i32 s51, s53, 0x2000
	s_add_u32 s68, s82, 0x40000
	v_add_u32_e32 v141, s50, v139
	s_addc_u32 s69, s83, 0
	s_add_i32 s87, s52, s27
	ds_read_b128 v[142:145], v141
	ds_read_b128 v[146:149], v141 offset:1024
	ds_read_b128 v[150:153], v141 offset:2048
	ds_read_b128 v[176:179], v141 offset:3072
	s_add_i32 s86, s87, 0x2000
	s_add_i32 s49, 0, 0x18000
	s_add_u32 s46, s80, 0x40000
	s_addc_u32 s47, s81, 0
	s_add_i32 s48, s49, s27
	s_add_i32 s7, 0, 0x1c000
	s_add_i32 s5, s48, 0x2000
	s_add_u32 s36, s82, 0x40080
	s_addc_u32 s37, s83, 0
	s_add_i32 s50, s7, s27
	s_add_i32 s88, s50, 0x2000
	v_lshl_add_u64 v[162:163], s[84:85], 0, v[136:137]
	ds_read_b128 v[180:183], v140
	ds_read_b128 v[184:187], v140 offset:1024
	ds_read_b128 v[188:191], v140 offset:2048
	ds_read_b128 v[192:195], v140 offset:3072
	ds_read_b128 v[196:199], v140 offset:4096
	ds_read_b128 v[200:203], v140 offset:5120
	ds_read_b128 v[204:207], v140 offset:6144
	ds_read_b128 v[214:217], v140 offset:7168
	global_load_lds_dwordx4 v[162:163], off
	v_lshl_add_u64 v[162:163], s[84:85], 0, v[132:133]
	s_mov_b32 m0, s54
	s_nop 0
	global_load_lds_dwordx4 v[162:163], off
	s_waitcnt lgkmcnt(8)
	s_barrier
	s_waitcnt lgkmcnt(0)
	s_setprio 1
	v_mfma_f32_16x16x32_bf16 v[126:129], v[142:145], v[180:183], v[126:129]
	v_mfma_f32_16x16x32_bf16 v[122:125], v[150:153], v[180:183], v[122:125]
	v_mfma_f32_16x16x32_bf16 v[118:121], v[142:145], v[188:191], v[118:121]
	v_mfma_f32_16x16x32_bf16 v[114:117], v[150:153], v[188:191], v[114:117]
	v_mfma_f32_16x16x32_bf16 v[102:105], v[142:145], v[196:199], v[102:105]
	v_mfma_f32_16x16x32_bf16 v[98:101], v[150:153], v[196:199], v[98:101]
	v_mfma_f32_16x16x32_bf16 v[86:89], v[142:145], v[204:207], v[86:89]
	v_mfma_f32_16x16x32_bf16 v[82:85], v[150:153], v[204:207], v[82:85]
	v_mfma_f32_16x16x32_bf16 v[126:129], v[146:149], v[184:187], v[126:129]
	v_mfma_f32_16x16x32_bf16 v[122:125], v[176:179], v[184:187], v[122:125]
	v_mfma_f32_16x16x32_bf16 v[118:121], v[146:149], v[192:195], v[118:121]
	v_mfma_f32_16x16x32_bf16 v[114:117], v[176:179], v[192:195], v[114:117]
	v_mfma_f32_16x16x32_bf16 v[102:105], v[146:149], v[200:203], v[102:105]
	v_mfma_f32_16x16x32_bf16 v[98:101], v[176:179], v[200:203], v[98:101]
	v_mfma_f32_16x16x32_bf16 v[86:89], v[146:149], v[214:217], v[86:89]
	v_mfma_f32_16x16x32_bf16 v[82:85], v[176:179], v[214:217], v[82:85]
	s_setprio 0
	s_barrier
	s_mov_b32 m0, s53
	v_add_u32_e32 v141, s52, v139
	v_lshl_add_u64 v[162:163], s[82:83], 0, v[134:135]
	ds_read_b128 v[218:221], v141
	ds_read_b128 v[222:225], v141 offset:1024
	ds_read_b128 v[226:229], v141 offset:2048
	ds_read_b128 v[230:233], v141 offset:3072
	global_load_lds_dwordx4 v[162:163], off
	v_lshl_add_u64 v[164:165], s[82:83], 0, v[130:131]
	s_mov_b32 m0, s51
	s_nop 0
	global_load_lds_dwordx4 v[164:165], off
	s_barrier
	s_waitcnt lgkmcnt(0)
	s_setprio 1
	v_mfma_f32_16x16x32_bf16 v[110:113], v[218:221], v[180:183], v[110:113]
	v_mfma_f32_16x16x32_bf16 v[106:109], v[226:229], v[180:183], v[106:109]
	v_mfma_f32_16x16x32_bf16 v[94:97], v[218:221], v[188:191], v[94:97]
	v_mfma_f32_16x16x32_bf16 v[90:93], v[226:229], v[188:191], v[90:93]
	v_mfma_f32_16x16x32_bf16 v[78:81], v[218:221], v[196:199], v[78:81]
	v_mfma_f32_16x16x32_bf16 v[74:77], v[226:229], v[196:199], v[74:77]
	v_mfma_f32_16x16x32_bf16 v[70:73], v[218:221], v[204:207], v[70:73]
	v_mfma_f32_16x16x32_bf16 v[66:69], v[226:229], v[204:207], v[66:69]
	v_mfma_f32_16x16x32_bf16 v[110:113], v[222:225], v[184:187], v[110:113]
	v_mfma_f32_16x16x32_bf16 v[106:109], v[230:233], v[184:187], v[106:109]
	v_mfma_f32_16x16x32_bf16 v[94:97], v[222:225], v[192:195], v[94:97]
	v_mfma_f32_16x16x32_bf16 v[90:93], v[230:233], v[192:195], v[90:93]
	v_mfma_f32_16x16x32_bf16 v[78:81], v[222:225], v[200:203], v[78:81]
	v_mfma_f32_16x16x32_bf16 v[74:77], v[230:233], v[200:203], v[74:77]
	v_mfma_f32_16x16x32_bf16 v[70:73], v[222:225], v[214:217], v[70:73]
	v_mfma_f32_16x16x32_bf16 v[66:69], v[230:233], v[214:217], v[66:69]
	s_setprio 0
	s_mov_b32 m0, s38
	v_lshl_add_u64 v[208:209], s[80:81], 0, v[136:137]
	s_barrier
	ds_read_b128 v[180:183], v140 offset:16384
	ds_read_b128 v[184:187], v140 offset:17408
	ds_read_b128 v[188:191], v140 offset:18432
	ds_read_b128 v[192:195], v140 offset:19456
	ds_read_b128 v[196:199], v140 offset:20480
	ds_read_b128 v[200:203], v140 offset:21504
	ds_read_b128 v[204:207], v140 offset:22528
	ds_read_b128 v[214:217], v140 offset:23552
	global_load_lds_dwordx4 v[208:209], off
	v_lshl_add_u64 v[234:235], s[80:81], 0, v[132:133]
	s_mov_b32 m0, s39
	s_nop 0
	global_load_lds_dwordx4 v[234:235], off
	s_barrier
; #define PG8_STAGE(bufoff, gbase, voff) do { _Pragma("unroll") for (int _i = 0; _i < 2; ++_i) \
;         __builtin_amdgcn_global_load_lds((const unsigned*)((const char*)(gbase) + (voff)[_i]), (LAS unsigned*)(lds + (bufoff) + ldsw + _i * 8192), 16, 0, 0); } while (0)
; #define PG8_LDA(dst, b, h) do { _Pragma("unroll") for (int m = 0; m < 4; ++m) _Pragma("unroll") for (int k = 0; k < 2; ++k) dst[m][k] = *(const LAS bf16x8*)(lds + PG8_SA(b, h) + aoff + m * 2048 + k * 1024); } while (0)
; #define PG8_LDB(dst, b, h) do { _Pragma("unroll") for (int n = 0; n < 2; ++n) _Pragma("unroll") for (int k = 0; k < 2; ++k) dst[n][k] = *(const LAS bf16x8*)(lds + PG8_SB(b, h) + boff + n * 2048 + k * 1024); } while (0)
; #define PG8_MMA(ai, bj, At, Bt) do { __builtin_amdgcn_s_setprio(1); _Pragma("unroll") for (int m = 0; m < 4; ++m) _Pragma("unroll") for (int n = 0; n < 2; ++n) _Pragma("unroll") for (int k = 0; k < 2; ++k) \
;         acc[ai][bj][m][n] = __builtin_amdgcn_mfma_f32_16x16x32_bf16(Bt[n][k], At[m][k], acc[ai][bj][m][n], 0, 0, 0); __builtin_amdgcn_s_setprio(0); } while (0)
; #define PG8_WAIT_V(n) asm volatile("s_waitcnt vmcnt(" #n ")" ::: "memory")
; #define PG8_WAIT_L(n) asm volatile("s_waitcnt lgkmcnt(" #n ")" ::: "memory")
; #define PG8_BAR __builtin_amdgcn_s_barrier()
; #define PG8_SCHED __builtin_amdgcn_sched_barrier(0)
; template <class Epi>
; DEVI void gemm_phase(LAS unsigned char* lds, const Gemm g, const Epi& E) {
;     ...
;             PG8_BAR; PG8_WAIT_L(0); PG8_MMA(1, 0, At, B0); PG8_BAR; PG8_SCHED;
;             PG8_STAGE(PG8_SB(0, 1), b2 + hstepB, voffB);
;             PG8_WAIT_V(6); PG8_BAR; PG8_MMA(1, 1, At, B1); PG8_BAR;
;             PG8_LDB(B0, 1, 0); PG8_SCHED; PG8_LDA(At, 1, 0); PG8_STAGE(PG8_SA(0, 1), a2 + hstepA, voffA);
;             PG8_WAIT_L(8); PG8_BAR; PG8_WAIT_L(0); PG8_MMA(0, 0, At, B0); PG8_BAR; PG8_SCHED;
;             PG8_LDB(B1, 1, 1); PG8_STAGE(PG8_SB(1, 0), b3, voffB);
;             PG8_BAR; PG8_WAIT_L(0); PG8_MMA(0, 1, At, B1); PG8_BAR;
;             PG8_LDA(At, 1, 1); PG8_STAGE(PG8_SA(1, 0), a3, voffA);
;             PG8_BAR; PG8_WAIT_L(0); PG8_MMA(1, 0, At, B0); PG8_BAR; PG8_SCHED;
	s_waitcnt lgkmcnt(0)
	s_setprio 1
	v_mfma_f32_16x16x32_bf16 v[62:65], v[142:145], v[180:183], v[62:65]
	v_mfma_f32_16x16x32_bf16 v[58:61], v[150:153], v[180:183], v[58:61]
	v_mfma_f32_16x16x32_bf16 v[54:57], v[142:145], v[188:191], v[54:57]
	v_mfma_f32_16x16x32_bf16 v[50:53], v[150:153], v[188:191], v[50:53]
	v_mfma_f32_16x16x32_bf16 v[38:41], v[142:145], v[196:199], v[38:41]
	v_mfma_f32_16x16x32_bf16 v[34:37], v[150:153], v[196:199], v[34:37]
	v_mfma_f32_16x16x32_bf16 v[22:25], v[142:145], v[204:207], v[22:25]
	v_mfma_f32_16x16x32_bf16 v[18:21], v[150:153], v[204:207], v[18:21]
	v_mfma_f32_16x16x32_bf16 v[62:65], v[146:149], v[184:187], v[62:65]
	v_mfma_f32_16x16x32_bf16 v[58:61], v[176:179], v[184:187], v[58:61]
	v_mfma_f32_16x16x32_bf16 v[54:57], v[146:149], v[192:195], v[54:57]
	v_mfma_f32_16x16x32_bf16 v[50:53], v[176:179], v[192:195], v[50:53]
	v_mfma_f32_16x16x32_bf16 v[38:41], v[146:149], v[200:203], v[38:41]
	v_mfma_f32_16x16x32_bf16 v[34:37], v[176:179], v[200:203], v[34:37]
	v_mfma_f32_16x16x32_bf16 v[22:25], v[146:149], v[214:217], v[22:25]
	v_mfma_f32_16x16x32_bf16 v[18:21], v[176:179], v[214:217], v[18:21]
	s_setprio 0
	s_barrier
	s_mov_b32 m0, s87
	v_lshl_add_u64 v[142:143], s[68:69], 0, v[134:135]
	global_load_lds_dwordx4 v[142:143], off
	v_lshl_add_u64 v[142:143], s[68:69], 0, v[130:131]
	s_mov_b32 m0, s86
	s_nop 0
	global_load_lds_dwordx4 v[142:143], off
	s_waitcnt vmcnt(6)
	s_barrier
	s_setprio 1
	v_mfma_f32_16x16x32_bf16 v[46:49], v[218:221], v[180:183], v[46:49]
	v_mfma_f32_16x16x32_bf16 v[42:45], v[226:229], v[180:183], v[42:45]
	v_mfma_f32_16x16x32_bf16 v[30:33], v[218:221], v[188:191], v[30:33]
	v_mfma_f32_16x16x32_bf16 v[26:29], v[226:229], v[188:191], v[26:29]
	v_mfma_f32_16x16x32_bf16 v[14:17], v[218:221], v[196:199], v[14:17]
	v_mfma_f32_16x16x32_bf16 v[10:13], v[226:229], v[196:199], v[10:13]
	v_mfma_f32_16x16x32_bf16 v[4:7], v[218:221], v[204:207], v[4:7]
	v_mfma_f32_16x16x32_bf16 v[0:3], v[226:229], v[204:207], v[0:3]
	v_mfma_f32_16x16x32_bf16 v[46:49], v[222:225], v[184:187], v[46:49]
	v_mfma_f32_16x16x32_bf16 v[42:45], v[230:233], v[184:187], v[42:45]
	v_mfma_f32_16x16x32_bf16 v[30:33], v[222:225], v[192:195], v[30:33]
	v_mfma_f32_16x16x32_bf16 v[26:29], v[230:233], v[192:195], v[26:29]
	v_mfma_f32_16x16x32_bf16 v[14:17], v[222:225], v[200:203], v[14:17]
	v_mfma_f32_16x16x32_bf16 v[10:13], v[230:233], v[200:203], v[10:13]
	v_mfma_f32_16x16x32_bf16 v[4:7], v[222:225], v[214:217], v[4:7]
	v_mfma_f32_16x16x32_bf16 v[0:3], v[230:233], v[214:217], v[0:3]
	s_setprio 0
	v_add_u32_e32 v141, s49, v139
	s_barrier
	ds_read_b128 v[142:145], v141
	ds_read_b128 v[146:149], v141 offset:1024
	ds_read_b128 v[150:153], v141 offset:2048
	ds_read_b128 v[176:179], v141 offset:3072
	s_mov_b32 m0, s40
	v_lshl_add_u64 v[218:219], s[46:47], 0, v[136:137]
	ds_read_b128 v[180:183], v140 offset:32768
	ds_read_b128 v[184:187], v140 offset:33792
	ds_read_b128 v[188:191], v140 offset:34816
	ds_read_b128 v[192:195], v140 offset:35840
	ds_read_b128 v[196:199], v140 offset:36864
	ds_read_b128 v[200:203], v140 offset:37888
	ds_read_b128 v[204:207], v140 offset:38912
	ds_read_b128 v[214:217], v140 offset:39936
	global_load_lds_dwordx4 v[218:219], off
	v_lshl_add_u64 v[218:219], s[46:47], 0, v[132:133]
	s_mov_b32 m0, s41
	s_nop 0
	global_load_lds_dwordx4 v[218:219], off
	s_waitcnt lgkmcnt(8)
	s_barrier
	s_waitcnt lgkmcnt(0)
	s_setprio 1
	v_mfma_f32_16x16x32_bf16 v[126:129], v[142:145], v[180:183], v[126:129]
	v_mfma_f32_16x16x32_bf16 v[122:125], v[150:153], v[180:183], v[122:125]
	v_mfma_f32_16x16x32_bf16 v[118:121], v[142:145], v[188:191], v[118:121]
	v_mfma_f32_16x16x32_bf16 v[114:117], v[150:153], v[188:191], v[114:117]
	v_mfma_f32_16x16x32_bf16 v[102:105], v[142:145], v[196:199], v[102:105]
	v_mfma_f32_16x16x32_bf16 v[98:101], v[150:153], v[196:199], v[98:101]
	v_mfma_f32_16x16x32_bf16 v[86:89], v[142:145], v[204:207], v[86:89]
	v_mfma_f32_16x16x32_bf16 v[82:85], v[150:153], v[204:207], v[82:85]
	v_mfma_f32_16x16x32_bf16 v[126:129], v[146:149], v[184:187], v[126:129]
	v_mfma_f32_16x16x32_bf16 v[122:125], v[176:179], v[184:187], v[122:125]
	v_mfma_f32_16x16x32_bf16 v[118:121], v[146:149], v[192:195], v[118:121]
	v_mfma_f32_16x16x32_bf16 v[114:117], v[176:179], v[192:195], v[114:117]
	v_mfma_f32_16x16x32_bf16 v[102:105], v[146:149], v[200:203], v[102:105]
	v_mfma_f32_16x16x32_bf16 v[98:101], v[176:179], v[200:203], v[98:101]
	v_mfma_f32_16x16x32_bf16 v[86:89], v[146:149], v[214:217], v[86:89]
	v_mfma_f32_16x16x32_bf16 v[82:85], v[176:179], v[214:217], v[82:85]
	s_setprio 0
	s_barrier
	s_mov_b32 m0, s48
	v_add_u32_e32 v141, s7, v139
	v_lshl_add_u64 v[162:163], v[162:163], 0, s[70:71]
	ds_read_b128 v[218:221], v141
	ds_read_b128 v[222:225], v141 offset:1024
	ds_read_b128 v[226:229], v141 offset:2048
	ds_read_b128 v[230:233], v141 offset:3072
	global_load_lds_dwordx4 v[162:163], off
	v_lshl_add_u64 v[162:163], v[164:165], 0, s[70:71]
	s_mov_b32 m0, s5
	s_nop 0
	global_load_lds_dwordx4 v[162:163], off
	s_barrier
	s_waitcnt lgkmcnt(0)
	s_setprio 1
	v_mfma_f32_16x16x32_bf16 v[110:113], v[218:221], v[180:183], v[110:113]
	v_mfma_f32_16x16x32_bf16 v[106:109], v[226:229], v[180:183], v[106:109]
	v_mfma_f32_16x16x32_bf16 v[94:97], v[218:221], v[188:191], v[94:97]
	v_mfma_f32_16x16x32_bf16 v[90:93], v[226:229], v[188:191], v[90:93]
	v_mfma_f32_16x16x32_bf16 v[78:81], v[218:221], v[196:199], v[78:81]
	v_mfma_f32_16x16x32_bf16 v[74:77], v[226:229], v[196:199], v[74:77]
	v_mfma_f32_16x16x32_bf16 v[70:73], v[218:221], v[204:207], v[70:73]
	v_mfma_f32_16x16x32_bf16 v[66:69], v[226:229], v[204:207], v[66:69]
	v_mfma_f32_16x16x32_bf16 v[110:113], v[222:225], v[184:187], v[110:113]
	v_mfma_f32_16x16x32_bf16 v[106:109], v[230:233], v[184:187], v[106:109]
	v_mfma_f32_16x16x32_bf16 v[94:97], v[222:225], v[192:195], v[94:97]
	v_mfma_f32_16x16x32_bf16 v[90:93], v[230:233], v[192:195], v[90:93]
	v_mfma_f32_16x16x32_bf16 v[78:81], v[222:225], v[200:203], v[78:81]
	v_mfma_f32_16x16x32_bf16 v[74:77], v[230:233], v[200:203], v[74:77]
	v_mfma_f32_16x16x32_bf16 v[70:73], v[222:225], v[214:217], v[70:73]
	v_mfma_f32_16x16x32_bf16 v[66:69], v[230:233], v[214:217], v[66:69]
	s_setprio 0
	s_mov_b32 m0, s42
	v_lshl_add_u64 v[162:163], v[208:209], 0, s[70:71]
	s_barrier
; #define PG8_STAGE(bufoff, gbase, voff) do { _Pragma("unroll") for (int _i = 0; _i < 2; ++_i) \
;         __builtin_amdgcn_global_load_lds((const unsigned*)((const char*)(gbase) + (voff)[_i]), (LAS unsigned*)(lds + (bufoff) + ldsw + _i * 8192), 16, 0, 0); } while (0)
; #define PG8_LDA(dst, b, h) do { _Pragma("unroll") for (int m = 0; m < 4; ++m) _Pragma("unroll") for (int k = 0; k < 2; ++k) dst[m][k] = *(const LAS bf16x8*)(lds + PG8_SA(b, h) + aoff + m * 2048 + k * 1024); } while (0)
; #define PG8_LDB(dst, b, h) do { _Pragma("unroll") for (int n = 0; n < 2; ++n) _Pragma("unroll") for (int k = 0; k < 2; ++k) dst[n][k] = *(const LAS bf16x8*)(lds + PG8_SB(b, h) + boff + n * 2048 + k * 1024); } while (0)
; #define PG8_MMA(ai, bj, At, Bt) do { __builtin_amdgcn_s_setprio(1); _Pragma("unroll") for (int m = 0; m < 4; ++m) _Pragma("unroll") for (int n = 0; n < 2; ++n) _Pragma("unroll") for (int k = 0; k < 2; ++k) \
;         acc[ai][bj][m][n] = __builtin_amdgcn_mfma_f32_16x16x32_bf16(Bt[n][k], At[m][k], acc[ai][bj][m][n], 0, 0, 0); __builtin_amdgcn_s_setprio(0); } while (0)
; #define PG8_WAIT_V(n) asm volatile("s_waitcnt vmcnt(" #n ")" ::: "memory")
; #define PG8_WAIT_L(n) asm volatile("s_waitcnt lgkmcnt(" #n ")" ::: "memory")
; #define PG8_BAR __builtin_amdgcn_s_barrier()
; #define PG8_SCHED __builtin_amdgcn_sched_barrier(0)
; template <class Epi>
; DEVI void gemm_phase(LAS unsigned char* lds, const Gemm g, const Epi& E) {
;     ...
;             PG8_LDB(B0, 1, 0); PG8_SCHED; PG8_LDA(At, 1, 0); PG8_STAGE(PG8_SA(0, 1), a2 + hstepA, voffA);
;             PG8_WAIT_L(8); PG8_BAR; PG8_WAIT_L(0); PG8_MMA(0, 0, At, B0); PG8_BAR; PG8_SCHED;
;             PG8_LDB(B1, 1, 1); PG8_STAGE(PG8_SB(1, 0), b3, voffB);
;             PG8_BAR; PG8_WAIT_L(0); PG8_MMA(0, 1, At, B1); PG8_BAR;
;             PG8_LDA(At, 1, 1); PG8_STAGE(PG8_SA(1, 0), a3, voffA);
;             PG8_BAR; PG8_WAIT_L(0); PG8_MMA(1, 0, At, B0); PG8_BAR; PG8_SCHED;
;             PG8_STAGE(PG8_SB(1, 1), b3 + hstepB, voffB);
;             PG8_WAIT_V(6); PG8_BAR; PG8_MMA(1, 1, At, B1); PG8_BAR;
;         }
	ds_read_b128 v[180:183], v140 offset:49152
	ds_read_b128 v[184:187], v140 offset:50176
	ds_read_b128 v[188:191], v140 offset:51200
	ds_read_b128 v[192:195], v140 offset:52224
	ds_read_b128 v[196:199], v140 offset:53248
	ds_read_b128 v[200:203], v140 offset:54272
	ds_read_b128 v[204:207], v140 offset:55296
	ds_read_b128 v[214:217], v140 offset:56320
	global_load_lds_dwordx4 v[162:163], off
	v_lshl_add_u64 v[162:163], v[234:235], 0, s[70:71]
	s_mov_b32 m0, s43
	s_nop 0
	global_load_lds_dwordx4 v[162:163], off
	s_barrier
	s_waitcnt lgkmcnt(0)
	s_setprio 1
	v_mfma_f32_16x16x32_bf16 v[62:65], v[142:145], v[180:183], v[62:65]
	v_mfma_f32_16x16x32_bf16 v[58:61], v[150:153], v[180:183], v[58:61]
	v_mfma_f32_16x16x32_bf16 v[54:57], v[142:145], v[188:191], v[54:57]
	v_mfma_f32_16x16x32_bf16 v[50:53], v[150:153], v[188:191], v[50:53]
	v_mfma_f32_16x16x32_bf16 v[38:41], v[142:145], v[196:199], v[38:41]
	v_mfma_f32_16x16x32_bf16 v[34:37], v[150:153], v[196:199], v[34:37]
	v_mfma_f32_16x16x32_bf16 v[22:25], v[142:145], v[204:207], v[22:25]
	v_mfma_f32_16x16x32_bf16 v[18:21], v[150:153], v[204:207], v[18:21]
	v_mfma_f32_16x16x32_bf16 v[62:65], v[146:149], v[184:187], v[62:65]
	v_mfma_f32_16x16x32_bf16 v[58:61], v[176:179], v[184:187], v[58:61]
	v_mfma_f32_16x16x32_bf16 v[54:57], v[146:149], v[192:195], v[54:57]
	v_mfma_f32_16x16x32_bf16 v[50:53], v[176:179], v[192:195], v[50:53]
	v_mfma_f32_16x16x32_bf16 v[38:41], v[146:149], v[200:203], v[38:41]
	v_mfma_f32_16x16x32_bf16 v[34:37], v[176:179], v[200:203], v[34:37]
	v_mfma_f32_16x16x32_bf16 v[22:25], v[146:149], v[214:217], v[22:25]
	v_mfma_f32_16x16x32_bf16 v[18:21], v[176:179], v[214:217], v[18:21]
	s_setprio 0
	s_barrier
	s_mov_b32 m0, s50
	v_lshl_add_u64 v[142:143], s[36:37], 0, v[134:135]
	global_load_lds_dwordx4 v[142:143], off
	v_lshl_add_u64 v[142:143], s[36:37], 0, v[130:131]
	s_mov_b32 m0, s88
	s_nop 0
	global_load_lds_dwordx4 v[142:143], off
	s_waitcnt vmcnt(6)
	s_barrier
	s_setprio 1
	v_mfma_f32_16x16x32_bf16 v[46:49], v[218:221], v[180:183], v[46:49]
	v_mfma_f32_16x16x32_bf16 v[42:45], v[226:229], v[180:183], v[42:45]
	v_mfma_f32_16x16x32_bf16 v[30:33], v[218:221], v[188:191], v[30:33]
	v_mfma_f32_16x16x32_bf16 v[26:29], v[226:229], v[188:191], v[26:29]
	v_mfma_f32_16x16x32_bf16 v[14:17], v[218:221], v[196:199], v[14:17]
	v_mfma_f32_16x16x32_bf16 v[10:13], v[226:229], v[196:199], v[10:13]
	v_mfma_f32_16x16x32_bf16 v[4:7], v[218:221], v[204:207], v[4:7]
	v_mfma_f32_16x16x32_bf16 v[0:3], v[226:229], v[204:207], v[0:3]
	v_mfma_f32_16x16x32_bf16 v[46:49], v[222:225], v[184:187], v[46:49]
	v_mfma_f32_16x16x32_bf16 v[42:45], v[230:233], v[184:187], v[42:45]
	v_mfma_f32_16x16x32_bf16 v[30:33], v[222:225], v[192:195], v[30:33]
	v_mfma_f32_16x16x32_bf16 v[26:29], v[230:233], v[192:195], v[26:29]
	v_mfma_f32_16x16x32_bf16 v[14:17], v[222:225], v[200:203], v[14:17]
	v_mfma_f32_16x16x32_bf16 v[10:13], v[230:233], v[200:203], v[10:13]
	v_mfma_f32_16x16x32_bf16 v[4:7], v[222:225], v[214:217], v[4:7]
	v_mfma_f32_16x16x32_bf16 v[0:3], v[230:233], v[214:217], v[0:3]
	s_setprio 0
	s_movk_i32 s5, 0x100
	s_andn2_b64 vcc, exec, s[16:17]
	s_mov_b64 s[36:37], -1
	s_mov_b64 s[16:17], 0
	s_barrier
	s_cbranch_vccz .LBB0_1214
; template <class Epi>
; DEVI void gemm_phase(LAS unsigned char* lds, const Gemm g, const Epi& E) {
;     ...
;                 for (int mm = 0; mm < 2; ++mm) {
;                     const int m = m0 + mm;
;                     const int r = row0 + ai * HALF + m * 16; float rs = 1.f, part = 0.f;
;                     if constexpr (Epi::RS) rs = rsv[ai * 4 + m];
;                     if constexpr (Epi::PAIR) E.pair8(cur.b, r, cur.pn * HALF + wc * 32 + 8 * fq, acc[ai][0][m][0] * rs, acc[ai][0][m][1] * rs, acc[ai][1][m][0] * rs, acc[ai][1][m][1] * rs);
;                     else
; #pragma unroll
;                     for (int bj = 0; bj < 2; ++bj) {
;                         const int c = col0 + bj * HALF; f32x4 v0 = acc[ai][bj][m][0], v1 = acc[ai][bj][m][1];
;                         if constexpr (Epi::RS) { v0 = v0 * rs; v1 = v1 * rs; }
;                         if constexpr (Epi::PRE) part += E.frag_pre8(cur.b, r, c, v0, v1, pre[mm][bj][0], pre[mm][bj][1]);
;                         else if constexpr (Epi::PERM) E.frag8(cur.b, r, c, v0, v1);
;                         else { E.frag(cur.b, r, c, v0); E.frag(cur.b, r, c + 16, v1); }
;                     }
	s_ashr_i32 s8, s44, 2
	s_ashr_i32 s9, s8, 31
	s_lshl_b64 s[8:9], s[8:9], 21
	s_add_u32 s5, s62, s8
	s_addc_u32 s7, s63, s9
	s_lshl_b32 s8, s44, 9
	v_lshl_add_u32 v142, s66, 8, v138
	s_and_b32 s8, s8, 0x600
	s_add_u32 s8, s5, s8
	v_ashrrev_i32_e32 v143, 31, v142
	s_addc_u32 s9, s7, 0
	v_lshlrev_b64 v[144:145], 11, v[142:143]
	v_cvt_pk_bf16_f32 v110, v110, v111
	v_cvt_pk_bf16_f32 v111, v112, v113
	v_cvt_pk_bf16_f32 v112, v106, v107
	v_or_b32_e32 v106, 16, v142
	v_lshl_add_u64 v[144:145], s[8:9], 0, v[144:145]
	v_ashrrev_i32_e32 v107, 31, v106
	v_cvt_pk_bf16_f32 v126, v126, v127
	v_cvt_pk_bf16_f32 v127, v128, v129
	v_cvt_pk_bf16_f32 v128, v122, v123
	v_lshl_add_u64 v[122:123], v[144:145], 0, v[8:9]
	v_cvt_pk_bf16_f32 v113, v108, v109
	v_lshlrev_b64 v[106:107], 11, v[106:107]
	v_cvt_pk_bf16_f32 v94, v94, v95
	v_cvt_pk_bf16_f32 v95, v96, v97
	v_cvt_pk_bf16_f32 v96, v90, v91
	v_or_b32_e32 v90, 32, v142
	global_store_dwordx4 v[122:123], v[110:113], off offset:256
	v_ashrrev_i32_e32 v91, 31, v90
	v_cvt_pk_bf16_f32 v97, v92, v93
	v_lshl_add_u64 v[110:111], s[8:9], 0, v[106:107]
	v_lshl_add_u64 v[110:111], v[110:111], 0, v[8:9]
	v_lshlrev_b64 v[90:91], 11, v[90:91]
	v_cvt_pk_bf16_f32 v78, v78, v79
	v_cvt_pk_bf16_f32 v79, v80, v81
	v_cvt_pk_bf16_f32 v80, v74, v75
	v_or_b32_e32 v74, 48, v142
	global_store_dwordx4 v[110:111], v[94:97], off offset:256
	v_ashrrev_i32_e32 v75, 31, v74
	v_cvt_pk_bf16_f32 v81, v76, v77
	v_lshl_add_u64 v[94:95], s[8:9], 0, v[90:91]
	v_lshl_add_u64 v[94:95], v[94:95], 0, v[8:9]
	v_lshlrev_b64 v[74:75], 11, v[74:75]
	s_mov_b32 s5, 0x40000
	global_store_dwordx4 v[94:95], v[78:81], off offset:256
	v_cvt_pk_bf16_f32 v62, v62, v63
	v_cvt_pk_bf16_f32 v63, v64, v65
	v_lshl_add_u64 v[78:79], s[8:9], 0, v[74:75]
	v_cvt_pk_bf16_f32 v65, v60, v61
	s_mov_b64 s[8:9], 0x40000
	v_add_co_u32_e32 v60, vcc, s5, v122
	v_cvt_pk_bf16_f32 v64, v58, v59
	v_lshl_add_u64 v[58:59], v[122:123], 0, s[8:9]
	v_addc_co_u32_e32 v61, vcc, 0, v123, vcc
	v_cvt_pk_bf16_f32 v46, v46, v47
	v_cvt_pk_bf16_f32 v47, v48, v49
	v_cvt_pk_bf16_f32 v48, v42, v43
	v_cvt_pk_bf16_f32 v49, v44, v45
	s_mov_b32 s5, 0x48000
	global_store_dwordx4 v[58:59], v[46:49], off offset:256
	s_mov_b64 s[8:9], 0x48000
	v_cvt_pk_bf16_f32 v30, v30, v31
	v_add_co_u32_e32 v48, vcc, s5, v122
	v_lshl_add_u64 v[46:47], v[122:123], 0, s[8:9]
	s_nop 0
	v_addc_co_u32_e32 v49, vcc, 0, v123, vcc
	v_cvt_pk_bf16_f32 v31, v32, v33
	v_cvt_pk_bf16_f32 v32, v26, v27
	v_cvt_pk_bf16_f32 v33, v28, v29
	s_mov_b32 s5, 0x50000
	global_store_dwordx4 v[46:47], v[30:33], off offset:256
	s_mov_b64 s[8:9], 0x50000
	v_cvt_pk_bf16_f32 v14, v14, v15
	v_add_co_u32_e32 v32, vcc, s5, v122
	v_lshl_add_u64 v[30:31], v[122:123], 0, s[8:9]
	s_nop 0
	v_addc_co_u32_e32 v33, vcc, 0, v123, vcc
	v_cvt_pk_bf16_f32 v15, v16, v17
	v_cvt_pk_bf16_f32 v16, v10, v11
	v_cvt_pk_bf16_f32 v17, v12, v13
	s_mov_b32 s5, 0x58000
	global_store_dwordx4 v[30:31], v[14:17], off offset:256
	s_mov_b64 s[8:9], 0x58000
	v_cvt_pk_bf16_f32 v129, v124, v125
	v_add_co_u32_e32 v16, vcc, s5, v122
	v_cvt_pk_bf16_f32 v106, v118, v119
	s_nop 0
	v_addc_co_u32_e32 v17, vcc, 0, v123, vcc
	v_cvt_pk_bf16_f32 v107, v120, v121
	v_cvt_pk_bf16_f32 v108, v114, v115
	v_cvt_pk_bf16_f32 v109, v116, v117
	v_cvt_pk_bf16_f32 v90, v102, v103
	v_cvt_pk_bf16_f32 v91, v104, v105
	v_cvt_pk_bf16_f32 v92, v98, v99
	v_cvt_pk_bf16_f32 v93, v100, v101
	v_cvt_pk_bf16_f32 v74, v86, v87
	v_cvt_pk_bf16_f32 v75, v88, v89
	v_cvt_pk_bf16_f32 v76, v82, v83
	v_cvt_pk_bf16_f32 v77, v84, v85
	v_lshl_add_u64 v[78:79], v[78:79], 0, v[8:9]
	v_cvt_pk_bf16_f32 v70, v70, v71
	v_cvt_pk_bf16_f32 v71, v72, v73
	v_cvt_pk_bf16_f32 v72, v66, v67
	v_cvt_pk_bf16_f32 v73, v68, v69
	v_cvt_pk_bf16_f32 v42, v54, v55
	v_cvt_pk_bf16_f32 v43, v56, v57
	v_cvt_pk_bf16_f32 v44, v50, v51
	v_cvt_pk_bf16_f32 v45, v52, v53
	v_cvt_pk_bf16_f32 v26, v38, v39
	v_cvt_pk_bf16_f32 v27, v40, v41
	v_cvt_pk_bf16_f32 v28, v34, v35
	v_cvt_pk_bf16_f32 v29, v36, v37
	v_cvt_pk_bf16_f32 v10, v22, v23
	v_cvt_pk_bf16_f32 v11, v24, v25
	v_cvt_pk_bf16_f32 v12, v18, v19
	v_cvt_pk_bf16_f32 v13, v20, v21
	v_lshl_add_u64 v[14:15], v[122:123], 0, s[8:9]
	v_cvt_pk_bf16_f32 v4, v4, v5
	v_cvt_pk_bf16_f32 v5, v6, v7
	v_cvt_pk_bf16_f32 v6, v0, v1
	v_cvt_pk_bf16_f32 v7, v2, v3
	s_and_b64 vcc, exec, s[12:13]
	s_mov_b32 s44, s4
	s_mov_b32 s66, s6
	s_mov_b64 s[10:11], s[2:3]
	s_mov_b64 s[8:9], s[14:15]
	s_movk_i32 s52, 0x110
	global_store_dwordx4 v[122:123], v[126:129], off
	global_store_dwordx4 v[110:111], v[106:109], off
	global_store_dwordx4 v[94:95], v[90:93], off
	global_store_dwordx4 v[78:79], v[74:77], off
	global_store_dwordx4 v[78:79], v[70:73], off offset:256
	global_store_dwordx4 v[60:61], v[62:65], off
	global_store_dwordx4 v[48:49], v[42:45], off
	global_store_dwordx4 v[32:33], v[26:29], off
	global_store_dwordx4 v[16:17], v[10:13], off
	global_store_dwordx4 v[14:15], v[4:7], off offset:256
	s_cbranch_vccz .LBB0_1207
	s_waitcnt vmcnt(0)
	s_cmpk_gt_u32 s0, 0xff
	v_readlane_b32 s40, v254, 1
	s_cbranch_scc1 .LBB0_1218
	s_barrier

; #define PG8_STAGE(bufoff, gbase, voff) do { _Pragma("unroll") for (int _i = 0; _i < 2; ++_i) \
;         __builtin_amdgcn_global_load_lds((const unsigned*)((const char*)(gbase) + (voff)[_i]), (LAS unsigned*)(lds + (bufoff) + ldsw + _i * 8192), 16, 0, 0); } while (0)
; #define PG8_LDA(dst, b, h) do { _Pragma("unroll") for (int m = 0; m < 4; ++m) _Pragma("unroll") for (int k = 0; k < 2; ++k) dst[m][k] = *(const LAS bf16x8*)(lds + PG8_SA(b, h) + aoff + m * 2048 + k * 1024); } while (0)
; #define PG8_LDB(dst, b, h) do { _Pragma("unroll") for (int n = 0; n < 2; ++n) _Pragma("unroll") for (int k = 0; k < 2; ++k) dst[n][k] = *(const LAS bf16x8*)(lds + PG8_SB(b, h) + boff + n * 2048 + k * 1024); } while (0)
; #define PG8_MMA(ai, bj, At, Bt) do { __builtin_amdgcn_s_setprio(1); _Pragma("unroll") for (int m = 0; m < 4; ++m) _Pragma("unroll") for (int n = 0; n < 2; ++n) _Pragma("unroll") for (int k = 0; k < 2; ++k) \
;         acc[ai][bj][m][n] = __builtin_amdgcn_mfma_f32_16x16x32_bf16(Bt[n][k], At[m][k], acc[ai][bj][m][n], 0, 0, 0); __builtin_amdgcn_s_setprio(0); } while (0)
; #define PG8_WAIT_V(n) asm volatile("s_waitcnt vmcnt(" #n ")" ::: "memory")
; #define PG8_WAIT_L(n) asm volatile("s_waitcnt lgkmcnt(" #n ")" ::: "memory")
; #define PG8_BAR __builtin_amdgcn_s_barrier()
; #define PG8_SCHED __builtin_amdgcn_sched_barrier(0)
; template <class Epi>
; DEVI void gemm_phase(LAS unsigned char* lds, const Gemm g, const Epi& E) {
;     ...
;             PG8_LDB(B0, 0, 0); PG8_SCHED; PG8_LDA(At, 0, 0); PG8_STAGE(PG8_SA(1, 1), a1 + hstepA, voffA);
;             PG8_WAIT_L(8); PG8_BAR; PG8_WAIT_L(0); PG8_MMA(0, 0, At, B0); PG8_BAR; PG8_SCHED;
;             PG8_LDB(B1, 0, 1); PG8_STAGE(PG8_SB(0, 0), b2, voffB);
;             PG8_BAR; PG8_WAIT_L(0); PG8_MMA(0, 1, At, B1); PG8_BAR;
;             PG8_LDA(At, 0, 1); PG8_STAGE(PG8_SA(0, 0), a2, voffA);
;             PG8_BAR; PG8_WAIT_L(0); PG8_MMA(1, 0, At, B0); PG8_BAR; PG8_SCHED;
;             PG8_STAGE(PG8_SB(0, 1), b2 + hstepB, voffB);
;             PG8_WAIT_V(6); PG8_BAR; PG8_MMA(1, 1, At, B1); PG8_BAR;
;             PG8_LDB(B0, 1, 0); PG8_SCHED; PG8_LDA(At, 1, 0); PG8_STAGE(PG8_SA(0, 1), a2 + hstepA, voffA);
;             PG8_WAIT_L(8); PG8_BAR; PG8_WAIT_L(0); PG8_MMA(0, 0, At, B0); PG8_BAR; PG8_SCHED;
.LBB0_1278:
	s_add_u32 s12, s10, 0x100
	s_addc_u32 s13, s11, 0
	s_add_i32 s38, 0, 0x10000
	v_add_u32_e32 v146, s38, v149
	ds_read_b128 v[142:145], v146
	ds_read_b128 v[176:179], v146 offset:1024
	ds_read_b128 v[180:183], v146 offset:2048
	ds_read_b128 v[184:187], v146 offset:3072
	s_cmp_eq_u32 s27, 6
	s_cselect_b32 s17, s5, s13
	s_cselect_b32 s16, s4, s12
	s_cselect_b32 s15, s7, s26
	s_cselect_b32 s14, s6, s19
	v_lshl_add_u64 v[146:147], s[10:11], 0, v[138:139]
	s_add_i32 m0, s46, 0xc000
	ds_read_b128 v[188:191], v151
	ds_read_b128 v[192:195], v151 offset:1024
	ds_read_b128 v[196:199], v151 offset:2048
	ds_read_b128 v[200:203], v151 offset:3072
	ds_read_b128 v[204:207], v151 offset:4096
	ds_read_b128 v[214:217], v151 offset:5120
	ds_read_b128 v[218:221], v151 offset:6144
	ds_read_b128 v[222:225], v151 offset:7168
	global_load_lds_dwordx4 v[146:147], off
	v_lshl_add_u64 v[146:147], s[10:11], 0, v[140:141]
	s_add_i32 m0, s46, 0xe000
	s_nop 0
	global_load_lds_dwordx4 v[146:147], off
	s_waitcnt lgkmcnt(8)
	s_barrier
	s_waitcnt lgkmcnt(0)
	s_setprio 1
	v_mfma_f32_16x16x32_bf16 v[126:129], v[142:145], v[188:191], v[126:129]
	v_mfma_f32_16x16x32_bf16 v[122:125], v[180:183], v[188:191], v[122:125]
	v_mfma_f32_16x16x32_bf16 v[110:113], v[142:145], v[196:199], v[110:113]
	v_mfma_f32_16x16x32_bf16 v[106:109], v[180:183], v[196:199], v[106:109]
	v_mfma_f32_16x16x32_bf16 v[94:97], v[142:145], v[204:207], v[94:97]
	v_mfma_f32_16x16x32_bf16 v[90:93], v[180:183], v[204:207], v[90:93]
	v_mfma_f32_16x16x32_bf16 v[78:81], v[142:145], v[218:221], v[78:81]
	v_mfma_f32_16x16x32_bf16 v[74:77], v[180:183], v[218:221], v[74:77]
	v_mfma_f32_16x16x32_bf16 v[126:129], v[176:179], v[192:195], v[126:129]
	v_mfma_f32_16x16x32_bf16 v[122:125], v[184:187], v[192:195], v[122:125]
	v_mfma_f32_16x16x32_bf16 v[110:113], v[176:179], v[200:203], v[110:113]
	v_mfma_f32_16x16x32_bf16 v[106:109], v[184:187], v[200:203], v[106:109]
	v_mfma_f32_16x16x32_bf16 v[94:97], v[176:179], v[214:217], v[94:97]
	v_mfma_f32_16x16x32_bf16 v[90:93], v[184:187], v[214:217], v[90:93]
	v_mfma_f32_16x16x32_bf16 v[78:81], v[176:179], v[222:225], v[78:81]
	v_mfma_f32_16x16x32_bf16 v[74:77], v[184:187], v[222:225], v[74:77]
	s_setprio 0
	s_barrier
	s_add_i32 s39, 0, 0x14000
	v_add_u32_e32 v146, s39, v149
	s_add_i32 s10, s38, s37
	ds_read_b128 v[226:229], v146
	ds_read_b128 v[230:233], v146 offset:1024
	ds_read_b128 v[234:237], v146 offset:2048
	ds_read_b128 v[238:241], v146 offset:3072
	v_lshl_add_u64 v[146:147], s[14:15], 0, v[8:9]
	s_mov_b32 m0, s10
	v_lshl_add_u64 v[152:153], s[14:15], 0, v[130:131]
	global_load_lds_dwordx4 v[146:147], off
	s_add_i32 m0, s10, 0x2000
	s_nop 0
	global_load_lds_dwordx4 v[152:153], off
	s_barrier
	s_waitcnt lgkmcnt(0)
	s_setprio 1
	v_mfma_f32_16x16x32_bf16 v[118:121], v[226:229], v[188:191], v[118:121]
	v_mfma_f32_16x16x32_bf16 v[114:117], v[234:237], v[188:191], v[114:117]
	v_mfma_f32_16x16x32_bf16 v[102:105], v[226:229], v[196:199], v[102:105]
	v_mfma_f32_16x16x32_bf16 v[98:101], v[234:237], v[196:199], v[98:101]
	v_mfma_f32_16x16x32_bf16 v[86:89], v[226:229], v[204:207], v[86:89]
	v_mfma_f32_16x16x32_bf16 v[82:85], v[234:237], v[204:207], v[82:85]
	v_mfma_f32_16x16x32_bf16 v[70:73], v[226:229], v[218:221], v[70:73]
	v_mfma_f32_16x16x32_bf16 v[66:69], v[234:237], v[218:221], v[66:69]
	v_mfma_f32_16x16x32_bf16 v[118:121], v[230:233], v[192:195], v[118:121]
	v_mfma_f32_16x16x32_bf16 v[114:117], v[238:241], v[192:195], v[114:117]
	v_mfma_f32_16x16x32_bf16 v[102:105], v[230:233], v[200:203], v[102:105]
	v_mfma_f32_16x16x32_bf16 v[98:101], v[238:241], v[200:203], v[98:101]
	v_mfma_f32_16x16x32_bf16 v[86:89], v[230:233], v[214:217], v[86:89]
	v_mfma_f32_16x16x32_bf16 v[82:85], v[238:241], v[214:217], v[82:85]
	v_mfma_f32_16x16x32_bf16 v[70:73], v[230:233], v[222:225], v[70:73]
	v_mfma_f32_16x16x32_bf16 v[66:69], v[238:241], v[222:225], v[66:69]
	s_setprio 0
	s_mov_b32 m0, s46
	v_lshl_add_u64 v[162:163], s[16:17], 0, v[134:135]
	s_barrier
	ds_read_b128 v[188:191], v151 offset:16384
	ds_read_b128 v[192:195], v151 offset:17408
	ds_read_b128 v[196:199], v151 offset:18432
	ds_read_b128 v[200:203], v151 offset:19456
	ds_read_b128 v[204:207], v151 offset:20480
	ds_read_b128 v[214:217], v151 offset:21504
	ds_read_b128 v[218:221], v151 offset:22528
	ds_read_b128 v[222:225], v151 offset:23552
	global_load_lds_dwordx4 v[162:163], off
	v_lshl_add_u64 v[164:165], s[16:17], 0, v[132:133]
	s_mov_b32 m0, s47
	s_nop 0
	global_load_lds_dwordx4 v[164:165], off
	s_barrier
	s_waitcnt lgkmcnt(0)
	s_setprio 1
	v_mfma_f32_16x16x32_bf16 v[62:65], v[142:145], v[188:191], v[62:65]
	v_mfma_f32_16x16x32_bf16 v[58:61], v[180:183], v[188:191], v[58:61]
	v_mfma_f32_16x16x32_bf16 v[46:49], v[142:145], v[196:199], v[46:49]
	v_mfma_f32_16x16x32_bf16 v[42:45], v[180:183], v[196:199], v[42:45]
	v_mfma_f32_16x16x32_bf16 v[30:33], v[142:145], v[204:207], v[30:33]
	v_mfma_f32_16x16x32_bf16 v[26:29], v[180:183], v[204:207], v[26:29]
	v_mfma_f32_16x16x32_bf16 v[14:17], v[142:145], v[218:221], v[14:17]
	v_mfma_f32_16x16x32_bf16 v[10:13], v[180:183], v[218:221], v[10:13]
	v_mfma_f32_16x16x32_bf16 v[62:65], v[176:179], v[192:195], v[62:65]
	v_mfma_f32_16x16x32_bf16 v[58:61], v[184:187], v[192:195], v[58:61]
	v_mfma_f32_16x16x32_bf16 v[46:49], v[176:179], v[200:203], v[46:49]
	v_mfma_f32_16x16x32_bf16 v[42:45], v[184:187], v[200:203], v[42:45]
	v_mfma_f32_16x16x32_bf16 v[30:33], v[176:179], v[214:217], v[30:33]
	v_mfma_f32_16x16x32_bf16 v[26:29], v[184:187], v[214:217], v[26:29]
	v_mfma_f32_16x16x32_bf16 v[14:17], v[176:179], v[222:225], v[14:17]
	v_mfma_f32_16x16x32_bf16 v[10:13], v[184:187], v[222:225], v[10:13]
	s_setprio 0
	s_barrier
; #define PG8_STAGE(bufoff, gbase, voff) do { _Pragma("unroll") for (int _i = 0; _i < 2; ++_i) \
;         __builtin_amdgcn_global_load_lds((const unsigned*)((const char*)(gbase) + (voff)[_i]), (LAS unsigned*)(lds + (bufoff) + ldsw + _i * 8192), 16, 0, 0); } while (0)
; #define PG8_LDA(dst, b, h) do { _Pragma("unroll") for (int m = 0; m < 4; ++m) _Pragma("unroll") for (int k = 0; k < 2; ++k) dst[m][k] = *(const LAS bf16x8*)(lds + PG8_SA(b, h) + aoff + m * 2048 + k * 1024); } while (0)
; #define PG8_LDB(dst, b, h) do { _Pragma("unroll") for (int n = 0; n < 2; ++n) _Pragma("unroll") for (int k = 0; k < 2; ++k) dst[n][k] = *(const LAS bf16x8*)(lds + PG8_SB(b, h) + boff + n * 2048 + k * 1024); } while (0)
; #define PG8_MMA(ai, bj, At, Bt) do { __builtin_amdgcn_s_setprio(1); _Pragma("unroll") for (int m = 0; m < 4; ++m) _Pragma("unroll") for (int n = 0; n < 2; ++n) _Pragma("unroll") for (int k = 0; k < 2; ++k) \
;         acc[ai][bj][m][n] = __builtin_amdgcn_mfma_f32_16x16x32_bf16(Bt[n][k], At[m][k], acc[ai][bj][m][n], 0, 0, 0); __builtin_amdgcn_s_setprio(0); } while (0)
; #define PG8_WAIT_V(n) asm volatile("s_waitcnt vmcnt(" #n ")" ::: "memory")
; #define PG8_WAIT_L(n) asm volatile("s_waitcnt lgkmcnt(" #n ")" ::: "memory")
; #define PG8_BAR __builtin_amdgcn_s_barrier()
; #define PG8_SCHED __builtin_amdgcn_sched_barrier(0)
; template <class Epi>
; DEVI void gemm_phase(LAS unsigned char* lds, const Gemm g, const Epi& E) {
;     ...
;             PG8_STAGE(PG8_SB(0, 1), b2 + hstepB, voffB);
;             PG8_WAIT_V(6); PG8_BAR; PG8_MMA(1, 1, At, B1); PG8_BAR;
;             PG8_LDB(B0, 1, 0); PG8_SCHED; PG8_LDA(At, 1, 0); PG8_STAGE(PG8_SA(0, 1), a2 + hstepA, voffA);
;             PG8_WAIT_L(8); PG8_BAR; PG8_WAIT_L(0); PG8_MMA(0, 0, At, B0); PG8_BAR; PG8_SCHED;
;             PG8_LDB(B1, 1, 1); PG8_STAGE(PG8_SB(1, 0), b3, voffB);
;             PG8_BAR; PG8_WAIT_L(0); PG8_MMA(0, 1, At, B1); PG8_BAR;
;             PG8_LDA(At, 1, 1); PG8_STAGE(PG8_SA(1, 0), a3, voffA);
	s_add_u32 s10, s14, 0x28000
	s_addc_u32 s11, s15, 0
	s_add_i32 s38, s39, s37
	v_lshl_add_u64 v[142:143], s[10:11], 0, v[8:9]
	s_mov_b32 m0, s38
	s_nop 0
	global_load_lds_dwordx4 v[142:143], off
	v_lshl_add_u64 v[142:143], s[10:11], 0, v[130:131]
	s_add_i32 m0, s38, 0x2000
	s_nop 0
	global_load_lds_dwordx4 v[142:143], off
	s_waitcnt vmcnt(6)
	s_barrier
	s_setprio 1
	v_mfma_f32_16x16x32_bf16 v[54:57], v[226:229], v[188:191], v[54:57]
	v_mfma_f32_16x16x32_bf16 v[50:53], v[234:237], v[188:191], v[50:53]
	v_mfma_f32_16x16x32_bf16 v[38:41], v[226:229], v[196:199], v[38:41]
	v_mfma_f32_16x16x32_bf16 v[34:37], v[234:237], v[196:199], v[34:37]
	v_mfma_f32_16x16x32_bf16 v[22:25], v[226:229], v[204:207], v[22:25]
	v_mfma_f32_16x16x32_bf16 v[18:21], v[234:237], v[204:207], v[18:21]
	v_mfma_f32_16x16x32_bf16 v[4:7], v[226:229], v[218:221], v[4:7]
	v_mfma_f32_16x16x32_bf16 v[0:3], v[234:237], v[218:221], v[0:3]
	v_mfma_f32_16x16x32_bf16 v[54:57], v[230:233], v[192:195], v[54:57]
	v_mfma_f32_16x16x32_bf16 v[50:53], v[238:241], v[192:195], v[50:53]
	v_mfma_f32_16x16x32_bf16 v[38:41], v[230:233], v[200:203], v[38:41]
	v_mfma_f32_16x16x32_bf16 v[34:37], v[238:241], v[200:203], v[34:37]
	v_mfma_f32_16x16x32_bf16 v[22:25], v[230:233], v[214:217], v[22:25]
	v_mfma_f32_16x16x32_bf16 v[18:21], v[238:241], v[214:217], v[18:21]
	v_mfma_f32_16x16x32_bf16 v[4:7], v[230:233], v[222:225], v[4:7]
	v_mfma_f32_16x16x32_bf16 v[0:3], v[238:241], v[222:225], v[0:3]
	s_setprio 0
	s_add_i32 s38, 0, 0x18000
	v_add_u32_e32 v184, s38, v149
	s_barrier
	ds_read_b128 v[142:145], v184
	ds_read_b128 v[176:179], v184 offset:1024
	ds_read_b128 v[180:183], v184 offset:2048
	ds_read_b128 v[184:187], v184 offset:3072
	s_add_u32 s10, s16, 0x28000
	s_addc_u32 s11, s17, 0
	s_mov_b32 m0, s66
	v_lshl_add_u64 v[208:209], s[10:11], 0, v[134:135]
	ds_read_b128 v[188:191], v151 offset:32768
	ds_read_b128 v[192:195], v151 offset:33792
	ds_read_b128 v[196:199], v151 offset:34816
	ds_read_b128 v[200:203], v151 offset:35840
	ds_read_b128 v[204:207], v151 offset:36864
	ds_read_b128 v[214:217], v151 offset:37888
	ds_read_b128 v[218:221], v151 offset:38912
	ds_read_b128 v[222:225], v151 offset:39936
	global_load_lds_dwordx4 v[208:209], off
	v_lshl_add_u64 v[208:209], s[10:11], 0, v[132:133]
	s_mov_b32 m0, s68
	s_nop 0
	global_load_lds_dwordx4 v[208:209], off
	s_waitcnt lgkmcnt(8)
	s_barrier
	s_waitcnt lgkmcnt(0)
	s_setprio 1
	v_mfma_f32_16x16x32_bf16 v[126:129], v[142:145], v[188:191], v[126:129]
	v_mfma_f32_16x16x32_bf16 v[122:125], v[180:183], v[188:191], v[122:125]
	v_mfma_f32_16x16x32_bf16 v[110:113], v[142:145], v[196:199], v[110:113]
	v_mfma_f32_16x16x32_bf16 v[106:109], v[180:183], v[196:199], v[106:109]
	v_mfma_f32_16x16x32_bf16 v[94:97], v[142:145], v[204:207], v[94:97]
	v_mfma_f32_16x16x32_bf16 v[90:93], v[180:183], v[204:207], v[90:93]
	v_mfma_f32_16x16x32_bf16 v[78:81], v[142:145], v[218:221], v[78:81]
	v_mfma_f32_16x16x32_bf16 v[74:77], v[180:183], v[218:221], v[74:77]
	v_mfma_f32_16x16x32_bf16 v[126:129], v[176:179], v[192:195], v[126:129]
	v_mfma_f32_16x16x32_bf16 v[122:125], v[184:187], v[192:195], v[122:125]
	v_mfma_f32_16x16x32_bf16 v[110:113], v[176:179], v[200:203], v[110:113]
	v_mfma_f32_16x16x32_bf16 v[106:109], v[184:187], v[200:203], v[106:109]
	v_mfma_f32_16x16x32_bf16 v[94:97], v[176:179], v[214:217], v[94:97]
	v_mfma_f32_16x16x32_bf16 v[90:93], v[184:187], v[214:217], v[90:93]
	v_mfma_f32_16x16x32_bf16 v[78:81], v[176:179], v[222:225], v[78:81]
	v_mfma_f32_16x16x32_bf16 v[74:77], v[184:187], v[222:225], v[74:77]
	s_setprio 0
	s_barrier
	s_add_i32 s16, 0, 0x1c000
	s_add_i32 s10, s38, s37
	v_add_u32_e32 v208, s16, v149
	v_lshl_add_u64 v[146:147], v[146:147], 0, s[70:71]
	s_mov_b32 m0, s10
	ds_read_b128 v[226:229], v208
	ds_read_b128 v[230:233], v208 offset:1024
	ds_read_b128 v[234:237], v208 offset:2048
	ds_read_b128 v[238:241], v208 offset:3072
	global_load_lds_dwordx4 v[146:147], off
	v_lshl_add_u64 v[146:147], v[152:153], 0, s[70:71]
	s_add_i32 m0, s10, 0x2000
	s_nop 0
	global_load_lds_dwordx4 v[146:147], off
	s_barrier
	s_waitcnt lgkmcnt(0)
	s_setprio 1
	v_mfma_f32_16x16x32_bf16 v[118:121], v[226:229], v[188:191], v[118:121]
	v_mfma_f32_16x16x32_bf16 v[114:117], v[234:237], v[188:191], v[114:117]
	v_mfma_f32_16x16x32_bf16 v[102:105], v[226:229], v[196:199], v[102:105]
	v_mfma_f32_16x16x32_bf16 v[98:101], v[234:237], v[196:199], v[98:101]
	v_mfma_f32_16x16x32_bf16 v[86:89], v[226:229], v[204:207], v[86:89]
	v_mfma_f32_16x16x32_bf16 v[82:85], v[234:237], v[204:207], v[82:85]
	v_mfma_f32_16x16x32_bf16 v[70:73], v[226:229], v[218:221], v[70:73]
	v_mfma_f32_16x16x32_bf16 v[66:69], v[234:237], v[218:221], v[66:69]
	v_mfma_f32_16x16x32_bf16 v[118:121], v[230:233], v[192:195], v[118:121]
	v_mfma_f32_16x16x32_bf16 v[114:117], v[238:241], v[192:195], v[114:117]
	v_mfma_f32_16x16x32_bf16 v[102:105], v[230:233], v[200:203], v[102:105]
	v_mfma_f32_16x16x32_bf16 v[98:101], v[238:241], v[200:203], v[98:101]
	v_mfma_f32_16x16x32_bf16 v[86:89], v[230:233], v[214:217], v[86:89]
	v_mfma_f32_16x16x32_bf16 v[82:85], v[238:241], v[214:217], v[82:85]
	v_mfma_f32_16x16x32_bf16 v[70:73], v[230:233], v[222:225], v[70:73]
	v_mfma_f32_16x16x32_bf16 v[66:69], v[238:241], v[222:225], v[66:69]
	s_setprio 0
	s_mov_b32 m0, s69
	v_lshl_add_u64 v[146:147], v[162:163], 0, s[70:71]
	s_barrier
	ds_read_b128 v[188:191], v151 offset:49152
	ds_read_b128 v[192:195], v151 offset:50176
	ds_read_b128 v[196:199], v151 offset:51200
	ds_read_b128 v[200:203], v151 offset:52224
	ds_read_b128 v[204:207], v151 offset:53248
	ds_read_b128 v[214:217], v151 offset:54272
	ds_read_b128 v[218:221], v151 offset:55296
	ds_read_b128 v[222:225], v151 offset:56320
	global_load_lds_dwordx4 v[146:147], off
	v_lshl_add_u64 v[146:147], v[164:165], 0, s[70:71]
	s_mov_b32 m0, s80
	s_nop 0
	global_load_lds_dwordx4 v[146:147], off
	s_barrier
; #define PG8_STAGE(bufoff, gbase, voff) do { _Pragma("unroll") for (int _i = 0; _i < 2; ++_i) \
;         __builtin_amdgcn_global_load_lds((const unsigned*)((const char*)(gbase) + (voff)[_i]), (LAS unsigned*)(lds + (bufoff) + ldsw + _i * 8192), 16, 0, 0); } while (0)
; #define PG8_MMA(ai, bj, At, Bt) do { __builtin_amdgcn_s_setprio(1); _Pragma("unroll") for (int m = 0; m < 4; ++m) _Pragma("unroll") for (int n = 0; n < 2; ++n) _Pragma("unroll") for (int k = 0; k < 2; ++k) \
;         acc[ai][bj][m][n] = __builtin_amdgcn_mfma_f32_16x16x32_bf16(Bt[n][k], At[m][k], acc[ai][bj][m][n], 0, 0, 0); __builtin_amdgcn_s_setprio(0); } while (0)
; #define PG8_WAIT_V(n) asm volatile("s_waitcnt vmcnt(" #n ")" ::: "memory")
; #define PG8_WAIT_L(n) asm volatile("s_waitcnt lgkmcnt(" #n ")" ::: "memory")
; #define PG8_BAR __builtin_amdgcn_s_barrier()
; #define PG8_SCHED __builtin_amdgcn_sched_barrier(0)
; template <class Epi>
; DEVI void gemm_phase(LAS unsigned char* lds, const Gemm g, const Epi& E) {
;     ...
;             PG8_BAR; PG8_WAIT_L(0); PG8_MMA(1, 0, At, B0); PG8_BAR; PG8_SCHED;
;             PG8_STAGE(PG8_SB(1, 1), b3 + hstepB, voffB);
;             PG8_WAIT_V(6); PG8_BAR; PG8_MMA(1, 1, At, B1); PG8_BAR;
;         }
;         {
;             const int row0 = cur.pm * BM + wr * 64 + fr, col0 = cur.pn * BM + wc * 32 + (Epi::PERM ? 8 : 4) * fq; constexpr int NST = Epi::PERM ? 4 : 16;
	s_waitcnt lgkmcnt(0)
	s_setprio 1
	v_mfma_f32_16x16x32_bf16 v[62:65], v[142:145], v[188:191], v[62:65]
	v_mfma_f32_16x16x32_bf16 v[58:61], v[180:183], v[188:191], v[58:61]
	v_mfma_f32_16x16x32_bf16 v[46:49], v[142:145], v[196:199], v[46:49]
	v_mfma_f32_16x16x32_bf16 v[42:45], v[180:183], v[196:199], v[42:45]
	v_mfma_f32_16x16x32_bf16 v[30:33], v[142:145], v[204:207], v[30:33]
	v_mfma_f32_16x16x32_bf16 v[26:29], v[180:183], v[204:207], v[26:29]
	v_mfma_f32_16x16x32_bf16 v[14:17], v[142:145], v[218:221], v[14:17]
	v_mfma_f32_16x16x32_bf16 v[10:13], v[180:183], v[218:221], v[10:13]
	v_mfma_f32_16x16x32_bf16 v[62:65], v[176:179], v[192:195], v[62:65]
	v_mfma_f32_16x16x32_bf16 v[58:61], v[184:187], v[192:195], v[58:61]
	v_mfma_f32_16x16x32_bf16 v[46:49], v[176:179], v[200:203], v[46:49]
	v_mfma_f32_16x16x32_bf16 v[42:45], v[184:187], v[200:203], v[42:45]
	v_mfma_f32_16x16x32_bf16 v[30:33], v[176:179], v[214:217], v[30:33]
	v_mfma_f32_16x16x32_bf16 v[26:29], v[184:187], v[214:217], v[26:29]
	v_mfma_f32_16x16x32_bf16 v[14:17], v[176:179], v[222:225], v[14:17]
	v_mfma_f32_16x16x32_bf16 v[10:13], v[184:187], v[222:225], v[10:13]
	s_setprio 0
	s_barrier
	s_add_u32 s10, s14, 0x28080
	s_addc_u32 s11, s15, 0
	s_add_i32 s14, s16, s37
	v_lshl_add_u64 v[142:143], s[10:11], 0, v[8:9]
	s_mov_b32 m0, s14
	s_nop 0
	global_load_lds_dwordx4 v[142:143], off
	v_lshl_add_u64 v[142:143], s[10:11], 0, v[130:131]
	s_add_i32 m0, s14, 0x2000
	s_nop 0
	global_load_lds_dwordx4 v[142:143], off
	s_waitcnt vmcnt(6)
	s_barrier
	s_setprio 1
	v_mfma_f32_16x16x32_bf16 v[54:57], v[226:229], v[188:191], v[54:57]
	v_mfma_f32_16x16x32_bf16 v[50:53], v[234:237], v[188:191], v[50:53]
	v_mfma_f32_16x16x32_bf16 v[38:41], v[226:229], v[196:199], v[38:41]
	v_mfma_f32_16x16x32_bf16 v[34:37], v[234:237], v[196:199], v[34:37]
	v_mfma_f32_16x16x32_bf16 v[22:25], v[226:229], v[204:207], v[22:25]
	v_mfma_f32_16x16x32_bf16 v[18:21], v[234:237], v[204:207], v[18:21]
	v_mfma_f32_16x16x32_bf16 v[4:7], v[226:229], v[218:221], v[4:7]
	v_mfma_f32_16x16x32_bf16 v[0:3], v[234:237], v[218:221], v[0:3]
	v_mfma_f32_16x16x32_bf16 v[54:57], v[230:233], v[192:195], v[54:57]
	v_mfma_f32_16x16x32_bf16 v[50:53], v[238:241], v[192:195], v[50:53]
	v_mfma_f32_16x16x32_bf16 v[38:41], v[230:233], v[200:203], v[38:41]
	v_mfma_f32_16x16x32_bf16 v[34:37], v[238:241], v[200:203], v[34:37]
	v_mfma_f32_16x16x32_bf16 v[22:25], v[230:233], v[214:217], v[22:25]
	v_mfma_f32_16x16x32_bf16 v[18:21], v[238:241], v[214:217], v[18:21]
	v_mfma_f32_16x16x32_bf16 v[4:7], v[230:233], v[222:225], v[4:7]
	v_mfma_f32_16x16x32_bf16 v[0:3], v[238:241], v[222:225], v[0:3]
	s_setprio 0
	s_add_i32 s27, s27, 2
	s_add_u32 s19, s19, 0x100
	s_addc_u32 s26, s26, 0
	s_cmp_gt_u32 s27, 7
	s_mov_b64 s[10:11], s[12:13]
	s_barrier
	s_cbranch_scc0 .LBB0_1278
	v_lshl_add_u32 v144, s18, 8, v148
	v_ashrrev_i32_e32 v145, 31, v144
	v_lshlrev_b64 v[142:143], 16, v[144:145]
	v_mul_f32_e32 v145, 0x3d372713, v126
	v_mul_f32_e32 v145, v126, v145
	v_fma_f32 v145, v126, v145, v126
	v_mul_f32_e32 v145, 0x3f4c422a, v145
	v_add_f32_e32 v145, v145, v145
	v_mul_f32_e32 v145, 0xbfb8aa3b, v145
	v_exp_f32_e32 v145, v145
	v_lshl_or_b32 v164, s1, 8, v150
	s_lshl_b32 s0, s0, 4
	s_ashr_i32 s1, s0, 31
	v_add_f32_e32 v145, 1.0, v145
	v_rcp_f32_e32 v152, v145
	v_mul_f32_e32 v145, 0x3d372713, v122
	v_mul_f32_e32 v145, v122, v145
	v_fma_f32 v145, v122, v145, v122
	v_mul_f32_e32 v145, 0x3f4c422a, v145
	v_add_f32_e32 v145, v145, v145
	v_mul_f32_e32 v145, 0xbfb8aa3b, v145
	v_exp_f32_e32 v145, v145
	v_lshl_add_u64 v[146:147], s[0:1], 1, v[136:137]
	v_lshl_add_u64 v[142:143], v[146:147], 0, v[142:143]
	s_mov_b64 s[0:1], 0x800000
	v_add_f32_e32 v145, 1.0, v145
	v_rcp_f32_e32 v162, v145
	v_mul_f32_e32 v145, 0x3d372713, v127
	v_mul_f32_e32 v145, v127, v145
	v_fma_f32 v145, v127, v145, v127
	v_mul_f32_e32 v145, 0x3f4c422a, v145
	v_add_f32_e32 v145, v145, v145
	v_mul_f32_e32 v145, 0xbfb8aa3b, v145
	v_exp_f32_e32 v145, v145
	s_and_b64 vcc, exec, s[2:3]
	s_mov_b32 s18, s82
	s_mov_b64 s[12:13], s[6:7]
	v_add_f32_e32 v145, 1.0, v145
	v_rcp_f32_e32 v153, v145
	v_mul_f32_e32 v145, 0x3d372713, v123
	v_mul_f32_e32 v145, v123, v145
	v_fma_f32 v145, v123, v145, v123
	v_mul_f32_e32 v145, 0x3f4c422a, v145
	v_add_f32_e32 v145, v145, v145
	v_mul_f32_e32 v145, 0xbfb8aa3b, v145
	v_exp_f32_e32 v145, v145
	v_pk_mul_f32 v[126:127], v[126:127], v[152:153]
	s_mov_b64 s[10:11], s[4:5]
	v_add_f32_e32 v145, 1.0, v145
	v_rcp_f32_e32 v163, v145
	v_mul_f32_e32 v145, 0x3d372713, v128
	v_mul_f32_e32 v145, v128, v145
	v_fma_f32 v145, v128, v145, v128
	v_mul_f32_e32 v145, 0x3f4c422a, v145
	v_add_f32_e32 v145, v145, v145
	v_mul_f32_e32 v145, 0xbfb8aa3b, v145
	v_exp_f32_e32 v145, v145
	v_pk_mul_f32 v[122:123], v[122:123], v[162:163]
	v_add_f32_e32 v145, 1.0, v145
	v_rcp_f32_e32 v152, v145
	v_mul_f32_e32 v145, 0x3d372713, v124
	v_mul_f32_e32 v145, v124, v145
	v_fma_f32 v145, v124, v145, v124
	v_mul_f32_e32 v145, 0x3f4c422a, v145
	v_add_f32_e32 v145, v145, v145
	v_mul_f32_e32 v145, 0xbfb8aa3b, v145
	v_exp_f32_e32 v145, v145
	s_nop 0
	v_add_f32_e32 v145, 1.0, v145
	v_rcp_f32_e32 v162, v145
	v_mul_f32_e32 v145, 0x3d372713, v129
	v_mul_f32_e32 v145, v129, v145
	v_fma_f32 v145, v129, v145, v129
	v_mul_f32_e32 v145, 0x3f4c422a, v145
	v_add_f32_e32 v145, v145, v145
	v_mul_f32_e32 v145, 0xbfb8aa3b, v145
	v_exp_f32_e32 v145, v145
	s_nop 0
	v_add_f32_e32 v145, 1.0, v145
	v_rcp_f32_e32 v153, v145
	v_mul_f32_e32 v145, 0x3d372713, v125
	v_mul_f32_e32 v145, v125, v145
	v_fma_f32 v145, v125, v145, v125
	v_mul_f32_e32 v145, 0x3f4c422a, v145
	v_add_f32_e32 v145, v145, v145
	v_mul_f32_e32 v145, 0xbfb8aa3b, v145
	v_exp_f32_e32 v145, v145
; DEVI float sigmoidf_(float x) { return __builtin_amdgcn_rcpf(1.f + __expf(-x)); }
; DEVI float siluf_(float x) { return x * __builtin_amdgcn_rcpf(1.f + __expf(-x)); }
; DEVI float logsigf_(float x) { return fminf(x, 0.f) - __logf(1.f + __expf(-fabsf(x))); }
	v_pk_mul_f32 v[128:129], v[128:129], v[152:153]
	v_add_f32_e32 v145, 1.0, v145
	v_rcp_f32_e32 v163, v145
	s_nop 0
	v_pk_mul_f32 v[152:153], v[124:125], v[162:163]
	v_cvt_pk_bf16_f32 v125, v128, v129
	v_ashrrev_i32_e32 v128, 4, v164
	v_ashrrev_i32_e32 v129, 31, v128
	v_cvt_pk_bf16_f32 v124, v126, v127
	v_cvt_pk_bf16_f32 v126, v122, v123
	v_lshlrev_b64 v[122:123], 11, v[128:129]
	v_cvt_pk_bf16_f32 v127, v152, v153
	v_lshl_add_u64 v[152:153], v[142:143], 0, v[122:123]
	global_store_dwordx4 v[152:153], v[124:127], off
	s_nop 1
	v_mul_f32_e32 v125, 0x3d372713, v114
	v_mul_f32_e32 v125, v114, v125
	v_fma_f32 v125, v114, v125, v114
	v_mul_f32_e32 v125, 0x3f4c422a, v125
	v_add_f32_e32 v125, v125, v125
	v_mul_f32_e32 v125, 0xbfb8aa3b, v125
	v_exp_f32_e32 v125, v125
	v_mul_f32_e32 v124, 0x3d372713, v118
	v_mul_f32_e32 v124, v118, v124
	v_fma_f32 v124, v118, v124, v118
	v_add_f32_e32 v125, 1.0, v125
	v_rcp_f32_e32 v126, v125
	v_mul_f32_e32 v125, 0x3d372713, v119
	v_mul_f32_e32 v125, v119, v125
	v_fma_f32 v125, v119, v125, v119
	v_mul_f32_e32 v124, 0x3f4c422a, v124
	v_mul_f32_e32 v125, 0x3f4c422a, v125
	v_add_f32_e32 v124, v124, v124
	v_add_f32_e32 v125, v125, v125
	v_mul_f32_e32 v124, 0xbfb8aa3b, v124
	v_mul_f32_e32 v125, 0xbfb8aa3b, v125
	v_exp_f32_e32 v124, v124
	v_exp_f32_e32 v125, v125
	v_add_f32_e32 v124, 1.0, v124
	v_add_f32_e32 v125, 1.0, v125
	v_rcp_f32_e32 v124, v124
	v_rcp_f32_e32 v125, v125
	s_nop 0
	v_pk_mul_f32 v[118:119], v[118:119], v[124:125]
	v_mul_f32_e32 v124, 0x3d372713, v115
	v_mul_f32_e32 v124, v115, v124
	v_fma_f32 v124, v115, v124, v115
	v_mul_f32_e32 v124, 0x3f4c422a, v124
	v_add_f32_e32 v124, v124, v124
	v_mul_f32_e32 v125, 0x3d372713, v116
	v_mul_f32_e32 v124, 0xbfb8aa3b, v124
	v_mul_f32_e32 v125, v116, v125
	v_exp_f32_e32 v124, v124
	v_fma_f32 v125, v116, v125, v116
	v_mul_f32_e32 v125, 0x3f4c422a, v125
	v_add_f32_e32 v125, v125, v125
	v_mul_f32_e32 v125, 0xbfb8aa3b, v125
	v_add_f32_e32 v124, 1.0, v124
	v_exp_f32_e32 v125, v125
	v_rcp_f32_e32 v127, v124
	v_mul_f32_e32 v124, 0x3d372713, v120
	v_mul_f32_e32 v124, v120, v124
	v_add_f32_e32 v125, 1.0, v125
	v_pk_mul_f32 v[114:115], v[114:115], v[126:127]
	v_rcp_f32_e32 v126, v125
	v_mul_f32_e32 v125, 0x3d372713, v121
	v_mul_f32_e32 v125, v121, v125
	v_fma_f32 v124, v120, v124, v120
	v_fma_f32 v125, v121, v125, v121
	v_mul_f32_e32 v124, 0x3f4c422a, v124
	v_mul_f32_e32 v125, 0x3f4c422a, v125
	v_add_f32_e32 v124, v124, v124
	v_add_f32_e32 v125, v125, v125
	v_mul_f32_e32 v124, 0xbfb8aa3b, v124
	v_mul_f32_e32 v125, 0xbfb8aa3b, v125
	v_exp_f32_e32 v124, v124
	v_exp_f32_e32 v125, v125
	v_add_f32_e32 v124, 1.0, v124
	v_add_f32_e32 v125, 1.0, v125
	v_rcp_f32_e32 v124, v124
	v_rcp_f32_e32 v125, v125
	s_nop 0
	v_pk_mul_f32 v[120:121], v[120:121], v[124:125]
	v_mul_f32_e32 v124, 0x3d372713, v117
	v_mul_f32_e32 v124, v117, v124
	v_fma_f32 v124, v117, v124, v117
	v_mul_f32_e32 v124, 0x3f4c422a, v124
	v_add_f32_e32 v124, v124, v124
	v_mul_f32_e32 v124, 0xbfb8aa3b, v124
	v_exp_f32_e32 v124, v124
	s_nop 0
	v_add_f32_e32 v124, 1.0, v124
	v_rcp_f32_e32 v127, v124
	s_nop 0
	v_pk_mul_f32 v[124:125], v[116:117], v[126:127]
	v_cvt_pk_bf16_f32 v116, v118, v119
	v_cvt_pk_bf16_f32 v118, v114, v115
	v_or_b32_e32 v114, 8, v128
	v_ashrrev_i32_e32 v115, 31, v114
	v_lshlrev_b64 v[114:115], 11, v[114:115]
	v_cvt_pk_bf16_f32 v117, v120, v121
	v_cvt_pk_bf16_f32 v119, v124, v125
	v_lshl_add_u64 v[120:121], v[142:143], 0, v[114:115]
	global_store_dwordx4 v[120:121], v[116:119], off
	s_nop 1
	v_mul_f32_e32 v119, 0x3d372713, v106
	v_mul_f32_e32 v119, v106, v119
	v_fma_f32 v119, v106, v119, v106
	v_mul_f32_e32 v119, 0x3f4c422a, v119
	v_add_f32_e32 v119, v119, v119
	v_mul_f32_e32 v119, 0xbfb8aa3b, v119
	v_exp_f32_e32 v119, v119
	v_mul_f32_e32 v118, 0x3d372713, v110
	v_mul_f32_e32 v118, v110, v118
	v_fma_f32 v118, v110, v118, v110
	v_add_f32_e32 v119, 1.0, v119
	v_rcp_f32_e32 v120, v119
	v_mul_f32_e32 v119, 0x3d372713, v111
	v_mul_f32_e32 v119, v111, v119
	v_fma_f32 v119, v111, v119, v111
	v_mul_f32_e32 v118, 0x3f4c422a, v118
	v_mul_f32_e32 v119, 0x3f4c422a, v119
	v_add_f32_e32 v118, v118, v118
	v_add_f32_e32 v119, v119, v119
	v_mul_f32_e32 v118, 0xbfb8aa3b, v118
	v_mul_f32_e32 v119, 0xbfb8aa3b, v119
	v_exp_f32_e32 v118, v118
	v_exp_f32_e32 v119, v119
	v_or_b32_e32 v116, 16, v144
	v_ashrrev_i32_e32 v117, 31, v116
	v_add_f32_e32 v118, 1.0, v118
	v_add_f32_e32 v119, 1.0, v119
	v_rcp_f32_e32 v118, v118
	v_rcp_f32_e32 v119, v119
	v_lshlrev_b64 v[116:117], 16, v[116:117]
	v_lshl_add_u64 v[116:117], v[146:147], 0, v[116:117]
	v_pk_mul_f32 v[110:111], v[110:111], v[118:119]
	v_mul_f32_e32 v118, 0x3d372713, v107
	v_mul_f32_e32 v118, v107, v118
	v_fma_f32 v118, v107, v118, v107
	v_mul_f32_e32 v118, 0x3f4c422a, v118
	v_add_f32_e32 v118, v118, v118
	v_mul_f32_e32 v118, 0xbfb8aa3b, v118
	v_exp_f32_e32 v118, v118
	s_nop 0
	v_add_f32_e32 v118, 1.0, v118
	v_rcp_f32_e32 v121, v118
	s_nop 0
	v_pk_mul_f32 v[118:119], v[106:107], v[120:121]
	v_mul_f32_e32 v107, 0x3d372713, v108
	v_mul_f32_e32 v107, v108, v107
	v_fma_f32 v107, v108, v107, v108
	v_mul_f32_e32 v107, 0x3f4c422a, v107
	v_add_f32_e32 v107, v107, v107
	v_mul_f32_e32 v107, 0xbfb8aa3b, v107
	v_exp_f32_e32 v107, v107
	v_mul_f32_e32 v106, 0x3d372713, v112
	v_mul_f32_e32 v106, v112, v106
	v_fma_f32 v106, v112, v106, v112
	v_add_f32_e32 v107, 1.0, v107
	v_rcp_f32_e32 v120, v107
	v_mul_f32_e32 v107, 0x3d372713, v113
	v_mul_f32_e32 v107, v113, v107
	v_fma_f32 v107, v113, v107, v113
	v_mul_f32_e32 v106, 0x3f4c422a, v106
	v_mul_f32_e32 v107, 0x3f4c422a, v107
	v_add_f32_e32 v106, v106, v106
	v_add_f32_e32 v107, v107, v107
	v_mul_f32_e32 v106, 0xbfb8aa3b, v106
	v_mul_f32_e32 v107, 0xbfb8aa3b, v107
; DEVI float sigmoidf_(float x) { return __builtin_amdgcn_rcpf(1.f + __expf(-x)); }
; DEVI float siluf_(float x) { return x * __builtin_amdgcn_rcpf(1.f + __expf(-x)); }
; DEVI float logsigf_(float x) { return fminf(x, 0.f) - __logf(1.f + __expf(-fabsf(x))); }
	v_exp_f32_e32 v106, v106
	v_exp_f32_e32 v107, v107
	v_add_f32_e32 v106, 1.0, v106
	v_add_f32_e32 v107, 1.0, v107
	v_rcp_f32_e32 v106, v106
	v_rcp_f32_e32 v107, v107
	s_nop 0
	v_pk_mul_f32 v[112:113], v[112:113], v[106:107]
	v_mul_f32_e32 v106, 0x3d372713, v109
	v_mul_f32_e32 v106, v109, v106
	v_fma_f32 v106, v109, v106, v109
	v_mul_f32_e32 v106, 0x3f4c422a, v106
	v_add_f32_e32 v106, v106, v106
	v_mul_f32_e32 v106, 0xbfb8aa3b, v106
	v_exp_f32_e32 v106, v106
	v_cvt_pk_bf16_f32 v107, v112, v113
	v_add_f32_e32 v106, 1.0, v106
	v_rcp_f32_e32 v121, v106
	v_cvt_pk_bf16_f32 v106, v110, v111
	v_lshl_add_u64 v[110:111], v[116:117], 0, v[122:123]
	v_pk_mul_f32 v[120:121], v[108:109], v[120:121]
	v_cvt_pk_bf16_f32 v108, v118, v119
	v_cvt_pk_bf16_f32 v109, v120, v121
	global_store_dwordx4 v[110:111], v[106:109], off
	s_nop 1
	v_mul_f32_e32 v107, 0x3d372713, v98
	v_mul_f32_e32 v107, v98, v107
	v_fma_f32 v107, v98, v107, v98
	v_mul_f32_e32 v107, 0x3f4c422a, v107
	v_add_f32_e32 v107, v107, v107
	v_mul_f32_e32 v107, 0xbfb8aa3b, v107
	v_exp_f32_e32 v107, v107
	v_mul_f32_e32 v106, 0x3d372713, v102
	v_mul_f32_e32 v106, v102, v106
	v_fma_f32 v106, v102, v106, v102
	v_add_f32_e32 v107, 1.0, v107
	v_rcp_f32_e32 v108, v107
	v_mul_f32_e32 v107, 0x3d372713, v103
	v_mul_f32_e32 v107, v103, v107
	v_fma_f32 v107, v103, v107, v103
	v_mul_f32_e32 v106, 0x3f4c422a, v106
	v_mul_f32_e32 v107, 0x3f4c422a, v107
	v_add_f32_e32 v106, v106, v106
	v_add_f32_e32 v107, v107, v107
	v_mul_f32_e32 v106, 0xbfb8aa3b, v106
	v_mul_f32_e32 v107, 0xbfb8aa3b, v107
	v_exp_f32_e32 v106, v106
	v_exp_f32_e32 v107, v107
	v_add_f32_e32 v106, 1.0, v106
	v_add_f32_e32 v107, 1.0, v107
	v_rcp_f32_e32 v106, v106
	v_rcp_f32_e32 v107, v107
	s_nop 0
	v_pk_mul_f32 v[102:103], v[102:103], v[106:107]
	v_mul_f32_e32 v106, 0x3d372713, v99
	v_mul_f32_e32 v106, v99, v106
	v_fma_f32 v106, v99, v106, v99
	v_mul_f32_e32 v106, 0x3f4c422a, v106
	v_add_f32_e32 v106, v106, v106
	v_mul_f32_e32 v106, 0xbfb8aa3b, v106
	v_exp_f32_e32 v106, v106
	s_nop 0
	v_add_f32_e32 v106, 1.0, v106
	v_rcp_f32_e32 v109, v106
	s_nop 0
	v_pk_mul_f32 v[106:107], v[98:99], v[108:109]
	v_mul_f32_e32 v99, 0x3d372713, v100
	v_mul_f32_e32 v99, v100, v99
	v_fma_f32 v99, v100, v99, v100
	v_mul_f32_e32 v99, 0x3f4c422a, v99
	v_add_f32_e32 v99, v99, v99
	v_mul_f32_e32 v99, 0xbfb8aa3b, v99
	v_exp_f32_e32 v99, v99
	v_mul_f32_e32 v98, 0x3d372713, v104
	v_mul_f32_e32 v98, v104, v98
	v_fma_f32 v98, v104, v98, v104
	v_add_f32_e32 v99, 1.0, v99
	v_rcp_f32_e32 v108, v99
	v_mul_f32_e32 v99, 0x3d372713, v105
	v_mul_f32_e32 v99, v105, v99
	v_fma_f32 v99, v105, v99, v105
	v_mul_f32_e32 v98, 0x3f4c422a, v98
	v_mul_f32_e32 v99, 0x3f4c422a, v99
	v_add_f32_e32 v98, v98, v98
	v_add_f32_e32 v99, v99, v99
	v_mul_f32_e32 v98, 0xbfb8aa3b, v98
	v_mul_f32_e32 v99, 0xbfb8aa3b, v99
	v_exp_f32_e32 v98, v98
	v_exp_f32_e32 v99, v99
	v_add_f32_e32 v98, 1.0, v98
	v_add_f32_e32 v99, 1.0, v99
	v_rcp_f32_e32 v98, v98
	v_rcp_f32_e32 v99, v99
	s_nop 0
	v_pk_mul_f32 v[104:105], v[104:105], v[98:99]
	v_mul_f32_e32 v98, 0x3d372713, v101
	v_mul_f32_e32 v98, v101, v98
	v_fma_f32 v98, v101, v98, v101
	v_mul_f32_e32 v98, 0x3f4c422a, v98
	v_add_f32_e32 v98, v98, v98
	v_mul_f32_e32 v98, 0xbfb8aa3b, v98
	v_exp_f32_e32 v98, v98
	v_cvt_pk_bf16_f32 v99, v104, v105
	v_add_f32_e32 v98, 1.0, v98
	v_rcp_f32_e32 v109, v98
	v_cvt_pk_bf16_f32 v98, v102, v103
	v_lshl_add_u64 v[102:103], v[116:117], 0, v[114:115]
	v_pk_mul_f32 v[108:109], v[100:101], v[108:109]
	v_cvt_pk_bf16_f32 v100, v106, v107
	v_cvt_pk_bf16_f32 v101, v108, v109
	global_store_dwordx4 v[102:103], v[98:101], off
	s_nop 1
	v_mul_f32_e32 v101, 0x3d372713, v90
	v_mul_f32_e32 v101, v90, v101
	v_fma_f32 v101, v90, v101, v90
	v_mul_f32_e32 v101, 0x3f4c422a, v101
	v_add_f32_e32 v101, v101, v101
	v_mul_f32_e32 v101, 0xbfb8aa3b, v101
	v_exp_f32_e32 v101, v101
	v_mul_f32_e32 v100, 0x3d372713, v94
	v_mul_f32_e32 v100, v94, v100
	v_fma_f32 v100, v94, v100, v94
	v_add_f32_e32 v101, 1.0, v101
	v_rcp_f32_e32 v102, v101
	v_mul_f32_e32 v101, 0x3d372713, v95
	v_mul_f32_e32 v101, v95, v101
	v_fma_f32 v101, v95, v101, v95
	v_mul_f32_e32 v100, 0x3f4c422a, v100
	v_mul_f32_e32 v101, 0x3f4c422a, v101
	v_add_f32_e32 v100, v100, v100
	v_add_f32_e32 v101, v101, v101
	v_mul_f32_e32 v100, 0xbfb8aa3b, v100
	v_mul_f32_e32 v101, 0xbfb8aa3b, v101
	v_exp_f32_e32 v100, v100
	v_exp_f32_e32 v101, v101
	v_or_b32_e32 v98, 32, v144
	v_ashrrev_i32_e32 v99, 31, v98
	v_add_f32_e32 v100, 1.0, v100
	v_add_f32_e32 v101, 1.0, v101
	v_rcp_f32_e32 v100, v100
	v_rcp_f32_e32 v101, v101
	v_lshlrev_b64 v[98:99], 16, v[98:99]
	v_lshl_add_u64 v[98:99], v[146:147], 0, v[98:99]
	v_pk_mul_f32 v[94:95], v[94:95], v[100:101]
	v_mul_f32_e32 v100, 0x3d372713, v91
	v_mul_f32_e32 v100, v91, v100
	v_fma_f32 v100, v91, v100, v91
	v_mul_f32_e32 v100, 0x3f4c422a, v100
	v_add_f32_e32 v100, v100, v100
	v_mul_f32_e32 v100, 0xbfb8aa3b, v100
	v_exp_f32_e32 v100, v100
	s_nop 0
	v_add_f32_e32 v100, 1.0, v100
	v_rcp_f32_e32 v103, v100
	s_nop 0
	v_pk_mul_f32 v[100:101], v[90:91], v[102:103]
	v_mul_f32_e32 v91, 0x3d372713, v92
	v_mul_f32_e32 v91, v92, v91
	v_fma_f32 v91, v92, v91, v92
	v_mul_f32_e32 v91, 0x3f4c422a, v91
	v_add_f32_e32 v91, v91, v91
	v_mul_f32_e32 v91, 0xbfb8aa3b, v91
	v_exp_f32_e32 v91, v91
	v_mul_f32_e32 v90, 0x3d372713, v96
	v_mul_f32_e32 v90, v96, v90
	v_fma_f32 v90, v96, v90, v96
	v_add_f32_e32 v91, 1.0, v91
	v_rcp_f32_e32 v102, v91
	v_mul_f32_e32 v91, 0x3d372713, v97
	v_mul_f32_e32 v91, v97, v91
	v_fma_f32 v91, v97, v91, v97
	v_mul_f32_e32 v90, 0x3f4c422a, v90
	v_mul_f32_e32 v91, 0x3f4c422a, v91
	v_add_f32_e32 v90, v90, v90
	v_add_f32_e32 v91, v91, v91
	v_mul_f32_e32 v90, 0xbfb8aa3b, v90
; DEVI float sigmoidf_(float x) { return __builtin_amdgcn_rcpf(1.f + __expf(-x)); }
; DEVI float siluf_(float x) { return x * __builtin_amdgcn_rcpf(1.f + __expf(-x)); }
; DEVI float logsigf_(float x) { return fminf(x, 0.f) - __logf(1.f + __expf(-fabsf(x))); }
	v_mul_f32_e32 v91, 0xbfb8aa3b, v91
	v_exp_f32_e32 v90, v90
	v_exp_f32_e32 v91, v91
	v_add_f32_e32 v90, 1.0, v90
	v_add_f32_e32 v91, 1.0, v91
	v_rcp_f32_e32 v90, v90
	v_rcp_f32_e32 v91, v91
	s_nop 0
	v_pk_mul_f32 v[96:97], v[96:97], v[90:91]
	v_mul_f32_e32 v90, 0x3d372713, v93
	v_mul_f32_e32 v90, v93, v90
	v_fma_f32 v90, v93, v90, v93
	v_mul_f32_e32 v90, 0x3f4c422a, v90
	v_add_f32_e32 v90, v90, v90
	v_mul_f32_e32 v90, 0xbfb8aa3b, v90
	v_exp_f32_e32 v90, v90
	v_cvt_pk_bf16_f32 v91, v96, v97
	v_add_f32_e32 v90, 1.0, v90
	v_rcp_f32_e32 v103, v90
	v_cvt_pk_bf16_f32 v90, v94, v95
	v_lshl_add_u64 v[94:95], v[98:99], 0, v[122:123]
	v_pk_mul_f32 v[102:103], v[92:93], v[102:103]
	v_cvt_pk_bf16_f32 v92, v100, v101
	v_cvt_pk_bf16_f32 v93, v102, v103
	global_store_dwordx4 v[94:95], v[90:93], off
	s_nop 1
	v_mul_f32_e32 v91, 0x3d372713, v82
	v_mul_f32_e32 v91, v82, v91
	v_fma_f32 v91, v82, v91, v82
	v_mul_f32_e32 v91, 0x3f4c422a, v91
	v_add_f32_e32 v91, v91, v91
	v_mul_f32_e32 v91, 0xbfb8aa3b, v91
	v_exp_f32_e32 v91, v91
	v_mul_f32_e32 v90, 0x3d372713, v86
	v_mul_f32_e32 v90, v86, v90
	v_fma_f32 v90, v86, v90, v86
	v_add_f32_e32 v91, 1.0, v91
	v_rcp_f32_e32 v92, v91
	v_mul_f32_e32 v91, 0x3d372713, v87
	v_mul_f32_e32 v91, v87, v91
	v_fma_f32 v91, v87, v91, v87
	v_mul_f32_e32 v90, 0x3f4c422a, v90
	v_mul_f32_e32 v91, 0x3f4c422a, v91
	v_add_f32_e32 v90, v90, v90
	v_add_f32_e32 v91, v91, v91
	v_mul_f32_e32 v90, 0xbfb8aa3b, v90
	v_mul_f32_e32 v91, 0xbfb8aa3b, v91
	v_exp_f32_e32 v90, v90
	v_exp_f32_e32 v91, v91
	v_add_f32_e32 v90, 1.0, v90
	v_add_f32_e32 v91, 1.0, v91
	v_rcp_f32_e32 v90, v90
	v_rcp_f32_e32 v91, v91
	s_nop 0
	v_pk_mul_f32 v[86:87], v[86:87], v[90:91]
	v_mul_f32_e32 v90, 0x3d372713, v83
	v_mul_f32_e32 v90, v83, v90
	v_fma_f32 v90, v83, v90, v83
	v_mul_f32_e32 v90, 0x3f4c422a, v90
	v_add_f32_e32 v90, v90, v90
	v_mul_f32_e32 v90, 0xbfb8aa3b, v90
	v_exp_f32_e32 v90, v90
	s_nop 0
	v_add_f32_e32 v90, 1.0, v90
	v_rcp_f32_e32 v93, v90
	s_nop 0
	v_pk_mul_f32 v[90:91], v[82:83], v[92:93]
	v_mul_f32_e32 v83, 0x3d372713, v84
	v_mul_f32_e32 v83, v84, v83
	v_fma_f32 v83, v84, v83, v84
	v_mul_f32_e32 v83, 0x3f4c422a, v83
	v_add_f32_e32 v83, v83, v83
	v_mul_f32_e32 v83, 0xbfb8aa3b, v83
	v_exp_f32_e32 v83, v83
	v_mul_f32_e32 v82, 0x3d372713, v88
	v_mul_f32_e32 v82, v88, v82
	v_fma_f32 v82, v88, v82, v88
	v_add_f32_e32 v83, 1.0, v83
	v_rcp_f32_e32 v92, v83
	v_mul_f32_e32 v83, 0x3d372713, v89
	v_mul_f32_e32 v83, v89, v83
	v_fma_f32 v83, v89, v83, v89
	v_mul_f32_e32 v82, 0x3f4c422a, v82
	v_mul_f32_e32 v83, 0x3f4c422a, v83
	v_add_f32_e32 v82, v82, v82
	v_add_f32_e32 v83, v83, v83
	v_mul_f32_e32 v82, 0xbfb8aa3b, v82
	v_mul_f32_e32 v83, 0xbfb8aa3b, v83
	v_exp_f32_e32 v82, v82
	v_exp_f32_e32 v83, v83
	v_add_f32_e32 v82, 1.0, v82
	v_add_f32_e32 v83, 1.0, v83
	v_rcp_f32_e32 v82, v82
	v_rcp_f32_e32 v83, v83
	s_nop 0
	v_pk_mul_f32 v[88:89], v[88:89], v[82:83]
	v_mul_f32_e32 v82, 0x3d372713, v85
	v_mul_f32_e32 v82, v85, v82
	v_fma_f32 v82, v85, v82, v85
	v_mul_f32_e32 v82, 0x3f4c422a, v82
	v_add_f32_e32 v82, v82, v82
	v_mul_f32_e32 v82, 0xbfb8aa3b, v82
	v_exp_f32_e32 v82, v82
	v_cvt_pk_bf16_f32 v83, v88, v89
	v_add_f32_e32 v82, 1.0, v82
	v_rcp_f32_e32 v93, v82
	v_cvt_pk_bf16_f32 v82, v86, v87
	v_lshl_add_u64 v[86:87], v[98:99], 0, v[114:115]
	v_pk_mul_f32 v[92:93], v[84:85], v[92:93]
	v_cvt_pk_bf16_f32 v84, v90, v91
	v_cvt_pk_bf16_f32 v85, v92, v93
	global_store_dwordx4 v[86:87], v[82:85], off
	s_nop 1
	v_mul_f32_e32 v85, 0x3d372713, v74
	v_mul_f32_e32 v85, v74, v85
	v_fma_f32 v85, v74, v85, v74
	v_mul_f32_e32 v85, 0x3f4c422a, v85
	v_add_f32_e32 v85, v85, v85
	v_mul_f32_e32 v85, 0xbfb8aa3b, v85
	v_exp_f32_e32 v85, v85
	v_mul_f32_e32 v84, 0x3d372713, v78
	v_mul_f32_e32 v84, v78, v84
	v_fma_f32 v84, v78, v84, v78
	v_add_f32_e32 v85, 1.0, v85
	v_rcp_f32_e32 v86, v85
	v_mul_f32_e32 v85, 0x3d372713, v79
	v_mul_f32_e32 v85, v79, v85
	v_fma_f32 v85, v79, v85, v79
	v_mul_f32_e32 v84, 0x3f4c422a, v84
	v_mul_f32_e32 v85, 0x3f4c422a, v85
	v_add_f32_e32 v84, v84, v84
	v_add_f32_e32 v85, v85, v85
	v_mul_f32_e32 v84, 0xbfb8aa3b, v84
	v_mul_f32_e32 v85, 0xbfb8aa3b, v85
	v_exp_f32_e32 v84, v84
	v_exp_f32_e32 v85, v85
	v_or_b32_e32 v82, 48, v144
	v_ashrrev_i32_e32 v83, 31, v82
	v_add_f32_e32 v84, 1.0, v84
	v_add_f32_e32 v85, 1.0, v85
	v_rcp_f32_e32 v84, v84
	v_rcp_f32_e32 v85, v85
	v_lshlrev_b64 v[82:83], 16, v[82:83]
	v_lshl_add_u64 v[82:83], v[146:147], 0, v[82:83]
	v_pk_mul_f32 v[78:79], v[78:79], v[84:85]
	v_mul_f32_e32 v84, 0x3d372713, v75
	v_mul_f32_e32 v84, v75, v84
	v_fma_f32 v84, v75, v84, v75
	v_mul_f32_e32 v84, 0x3f4c422a, v84
	v_add_f32_e32 v84, v84, v84
	v_mul_f32_e32 v84, 0xbfb8aa3b, v84
	v_exp_f32_e32 v84, v84
	s_nop 0
	v_add_f32_e32 v84, 1.0, v84
	v_rcp_f32_e32 v87, v84
	s_nop 0
	v_pk_mul_f32 v[84:85], v[74:75], v[86:87]
	v_mul_f32_e32 v75, 0x3d372713, v76
	v_mul_f32_e32 v75, v76, v75
	v_fma_f32 v75, v76, v75, v76
	v_mul_f32_e32 v75, 0x3f4c422a, v75
	v_add_f32_e32 v75, v75, v75
	v_mul_f32_e32 v75, 0xbfb8aa3b, v75
	v_exp_f32_e32 v75, v75
	v_mul_f32_e32 v74, 0x3d372713, v80
	v_mul_f32_e32 v74, v80, v74
	v_fma_f32 v74, v80, v74, v80
	v_add_f32_e32 v75, 1.0, v75
	v_rcp_f32_e32 v86, v75
	v_mul_f32_e32 v75, 0x3d372713, v81
	v_mul_f32_e32 v75, v81, v75
	v_fma_f32 v75, v81, v75, v81
	v_mul_f32_e32 v74, 0x3f4c422a, v74
	v_mul_f32_e32 v75, 0x3f4c422a, v75
	v_add_f32_e32 v74, v74, v74
	v_add_f32_e32 v75, v75, v75
	v_mul_f32_e32 v74, 0xbfb8aa3b, v74
	v_mul_f32_e32 v75, 0xbfb8aa3b, v75
	v_exp_f32_e32 v74, v74
	v_exp_f32_e32 v75, v75
	v_add_f32_e32 v74, 1.0, v74
	v_add_f32_e32 v75, 1.0, v75
	v_rcp_f32_e32 v74, v74
	v_rcp_f32_e32 v75, v75
	s_nop 0
	v_pk_mul_f32 v[80:81], v[80:81], v[74:75]
; DEVI float sigmoidf_(float x) { return __builtin_amdgcn_rcpf(1.f + __expf(-x)); }
; DEVI float siluf_(float x) { return x * __builtin_amdgcn_rcpf(1.f + __expf(-x)); }
; DEVI float logsigf_(float x) { return fminf(x, 0.f) - __logf(1.f + __expf(-fabsf(x))); }
	v_mul_f32_e32 v74, 0x3d372713, v77
	v_mul_f32_e32 v74, v77, v74
	v_fma_f32 v74, v77, v74, v77
	v_mul_f32_e32 v74, 0x3f4c422a, v74
	v_add_f32_e32 v74, v74, v74
	v_mul_f32_e32 v74, 0xbfb8aa3b, v74
	v_exp_f32_e32 v74, v74
	v_cvt_pk_bf16_f32 v75, v80, v81
	v_add_f32_e32 v74, 1.0, v74
	v_rcp_f32_e32 v87, v74
	v_cvt_pk_bf16_f32 v74, v78, v79
	v_lshl_add_u64 v[78:79], v[82:83], 0, v[122:123]
	v_pk_mul_f32 v[86:87], v[76:77], v[86:87]
	v_cvt_pk_bf16_f32 v76, v84, v85
	v_cvt_pk_bf16_f32 v77, v86, v87
	global_store_dwordx4 v[78:79], v[74:77], off
	s_nop 1
	v_mul_f32_e32 v75, 0x3d372713, v66
	v_mul_f32_e32 v75, v66, v75
	v_fma_f32 v75, v66, v75, v66
	v_mul_f32_e32 v75, 0x3f4c422a, v75
	v_add_f32_e32 v75, v75, v75
	v_mul_f32_e32 v75, 0xbfb8aa3b, v75
	v_exp_f32_e32 v75, v75
	v_mul_f32_e32 v74, 0x3d372713, v70
	v_mul_f32_e32 v74, v70, v74
	v_fma_f32 v74, v70, v74, v70
	v_add_f32_e32 v75, 1.0, v75
	v_rcp_f32_e32 v76, v75
	v_mul_f32_e32 v75, 0x3d372713, v71
	v_mul_f32_e32 v75, v71, v75
	v_fma_f32 v75, v71, v75, v71
	v_mul_f32_e32 v74, 0x3f4c422a, v74
	v_mul_f32_e32 v75, 0x3f4c422a, v75
	v_add_f32_e32 v74, v74, v74
	v_add_f32_e32 v75, v75, v75
	v_mul_f32_e32 v74, 0xbfb8aa3b, v74
	v_mul_f32_e32 v75, 0xbfb8aa3b, v75
	v_exp_f32_e32 v74, v74
	v_exp_f32_e32 v75, v75
	v_add_f32_e32 v74, 1.0, v74
	v_add_f32_e32 v75, 1.0, v75
	v_rcp_f32_e32 v74, v74
	v_rcp_f32_e32 v75, v75
	s_nop 0
	v_pk_mul_f32 v[70:71], v[70:71], v[74:75]
	v_mul_f32_e32 v74, 0x3d372713, v67
	v_mul_f32_e32 v74, v67, v74
	v_fma_f32 v74, v67, v74, v67
	v_mul_f32_e32 v74, 0x3f4c422a, v74
	v_add_f32_e32 v74, v74, v74
	v_mul_f32_e32 v74, 0xbfb8aa3b, v74
	v_exp_f32_e32 v74, v74
	s_nop 0
	v_add_f32_e32 v74, 1.0, v74
	v_rcp_f32_e32 v77, v74
	s_nop 0
	v_pk_mul_f32 v[74:75], v[66:67], v[76:77]
	v_mul_f32_e32 v67, 0x3d372713, v68
	v_mul_f32_e32 v67, v68, v67
	v_fma_f32 v67, v68, v67, v68
	v_mul_f32_e32 v67, 0x3f4c422a, v67
	v_add_f32_e32 v67, v67, v67
	v_mul_f32_e32 v67, 0xbfb8aa3b, v67
	v_exp_f32_e32 v67, v67
	v_mul_f32_e32 v66, 0x3d372713, v72
	v_mul_f32_e32 v66, v72, v66
	v_fma_f32 v66, v72, v66, v72
	v_add_f32_e32 v67, 1.0, v67
	v_rcp_f32_e32 v76, v67
	v_mul_f32_e32 v67, 0x3d372713, v73
	v_mul_f32_e32 v67, v73, v67
	v_fma_f32 v67, v73, v67, v73
	v_mul_f32_e32 v66, 0x3f4c422a, v66
	v_mul_f32_e32 v67, 0x3f4c422a, v67
	v_add_f32_e32 v66, v66, v66
	v_add_f32_e32 v67, v67, v67
	v_mul_f32_e32 v66, 0xbfb8aa3b, v66
	v_mul_f32_e32 v67, 0xbfb8aa3b, v67
	v_exp_f32_e32 v66, v66
	v_exp_f32_e32 v67, v67
	v_add_f32_e32 v66, 1.0, v66
	v_add_f32_e32 v67, 1.0, v67
	v_rcp_f32_e32 v66, v66
	v_rcp_f32_e32 v67, v67
	s_nop 0
	v_pk_mul_f32 v[72:73], v[72:73], v[66:67]
	v_mul_f32_e32 v66, 0x3d372713, v69
	v_mul_f32_e32 v66, v69, v66
	v_fma_f32 v66, v69, v66, v69
	v_mul_f32_e32 v66, 0x3f4c422a, v66
	v_add_f32_e32 v66, v66, v66
	v_mul_f32_e32 v66, 0xbfb8aa3b, v66
	v_exp_f32_e32 v66, v66
	v_cvt_pk_bf16_f32 v67, v72, v73
	v_add_f32_e32 v66, 1.0, v66
	v_rcp_f32_e32 v77, v66
	v_cvt_pk_bf16_f32 v66, v70, v71
	v_lshl_add_u64 v[70:71], v[82:83], 0, v[114:115]
	v_pk_mul_f32 v[76:77], v[68:69], v[76:77]
	v_cvt_pk_bf16_f32 v68, v74, v75
	v_cvt_pk_bf16_f32 v69, v76, v77
	global_store_dwordx4 v[70:71], v[66:69], off
	s_nop 1
	v_mul_f32_e32 v69, 0x3d372713, v58
	v_mul_f32_e32 v69, v58, v69
	v_fma_f32 v69, v58, v69, v58
	v_mul_f32_e32 v69, 0x3f4c422a, v69
	v_add_f32_e32 v69, v69, v69
	v_mul_f32_e32 v69, 0xbfb8aa3b, v69
	v_exp_f32_e32 v69, v69
	v_mul_f32_e32 v68, 0x3d372713, v62
	v_mul_f32_e32 v68, v62, v68
	v_fma_f32 v68, v62, v68, v62
	v_add_f32_e32 v69, 1.0, v69
	v_rcp_f32_e32 v70, v69
	v_mul_f32_e32 v69, 0x3d372713, v63
	v_mul_f32_e32 v69, v63, v69
	v_fma_f32 v69, v63, v69, v63
	v_mul_f32_e32 v68, 0x3f4c422a, v68
	v_mul_f32_e32 v69, 0x3f4c422a, v69
	v_add_f32_e32 v68, v68, v68
	v_add_f32_e32 v69, v69, v69
	v_mul_f32_e32 v68, 0xbfb8aa3b, v68
	v_mul_f32_e32 v69, 0xbfb8aa3b, v69
	v_exp_f32_e32 v68, v68
	v_exp_f32_e32 v69, v69
	v_lshl_add_u64 v[66:67], v[142:143], 0, s[0:1]
	s_mov_b64 s[0:1], 0x900000
	v_add_f32_e32 v68, 1.0, v68
	v_add_f32_e32 v69, 1.0, v69
	v_rcp_f32_e32 v68, v68
	v_rcp_f32_e32 v69, v69
	s_nop 0
	v_pk_mul_f32 v[62:63], v[62:63], v[68:69]
	v_mul_f32_e32 v68, 0x3d372713, v59
	v_mul_f32_e32 v68, v59, v68
	v_fma_f32 v68, v59, v68, v59
	v_mul_f32_e32 v68, 0x3f4c422a, v68
	v_add_f32_e32 v68, v68, v68
	v_mul_f32_e32 v68, 0xbfb8aa3b, v68
	v_exp_f32_e32 v68, v68
	s_nop 0
	v_add_f32_e32 v68, 1.0, v68
	v_rcp_f32_e32 v71, v68
	s_nop 0
	v_pk_mul_f32 v[68:69], v[58:59], v[70:71]
	v_mul_f32_e32 v59, 0x3d372713, v60
	v_mul_f32_e32 v59, v60, v59
	v_fma_f32 v59, v60, v59, v60
	v_mul_f32_e32 v59, 0x3f4c422a, v59
	v_add_f32_e32 v59, v59, v59
	v_mul_f32_e32 v59, 0xbfb8aa3b, v59
	v_exp_f32_e32 v59, v59
	v_mul_f32_e32 v58, 0x3d372713, v64
	v_mul_f32_e32 v58, v64, v58
	v_fma_f32 v58, v64, v58, v64
	v_add_f32_e32 v59, 1.0, v59
	v_rcp_f32_e32 v70, v59
	v_mul_f32_e32 v59, 0x3d372713, v65
	v_mul_f32_e32 v59, v65, v59
	v_fma_f32 v59, v65, v59, v65
	v_mul_f32_e32 v58, 0x3f4c422a, v58
	v_mul_f32_e32 v59, 0x3f4c422a, v59
	v_add_f32_e32 v58, v58, v58
	v_add_f32_e32 v59, v59, v59
	v_mul_f32_e32 v58, 0xbfb8aa3b, v58
	v_mul_f32_e32 v59, 0xbfb8aa3b, v59
	v_exp_f32_e32 v58, v58
	v_exp_f32_e32 v59, v59
	v_add_f32_e32 v58, 1.0, v58
	v_add_f32_e32 v59, 1.0, v59
	v_rcp_f32_e32 v58, v58
	v_rcp_f32_e32 v59, v59
	s_nop 0
	v_pk_mul_f32 v[64:65], v[64:65], v[58:59]
	v_mul_f32_e32 v58, 0x3d372713, v61
	v_mul_f32_e32 v58, v61, v58
	v_fma_f32 v58, v61, v58, v61
	v_mul_f32_e32 v58, 0x3f4c422a, v58
	v_add_f32_e32 v58, v58, v58
	v_mul_f32_e32 v58, 0xbfb8aa3b, v58
	v_exp_f32_e32 v58, v58
	v_cvt_pk_bf16_f32 v59, v64, v65
	v_add_f32_e32 v58, 1.0, v58
	v_rcp_f32_e32 v71, v58
; DEVI float sigmoidf_(float x) { return __builtin_amdgcn_rcpf(1.f + __expf(-x)); }
; DEVI float siluf_(float x) { return x * __builtin_amdgcn_rcpf(1.f + __expf(-x)); }
; DEVI float logsigf_(float x) { return fminf(x, 0.f) - __logf(1.f + __expf(-fabsf(x))); }
	v_cvt_pk_bf16_f32 v58, v62, v63
	v_lshl_add_u64 v[62:63], v[66:67], 0, v[122:123]
	v_pk_mul_f32 v[70:71], v[60:61], v[70:71]
	v_cvt_pk_bf16_f32 v60, v68, v69
	v_cvt_pk_bf16_f32 v61, v70, v71
	global_store_dwordx4 v[62:63], v[58:61], off
	s_nop 1
	v_mul_f32_e32 v59, 0x3d372713, v50
	v_mul_f32_e32 v59, v50, v59
	v_fma_f32 v59, v50, v59, v50
	v_mul_f32_e32 v59, 0x3f4c422a, v59
	v_add_f32_e32 v59, v59, v59
	v_mul_f32_e32 v59, 0xbfb8aa3b, v59
	v_exp_f32_e32 v59, v59
	v_mul_f32_e32 v58, 0x3d372713, v54
	v_mul_f32_e32 v58, v54, v58
	v_fma_f32 v58, v54, v58, v54
	v_add_f32_e32 v59, 1.0, v59
	v_rcp_f32_e32 v60, v59
	v_mul_f32_e32 v59, 0x3d372713, v55
	v_mul_f32_e32 v59, v55, v59
	v_fma_f32 v59, v55, v59, v55
	v_mul_f32_e32 v58, 0x3f4c422a, v58
	v_mul_f32_e32 v59, 0x3f4c422a, v59
	v_add_f32_e32 v58, v58, v58
	v_add_f32_e32 v59, v59, v59
	v_mul_f32_e32 v58, 0xbfb8aa3b, v58
	v_mul_f32_e32 v59, 0xbfb8aa3b, v59
	v_exp_f32_e32 v58, v58
	v_exp_f32_e32 v59, v59
	v_add_f32_e32 v58, 1.0, v58
	v_add_f32_e32 v59, 1.0, v59
	v_rcp_f32_e32 v58, v58
	v_rcp_f32_e32 v59, v59
	s_nop 0
	v_pk_mul_f32 v[54:55], v[54:55], v[58:59]
	v_mul_f32_e32 v58, 0x3d372713, v51
	v_mul_f32_e32 v58, v51, v58
	v_fma_f32 v58, v51, v58, v51
	v_mul_f32_e32 v58, 0x3f4c422a, v58
	v_add_f32_e32 v58, v58, v58
	v_mul_f32_e32 v58, 0xbfb8aa3b, v58
	v_exp_f32_e32 v58, v58
	s_nop 0
	v_add_f32_e32 v58, 1.0, v58
	v_rcp_f32_e32 v61, v58
	s_nop 0
	v_pk_mul_f32 v[58:59], v[50:51], v[60:61]
	v_mul_f32_e32 v51, 0x3d372713, v52
	v_mul_f32_e32 v51, v52, v51
	v_fma_f32 v51, v52, v51, v52
	v_mul_f32_e32 v51, 0x3f4c422a, v51
	v_add_f32_e32 v51, v51, v51
	v_mul_f32_e32 v51, 0xbfb8aa3b, v51
	v_exp_f32_e32 v51, v51
	v_mul_f32_e32 v50, 0x3d372713, v56
	v_mul_f32_e32 v50, v56, v50
	v_fma_f32 v50, v56, v50, v56
	v_add_f32_e32 v51, 1.0, v51
	v_rcp_f32_e32 v60, v51
	v_mul_f32_e32 v51, 0x3d372713, v57
	v_mul_f32_e32 v51, v57, v51
	v_fma_f32 v51, v57, v51, v57
	v_mul_f32_e32 v50, 0x3f4c422a, v50
	v_mul_f32_e32 v51, 0x3f4c422a, v51
	v_add_f32_e32 v50, v50, v50
	v_add_f32_e32 v51, v51, v51
	v_mul_f32_e32 v50, 0xbfb8aa3b, v50
	v_mul_f32_e32 v51, 0xbfb8aa3b, v51
	v_exp_f32_e32 v50, v50
	v_exp_f32_e32 v51, v51
	v_add_f32_e32 v50, 1.0, v50
	v_add_f32_e32 v51, 1.0, v51
	v_rcp_f32_e32 v50, v50
	v_rcp_f32_e32 v51, v51
	s_nop 0
	v_pk_mul_f32 v[56:57], v[56:57], v[50:51]
	v_mul_f32_e32 v50, 0x3d372713, v53
	v_mul_f32_e32 v50, v53, v50
	v_fma_f32 v50, v53, v50, v53
	v_mul_f32_e32 v50, 0x3f4c422a, v50
	v_add_f32_e32 v50, v50, v50
	v_mul_f32_e32 v50, 0xbfb8aa3b, v50
	v_exp_f32_e32 v50, v50
	v_cvt_pk_bf16_f32 v51, v56, v57
	v_add_f32_e32 v50, 1.0, v50
	v_rcp_f32_e32 v61, v50
	v_cvt_pk_bf16_f32 v50, v54, v55
	v_lshl_add_u64 v[54:55], v[66:67], 0, v[114:115]
	v_pk_mul_f32 v[60:61], v[52:53], v[60:61]
	v_cvt_pk_bf16_f32 v52, v58, v59
	v_cvt_pk_bf16_f32 v53, v60, v61
	global_store_dwordx4 v[54:55], v[50:53], off
	s_nop 1
	v_mul_f32_e32 v53, 0x3d372713, v42
	v_mul_f32_e32 v53, v42, v53
	v_fma_f32 v53, v42, v53, v42
	v_mul_f32_e32 v53, 0x3f4c422a, v53
	v_add_f32_e32 v53, v53, v53
	v_mul_f32_e32 v53, 0xbfb8aa3b, v53
	v_exp_f32_e32 v53, v53
	v_mul_f32_e32 v52, 0x3d372713, v46
	v_mul_f32_e32 v52, v46, v52
	v_fma_f32 v52, v46, v52, v46
	v_add_f32_e32 v53, 1.0, v53
	v_rcp_f32_e32 v54, v53
	v_mul_f32_e32 v53, 0x3d372713, v47
	v_mul_f32_e32 v53, v47, v53
	v_fma_f32 v53, v47, v53, v47
	v_mul_f32_e32 v52, 0x3f4c422a, v52
	v_mul_f32_e32 v53, 0x3f4c422a, v53
	v_add_f32_e32 v52, v52, v52
	v_add_f32_e32 v53, v53, v53
	v_mul_f32_e32 v52, 0xbfb8aa3b, v52
	v_mul_f32_e32 v53, 0xbfb8aa3b, v53
	v_exp_f32_e32 v52, v52
	v_exp_f32_e32 v53, v53
	v_lshl_add_u64 v[50:51], v[142:143], 0, s[0:1]
	s_mov_b64 s[0:1], 0xa00000
	v_add_f32_e32 v52, 1.0, v52
	v_add_f32_e32 v53, 1.0, v53
	v_rcp_f32_e32 v52, v52
	v_rcp_f32_e32 v53, v53
	s_nop 0
	v_pk_mul_f32 v[46:47], v[46:47], v[52:53]
	v_mul_f32_e32 v52, 0x3d372713, v43
	v_mul_f32_e32 v52, v43, v52
	v_fma_f32 v52, v43, v52, v43
	v_mul_f32_e32 v52, 0x3f4c422a, v52
	v_add_f32_e32 v52, v52, v52
	v_mul_f32_e32 v52, 0xbfb8aa3b, v52
	v_exp_f32_e32 v52, v52
	s_nop 0
	v_add_f32_e32 v52, 1.0, v52
	v_rcp_f32_e32 v55, v52
	s_nop 0
	v_pk_mul_f32 v[52:53], v[42:43], v[54:55]
	v_mul_f32_e32 v43, 0x3d372713, v44
	v_mul_f32_e32 v43, v44, v43
	v_fma_f32 v43, v44, v43, v44
	v_mul_f32_e32 v43, 0x3f4c422a, v43
	v_add_f32_e32 v43, v43, v43
	v_mul_f32_e32 v43, 0xbfb8aa3b, v43
	v_exp_f32_e32 v43, v43
	v_mul_f32_e32 v42, 0x3d372713, v48
	v_mul_f32_e32 v42, v48, v42
	v_fma_f32 v42, v48, v42, v48
	v_add_f32_e32 v43, 1.0, v43
	v_rcp_f32_e32 v54, v43
	v_mul_f32_e32 v43, 0x3d372713, v49
	v_mul_f32_e32 v43, v49, v43
	v_fma_f32 v43, v49, v43, v49
	v_mul_f32_e32 v42, 0x3f4c422a, v42
	v_mul_f32_e32 v43, 0x3f4c422a, v43
	v_add_f32_e32 v42, v42, v42
	v_add_f32_e32 v43, v43, v43
	v_mul_f32_e32 v42, 0xbfb8aa3b, v42
	v_mul_f32_e32 v43, 0xbfb8aa3b, v43
	v_exp_f32_e32 v42, v42
	v_exp_f32_e32 v43, v43
	v_add_f32_e32 v42, 1.0, v42
	v_add_f32_e32 v43, 1.0, v43
	v_rcp_f32_e32 v42, v42
	v_rcp_f32_e32 v43, v43
	s_nop 0
	v_pk_mul_f32 v[48:49], v[48:49], v[42:43]
	v_mul_f32_e32 v42, 0x3d372713, v45
	v_mul_f32_e32 v42, v45, v42
	v_fma_f32 v42, v45, v42, v45
	v_mul_f32_e32 v42, 0x3f4c422a, v42
	v_add_f32_e32 v42, v42, v42
	v_mul_f32_e32 v42, 0xbfb8aa3b, v42
	v_exp_f32_e32 v42, v42
	v_cvt_pk_bf16_f32 v43, v48, v49
	v_add_f32_e32 v42, 1.0, v42
	v_rcp_f32_e32 v55, v42
	v_cvt_pk_bf16_f32 v42, v46, v47
	v_lshl_add_u64 v[46:47], v[50:51], 0, v[122:123]
	v_pk_mul_f32 v[54:55], v[44:45], v[54:55]
	v_cvt_pk_bf16_f32 v44, v52, v53
	v_cvt_pk_bf16_f32 v45, v54, v55
	global_store_dwordx4 v[46:47], v[42:45], off
	s_nop 1
	v_mul_f32_e32 v43, 0x3d372713, v34
	v_mul_f32_e32 v43, v34, v43
; DEVI float sigmoidf_(float x) { return __builtin_amdgcn_rcpf(1.f + __expf(-x)); }
; DEVI float siluf_(float x) { return x * __builtin_amdgcn_rcpf(1.f + __expf(-x)); }
; DEVI float logsigf_(float x) { return fminf(x, 0.f) - __logf(1.f + __expf(-fabsf(x))); }
	v_fma_f32 v43, v34, v43, v34
	v_mul_f32_e32 v43, 0x3f4c422a, v43
	v_add_f32_e32 v43, v43, v43
	v_mul_f32_e32 v43, 0xbfb8aa3b, v43
	v_exp_f32_e32 v43, v43
	v_mul_f32_e32 v42, 0x3d372713, v38
	v_mul_f32_e32 v42, v38, v42
	v_fma_f32 v42, v38, v42, v38
	v_add_f32_e32 v43, 1.0, v43
	v_rcp_f32_e32 v44, v43
	v_mul_f32_e32 v43, 0x3d372713, v39
	v_mul_f32_e32 v43, v39, v43
	v_fma_f32 v43, v39, v43, v39
	v_mul_f32_e32 v42, 0x3f4c422a, v42
	v_mul_f32_e32 v43, 0x3f4c422a, v43
	v_add_f32_e32 v42, v42, v42
	v_add_f32_e32 v43, v43, v43
	v_mul_f32_e32 v42, 0xbfb8aa3b, v42
	v_mul_f32_e32 v43, 0xbfb8aa3b, v43
	v_exp_f32_e32 v42, v42
	v_exp_f32_e32 v43, v43
	v_add_f32_e32 v42, 1.0, v42
	v_add_f32_e32 v43, 1.0, v43
	v_rcp_f32_e32 v42, v42
	v_rcp_f32_e32 v43, v43
	s_nop 0
	v_pk_mul_f32 v[38:39], v[38:39], v[42:43]
	v_mul_f32_e32 v42, 0x3d372713, v35
	v_mul_f32_e32 v42, v35, v42
	v_fma_f32 v42, v35, v42, v35
	v_mul_f32_e32 v42, 0x3f4c422a, v42
	v_add_f32_e32 v42, v42, v42
	v_mul_f32_e32 v42, 0xbfb8aa3b, v42
	v_exp_f32_e32 v42, v42
	s_nop 0
	v_add_f32_e32 v42, 1.0, v42
	v_rcp_f32_e32 v45, v42
	s_nop 0
	v_pk_mul_f32 v[42:43], v[34:35], v[44:45]
	v_mul_f32_e32 v35, 0x3d372713, v36
	v_mul_f32_e32 v35, v36, v35
	v_fma_f32 v35, v36, v35, v36
	v_mul_f32_e32 v35, 0x3f4c422a, v35
	v_add_f32_e32 v35, v35, v35
	v_mul_f32_e32 v35, 0xbfb8aa3b, v35
	v_exp_f32_e32 v35, v35
	v_mul_f32_e32 v34, 0x3d372713, v40
	v_mul_f32_e32 v34, v40, v34
	v_fma_f32 v34, v40, v34, v40
	v_add_f32_e32 v35, 1.0, v35
	v_rcp_f32_e32 v44, v35
	v_mul_f32_e32 v35, 0x3d372713, v41
	v_mul_f32_e32 v35, v41, v35
	v_fma_f32 v35, v41, v35, v41
	v_mul_f32_e32 v34, 0x3f4c422a, v34
	v_mul_f32_e32 v35, 0x3f4c422a, v35
	v_add_f32_e32 v34, v34, v34
	v_add_f32_e32 v35, v35, v35
	v_mul_f32_e32 v34, 0xbfb8aa3b, v34
	v_mul_f32_e32 v35, 0xbfb8aa3b, v35
	v_exp_f32_e32 v34, v34
	v_exp_f32_e32 v35, v35
	v_add_f32_e32 v34, 1.0, v34
	v_add_f32_e32 v35, 1.0, v35
	v_rcp_f32_e32 v34, v34
	v_rcp_f32_e32 v35, v35
	s_nop 0
	v_pk_mul_f32 v[40:41], v[40:41], v[34:35]
	v_mul_f32_e32 v34, 0x3d372713, v37
	v_mul_f32_e32 v34, v37, v34
	v_fma_f32 v34, v37, v34, v37
	v_mul_f32_e32 v34, 0x3f4c422a, v34
	v_add_f32_e32 v34, v34, v34
	v_mul_f32_e32 v34, 0xbfb8aa3b, v34
	v_exp_f32_e32 v34, v34
	v_cvt_pk_bf16_f32 v35, v40, v41
	v_add_f32_e32 v34, 1.0, v34
	v_rcp_f32_e32 v45, v34
	v_cvt_pk_bf16_f32 v34, v38, v39
	v_lshl_add_u64 v[38:39], v[50:51], 0, v[114:115]
	v_pk_mul_f32 v[44:45], v[36:37], v[44:45]
	v_cvt_pk_bf16_f32 v36, v42, v43
	v_cvt_pk_bf16_f32 v37, v44, v45
	global_store_dwordx4 v[38:39], v[34:37], off
	s_nop 1
	v_mul_f32_e32 v37, 0x3d372713, v26
	v_mul_f32_e32 v37, v26, v37
	v_fma_f32 v37, v26, v37, v26
	v_mul_f32_e32 v37, 0x3f4c422a, v37
	v_add_f32_e32 v37, v37, v37
	v_mul_f32_e32 v37, 0xbfb8aa3b, v37
	v_exp_f32_e32 v37, v37
	v_mul_f32_e32 v36, 0x3d372713, v30
	v_mul_f32_e32 v36, v30, v36
	v_fma_f32 v36, v30, v36, v30
	v_add_f32_e32 v37, 1.0, v37
	v_rcp_f32_e32 v38, v37
	v_mul_f32_e32 v37, 0x3d372713, v31
	v_mul_f32_e32 v37, v31, v37
	v_fma_f32 v37, v31, v37, v31
	v_mul_f32_e32 v36, 0x3f4c422a, v36
	v_mul_f32_e32 v37, 0x3f4c422a, v37
	v_add_f32_e32 v36, v36, v36
	v_add_f32_e32 v37, v37, v37
	v_mul_f32_e32 v36, 0xbfb8aa3b, v36
	v_mul_f32_e32 v37, 0xbfb8aa3b, v37
	v_exp_f32_e32 v36, v36
	v_exp_f32_e32 v37, v37
	v_lshl_add_u64 v[34:35], v[142:143], 0, s[0:1]
	s_mov_b64 s[0:1], 0xb00000
	v_add_f32_e32 v36, 1.0, v36
	v_add_f32_e32 v37, 1.0, v37
	v_rcp_f32_e32 v36, v36
	v_rcp_f32_e32 v37, v37
	s_nop 0
	v_pk_mul_f32 v[30:31], v[30:31], v[36:37]
	v_mul_f32_e32 v36, 0x3d372713, v27
	v_mul_f32_e32 v36, v27, v36
	v_fma_f32 v36, v27, v36, v27
	v_mul_f32_e32 v36, 0x3f4c422a, v36
	v_add_f32_e32 v36, v36, v36
	v_mul_f32_e32 v36, 0xbfb8aa3b, v36
	v_exp_f32_e32 v36, v36
	s_nop 0
	v_add_f32_e32 v36, 1.0, v36
	v_rcp_f32_e32 v39, v36
	s_nop 0
	v_pk_mul_f32 v[36:37], v[26:27], v[38:39]
	v_mul_f32_e32 v27, 0x3d372713, v28
	v_mul_f32_e32 v27, v28, v27
	v_fma_f32 v27, v28, v27, v28
	v_mul_f32_e32 v27, 0x3f4c422a, v27
	v_add_f32_e32 v27, v27, v27
	v_mul_f32_e32 v27, 0xbfb8aa3b, v27
	v_exp_f32_e32 v27, v27
	v_mul_f32_e32 v26, 0x3d372713, v32
	v_mul_f32_e32 v26, v32, v26
	v_fma_f32 v26, v32, v26, v32
	v_add_f32_e32 v27, 1.0, v27
	v_rcp_f32_e32 v38, v27
	v_mul_f32_e32 v27, 0x3d372713, v33
	v_mul_f32_e32 v27, v33, v27
	v_fma_f32 v27, v33, v27, v33
	v_mul_f32_e32 v26, 0x3f4c422a, v26
	v_mul_f32_e32 v27, 0x3f4c422a, v27
	v_add_f32_e32 v26, v26, v26
	v_add_f32_e32 v27, v27, v27
	v_mul_f32_e32 v26, 0xbfb8aa3b, v26
	v_mul_f32_e32 v27, 0xbfb8aa3b, v27
	v_exp_f32_e32 v26, v26
	v_exp_f32_e32 v27, v27
	v_add_f32_e32 v26, 1.0, v26
	v_add_f32_e32 v27, 1.0, v27
	v_rcp_f32_e32 v26, v26
	v_rcp_f32_e32 v27, v27
	s_nop 0
	v_pk_mul_f32 v[32:33], v[32:33], v[26:27]
	v_mul_f32_e32 v26, 0x3d372713, v29
	v_mul_f32_e32 v26, v29, v26
	v_fma_f32 v26, v29, v26, v29
	v_mul_f32_e32 v26, 0x3f4c422a, v26
	v_add_f32_e32 v26, v26, v26
	v_mul_f32_e32 v26, 0xbfb8aa3b, v26
	v_exp_f32_e32 v26, v26
	v_cvt_pk_bf16_f32 v27, v32, v33
	v_add_f32_e32 v26, 1.0, v26
	v_rcp_f32_e32 v39, v26
	v_cvt_pk_bf16_f32 v26, v30, v31
	v_lshl_add_u64 v[30:31], v[34:35], 0, v[122:123]
	v_pk_mul_f32 v[38:39], v[28:29], v[38:39]
	v_cvt_pk_bf16_f32 v28, v36, v37
	v_cvt_pk_bf16_f32 v29, v38, v39
	global_store_dwordx4 v[30:31], v[26:29], off
	s_nop 1
	v_mul_f32_e32 v27, 0x3d372713, v18
	v_mul_f32_e32 v27, v18, v27
	v_fma_f32 v27, v18, v27, v18
	v_mul_f32_e32 v27, 0x3f4c422a, v27
	v_add_f32_e32 v27, v27, v27
	v_mul_f32_e32 v27, 0xbfb8aa3b, v27
	v_exp_f32_e32 v27, v27
	v_mul_f32_e32 v26, 0x3d372713, v22
	v_mul_f32_e32 v26, v22, v26
	v_fma_f32 v26, v22, v26, v22
	v_add_f32_e32 v27, 1.0, v27
	v_rcp_f32_e32 v28, v27
; DEVI float sigmoidf_(float x) { return __builtin_amdgcn_rcpf(1.f + __expf(-x)); }
; DEVI float siluf_(float x) { return x * __builtin_amdgcn_rcpf(1.f + __expf(-x)); }
; DEVI float logsigf_(float x) { return fminf(x, 0.f) - __logf(1.f + __expf(-fabsf(x))); }
	v_mul_f32_e32 v27, 0x3d372713, v23
	v_mul_f32_e32 v27, v23, v27
	v_fma_f32 v27, v23, v27, v23
	v_mul_f32_e32 v26, 0x3f4c422a, v26
	v_mul_f32_e32 v27, 0x3f4c422a, v27
	v_add_f32_e32 v26, v26, v26
	v_add_f32_e32 v27, v27, v27
	v_mul_f32_e32 v26, 0xbfb8aa3b, v26
	v_mul_f32_e32 v27, 0xbfb8aa3b, v27
	v_exp_f32_e32 v26, v26
	v_exp_f32_e32 v27, v27
	v_add_f32_e32 v26, 1.0, v26
	v_add_f32_e32 v27, 1.0, v27
	v_rcp_f32_e32 v26, v26
	v_rcp_f32_e32 v27, v27
	s_nop 0
	v_pk_mul_f32 v[22:23], v[22:23], v[26:27]
	v_mul_f32_e32 v26, 0x3d372713, v19
	v_mul_f32_e32 v26, v19, v26
	v_fma_f32 v26, v19, v26, v19
	v_mul_f32_e32 v26, 0x3f4c422a, v26
	v_add_f32_e32 v26, v26, v26
	v_mul_f32_e32 v26, 0xbfb8aa3b, v26
	v_exp_f32_e32 v26, v26
	s_nop 0
	v_add_f32_e32 v26, 1.0, v26
	v_rcp_f32_e32 v29, v26
	s_nop 0
	v_pk_mul_f32 v[26:27], v[18:19], v[28:29]
	v_mul_f32_e32 v19, 0x3d372713, v20
	v_mul_f32_e32 v19, v20, v19
	v_fma_f32 v19, v20, v19, v20
	v_mul_f32_e32 v19, 0x3f4c422a, v19
	v_add_f32_e32 v19, v19, v19
	v_mul_f32_e32 v19, 0xbfb8aa3b, v19
	v_exp_f32_e32 v19, v19
	v_mul_f32_e32 v18, 0x3d372713, v24
	v_mul_f32_e32 v18, v24, v18
	v_fma_f32 v18, v24, v18, v24
	v_add_f32_e32 v19, 1.0, v19
	v_rcp_f32_e32 v28, v19
	v_mul_f32_e32 v19, 0x3d372713, v25
	v_mul_f32_e32 v19, v25, v19
	v_fma_f32 v19, v25, v19, v25
	v_mul_f32_e32 v18, 0x3f4c422a, v18
	v_mul_f32_e32 v19, 0x3f4c422a, v19
	v_add_f32_e32 v18, v18, v18
	v_add_f32_e32 v19, v19, v19
	v_mul_f32_e32 v18, 0xbfb8aa3b, v18
	v_mul_f32_e32 v19, 0xbfb8aa3b, v19
	v_exp_f32_e32 v18, v18
	v_exp_f32_e32 v19, v19
	v_add_f32_e32 v18, 1.0, v18
	v_add_f32_e32 v19, 1.0, v19
	v_rcp_f32_e32 v18, v18
	v_rcp_f32_e32 v19, v19
	s_nop 0
	v_pk_mul_f32 v[24:25], v[24:25], v[18:19]
	v_mul_f32_e32 v18, 0x3d372713, v21
	v_mul_f32_e32 v18, v21, v18
	v_fma_f32 v18, v21, v18, v21
	v_mul_f32_e32 v18, 0x3f4c422a, v18
	v_add_f32_e32 v18, v18, v18
	v_mul_f32_e32 v18, 0xbfb8aa3b, v18
	v_exp_f32_e32 v18, v18
	v_cvt_pk_bf16_f32 v19, v24, v25
	v_add_f32_e32 v18, 1.0, v18
	v_rcp_f32_e32 v29, v18
	v_cvt_pk_bf16_f32 v18, v22, v23
	v_lshl_add_u64 v[22:23], v[34:35], 0, v[114:115]
	v_pk_mul_f32 v[28:29], v[20:21], v[28:29]
	v_cvt_pk_bf16_f32 v20, v26, v27
	v_cvt_pk_bf16_f32 v21, v28, v29
	global_store_dwordx4 v[22:23], v[18:21], off
	s_nop 1
	v_mul_f32_e32 v21, 0x3d372713, v10
	v_mul_f32_e32 v21, v10, v21
	v_fma_f32 v21, v10, v21, v10
	v_mul_f32_e32 v21, 0x3f4c422a, v21
	v_add_f32_e32 v21, v21, v21
	v_mul_f32_e32 v21, 0xbfb8aa3b, v21
	v_exp_f32_e32 v21, v21
	v_mul_f32_e32 v20, 0x3d372713, v14
	v_mul_f32_e32 v20, v14, v20
	v_fma_f32 v20, v14, v20, v14
	v_add_f32_e32 v21, 1.0, v21
	v_rcp_f32_e32 v22, v21
	v_mul_f32_e32 v21, 0x3d372713, v15
	v_mul_f32_e32 v21, v15, v21
	v_fma_f32 v21, v15, v21, v15
	v_mul_f32_e32 v20, 0x3f4c422a, v20
	v_mul_f32_e32 v21, 0x3f4c422a, v21
	v_add_f32_e32 v20, v20, v20
	v_add_f32_e32 v21, v21, v21
	v_mul_f32_e32 v20, 0xbfb8aa3b, v20
	v_mul_f32_e32 v21, 0xbfb8aa3b, v21
	v_exp_f32_e32 v20, v20
	v_exp_f32_e32 v21, v21
	v_lshl_add_u64 v[18:19], v[142:143], 0, s[0:1]
	s_mov_b32 s0, s8
	v_add_f32_e32 v20, 1.0, v20
	v_add_f32_e32 v21, 1.0, v21
	v_rcp_f32_e32 v20, v20
	v_rcp_f32_e32 v21, v21
	s_mov_b32 s1, s9
	v_pk_mul_f32 v[14:15], v[14:15], v[20:21]
	v_mul_f32_e32 v20, 0x3d372713, v11
	v_mul_f32_e32 v20, v11, v20
	v_fma_f32 v20, v11, v20, v11
	v_mul_f32_e32 v20, 0x3f4c422a, v20
	v_add_f32_e32 v20, v20, v20
	v_mul_f32_e32 v20, 0xbfb8aa3b, v20
	v_exp_f32_e32 v20, v20
	s_nop 0
	v_add_f32_e32 v20, 1.0, v20
	v_rcp_f32_e32 v23, v20
	s_nop 0
	v_pk_mul_f32 v[20:21], v[10:11], v[22:23]
	v_mul_f32_e32 v11, 0x3d372713, v12
	v_mul_f32_e32 v11, v12, v11
	v_fma_f32 v11, v12, v11, v12
	v_mul_f32_e32 v11, 0x3f4c422a, v11
	v_add_f32_e32 v11, v11, v11
	v_mul_f32_e32 v11, 0xbfb8aa3b, v11
	v_exp_f32_e32 v11, v11
	v_mul_f32_e32 v10, 0x3d372713, v16
; #define PG8_WAIT_V(n) asm volatile("s_waitcnt vmcnt(" #n ")" ::: "memory")
; #define PG8_BAR __builtin_amdgcn_s_barrier()
; template <class Epi>
; DEVI void gemm_phase(LAS unsigned char* lds, const Gemm g, const Epi& E) {
;     ...
;         if (!has_next) break;
; #pragma unroll
;         for (int a = 0; a < 2; ++a)
; #pragma unroll
;             for (int b = 0; b < 2; ++b)
; #pragma unroll
;                 for (int m = 0; m < 4; ++m)
; #pragma unroll
;                     for (int n = 0; n < 2; ++n) acc[a][b][m][n] = (f32x4){0.f, 0.f, 0.f, 0.f};
;         cur = nxt; cA = nA; cB = nB; ++ui;
;     }
;     PG8_WAIT_V(0);
;     if (wr == 0) PG8_BAR;
;     PG8_BAR;
	v_mul_f32_e32 v10, v16, v10
	v_fma_f32 v10, v16, v10, v16
	v_add_f32_e32 v11, 1.0, v11
	v_rcp_f32_e32 v22, v11
	v_mul_f32_e32 v11, 0x3d372713, v17
	v_mul_f32_e32 v11, v17, v11
	v_fma_f32 v11, v17, v11, v17
	v_mul_f32_e32 v10, 0x3f4c422a, v10
	v_mul_f32_e32 v11, 0x3f4c422a, v11
	v_add_f32_e32 v10, v10, v10
	v_add_f32_e32 v11, v11, v11
	v_mul_f32_e32 v10, 0xbfb8aa3b, v10
	v_mul_f32_e32 v11, 0xbfb8aa3b, v11
	v_exp_f32_e32 v10, v10
	v_exp_f32_e32 v11, v11
	v_add_f32_e32 v10, 1.0, v10
	v_add_f32_e32 v11, 1.0, v11
	v_rcp_f32_e32 v10, v10
	v_rcp_f32_e32 v11, v11
	s_nop 0
	v_pk_mul_f32 v[16:17], v[16:17], v[10:11]
	v_mul_f32_e32 v10, 0x3d372713, v13
	v_mul_f32_e32 v10, v13, v10
	v_fma_f32 v10, v13, v10, v13
	v_mul_f32_e32 v10, 0x3f4c422a, v10
	v_add_f32_e32 v10, v10, v10
	v_mul_f32_e32 v10, 0xbfb8aa3b, v10
	v_exp_f32_e32 v10, v10
	v_cvt_pk_bf16_f32 v11, v16, v17
	v_add_f32_e32 v10, 1.0, v10
	v_rcp_f32_e32 v23, v10
	v_cvt_pk_bf16_f32 v10, v14, v15
	v_lshl_add_u64 v[14:15], v[18:19], 0, v[122:123]
	v_pk_mul_f32 v[22:23], v[12:13], v[22:23]
	v_cvt_pk_bf16_f32 v12, v20, v21
	v_cvt_pk_bf16_f32 v13, v22, v23
	global_store_dwordx4 v[14:15], v[10:13], off
	s_nop 1
	v_mul_f32_e32 v11, 0x3d372713, v0
	v_mul_f32_e32 v11, v0, v11
	v_fma_f32 v11, v0, v11, v0
	v_mul_f32_e32 v11, 0x3f4c422a, v11
	v_add_f32_e32 v11, v11, v11
	v_mul_f32_e32 v11, 0xbfb8aa3b, v11
	v_exp_f32_e32 v11, v11
	v_mul_f32_e32 v10, 0x3d372713, v4
	v_mul_f32_e32 v10, v4, v10
	v_fma_f32 v10, v4, v10, v4
	v_add_f32_e32 v11, 1.0, v11
	v_rcp_f32_e32 v12, v11
	v_mul_f32_e32 v11, 0x3d372713, v5
	v_mul_f32_e32 v11, v5, v11
	v_fma_f32 v11, v5, v11, v5
	v_mul_f32_e32 v10, 0x3f4c422a, v10
	v_mul_f32_e32 v11, 0x3f4c422a, v11
	v_add_f32_e32 v10, v10, v10
	v_add_f32_e32 v11, v11, v11
	v_mul_f32_e32 v10, 0xbfb8aa3b, v10
	v_mul_f32_e32 v11, 0xbfb8aa3b, v11
	v_exp_f32_e32 v10, v10
	v_exp_f32_e32 v11, v11
	v_add_f32_e32 v10, 1.0, v10
	v_add_f32_e32 v11, 1.0, v11
	v_rcp_f32_e32 v10, v10
	v_rcp_f32_e32 v11, v11
	s_nop 0
	v_pk_mul_f32 v[4:5], v[4:5], v[10:11]
	v_mul_f32_e32 v10, 0x3d372713, v1
	v_mul_f32_e32 v10, v1, v10
	v_fma_f32 v10, v1, v10, v1
	v_mul_f32_e32 v10, 0x3f4c422a, v10
	v_add_f32_e32 v10, v10, v10
	v_mul_f32_e32 v10, 0xbfb8aa3b, v10
	v_exp_f32_e32 v10, v10
	s_nop 0
	v_add_f32_e32 v10, 1.0, v10
	v_rcp_f32_e32 v13, v10
	s_nop 0
	v_pk_mul_f32 v[10:11], v[0:1], v[12:13]
	v_mul_f32_e32 v1, 0x3d372713, v2
	v_mul_f32_e32 v1, v2, v1
	v_fma_f32 v1, v2, v1, v2
	v_mul_f32_e32 v1, 0x3f4c422a, v1
	v_add_f32_e32 v1, v1, v1
	v_mul_f32_e32 v1, 0xbfb8aa3b, v1
	v_exp_f32_e32 v1, v1
	v_mul_f32_e32 v0, 0x3d372713, v6
	v_mul_f32_e32 v0, v6, v0
	v_fma_f32 v0, v6, v0, v6
	v_add_f32_e32 v1, 1.0, v1
	v_rcp_f32_e32 v12, v1
	v_mul_f32_e32 v1, 0x3d372713, v7
	v_mul_f32_e32 v1, v7, v1
	v_fma_f32 v1, v7, v1, v7
	v_mul_f32_e32 v0, 0x3f4c422a, v0
	v_mul_f32_e32 v1, 0x3f4c422a, v1
	v_add_f32_e32 v0, v0, v0
	v_add_f32_e32 v1, v1, v1
	v_mul_f32_e32 v0, 0xbfb8aa3b, v0
	v_mul_f32_e32 v1, 0xbfb8aa3b, v1
	v_exp_f32_e32 v0, v0
	v_exp_f32_e32 v1, v1
	v_add_f32_e32 v0, 1.0, v0
	v_add_f32_e32 v1, 1.0, v1
	v_rcp_f32_e32 v0, v0
	v_rcp_f32_e32 v1, v1
	s_nop 0
	v_pk_mul_f32 v[6:7], v[6:7], v[0:1]
	v_mul_f32_e32 v0, 0x3d372713, v3
	v_mul_f32_e32 v0, v3, v0
	v_fma_f32 v0, v3, v0, v3
	v_mul_f32_e32 v0, 0x3f4c422a, v0
	v_add_f32_e32 v0, v0, v0
	v_mul_f32_e32 v0, 0xbfb8aa3b, v0
	v_exp_f32_e32 v0, v0
	v_cvt_pk_bf16_f32 v1, v6, v7
	v_add_f32_e32 v0, 1.0, v0
	v_rcp_f32_e32 v13, v0
	v_cvt_pk_bf16_f32 v0, v4, v5
	v_lshl_add_u64 v[4:5], v[18:19], 0, v[114:115]
	v_pk_mul_f32 v[12:13], v[2:3], v[12:13]
	v_cvt_pk_bf16_f32 v2, v10, v11
	v_cvt_pk_bf16_f32 v3, v12, v13
	global_store_dwordx4 v[4:5], v[0:3], off
	s_cbranch_vccz .LBB0_1271
	s_waitcnt vmcnt(0)
	s_cmpk_gt_u32 s36, 0xff
	s_cbranch_scc1 .LBB0_1282
	s_barrier

; DEVI size_t gemm_offB(const Gemm& g, const Unit& u) { return (g.split ? (size_t)(u.b >> 2) * g.sB + (size_t)(u.b & 3) * g.sB_lo : (size_t)u.b * g.sB) + (size_t)(u.pm >> g.pmsh) * g.sBpm; }
; #define PG8_STAGE(bufoff, gbase, voff) do { _Pragma("unroll") for (int _i = 0; _i < 2; ++_i) \
;         __builtin_amdgcn_global_load_lds((const unsigned*)((const char*)(gbase) + (voff)[_i]), (LAS unsigned*)(lds + (bufoff) + ldsw + _i * 8192), 16, 0, 0); } while (0)
; #define PG8_LDA(dst, b, h) do { _Pragma("unroll") for (int m = 0; m < 4; ++m) _Pragma("unroll") for (int k = 0; k < 2; ++k) dst[m][k] = *(const LAS bf16x8*)(lds + PG8_SA(b, h) + aoff + m * 2048 + k * 1024); } while (0)
; #define PG8_LDB(dst, b, h) do { _Pragma("unroll") for (int n = 0; n < 2; ++n) _Pragma("unroll") for (int k = 0; k < 2; ++k) dst[n][k] = *(const LAS bf16x8*)(lds + PG8_SB(b, h) + boff + n * 2048 + k * 1024); } while (0)
; #define PG8_WAIT_L(n) asm volatile("s_waitcnt lgkmcnt(" #n ")" ::: "memory")
; #define PG8_BAR __builtin_amdgcn_s_barrier()
; #define PG8_SCHED __builtin_amdgcn_sched_barrier(0)
; template <class Epi>
; DEVI void gemm_phase(LAS unsigned char* lds, const Gemm g, const Epi& E) {
;     ...
;         const bool has_next = unit_next(g, ui + 1, nxt);
;         const char* nA = has_next ? (const char*)g.A + gemm_offA(g, nxt) * 2 + (size_t)nxt.pm * tstepA : cA;
;         const char* nB = has_next ? (const char*)g.Bt + gemm_offB(g, nxt) * 2 + (size_t)nxt.pn * tstepB : cB;
;         for (int t = 0; t < nt; t += 2) {
;             const bool last = (t == nt - 2);
;             const char* a1 = cA + (size_t)(t + 1) * kstep;
;             const char* a2 = last ? nA : cA + (size_t)(t + 2) * kstep; const char* b2 = last ? nB : cB + (size_t)(t + 2) * kstep;
;             const char* a3 = a2 + kstep; const char* b3 = b2 + kstep;
;             PG8_LDB(B0, 0, 0); PG8_SCHED; PG8_LDA(At, 0, 0); PG8_STAGE(PG8_SA(1, 1), a1 + hstepA, voffA);
;             PG8_WAIT_L(8); PG8_BAR; PG8_WAIT_L(0); PG8_MMA(0, 0, At, B0); PG8_BAR; PG8_SCHED;
;             PG8_LDB(B1, 0, 1); PG8_STAGE(PG8_SB(0, 0), b2, voffB);
;             PG8_BAR; PG8_WAIT_L(0); PG8_MMA(0, 1, At, B1); PG8_BAR;
;             PG8_LDA(At, 0, 1); PG8_STAGE(PG8_SA(0, 0), a2, voffA);
;             PG8_BAR; PG8_WAIT_L(0); PG8_MMA(1, 0, At, B0); PG8_BAR; PG8_SCHED;
.LBB0_1346:
	s_add_u32 s14, s12, 0xfffc0080
	s_addc_u32 s15, s13, -1
	s_add_i32 s38, 0, 0x10000
	v_add_u32_e32 v152, s38, v185
	ds_read_b128 v[114:117], v152
	ds_read_b128 v[126:129], v152 offset:1024
	ds_read_b128 v[130:133], v152 offset:2048
	ds_read_b128 v[176:179], v152 offset:3072
	s_cmp_eq_u32 s27, 12
	s_cselect_b32 s17, s1, s15
	s_cselect_b32 s16, s3, s14
	s_cselect_b32 s15, s5, s26
	s_cselect_b32 s14, s18, s19
	v_lshl_add_u64 v[152:153], s[12:13], 0, v[148:149]
	s_add_i32 m0, s11, 0xc000
	ds_read_b128 v[180:183], v187
	ds_read_b128 v[188:191], v187 offset:1024
	ds_read_b128 v[192:195], v187 offset:2048
	ds_read_b128 v[196:199], v187 offset:3072
	ds_read_b128 v[200:203], v187 offset:4096
	ds_read_b128 v[204:207], v187 offset:5120
	ds_read_b128 v[214:217], v187 offset:6144
	ds_read_b128 v[218:221], v187 offset:7168
	global_load_lds_dwordx4 v[152:153], off
	v_lshl_add_u64 v[152:153], s[12:13], 0, v[150:151]
	s_add_i32 m0, s11, 0xe000
	s_nop 0
	global_load_lds_dwordx4 v[152:153], off
	s_waitcnt lgkmcnt(8)
	s_barrier
	s_waitcnt lgkmcnt(0)
	s_setprio 1
	v_mfma_f32_16x16x32_bf16 v[138:141], v[114:117], v[180:183], v[138:141]
	v_mfma_f32_16x16x32_bf16 v[134:137], v[130:133], v[180:183], v[134:137]
	v_mfma_f32_16x16x32_bf16 v[110:113], v[114:117], v[192:195], v[110:113]
	v_mfma_f32_16x16x32_bf16 v[106:109], v[130:133], v[192:195], v[106:109]
	v_mfma_f32_16x16x32_bf16 v[94:97], v[114:117], v[200:203], v[94:97]
	v_mfma_f32_16x16x32_bf16 v[90:93], v[130:133], v[200:203], v[90:93]
	v_mfma_f32_16x16x32_bf16 v[78:81], v[114:117], v[214:217], v[78:81]
	v_mfma_f32_16x16x32_bf16 v[74:77], v[130:133], v[214:217], v[74:77]
	v_mfma_f32_16x16x32_bf16 v[138:141], v[126:129], v[188:191], v[138:141]
	v_mfma_f32_16x16x32_bf16 v[134:137], v[176:179], v[188:191], v[134:137]
	v_mfma_f32_16x16x32_bf16 v[110:113], v[126:129], v[196:199], v[110:113]
	v_mfma_f32_16x16x32_bf16 v[106:109], v[176:179], v[196:199], v[106:109]
	v_mfma_f32_16x16x32_bf16 v[94:97], v[126:129], v[204:207], v[94:97]
	v_mfma_f32_16x16x32_bf16 v[90:93], v[176:179], v[204:207], v[90:93]
	v_mfma_f32_16x16x32_bf16 v[78:81], v[126:129], v[218:221], v[78:81]
	v_mfma_f32_16x16x32_bf16 v[74:77], v[176:179], v[218:221], v[74:77]
	s_setprio 0
	s_barrier
	s_add_i32 s40, 0, 0x14000
	v_add_u32_e32 v152, s40, v185
	s_add_i32 s38, s38, s47
	ds_read_b128 v[222:225], v152
	ds_read_b128 v[226:229], v152 offset:1024
	ds_read_b128 v[230:233], v152 offset:2048
	ds_read_b128 v[234:237], v152 offset:3072
	v_lshl_add_u64 v[152:153], s[14:15], 0, v[8:9]
	s_mov_b32 m0, s38
	v_lshl_add_u64 v[162:163], s[14:15], 0, v[146:147]
	global_load_lds_dwordx4 v[152:153], off
	s_add_i32 m0, s38, 0x2000
	s_nop 0
	global_load_lds_dwordx4 v[162:163], off
	s_barrier
	s_waitcnt lgkmcnt(0)
	s_setprio 1
	v_mfma_f32_16x16x32_bf16 v[122:125], v[222:225], v[180:183], v[122:125]
	v_mfma_f32_16x16x32_bf16 v[118:121], v[230:233], v[180:183], v[118:121]
	v_mfma_f32_16x16x32_bf16 v[102:105], v[222:225], v[192:195], v[102:105]
	v_mfma_f32_16x16x32_bf16 v[98:101], v[230:233], v[192:195], v[98:101]
	v_mfma_f32_16x16x32_bf16 v[86:89], v[222:225], v[200:203], v[86:89]
	v_mfma_f32_16x16x32_bf16 v[82:85], v[230:233], v[200:203], v[82:85]
	v_mfma_f32_16x16x32_bf16 v[70:73], v[222:225], v[214:217], v[70:73]
	v_mfma_f32_16x16x32_bf16 v[66:69], v[230:233], v[214:217], v[66:69]
	v_mfma_f32_16x16x32_bf16 v[122:125], v[226:229], v[188:191], v[122:125]
	v_mfma_f32_16x16x32_bf16 v[118:121], v[234:237], v[188:191], v[118:121]
	v_mfma_f32_16x16x32_bf16 v[102:105], v[226:229], v[196:199], v[102:105]
	v_mfma_f32_16x16x32_bf16 v[98:101], v[234:237], v[196:199], v[98:101]
	v_mfma_f32_16x16x32_bf16 v[86:89], v[226:229], v[204:207], v[86:89]
	v_mfma_f32_16x16x32_bf16 v[82:85], v[234:237], v[204:207], v[82:85]
	v_mfma_f32_16x16x32_bf16 v[70:73], v[226:229], v[218:221], v[70:73]
	v_mfma_f32_16x16x32_bf16 v[66:69], v[234:237], v[218:221], v[66:69]
	s_setprio 0
	s_mov_b32 m0, s11
	v_lshl_add_u64 v[164:165], s[16:17], 0, v[142:143]
	s_barrier
	ds_read_b128 v[180:183], v187 offset:16384
	ds_read_b128 v[188:191], v187 offset:17408
	ds_read_b128 v[192:195], v187 offset:18432
	ds_read_b128 v[196:199], v187 offset:19456
	ds_read_b128 v[200:203], v187 offset:20480
	ds_read_b128 v[204:207], v187 offset:21504
	ds_read_b128 v[214:217], v187 offset:22528
	ds_read_b128 v[218:221], v187 offset:23552
	global_load_lds_dwordx4 v[164:165], off
	v_lshl_add_u64 v[208:209], s[16:17], 0, v[144:145]
	s_mov_b32 m0, s66
	s_nop 0
	global_load_lds_dwordx4 v[208:209], off
	s_barrier
	s_waitcnt lgkmcnt(0)
	s_setprio 1
	v_mfma_f32_16x16x32_bf16 v[62:65], v[114:117], v[180:183], v[62:65]
	v_mfma_f32_16x16x32_bf16 v[58:61], v[130:133], v[180:183], v[58:61]
	v_mfma_f32_16x16x32_bf16 v[46:49], v[114:117], v[192:195], v[46:49]
	v_mfma_f32_16x16x32_bf16 v[42:45], v[130:133], v[192:195], v[42:45]
	v_mfma_f32_16x16x32_bf16 v[30:33], v[114:117], v[200:203], v[30:33]
	v_mfma_f32_16x16x32_bf16 v[26:29], v[130:133], v[200:203], v[26:29]
	v_mfma_f32_16x16x32_bf16 v[14:17], v[114:117], v[214:217], v[14:17]
	v_mfma_f32_16x16x32_bf16 v[10:13], v[130:133], v[214:217], v[10:13]
	v_mfma_f32_16x16x32_bf16 v[62:65], v[126:129], v[188:191], v[62:65]
	v_mfma_f32_16x16x32_bf16 v[58:61], v[176:179], v[188:191], v[58:61]
	v_mfma_f32_16x16x32_bf16 v[46:49], v[126:129], v[196:199], v[46:49]
	v_mfma_f32_16x16x32_bf16 v[42:45], v[176:179], v[196:199], v[42:45]
	v_mfma_f32_16x16x32_bf16 v[30:33], v[126:129], v[204:207], v[30:33]
	v_mfma_f32_16x16x32_bf16 v[26:29], v[176:179], v[204:207], v[26:29]
	v_mfma_f32_16x16x32_bf16 v[14:17], v[126:129], v[218:221], v[14:17]
	v_mfma_f32_16x16x32_bf16 v[10:13], v[176:179], v[218:221], v[10:13]
	s_setprio 0
	s_barrier
; #define PG8_STAGE(bufoff, gbase, voff) do { _Pragma("unroll") for (int _i = 0; _i < 2; ++_i) \
;         __builtin_amdgcn_global_load_lds((const unsigned*)((const char*)(gbase) + (voff)[_i]), (LAS unsigned*)(lds + (bufoff) + ldsw + _i * 8192), 16, 0, 0); } while (0)
; #define PG8_LDA(dst, b, h) do { _Pragma("unroll") for (int m = 0; m < 4; ++m) _Pragma("unroll") for (int k = 0; k < 2; ++k) dst[m][k] = *(const LAS bf16x8*)(lds + PG8_SA(b, h) + aoff + m * 2048 + k * 1024); } while (0)
; #define PG8_LDB(dst, b, h) do { _Pragma("unroll") for (int n = 0; n < 2; ++n) _Pragma("unroll") for (int k = 0; k < 2; ++k) dst[n][k] = *(const LAS bf16x8*)(lds + PG8_SB(b, h) + boff + n * 2048 + k * 1024); } while (0)
; #define PG8_MMA(ai, bj, At, Bt) do { __builtin_amdgcn_s_setprio(1); _Pragma("unroll") for (int m = 0; m < 4; ++m) _Pragma("unroll") for (int n = 0; n < 2; ++n) _Pragma("unroll") for (int k = 0; k < 2; ++k) \
;         acc[ai][bj][m][n] = __builtin_amdgcn_mfma_f32_16x16x32_bf16(Bt[n][k], At[m][k], acc[ai][bj][m][n], 0, 0, 0); __builtin_amdgcn_s_setprio(0); } while (0)
; #define PG8_WAIT_V(n) asm volatile("s_waitcnt vmcnt(" #n ")" ::: "memory")
; #define PG8_WAIT_L(n) asm volatile("s_waitcnt lgkmcnt(" #n ")" ::: "memory")
; #define PG8_BAR __builtin_amdgcn_s_barrier()
; #define PG8_SCHED __builtin_amdgcn_sched_barrier(0)
; template <class Epi>
; DEVI void gemm_phase(LAS unsigned char* lds, const Gemm g, const Epi& E) {
;     ...
;             PG8_STAGE(PG8_SB(0, 1), b2 + hstepB, voffB);
;             PG8_WAIT_V(6); PG8_BAR; PG8_MMA(1, 1, At, B1); PG8_BAR;
;             PG8_LDB(B0, 1, 0); PG8_SCHED; PG8_LDA(At, 1, 0); PG8_STAGE(PG8_SA(0, 1), a2 + hstepA, voffA);
;             PG8_WAIT_L(8); PG8_BAR; PG8_WAIT_L(0); PG8_MMA(0, 0, At, B0); PG8_BAR; PG8_SCHED;
;             PG8_LDB(B1, 1, 1); PG8_STAGE(PG8_SB(1, 0), b3, voffB);
;             PG8_BAR; PG8_WAIT_L(0); PG8_MMA(0, 1, At, B1); PG8_BAR;
;             PG8_LDA(At, 1, 1); PG8_STAGE(PG8_SA(1, 0), a3, voffA);
;             PG8_BAR; PG8_WAIT_L(0); PG8_MMA(1, 0, At, B0); PG8_BAR; PG8_SCHED;
	s_add_u32 s38, s14, 0x40000
	s_addc_u32 s39, s15, 0
	s_add_i32 s40, s40, s47
	v_lshl_add_u64 v[114:115], s[38:39], 0, v[8:9]
	s_mov_b32 m0, s40
	s_nop 0
	global_load_lds_dwordx4 v[114:115], off
	v_lshl_add_u64 v[114:115], s[38:39], 0, v[146:147]
	s_add_i32 m0, s40, 0x2000
	s_nop 0
	global_load_lds_dwordx4 v[114:115], off
	s_waitcnt vmcnt(6)
	s_barrier
	s_setprio 1
	v_mfma_f32_16x16x32_bf16 v[54:57], v[222:225], v[180:183], v[54:57]
	v_mfma_f32_16x16x32_bf16 v[50:53], v[230:233], v[180:183], v[50:53]
	v_mfma_f32_16x16x32_bf16 v[38:41], v[222:225], v[192:195], v[38:41]
	v_mfma_f32_16x16x32_bf16 v[34:37], v[230:233], v[192:195], v[34:37]
	v_mfma_f32_16x16x32_bf16 v[22:25], v[222:225], v[200:203], v[22:25]
	v_mfma_f32_16x16x32_bf16 v[18:21], v[230:233], v[200:203], v[18:21]
	v_mfma_f32_16x16x32_bf16 v[4:7], v[222:225], v[214:217], v[4:7]
	v_mfma_f32_16x16x32_bf16 v[0:3], v[230:233], v[214:217], v[0:3]
	v_mfma_f32_16x16x32_bf16 v[54:57], v[226:229], v[188:191], v[54:57]
	v_mfma_f32_16x16x32_bf16 v[50:53], v[234:237], v[188:191], v[50:53]
	v_mfma_f32_16x16x32_bf16 v[38:41], v[226:229], v[196:199], v[38:41]
	v_mfma_f32_16x16x32_bf16 v[34:37], v[234:237], v[196:199], v[34:37]
	v_mfma_f32_16x16x32_bf16 v[22:25], v[226:229], v[204:207], v[22:25]
	v_mfma_f32_16x16x32_bf16 v[18:21], v[234:237], v[204:207], v[18:21]
	v_mfma_f32_16x16x32_bf16 v[4:7], v[226:229], v[218:221], v[4:7]
	v_mfma_f32_16x16x32_bf16 v[0:3], v[234:237], v[218:221], v[0:3]
	s_setprio 0
	s_add_i32 s38, 0, 0x18000
	v_add_u32_e32 v176, s38, v185
	s_barrier
	ds_read_b128 v[114:117], v176
	ds_read_b128 v[126:129], v176 offset:1024
	ds_read_b128 v[130:133], v176 offset:2048
	ds_read_b128 v[176:179], v176 offset:3072
	s_add_u32 s16, s16, 0x40000
	s_addc_u32 s17, s17, 0
	s_mov_b32 m0, s68
	v_lshl_add_u64 v[222:223], s[16:17], 0, v[142:143]
	ds_read_b128 v[180:183], v187 offset:32768
	ds_read_b128 v[188:191], v187 offset:33792
	ds_read_b128 v[192:195], v187 offset:34816
	ds_read_b128 v[196:199], v187 offset:35840
	ds_read_b128 v[200:203], v187 offset:36864
	ds_read_b128 v[204:207], v187 offset:37888
	ds_read_b128 v[214:217], v187 offset:38912
	ds_read_b128 v[218:221], v187 offset:39936
	global_load_lds_dwordx4 v[222:223], off
	v_lshl_add_u64 v[222:223], s[16:17], 0, v[144:145]
	s_mov_b32 m0, s69
	s_nop 0
	global_load_lds_dwordx4 v[222:223], off
	s_waitcnt lgkmcnt(8)
	s_barrier
	s_waitcnt lgkmcnt(0)
	s_setprio 1
	v_mfma_f32_16x16x32_bf16 v[138:141], v[114:117], v[180:183], v[138:141]
	v_mfma_f32_16x16x32_bf16 v[134:137], v[130:133], v[180:183], v[134:137]
	v_mfma_f32_16x16x32_bf16 v[110:113], v[114:117], v[192:195], v[110:113]
	v_mfma_f32_16x16x32_bf16 v[106:109], v[130:133], v[192:195], v[106:109]
	v_mfma_f32_16x16x32_bf16 v[94:97], v[114:117], v[200:203], v[94:97]
	v_mfma_f32_16x16x32_bf16 v[90:93], v[130:133], v[200:203], v[90:93]
	v_mfma_f32_16x16x32_bf16 v[78:81], v[114:117], v[214:217], v[78:81]
	v_mfma_f32_16x16x32_bf16 v[74:77], v[130:133], v[214:217], v[74:77]
	v_mfma_f32_16x16x32_bf16 v[138:141], v[126:129], v[188:191], v[138:141]
	v_mfma_f32_16x16x32_bf16 v[134:137], v[176:179], v[188:191], v[134:137]
	v_mfma_f32_16x16x32_bf16 v[110:113], v[126:129], v[196:199], v[110:113]
	v_mfma_f32_16x16x32_bf16 v[106:109], v[176:179], v[196:199], v[106:109]
	v_mfma_f32_16x16x32_bf16 v[94:97], v[126:129], v[204:207], v[94:97]
	v_mfma_f32_16x16x32_bf16 v[90:93], v[176:179], v[204:207], v[90:93]
	v_mfma_f32_16x16x32_bf16 v[78:81], v[126:129], v[218:221], v[78:81]
	v_mfma_f32_16x16x32_bf16 v[74:77], v[176:179], v[218:221], v[74:77]
	s_setprio 0
	s_barrier
	s_add_i32 s16, 0, 0x1c000
	s_add_i32 s17, s38, s47
	v_add_u32_e32 v213, s16, v185
	v_lshl_add_u64 v[152:153], v[152:153], 0, s[70:71]
	s_mov_b32 m0, s17
	ds_read_b128 v[222:225], v213
	ds_read_b128 v[226:229], v213 offset:1024
	ds_read_b128 v[230:233], v213 offset:2048
	ds_read_b128 v[234:237], v213 offset:3072
	global_load_lds_dwordx4 v[152:153], off
	v_lshl_add_u64 v[152:153], v[162:163], 0, s[70:71]
	s_add_i32 m0, s17, 0x2000
	s_nop 0
	global_load_lds_dwordx4 v[152:153], off
	s_barrier
	s_waitcnt lgkmcnt(0)
	s_setprio 1
	v_mfma_f32_16x16x32_bf16 v[122:125], v[222:225], v[180:183], v[122:125]
	v_mfma_f32_16x16x32_bf16 v[118:121], v[230:233], v[180:183], v[118:121]
	v_mfma_f32_16x16x32_bf16 v[102:105], v[222:225], v[192:195], v[102:105]
	v_mfma_f32_16x16x32_bf16 v[98:101], v[230:233], v[192:195], v[98:101]
	v_mfma_f32_16x16x32_bf16 v[86:89], v[222:225], v[200:203], v[86:89]
	v_mfma_f32_16x16x32_bf16 v[82:85], v[230:233], v[200:203], v[82:85]
	v_mfma_f32_16x16x32_bf16 v[70:73], v[222:225], v[214:217], v[70:73]
	v_mfma_f32_16x16x32_bf16 v[66:69], v[230:233], v[214:217], v[66:69]
	v_mfma_f32_16x16x32_bf16 v[122:125], v[226:229], v[188:191], v[122:125]
	v_mfma_f32_16x16x32_bf16 v[118:121], v[234:237], v[188:191], v[118:121]
	v_mfma_f32_16x16x32_bf16 v[102:105], v[226:229], v[196:199], v[102:105]
	v_mfma_f32_16x16x32_bf16 v[98:101], v[234:237], v[196:199], v[98:101]
	v_mfma_f32_16x16x32_bf16 v[86:89], v[226:229], v[204:207], v[86:89]
	v_mfma_f32_16x16x32_bf16 v[82:85], v[234:237], v[204:207], v[82:85]
	v_mfma_f32_16x16x32_bf16 v[70:73], v[226:229], v[218:221], v[70:73]
	v_mfma_f32_16x16x32_bf16 v[66:69], v[234:237], v[218:221], v[66:69]
	s_setprio 0
	s_mov_b32 m0, s80
	v_lshl_add_u64 v[152:153], v[164:165], 0, s[70:71]
	s_barrier
	ds_read_b128 v[180:183], v187 offset:49152
	ds_read_b128 v[188:191], v187 offset:50176
	ds_read_b128 v[192:195], v187 offset:51200
	ds_read_b128 v[196:199], v187 offset:52224
	ds_read_b128 v[200:203], v187 offset:53248
	ds_read_b128 v[204:207], v187 offset:54272
	ds_read_b128 v[214:217], v187 offset:55296
	ds_read_b128 v[218:221], v187 offset:56320
	global_load_lds_dwordx4 v[152:153], off
	v_lshl_add_u64 v[152:153], v[208:209], 0, s[70:71]
	s_mov_b32 m0, s81
	s_nop 0
	global_load_lds_dwordx4 v[152:153], off
	s_barrier
; #define PG8_STAGE(bufoff, gbase, voff) do { _Pragma("unroll") for (int _i = 0; _i < 2; ++_i) \
;         __builtin_amdgcn_global_load_lds((const unsigned*)((const char*)(gbase) + (voff)[_i]), (LAS unsigned*)(lds + (bufoff) + ldsw + _i * 8192), 16, 0, 0); } while (0)
; #define PG8_MMA(ai, bj, At, Bt) do { __builtin_amdgcn_s_setprio(1); _Pragma("unroll") for (int m = 0; m < 4; ++m) _Pragma("unroll") for (int n = 0; n < 2; ++n) _Pragma("unroll") for (int k = 0; k < 2; ++k) \
;         acc[ai][bj][m][n] = __builtin_amdgcn_mfma_f32_16x16x32_bf16(Bt[n][k], At[m][k], acc[ai][bj][m][n], 0, 0, 0); __builtin_amdgcn_s_setprio(0); } while (0)
; #define PG8_WAIT_V(n) asm volatile("s_waitcnt vmcnt(" #n ")" ::: "memory")
; #define PG8_WAIT_L(n) asm volatile("s_waitcnt lgkmcnt(" #n ")" ::: "memory")
; #define PG8_BAR __builtin_amdgcn_s_barrier()
; #define PG8_SCHED __builtin_amdgcn_sched_barrier(0)
;     DEVI f32x4 load(int r, int c) const { const bf16x4 y = *(const bf16x4*)(Y + (size_t)r * DM + c); return (f32x4){bf2f((u16)y[0]), bf2f((u16)y[1]), bf2f((u16)y[2]), bf2f((u16)y[3])}; }
; template <class Epi>
; DEVI void gemm_phase(LAS unsigned char* lds, const Gemm g, const Epi& E) {
;     ...
;             PG8_BAR; PG8_WAIT_L(0); PG8_MMA(1, 0, At, B0); PG8_BAR; PG8_SCHED;
;             PG8_STAGE(PG8_SB(1, 1), b3 + hstepB, voffB);
;             PG8_WAIT_V(6); PG8_BAR; PG8_MMA(1, 1, At, B1); PG8_BAR;
;     ...
;                 if constexpr (Epi::PRE) {
; #pragma unroll
;                     for (int m = 0; m < 2; ++m)
; #pragma unroll
;                         for (int bj = 0; bj < 2; ++bj)
; #pragma unroll
;                             for (int n = 0; n < 2; ++n) pre[m][bj][n] = E.load(row0 + ai * HALF + (m0 + m) * 16, col0 + bj * HALF + n * NST);
	s_waitcnt lgkmcnt(0)
	s_setprio 1
	v_mfma_f32_16x16x32_bf16 v[62:65], v[114:117], v[180:183], v[62:65]
	v_mfma_f32_16x16x32_bf16 v[58:61], v[130:133], v[180:183], v[58:61]
	v_mfma_f32_16x16x32_bf16 v[46:49], v[114:117], v[192:195], v[46:49]
	v_mfma_f32_16x16x32_bf16 v[42:45], v[130:133], v[192:195], v[42:45]
	v_mfma_f32_16x16x32_bf16 v[30:33], v[114:117], v[200:203], v[30:33]
	v_mfma_f32_16x16x32_bf16 v[26:29], v[130:133], v[200:203], v[26:29]
	v_mfma_f32_16x16x32_bf16 v[14:17], v[114:117], v[214:217], v[14:17]
	v_mfma_f32_16x16x32_bf16 v[10:13], v[130:133], v[214:217], v[10:13]
	v_mfma_f32_16x16x32_bf16 v[62:65], v[126:129], v[188:191], v[62:65]
	v_mfma_f32_16x16x32_bf16 v[58:61], v[176:179], v[188:191], v[58:61]
	v_mfma_f32_16x16x32_bf16 v[46:49], v[126:129], v[196:199], v[46:49]
	v_mfma_f32_16x16x32_bf16 v[42:45], v[176:179], v[196:199], v[42:45]
	v_mfma_f32_16x16x32_bf16 v[30:33], v[126:129], v[204:207], v[30:33]
	v_mfma_f32_16x16x32_bf16 v[26:29], v[176:179], v[204:207], v[26:29]
	v_mfma_f32_16x16x32_bf16 v[14:17], v[126:129], v[218:221], v[14:17]
	v_mfma_f32_16x16x32_bf16 v[10:13], v[176:179], v[218:221], v[10:13]
	s_setprio 0
	s_barrier
	s_add_u32 s14, s14, 0x40080
	s_addc_u32 s15, s15, 0
	s_add_i32 s16, s16, s47
	v_lshl_add_u64 v[114:115], s[14:15], 0, v[8:9]
	s_mov_b32 m0, s16
	s_nop 0
	global_load_lds_dwordx4 v[114:115], off
	v_lshl_add_u64 v[114:115], s[14:15], 0, v[146:147]
	s_add_i32 m0, s16, 0x2000
	s_nop 0
	global_load_lds_dwordx4 v[114:115], off
	s_waitcnt vmcnt(6)
	s_barrier
	s_setprio 1
	v_mfma_f32_16x16x32_bf16 v[54:57], v[222:225], v[180:183], v[54:57]
	v_mfma_f32_16x16x32_bf16 v[50:53], v[230:233], v[180:183], v[50:53]
	v_mfma_f32_16x16x32_bf16 v[38:41], v[222:225], v[192:195], v[38:41]
	v_mfma_f32_16x16x32_bf16 v[34:37], v[230:233], v[192:195], v[34:37]
	v_mfma_f32_16x16x32_bf16 v[22:25], v[222:225], v[200:203], v[22:25]
	v_mfma_f32_16x16x32_bf16 v[18:21], v[230:233], v[200:203], v[18:21]
	v_mfma_f32_16x16x32_bf16 v[4:7], v[222:225], v[214:217], v[4:7]
	v_mfma_f32_16x16x32_bf16 v[0:3], v[230:233], v[214:217], v[0:3]
	v_mfma_f32_16x16x32_bf16 v[54:57], v[226:229], v[188:191], v[54:57]
	v_mfma_f32_16x16x32_bf16 v[50:53], v[234:237], v[188:191], v[50:53]
	v_mfma_f32_16x16x32_bf16 v[38:41], v[226:229], v[196:199], v[38:41]
	v_mfma_f32_16x16x32_bf16 v[34:37], v[234:237], v[196:199], v[34:37]
	v_mfma_f32_16x16x32_bf16 v[22:25], v[226:229], v[204:207], v[22:25]
	v_mfma_f32_16x16x32_bf16 v[18:21], v[234:237], v[204:207], v[18:21]
	v_mfma_f32_16x16x32_bf16 v[4:7], v[226:229], v[218:221], v[4:7]
	v_mfma_f32_16x16x32_bf16 v[0:3], v[234:237], v[218:221], v[0:3]
	s_setprio 0
	s_add_i32 s27, s27, 2
	s_add_u32 s12, s12, 0x100
	s_addc_u32 s13, s13, 0
	s_add_u32 s19, s19, 0x100
	s_addc_u32 s26, s26, 0
	s_cmp_gt_u32 s27, 13
	s_barrier
	s_cbranch_scc0 .LBB0_1346
	v_lshl_add_u32 v180, s10, 8, v184
	v_lshl_or_b32 v152, s0, 8, v186
	v_ashrrev_i32_e32 v181, 31, v180
	v_lshlrev_b64 v[178:179], 11, v[180:181]
	v_ashrrev_i32_e32 v153, 31, v152
	v_lshl_add_u64 v[114:115], s[24:25], 0, v[178:179]
	v_lshlrev_b64 v[176:177], 1, v[152:153]
	v_lshl_add_u64 v[114:115], v[114:115], 0, v[176:177]
	global_load_dwordx4 v[188:191], v[114:115], off
	global_load_dwordx4 v[130:133], v[114:115], off offset:256
	v_or_b32_e32 v114, 16, v180
	v_ashrrev_i32_e32 v115, 31, v114
	v_lshlrev_b64 v[182:183], 11, v[114:115]
	v_readlane_b32 s48, v251, 40
	v_lshl_add_u64 v[114:115], s[24:25], 0, v[182:183]
	v_readlane_b32 s54, v251, 46
	v_readlane_b32 s55, v251, 47
	v_lshl_add_u64 v[114:115], v[114:115], 0, v[176:177]
	global_load_dwordx4 v[126:129], v[114:115], off
	s_nop 0
	global_load_dwordx4 v[114:117], v[114:115], off offset:256
	v_lshl_add_u64 v[152:153], v[152:153], 2, s[54:55]
	global_load_dwordx4 v[214:217], v[152:153], off
	global_load_dwordx4 v[218:221], v[152:153], off offset:16
	global_load_dwordx4 v[222:225], v[152:153], off offset:512
	global_load_dwordx4 v[226:229], v[152:153], off offset:528
	s_mov_b64 s[0:1], 0x40000
	v_readlane_b32 s52, v251, 44
	v_readlane_b32 s56, v251, 48
	v_readlane_b32 s57, v251, 49
	v_readlane_b32 s58, v251, 50
	v_readlane_b32 s59, v251, 51
	v_readlane_b32 s60, v251, 52
	v_readlane_b32 s61, v251, 53
	v_readlane_b32 s62, v251, 54
	v_readlane_b32 s63, v251, 55
	s_and_b64 vcc, exec, s[36:37]
	s_mov_b32 s10, s2
	s_mov_b64 s[14:15], s[8:9]
	s_mov_b64 s[12:13], s[6:7]
	s_mov_b64 s[56:57], s[42:43]
	s_mov_b64 s[58:59], s[44:45]
	s_mov_b32 s60, s41
	s_mov_b32 s61, s83
	s_mov_b32 s62, s84
	s_mov_b32 s63, s85
	v_readlane_b32 s55, v254, 0
	s_movk_i32 s52, 0x110
	v_readlane_b32 s49, v251, 41
	v_readlane_b32 s50, v251, 42
	v_readlane_b32 s51, v251, 43
	v_readlane_b32 s53, v251, 45
	v_readlane_b32 s40, v254, 1
	s_waitcnt vmcnt(0)
; DEVI float bf2f(u16 b) { return __uint_as_float(((unsigned)b) << 16); }
;     DEVI f32x4 load(int r, int c) const { const bf16x4 y = *(const bf16x4*)(Y + (size_t)r * DM + c); return (f32x4){bf2f((u16)y[0]), bf2f((u16)y[1]), bf2f((u16)y[2]), bf2f((u16)y[3])}; }
	v_and_b32_e32 v163, 0xffff0000, v188
	v_lshlrev_b32_e32 v162, 16, v188
	v_add_f32_e32 v134, v134, v218
	v_add_f32_e32 v138, v138, v214
	v_add_f32_e32 v139, v139, v215
	v_mul_f32_e32 v138, 0xbfb8aa3b, v138
	v_mul_f32_e32 v139, 0xbfb8aa3b, v139
	v_add_f32_e32 v135, v135, v219
	v_exp_f32_e32 v138, v138
	v_mul_f32_e32 v134, 0xbfb8aa3b, v134
	v_exp_f32_e32 v139, v139
	v_mul_f32_e32 v135, 0xbfb8aa3b, v135
	v_exp_f32_e32 v134, v134
	v_exp_f32_e32 v135, v135
	v_add_f32_e32 v138, 1.0, v138
	v_add_f32_e32 v139, 1.0, v139
	v_rcp_f32_e32 v138, v138
	v_add_f32_e32 v134, 1.0, v134
	v_rcp_f32_e32 v139, v139
	v_add_f32_e32 v135, 1.0, v135
	v_rcp_f32_e32 v134, v134
	v_rcp_f32_e32 v135, v135
	v_pk_mul_f32 v[138:139], v[138:139], v[162:163]
	v_and_b32_e32 v163, 0xffff0000, v190
	v_lshlrev_b32_e32 v162, 16, v190
	v_pk_mul_f32 v[162:163], v[134:135], v[162:163]
	v_add_f32_e32 v135, v136, v220
	v_mul_f32_e32 v135, 0xbfb8aa3b, v135
	v_exp_f32_e32 v135, v135
	v_add_f32_e32 v134, v140, v216
	v_mul_f32_e32 v134, 0xbfb8aa3b, v134
	v_exp_f32_e32 v134, v134
	v_add_f32_e32 v135, 1.0, v135
	v_rcp_f32_e32 v136, v135
	v_add_f32_e32 v135, v141, v217
	v_mul_f32_e32 v135, 0xbfb8aa3b, v135
	v_exp_f32_e32 v135, v135
	v_add_f32_e32 v134, 1.0, v134
	v_rcp_f32_e32 v134, v134
	v_and_b32_e32 v141, 0xffff0000, v189
	v_add_f32_e32 v135, 1.0, v135
	v_rcp_f32_e32 v135, v135
	v_lshlrev_b32_e32 v140, 16, v189
	v_pk_mul_f32 v[140:141], v[134:135], v[140:141]
	v_add_f32_e32 v134, v137, v221
	v_mul_f32_e32 v134, 0xbfb8aa3b, v134
	v_exp_f32_e32 v134, v134
	v_and_b32_e32 v135, 0xffff0000, v191
	v_add_f32_e32 v134, 1.0, v134
	v_rcp_f32_e32 v137, v134
	v_lshlrev_b32_e32 v134, 16, v191
	v_pk_mul_f32 v[164:165], v[136:137], v[134:135]
	v_cvt_pk_bf16_f32 v134, v138, v139
	v_lshl_add_u64 v[138:139], s[64:65], 0, v[178:179]
	v_cvt_pk_bf16_f32 v135, v140, v141
	v_cvt_pk_bf16_f32 v136, v162, v163
	v_cvt_pk_bf16_f32 v137, v164, v165
	v_lshl_add_u64 v[138:139], v[138:139], 0, v[176:177]
	global_store_dwordx4 v[138:139], v[134:137], off
	s_nop 0
	v_and_b32_e32 v141, 0xffff0000, v130
	v_lshlrev_b32_e32 v140, 16, v130
	v_lshlrev_b32_e32 v130, 16, v133
	v_add_f32_e32 v118, v118, v226
	v_add_f32_e32 v119, v119, v227
	v_add_f32_e32 v122, v122, v222
	v_mul_f32_e32 v118, 0xbfb8aa3b, v118
	v_add_f32_e32 v123, v123, v223
	v_mul_f32_e32 v119, 0xbfb8aa3b, v119
	v_add_f32_e32 v124, v124, v224
	v_add_f32_e32 v120, v120, v228
	v_add_f32_e32 v125, v125, v225
	v_add_f32_e32 v121, v121, v229
	v_mul_f32_e32 v122, 0xbfb8aa3b, v122
	v_exp_f32_e32 v118, v118
	v_mul_f32_e32 v123, 0xbfb8aa3b, v123
	v_exp_f32_e32 v119, v119
	v_mul_f32_e32 v124, 0xbfb8aa3b, v124
	v_mul_f32_e32 v120, 0xbfb8aa3b, v120
	v_mul_f32_e32 v125, 0xbfb8aa3b, v125
	v_mul_f32_e32 v121, 0xbfb8aa3b, v121
	v_exp_f32_e32 v122, v122
	v_exp_f32_e32 v123, v123
	v_exp_f32_e32 v124, v124
	v_exp_f32_e32 v120, v120
	v_exp_f32_e32 v125, v125
	v_exp_f32_e32 v121, v121
	v_add_f32_e32 v118, 1.0, v118
	v_add_f32_e32 v119, 1.0, v119
	v_add_f32_e32 v122, 1.0, v122
	v_rcp_f32_e32 v118, v118
	v_add_f32_e32 v123, 1.0, v123
	v_rcp_f32_e32 v119, v119
	v_add_f32_e32 v124, 1.0, v124
	v_add_f32_e32 v120, 1.0, v120
	v_add_f32_e32 v125, 1.0, v125
	v_add_f32_e32 v121, 1.0, v121
	v_rcp_f32_e32 v122, v122
	v_rcp_f32_e32 v123, v123
	v_rcp_f32_e32 v124, v124
	v_rcp_f32_e32 v120, v120
	v_rcp_f32_e32 v125, v125
	v_rcp_f32_e32 v121, v121
	v_and_b32_e32 v135, 0xffff0000, v132
	v_lshlrev_b32_e32 v134, 16, v132
	v_pk_mul_f32 v[118:119], v[118:119], v[134:135]
	v_and_b32_e32 v135, 0xffff0000, v131
	v_lshlrev_b32_e32 v134, 16, v131
	v_and_b32_e32 v131, 0xffff0000, v133
	v_pk_mul_f32 v[122:123], v[122:123], v[140:141]
	v_pk_mul_f32 v[124:125], v[124:125], v[134:135]
	v_pk_mul_f32 v[130:131], v[120:121], v[130:131]
	v_cvt_pk_bf16_f32 v120, v122, v123
	v_cvt_pk_bf16_f32 v121, v124, v125
	v_cvt_pk_bf16_f32 v122, v118, v119
	v_cvt_pk_bf16_f32 v123, v130, v131
	global_store_dwordx4 v[138:139], v[120:123], off offset:256
	s_nop 0
	v_add_f32_e32 v106, v106, v218
	v_add_f32_e32 v107, v107, v219
	v_mul_f32_e32 v106, 0xbfb8aa3b, v106
	v_mul_f32_e32 v107, 0xbfb8aa3b, v107
	v_exp_f32_e32 v106, v106
	v_exp_f32_e32 v107, v107
	v_and_b32_e32 v119, 0xffff0000, v128
	v_lshlrev_b32_e32 v118, 16, v128
	v_add_f32_e32 v106, 1.0, v106
	v_add_f32_e32 v107, 1.0, v107
	v_rcp_f32_e32 v106, v106
	v_rcp_f32_e32 v107, v107
	v_add_f32_e32 v110, v110, v214
	v_add_f32_e32 v111, v111, v215
	v_mul_f32_e32 v110, 0xbfb8aa3b, v110
	v_pk_mul_f32 v[118:119], v[106:107], v[118:119]
	v_add_f32_e32 v107, v108, v220
	v_mul_f32_e32 v107, 0xbfb8aa3b, v107
	v_exp_f32_e32 v107, v107
	v_add_f32_e32 v106, v112, v216
	v_mul_f32_e32 v106, 0xbfb8aa3b, v106
	v_exp_f32_e32 v106, v106
	v_add_f32_e32 v107, 1.0, v107
	v_rcp_f32_e32 v108, v107
	v_add_f32_e32 v107, v113, v217
	v_mul_f32_e32 v107, 0xbfb8aa3b, v107
	v_exp_f32_e32 v107, v107
	v_add_f32_e32 v106, 1.0, v106
	v_rcp_f32_e32 v106, v106
	v_and_b32_e32 v113, 0xffff0000, v127
	v_add_f32_e32 v107, 1.0, v107
	v_rcp_f32_e32 v107, v107
	v_lshlrev_b32_e32 v112, 16, v127
	v_mul_f32_e32 v111, 0xbfb8aa3b, v111
	v_exp_f32_e32 v110, v110
	v_pk_mul_f32 v[112:113], v[106:107], v[112:113]
	v_add_f32_e32 v106, v109, v221
	v_exp_f32_e32 v111, v111
	v_mul_f32_e32 v106, 0xbfb8aa3b, v106
	v_exp_f32_e32 v106, v106
	v_add_f32_e32 v110, 1.0, v110
	v_add_f32_e32 v111, 1.0, v111
	v_rcp_f32_e32 v110, v110
	v_rcp_f32_e32 v111, v111
	v_add_f32_e32 v106, 1.0, v106
	v_rcp_f32_e32 v109, v106
	v_and_b32_e32 v123, 0xffff0000, v126
	v_lshlrev_b32_e32 v122, 16, v126
	v_pk_mul_f32 v[110:111], v[110:111], v[122:123]
	v_and_b32_e32 v107, 0xffff0000, v129
	v_lshlrev_b32_e32 v106, 16, v129
	v_pk_mul_f32 v[120:121], v[108:109], v[106:107]
; DEVI float bf2f(u16 b) { return __uint_as_float(((unsigned)b) << 16); }
; template <class Epi>
; DEVI void gemm_phase(LAS unsigned char* lds, const Gemm g, const Epi& E) {
;     ...
;                 if constexpr (Epi::PRE) {
; #pragma unroll
;                     for (int m = 0; m < 2; ++m)
; #pragma unroll
;                         for (int bj = 0; bj < 2; ++bj)
; #pragma unroll
;                             for (int n = 0; n < 2; ++n) pre[m][bj][n] = E.load(row0 + ai * HALF + (m0 + m) * 16, col0 + bj * HALF + n * NST);
;     DEVI f32x4 load(int r, int c) const { const bf16x4 y = *(const bf16x4*)(Y + (size_t)r * DM + c); return (f32x4){bf2f((u16)y[0]), bf2f((u16)y[1]), bf2f((u16)y[2]), bf2f((u16)y[3])}; }
	v_cvt_pk_bf16_f32 v106, v110, v111
	v_lshl_add_u64 v[110:111], s[64:65], 0, v[182:183]
	v_cvt_pk_bf16_f32 v107, v112, v113
	v_cvt_pk_bf16_f32 v108, v118, v119
	v_cvt_pk_bf16_f32 v109, v120, v121
	v_lshl_add_u64 v[110:111], v[110:111], 0, v[176:177]
	global_store_dwordx4 v[110:111], v[106:109], off
	s_nop 0
	v_and_b32_e32 v113, 0xffff0000, v114
	v_lshlrev_b32_e32 v112, 16, v114
	v_add_f32_e32 v98, v98, v226
	v_add_f32_e32 v99, v99, v227
	v_mul_f32_e32 v98, 0xbfb8aa3b, v98
	v_mul_f32_e32 v99, 0xbfb8aa3b, v99
	v_exp_f32_e32 v98, v98
	v_exp_f32_e32 v99, v99
	v_and_b32_e32 v107, 0xffff0000, v116
	v_lshlrev_b32_e32 v106, 16, v116
	v_add_f32_e32 v98, 1.0, v98
	v_add_f32_e32 v99, 1.0, v99
	v_rcp_f32_e32 v98, v98
	v_rcp_f32_e32 v99, v99
	v_add_f32_e32 v102, v102, v222
	v_add_f32_e32 v103, v103, v223
	v_mul_f32_e32 v102, 0xbfb8aa3b, v102
	v_pk_mul_f32 v[106:107], v[98:99], v[106:107]
	v_add_f32_e32 v99, v100, v228
	v_mul_f32_e32 v99, 0xbfb8aa3b, v99
	v_exp_f32_e32 v99, v99
	v_add_f32_e32 v98, v104, v224
	v_mul_f32_e32 v98, 0xbfb8aa3b, v98
	v_exp_f32_e32 v98, v98
	v_add_f32_e32 v99, 1.0, v99
	v_rcp_f32_e32 v100, v99
	v_add_f32_e32 v99, v105, v225
	v_mul_f32_e32 v99, 0xbfb8aa3b, v99
	v_exp_f32_e32 v99, v99
	v_add_f32_e32 v98, 1.0, v98
	v_rcp_f32_e32 v98, v98
	v_and_b32_e32 v105, 0xffff0000, v115
	v_add_f32_e32 v99, 1.0, v99
	v_rcp_f32_e32 v99, v99
	v_lshlrev_b32_e32 v104, 16, v115
	v_mul_f32_e32 v103, 0xbfb8aa3b, v103
	v_exp_f32_e32 v102, v102
	v_pk_mul_f32 v[104:105], v[98:99], v[104:105]
	v_add_f32_e32 v98, v101, v229
	v_mul_f32_e32 v98, 0xbfb8aa3b, v98
	v_exp_f32_e32 v103, v103
	v_exp_f32_e32 v98, v98
	v_add_f32_e32 v102, 1.0, v102
	v_rcp_f32_e32 v102, v102
	v_add_f32_e32 v103, 1.0, v103
	v_add_f32_e32 v98, 1.0, v98
	v_rcp_f32_e32 v103, v103
	v_rcp_f32_e32 v101, v98
	v_and_b32_e32 v99, 0xffff0000, v117
	v_lshlrev_b32_e32 v98, 16, v117
	v_pk_mul_f32 v[102:103], v[102:103], v[112:113]
	v_pk_mul_f32 v[108:109], v[100:101], v[98:99]
	v_cvt_pk_bf16_f32 v98, v102, v103
	v_cvt_pk_bf16_f32 v99, v104, v105
	v_cvt_pk_bf16_f32 v100, v106, v107
	v_cvt_pk_bf16_f32 v101, v108, v109
	global_store_dwordx4 v[110:111], v[98:101], off offset:256
	s_nop 1
	v_or_b32_e32 v98, 32, v180
	v_ashrrev_i32_e32 v99, 31, v98
	v_lshlrev_b64 v[120:121], 11, v[98:99]
	v_lshl_add_u64 v[98:99], s[24:25], 0, v[120:121]
	v_lshl_add_u64 v[98:99], v[98:99], 0, v[176:177]
	global_load_dwordx4 v[110:113], v[98:99], off
	global_load_dwordx4 v[106:109], v[98:99], off offset:256
	v_or_b32_e32 v98, 48, v180
	v_ashrrev_i32_e32 v99, 31, v98
	v_lshlrev_b64 v[118:119], 11, v[98:99]
	v_lshl_add_u64 v[98:99], s[24:25], 0, v[118:119]
	v_lshl_add_u64 v[98:99], v[98:99], 0, v[176:177]
	global_load_dwordx4 v[102:105], v[98:99], off
	s_nop 0
	global_load_dwordx4 v[98:101], v[98:99], off offset:256
	s_nop 0
	s_waitcnt vmcnt(0)
	v_add_f32_e32 v90, v90, v218
	v_add_f32_e32 v91, v91, v219
	v_mul_f32_e32 v90, 0xbfb8aa3b, v90
	v_mul_f32_e32 v91, 0xbfb8aa3b, v91
	v_exp_f32_e32 v90, v90
	v_exp_f32_e32 v91, v91
	v_and_b32_e32 v115, 0xffff0000, v112
	v_lshlrev_b32_e32 v114, 16, v112
	v_add_f32_e32 v90, 1.0, v90
	v_add_f32_e32 v91, 1.0, v91
	v_rcp_f32_e32 v90, v90
	v_rcp_f32_e32 v91, v91
	v_add_f32_e32 v94, v94, v214
	v_add_f32_e32 v95, v95, v215
	v_mul_f32_e32 v94, 0xbfb8aa3b, v94
	v_pk_mul_f32 v[114:115], v[90:91], v[114:115]
	v_add_f32_e32 v91, v92, v220
	v_mul_f32_e32 v91, 0xbfb8aa3b, v91
	v_exp_f32_e32 v91, v91
	v_add_f32_e32 v90, v96, v216
	v_mul_f32_e32 v90, 0xbfb8aa3b, v90
	v_exp_f32_e32 v90, v90
	v_add_f32_e32 v91, 1.0, v91
	v_rcp_f32_e32 v92, v91
	v_add_f32_e32 v91, v97, v217
	v_mul_f32_e32 v91, 0xbfb8aa3b, v91
	v_exp_f32_e32 v91, v91
	v_add_f32_e32 v90, 1.0, v90
	v_rcp_f32_e32 v90, v90
	v_and_b32_e32 v97, 0xffff0000, v111
	v_add_f32_e32 v91, 1.0, v91
	v_rcp_f32_e32 v91, v91
	v_lshlrev_b32_e32 v96, 16, v111
	v_mul_f32_e32 v95, 0xbfb8aa3b, v95
	v_exp_f32_e32 v94, v94
	v_pk_mul_f32 v[96:97], v[90:91], v[96:97]
	v_add_f32_e32 v90, v93, v221
	v_exp_f32_e32 v95, v95
	v_mul_f32_e32 v90, 0xbfb8aa3b, v90
	v_exp_f32_e32 v90, v90
	v_add_f32_e32 v94, 1.0, v94
	v_add_f32_e32 v95, 1.0, v95
	v_rcp_f32_e32 v94, v94
	v_rcp_f32_e32 v95, v95
	v_add_f32_e32 v90, 1.0, v90
	v_rcp_f32_e32 v93, v90
	v_and_b32_e32 v123, 0xffff0000, v110
	v_lshlrev_b32_e32 v122, 16, v110
	v_pk_mul_f32 v[94:95], v[94:95], v[122:123]
	v_and_b32_e32 v91, 0xffff0000, v113
	v_lshlrev_b32_e32 v90, 16, v113
	v_pk_mul_f32 v[110:111], v[92:93], v[90:91]
	v_cvt_pk_bf16_f32 v90, v94, v95
	v_lshl_add_u64 v[94:95], s[64:65], 0, v[120:121]
	v_cvt_pk_bf16_f32 v91, v96, v97
	v_cvt_pk_bf16_f32 v92, v114, v115
	v_cvt_pk_bf16_f32 v93, v110, v111
	v_lshl_add_u64 v[94:95], v[94:95], 0, v[176:177]
	global_store_dwordx4 v[94:95], v[90:93], off
	s_nop 0
	v_and_b32_e32 v97, 0xffff0000, v106
	v_lshlrev_b32_e32 v96, 16, v106
	v_add_f32_e32 v82, v82, v226
	v_add_f32_e32 v83, v83, v227
	v_mul_f32_e32 v82, 0xbfb8aa3b, v82
	v_mul_f32_e32 v83, 0xbfb8aa3b, v83
	v_add_f32_e32 v88, v88, v224
	v_add_f32_e32 v89, v89, v225
	v_add_f32_e32 v86, v86, v222
	v_exp_f32_e32 v82, v82
	v_add_f32_e32 v87, v87, v223
	v_exp_f32_e32 v83, v83
	v_mul_f32_e32 v88, 0xbfb8aa3b, v88
	v_add_f32_e32 v84, v84, v228
	v_mul_f32_e32 v89, 0xbfb8aa3b, v89
	v_add_f32_e32 v85, v85, v229
	v_mul_f32_e32 v86, 0xbfb8aa3b, v86
	v_mul_f32_e32 v87, 0xbfb8aa3b, v87
	v_exp_f32_e32 v88, v88
	v_mul_f32_e32 v84, 0xbfb8aa3b, v84
	v_exp_f32_e32 v89, v89
	v_mul_f32_e32 v85, 0xbfb8aa3b, v85
	v_exp_f32_e32 v86, v86
	v_exp_f32_e32 v87, v87
	v_exp_f32_e32 v84, v84
	v_exp_f32_e32 v85, v85
	v_add_f32_e32 v82, 1.0, v82
	v_add_f32_e32 v83, 1.0, v83
	v_rcp_f32_e32 v82, v82
	v_rcp_f32_e32 v83, v83
	v_add_f32_e32 v88, 1.0, v88
; DEVI float bf2f(u16 b) { return __uint_as_float(((unsigned)b) << 16); }
; template <class Epi>
; DEVI void gemm_phase(LAS unsigned char* lds, const Gemm g, const Epi& E) {
;     ...
;                 if constexpr (Epi::PRE) {
; #pragma unroll
;                     for (int m = 0; m < 2; ++m)
; #pragma unroll
;                         for (int bj = 0; bj < 2; ++bj)
; #pragma unroll
;                             for (int n = 0; n < 2; ++n) pre[m][bj][n] = E.load(row0 + ai * HALF + (m0 + m) * 16, col0 + bj * HALF + n * NST);
;     DEVI f32x4 load(int r, int c) const { const bf16x4 y = *(const bf16x4*)(Y + (size_t)r * DM + c); return (f32x4){bf2f((u16)y[0]), bf2f((u16)y[1]), bf2f((u16)y[2]), bf2f((u16)y[3])}; }
	v_add_f32_e32 v89, 1.0, v89
	v_add_f32_e32 v86, 1.0, v86
	v_add_f32_e32 v87, 1.0, v87
	v_rcp_f32_e32 v88, v88
	v_add_f32_e32 v84, 1.0, v84
	v_rcp_f32_e32 v89, v89
	v_add_f32_e32 v85, 1.0, v85
	v_rcp_f32_e32 v86, v86
	v_rcp_f32_e32 v87, v87
	v_rcp_f32_e32 v84, v84
	v_rcp_f32_e32 v85, v85
	v_and_b32_e32 v91, 0xffff0000, v108
	v_lshlrev_b32_e32 v90, 16, v108
	v_pk_mul_f32 v[82:83], v[82:83], v[90:91]
	v_and_b32_e32 v91, 0xffff0000, v107
	v_lshlrev_b32_e32 v90, 16, v107
	v_pk_mul_f32 v[88:89], v[88:89], v[90:91]
	v_and_b32_e32 v91, 0xffff0000, v109
	v_lshlrev_b32_e32 v90, 16, v109
	v_pk_mul_f32 v[86:87], v[86:87], v[96:97]
	v_pk_mul_f32 v[90:91], v[84:85], v[90:91]
	v_cvt_pk_bf16_f32 v84, v86, v87
	v_cvt_pk_bf16_f32 v85, v88, v89
	v_cvt_pk_bf16_f32 v86, v82, v83
	v_cvt_pk_bf16_f32 v87, v90, v91
	global_store_dwordx4 v[94:95], v[84:87], off offset:256
	s_nop 0
	v_add_f32_e32 v74, v74, v218
	v_add_f32_e32 v75, v75, v219
	v_mul_f32_e32 v74, 0xbfb8aa3b, v74
	v_mul_f32_e32 v75, 0xbfb8aa3b, v75
	v_exp_f32_e32 v74, v74
	v_exp_f32_e32 v75, v75
	v_and_b32_e32 v83, 0xffff0000, v104
	v_lshlrev_b32_e32 v82, 16, v104
	v_add_f32_e32 v74, 1.0, v74
	v_add_f32_e32 v75, 1.0, v75
	v_rcp_f32_e32 v74, v74
	v_rcp_f32_e32 v75, v75
	v_add_f32_e32 v78, v78, v214
	v_add_f32_e32 v79, v79, v215
	v_mul_f32_e32 v78, 0xbfb8aa3b, v78
	v_pk_mul_f32 v[82:83], v[74:75], v[82:83]
	v_add_f32_e32 v75, v76, v220
	v_mul_f32_e32 v75, 0xbfb8aa3b, v75
	v_exp_f32_e32 v75, v75
	v_add_f32_e32 v74, v80, v216
	v_mul_f32_e32 v74, 0xbfb8aa3b, v74
	v_exp_f32_e32 v74, v74
	v_add_f32_e32 v75, 1.0, v75
	v_rcp_f32_e32 v76, v75
	v_add_f32_e32 v75, v81, v217
	v_mul_f32_e32 v75, 0xbfb8aa3b, v75
	v_exp_f32_e32 v75, v75
	v_add_f32_e32 v74, 1.0, v74
	v_rcp_f32_e32 v74, v74
	v_and_b32_e32 v81, 0xffff0000, v103
	v_add_f32_e32 v75, 1.0, v75
	v_rcp_f32_e32 v75, v75
	v_lshlrev_b32_e32 v80, 16, v103
	v_mul_f32_e32 v79, 0xbfb8aa3b, v79
	v_exp_f32_e32 v78, v78
	v_pk_mul_f32 v[80:81], v[74:75], v[80:81]
	v_add_f32_e32 v74, v77, v221
	v_exp_f32_e32 v79, v79
	v_mul_f32_e32 v74, 0xbfb8aa3b, v74
	v_exp_f32_e32 v74, v74
	v_add_f32_e32 v78, 1.0, v78
	v_add_f32_e32 v79, 1.0, v79
	v_rcp_f32_e32 v78, v78
	v_rcp_f32_e32 v79, v79
	v_add_f32_e32 v74, 1.0, v74
	v_rcp_f32_e32 v77, v74
	v_and_b32_e32 v87, 0xffff0000, v102
	v_lshlrev_b32_e32 v86, 16, v102
	v_pk_mul_f32 v[78:79], v[78:79], v[86:87]
	v_and_b32_e32 v75, 0xffff0000, v105
	v_lshlrev_b32_e32 v74, 16, v105
	v_pk_mul_f32 v[84:85], v[76:77], v[74:75]
	v_cvt_pk_bf16_f32 v74, v78, v79
	v_lshl_add_u64 v[78:79], s[64:65], 0, v[118:119]
	v_cvt_pk_bf16_f32 v75, v80, v81
	v_cvt_pk_bf16_f32 v76, v82, v83
	v_cvt_pk_bf16_f32 v77, v84, v85
	v_lshl_add_u64 v[78:79], v[78:79], 0, v[176:177]
	global_store_dwordx4 v[78:79], v[74:77], off
	s_nop 0
	v_lshl_add_u64 v[88:89], v[178:179], 0, s[0:1]
	s_mov_b64 s[0:1], 0x48000
	v_lshl_add_u64 v[86:87], v[178:179], 0, s[0:1]
	s_mov_b64 s[0:1], 0x50000
	v_add_f32_e32 v66, v66, v226
	v_add_f32_e32 v67, v67, v227
	v_mul_f32_e32 v66, 0xbfb8aa3b, v66
	v_mul_f32_e32 v67, 0xbfb8aa3b, v67
	v_exp_f32_e32 v66, v66
	v_exp_f32_e32 v67, v67
	v_and_b32_e32 v75, 0xffff0000, v100
	v_lshlrev_b32_e32 v74, 16, v100
	v_add_f32_e32 v66, 1.0, v66
	v_add_f32_e32 v67, 1.0, v67
	v_rcp_f32_e32 v66, v66
	v_rcp_f32_e32 v67, v67
	v_add_f32_e32 v70, v70, v222
	v_add_f32_e32 v71, v71, v223
	v_mul_f32_e32 v70, 0xbfb8aa3b, v70
	v_pk_mul_f32 v[74:75], v[66:67], v[74:75]
	v_add_f32_e32 v67, v68, v228
	v_mul_f32_e32 v67, 0xbfb8aa3b, v67
	v_exp_f32_e32 v67, v67
	v_add_f32_e32 v66, v72, v224
	v_mul_f32_e32 v66, 0xbfb8aa3b, v66
	v_exp_f32_e32 v66, v66
	v_add_f32_e32 v67, 1.0, v67
	v_rcp_f32_e32 v68, v67
	v_add_f32_e32 v67, v73, v225
	v_mul_f32_e32 v67, 0xbfb8aa3b, v67
	v_exp_f32_e32 v67, v67
	v_add_f32_e32 v66, 1.0, v66
	v_rcp_f32_e32 v66, v66
	v_and_b32_e32 v73, 0xffff0000, v99
	v_add_f32_e32 v67, 1.0, v67
	v_rcp_f32_e32 v67, v67
	v_lshlrev_b32_e32 v72, 16, v99
	v_mul_f32_e32 v71, 0xbfb8aa3b, v71
	v_exp_f32_e32 v70, v70
	v_pk_mul_f32 v[72:73], v[66:67], v[72:73]
	v_add_f32_e32 v66, v69, v229
	v_mul_f32_e32 v66, 0xbfb8aa3b, v66
	v_exp_f32_e32 v71, v71
	v_exp_f32_e32 v66, v66
	v_add_f32_e32 v70, 1.0, v70
	v_rcp_f32_e32 v70, v70
	v_add_f32_e32 v71, 1.0, v71
	v_add_f32_e32 v66, 1.0, v66
	v_rcp_f32_e32 v71, v71
	v_rcp_f32_e32 v69, v66
	v_and_b32_e32 v81, 0xffff0000, v98
	v_lshlrev_b32_e32 v80, 16, v98
	v_and_b32_e32 v67, 0xffff0000, v101
	v_lshlrev_b32_e32 v66, 16, v101
	v_pk_mul_f32 v[70:71], v[70:71], v[80:81]
	v_pk_mul_f32 v[76:77], v[68:69], v[66:67]
	v_cvt_pk_bf16_f32 v66, v70, v71
	v_cvt_pk_bf16_f32 v67, v72, v73
	v_cvt_pk_bf16_f32 v68, v74, v75
	v_cvt_pk_bf16_f32 v69, v76, v77
	global_store_dwordx4 v[78:79], v[66:69], off offset:256
	s_nop 1
	v_lshl_add_u64 v[66:67], s[24:25], 0, v[88:89]
	v_lshl_add_u64 v[66:67], v[66:67], 0, v[176:177]
	global_load_dwordx4 v[78:81], v[66:67], off
	global_load_dwordx4 v[74:77], v[66:67], off offset:256
	v_lshl_add_u64 v[66:67], s[24:25], 0, v[86:87]
	v_lshl_add_u64 v[66:67], v[66:67], 0, v[176:177]
	global_load_dwordx4 v[70:73], v[66:67], off
	s_nop 0
	global_load_dwordx4 v[66:69], v[66:67], off offset:256
	s_nop 0
	s_waitcnt vmcnt(0)
; DEVI float bf2f(u16 b) { return __uint_as_float(((unsigned)b) << 16); }
;     DEVI f32x4 load(int r, int c) const { const bf16x4 y = *(const bf16x4*)(Y + (size_t)r * DM + c); return (f32x4){bf2f((u16)y[0]), bf2f((u16)y[1]), bf2f((u16)y[2]), bf2f((u16)y[3])}; }
	v_add_f32_e32 v58, v58, v218
	v_add_f32_e32 v59, v59, v219
	v_mul_f32_e32 v58, 0xbfb8aa3b, v58
	v_mul_f32_e32 v59, 0xbfb8aa3b, v59
	v_exp_f32_e32 v58, v58
	v_exp_f32_e32 v59, v59
	v_and_b32_e32 v83, 0xffff0000, v80
	v_lshlrev_b32_e32 v82, 16, v80
	v_add_f32_e32 v58, 1.0, v58
	v_add_f32_e32 v59, 1.0, v59
	v_rcp_f32_e32 v58, v58
	v_rcp_f32_e32 v59, v59
	v_add_f32_e32 v62, v62, v214
	v_add_f32_e32 v63, v63, v215
	v_mul_f32_e32 v62, 0xbfb8aa3b, v62
	v_pk_mul_f32 v[82:83], v[58:59], v[82:83]
	v_add_f32_e32 v59, v60, v220
	v_mul_f32_e32 v59, 0xbfb8aa3b, v59
	v_exp_f32_e32 v59, v59
	v_add_f32_e32 v58, v64, v216
	v_mul_f32_e32 v58, 0xbfb8aa3b, v58
	v_exp_f32_e32 v58, v58
	v_add_f32_e32 v59, 1.0, v59
	v_rcp_f32_e32 v60, v59
	v_add_f32_e32 v59, v65, v217
	v_mul_f32_e32 v59, 0xbfb8aa3b, v59
	v_exp_f32_e32 v59, v59
	v_add_f32_e32 v58, 1.0, v58
	v_rcp_f32_e32 v58, v58
	v_and_b32_e32 v65, 0xffff0000, v79
	v_add_f32_e32 v59, 1.0, v59
	v_rcp_f32_e32 v59, v59
	v_lshlrev_b32_e32 v64, 16, v79
	v_mul_f32_e32 v63, 0xbfb8aa3b, v63
	v_exp_f32_e32 v62, v62
	v_pk_mul_f32 v[64:65], v[58:59], v[64:65]
	v_add_f32_e32 v58, v61, v221
	v_exp_f32_e32 v63, v63
	v_mul_f32_e32 v58, 0xbfb8aa3b, v58
	v_exp_f32_e32 v58, v58
	v_add_f32_e32 v62, 1.0, v62
	v_add_f32_e32 v63, 1.0, v63
	v_rcp_f32_e32 v62, v62
	v_rcp_f32_e32 v63, v63
	v_add_f32_e32 v58, 1.0, v58
	v_rcp_f32_e32 v61, v58
	v_and_b32_e32 v91, 0xffff0000, v78
	v_lshlrev_b32_e32 v90, 16, v78
	v_pk_mul_f32 v[62:63], v[62:63], v[90:91]
	v_and_b32_e32 v59, 0xffff0000, v81
	v_lshlrev_b32_e32 v58, 16, v81
	v_pk_mul_f32 v[78:79], v[60:61], v[58:59]
	v_cvt_pk_bf16_f32 v58, v62, v63
	v_lshl_add_u64 v[62:63], s[64:65], 0, v[88:89]
	v_cvt_pk_bf16_f32 v59, v64, v65
	v_cvt_pk_bf16_f32 v60, v82, v83
	v_cvt_pk_bf16_f32 v61, v78, v79
	v_lshl_add_u64 v[62:63], v[62:63], 0, v[176:177]
	global_store_dwordx4 v[62:63], v[58:61], off
	s_nop 0
	v_and_b32_e32 v65, 0xffff0000, v74
	v_lshlrev_b32_e32 v64, 16, v74
	v_add_f32_e32 v50, v50, v226
	v_add_f32_e32 v51, v51, v227
	v_mul_f32_e32 v50, 0xbfb8aa3b, v50
	v_mul_f32_e32 v51, 0xbfb8aa3b, v51
	v_add_f32_e32 v56, v56, v224
	v_add_f32_e32 v57, v57, v225
	v_add_f32_e32 v54, v54, v222
	v_exp_f32_e32 v50, v50
	v_add_f32_e32 v55, v55, v223
	v_exp_f32_e32 v51, v51
	v_mul_f32_e32 v56, 0xbfb8aa3b, v56
	v_add_f32_e32 v52, v52, v228
	v_mul_f32_e32 v57, 0xbfb8aa3b, v57
	v_add_f32_e32 v53, v53, v229
	v_mul_f32_e32 v54, 0xbfb8aa3b, v54
	v_mul_f32_e32 v55, 0xbfb8aa3b, v55
	v_exp_f32_e32 v56, v56
	v_mul_f32_e32 v52, 0xbfb8aa3b, v52
	v_exp_f32_e32 v57, v57
	v_mul_f32_e32 v53, 0xbfb8aa3b, v53
	v_exp_f32_e32 v54, v54
	v_exp_f32_e32 v55, v55
	v_exp_f32_e32 v52, v52
	v_exp_f32_e32 v53, v53
	v_add_f32_e32 v50, 1.0, v50
	v_add_f32_e32 v51, 1.0, v51
	v_rcp_f32_e32 v50, v50
	v_rcp_f32_e32 v51, v51
	v_add_f32_e32 v56, 1.0, v56
	v_add_f32_e32 v57, 1.0, v57
	v_add_f32_e32 v54, 1.0, v54
	v_add_f32_e32 v55, 1.0, v55
	v_rcp_f32_e32 v56, v56
	v_add_f32_e32 v52, 1.0, v52
	v_rcp_f32_e32 v57, v57
	v_add_f32_e32 v53, 1.0, v53
	v_rcp_f32_e32 v54, v54
	v_rcp_f32_e32 v55, v55
	v_rcp_f32_e32 v52, v52
	v_rcp_f32_e32 v53, v53
	v_and_b32_e32 v59, 0xffff0000, v76
	v_lshlrev_b32_e32 v58, 16, v76
	v_pk_mul_f32 v[50:51], v[50:51], v[58:59]
	v_and_b32_e32 v59, 0xffff0000, v75
	v_lshlrev_b32_e32 v58, 16, v75
	v_pk_mul_f32 v[56:57], v[56:57], v[58:59]
	v_and_b32_e32 v59, 0xffff0000, v77
	v_lshlrev_b32_e32 v58, 16, v77
	v_pk_mul_f32 v[54:55], v[54:55], v[64:65]
	v_pk_mul_f32 v[58:59], v[52:53], v[58:59]
	v_cvt_pk_bf16_f32 v52, v54, v55
	v_cvt_pk_bf16_f32 v53, v56, v57
	v_cvt_pk_bf16_f32 v54, v50, v51
	v_cvt_pk_bf16_f32 v55, v58, v59
	global_store_dwordx4 v[62:63], v[52:55], off offset:256
	s_nop 0
	v_add_f32_e32 v42, v42, v218
	v_add_f32_e32 v43, v43, v219
	v_mul_f32_e32 v42, 0xbfb8aa3b, v42
	v_mul_f32_e32 v43, 0xbfb8aa3b, v43
	v_exp_f32_e32 v42, v42
	v_exp_f32_e32 v43, v43
	v_and_b32_e32 v51, 0xffff0000, v72
	v_lshlrev_b32_e32 v50, 16, v72
	v_add_f32_e32 v42, 1.0, v42
	v_add_f32_e32 v43, 1.0, v43
	v_rcp_f32_e32 v42, v42
	v_rcp_f32_e32 v43, v43
	v_add_f32_e32 v46, v46, v214
	v_add_f32_e32 v47, v47, v215
	v_mul_f32_e32 v46, 0xbfb8aa3b, v46
	v_pk_mul_f32 v[50:51], v[42:43], v[50:51]
	v_add_f32_e32 v43, v44, v220
	v_mul_f32_e32 v43, 0xbfb8aa3b, v43
	v_exp_f32_e32 v43, v43
	v_add_f32_e32 v42, v48, v216
	v_mul_f32_e32 v42, 0xbfb8aa3b, v42
	v_exp_f32_e32 v42, v42
	v_add_f32_e32 v43, 1.0, v43
	v_rcp_f32_e32 v44, v43
	v_add_f32_e32 v43, v49, v217
	v_mul_f32_e32 v43, 0xbfb8aa3b, v43
	v_exp_f32_e32 v43, v43
	v_add_f32_e32 v42, 1.0, v42
	v_rcp_f32_e32 v42, v42
	v_and_b32_e32 v49, 0xffff0000, v71
	v_add_f32_e32 v43, 1.0, v43
	v_rcp_f32_e32 v43, v43
	v_lshlrev_b32_e32 v48, 16, v71
	v_mul_f32_e32 v47, 0xbfb8aa3b, v47
	v_exp_f32_e32 v46, v46
	v_pk_mul_f32 v[48:49], v[42:43], v[48:49]
	v_add_f32_e32 v42, v45, v221
	v_exp_f32_e32 v47, v47
	v_mul_f32_e32 v42, 0xbfb8aa3b, v42
	v_exp_f32_e32 v42, v42
	v_add_f32_e32 v46, 1.0, v46
	v_add_f32_e32 v47, 1.0, v47
	v_rcp_f32_e32 v46, v46
	v_rcp_f32_e32 v47, v47
	v_add_f32_e32 v42, 1.0, v42
	v_rcp_f32_e32 v45, v42
	v_and_b32_e32 v55, 0xffff0000, v70
	v_lshlrev_b32_e32 v54, 16, v70
	v_pk_mul_f32 v[46:47], v[46:47], v[54:55]
	v_and_b32_e32 v43, 0xffff0000, v73
	v_lshlrev_b32_e32 v42, 16, v73
	v_pk_mul_f32 v[52:53], v[44:45], v[42:43]
	v_cvt_pk_bf16_f32 v42, v46, v47
	v_lshl_add_u64 v[46:47], s[64:65], 0, v[86:87]
	v_cvt_pk_bf16_f32 v43, v48, v49
	v_cvt_pk_bf16_f32 v44, v50, v51
	v_cvt_pk_bf16_f32 v45, v52, v53
	v_lshl_add_u64 v[46:47], v[46:47], 0, v[176:177]
	global_store_dwordx4 v[46:47], v[42:45], off
	s_nop 0
	v_lshl_add_u64 v[56:57], v[178:179], 0, s[0:1]
	s_mov_b64 s[0:1], 0x58000
	v_lshl_add_u64 v[54:55], v[178:179], 0, s[0:1]
; DEVI float bf2f(u16 b) { return __uint_as_float(((unsigned)b) << 16); }
; template <class Epi>
; DEVI void gemm_phase(LAS unsigned char* lds, const Gemm g, const Epi& E) {
;     ...
;                 if constexpr (Epi::PRE) {
; #pragma unroll
;                     for (int m = 0; m < 2; ++m)
; #pragma unroll
;                         for (int bj = 0; bj < 2; ++bj)
; #pragma unroll
;                             for (int n = 0; n < 2; ++n) pre[m][bj][n] = E.load(row0 + ai * HALF + (m0 + m) * 16, col0 + bj * HALF + n * NST);
;     DEVI f32x4 load(int r, int c) const { const bf16x4 y = *(const bf16x4*)(Y + (size_t)r * DM + c); return (f32x4){bf2f((u16)y[0]), bf2f((u16)y[1]), bf2f((u16)y[2]), bf2f((u16)y[3])}; }
	s_mov_b32 s0, s4
	v_add_f32_e32 v34, v34, v226
	v_add_f32_e32 v35, v35, v227
	v_mul_f32_e32 v34, 0xbfb8aa3b, v34
	v_mul_f32_e32 v35, 0xbfb8aa3b, v35
	v_exp_f32_e32 v34, v34
	v_exp_f32_e32 v35, v35
	v_and_b32_e32 v43, 0xffff0000, v68
	v_lshlrev_b32_e32 v42, 16, v68
	v_add_f32_e32 v34, 1.0, v34
	v_add_f32_e32 v35, 1.0, v35
	v_rcp_f32_e32 v34, v34
	v_rcp_f32_e32 v35, v35
	v_add_f32_e32 v38, v38, v222
	v_add_f32_e32 v39, v39, v223
	v_mul_f32_e32 v38, 0xbfb8aa3b, v38
	v_pk_mul_f32 v[42:43], v[34:35], v[42:43]
	v_add_f32_e32 v35, v36, v228
	v_mul_f32_e32 v35, 0xbfb8aa3b, v35
	v_exp_f32_e32 v35, v35
	v_add_f32_e32 v34, v40, v224
	v_mul_f32_e32 v34, 0xbfb8aa3b, v34
	v_exp_f32_e32 v34, v34
	v_add_f32_e32 v35, 1.0, v35
	v_rcp_f32_e32 v36, v35
	v_add_f32_e32 v35, v41, v225
	v_mul_f32_e32 v35, 0xbfb8aa3b, v35
	v_exp_f32_e32 v35, v35
	v_add_f32_e32 v34, 1.0, v34
	v_rcp_f32_e32 v34, v34
	v_and_b32_e32 v41, 0xffff0000, v67
	v_add_f32_e32 v35, 1.0, v35
	v_rcp_f32_e32 v35, v35
	v_lshlrev_b32_e32 v40, 16, v67
	v_mul_f32_e32 v39, 0xbfb8aa3b, v39
	v_exp_f32_e32 v38, v38
	v_pk_mul_f32 v[40:41], v[34:35], v[40:41]
	v_add_f32_e32 v34, v37, v229
	v_mul_f32_e32 v34, 0xbfb8aa3b, v34
	v_exp_f32_e32 v39, v39
	v_exp_f32_e32 v34, v34
	v_add_f32_e32 v38, 1.0, v38
	v_rcp_f32_e32 v38, v38
	v_add_f32_e32 v39, 1.0, v39
	v_add_f32_e32 v34, 1.0, v34
	v_rcp_f32_e32 v39, v39
	v_rcp_f32_e32 v37, v34
	v_and_b32_e32 v49, 0xffff0000, v66
	v_lshlrev_b32_e32 v48, 16, v66
	v_and_b32_e32 v35, 0xffff0000, v69
	v_lshlrev_b32_e32 v34, 16, v69
	v_pk_mul_f32 v[38:39], v[38:39], v[48:49]
	v_pk_mul_f32 v[44:45], v[36:37], v[34:35]
	v_cvt_pk_bf16_f32 v34, v38, v39
	v_cvt_pk_bf16_f32 v35, v40, v41
	v_cvt_pk_bf16_f32 v36, v42, v43
	v_cvt_pk_bf16_f32 v37, v44, v45
	global_store_dwordx4 v[46:47], v[34:37], off offset:256
	s_nop 1
	v_lshl_add_u64 v[34:35], s[24:25], 0, v[56:57]
	v_lshl_add_u64 v[34:35], v[34:35], 0, v[176:177]
	global_load_dwordx4 v[46:49], v[34:35], off
	global_load_dwordx4 v[42:45], v[34:35], off offset:256
	v_lshl_add_u64 v[34:35], s[24:25], 0, v[54:55]
	v_lshl_add_u64 v[34:35], v[34:35], 0, v[176:177]
	global_load_dwordx4 v[38:41], v[34:35], off
	s_nop 0
	global_load_dwordx4 v[34:37], v[34:35], off offset:256
	s_nop 0
	s_waitcnt vmcnt(0)
	v_add_f32_e32 v26, v26, v218
	v_add_f32_e32 v27, v27, v219
	v_mul_f32_e32 v26, 0xbfb8aa3b, v26
	v_mul_f32_e32 v27, 0xbfb8aa3b, v27
	v_exp_f32_e32 v26, v26
	v_exp_f32_e32 v27, v27
	v_and_b32_e32 v51, 0xffff0000, v48
	v_lshlrev_b32_e32 v50, 16, v48
	v_add_f32_e32 v26, 1.0, v26
	v_add_f32_e32 v27, 1.0, v27
	v_rcp_f32_e32 v26, v26
	v_rcp_f32_e32 v27, v27
	v_add_f32_e32 v30, v30, v214
	v_add_f32_e32 v31, v31, v215
	v_mul_f32_e32 v30, 0xbfb8aa3b, v30
	v_pk_mul_f32 v[50:51], v[26:27], v[50:51]
	v_add_f32_e32 v27, v28, v220
	v_mul_f32_e32 v27, 0xbfb8aa3b, v27
	v_exp_f32_e32 v27, v27
	v_add_f32_e32 v26, v32, v216
	v_mul_f32_e32 v26, 0xbfb8aa3b, v26
	v_exp_f32_e32 v26, v26
	v_add_f32_e32 v27, 1.0, v27
	v_rcp_f32_e32 v28, v27
	v_add_f32_e32 v27, v33, v217
	v_mul_f32_e32 v27, 0xbfb8aa3b, v27
	v_exp_f32_e32 v27, v27
	v_add_f32_e32 v26, 1.0, v26
	v_rcp_f32_e32 v26, v26
	v_and_b32_e32 v33, 0xffff0000, v47
	v_add_f32_e32 v27, 1.0, v27
	v_rcp_f32_e32 v27, v27
	v_lshlrev_b32_e32 v32, 16, v47
	v_mul_f32_e32 v31, 0xbfb8aa3b, v31
	v_exp_f32_e32 v30, v30
	v_pk_mul_f32 v[32:33], v[26:27], v[32:33]
	v_add_f32_e32 v26, v29, v221
	v_exp_f32_e32 v31, v31
	v_mul_f32_e32 v26, 0xbfb8aa3b, v26
	v_exp_f32_e32 v26, v26
	v_add_f32_e32 v30, 1.0, v30
	v_add_f32_e32 v31, 1.0, v31
	v_rcp_f32_e32 v30, v30
	v_rcp_f32_e32 v31, v31
	v_add_f32_e32 v26, 1.0, v26
	v_rcp_f32_e32 v29, v26
	v_and_b32_e32 v59, 0xffff0000, v46
	v_lshlrev_b32_e32 v58, 16, v46
	v_pk_mul_f32 v[30:31], v[30:31], v[58:59]
	v_and_b32_e32 v27, 0xffff0000, v49
	v_lshlrev_b32_e32 v26, 16, v49
	v_pk_mul_f32 v[46:47], v[28:29], v[26:27]
	v_cvt_pk_bf16_f32 v26, v30, v31
	v_lshl_add_u64 v[30:31], s[64:65], 0, v[56:57]
	v_cvt_pk_bf16_f32 v27, v32, v33
	v_cvt_pk_bf16_f32 v28, v50, v51
	v_cvt_pk_bf16_f32 v29, v46, v47
	v_lshl_add_u64 v[30:31], v[30:31], 0, v[176:177]
	global_store_dwordx4 v[30:31], v[26:29], off
	s_nop 0
	v_and_b32_e32 v33, 0xffff0000, v42
	v_lshlrev_b32_e32 v32, 16, v42
	v_add_f32_e32 v18, v18, v226
	v_add_f32_e32 v19, v19, v227
	v_mul_f32_e32 v18, 0xbfb8aa3b, v18
	v_mul_f32_e32 v19, 0xbfb8aa3b, v19
	v_add_f32_e32 v24, v24, v224
	v_add_f32_e32 v25, v25, v225
	v_add_f32_e32 v22, v22, v222
	v_exp_f32_e32 v18, v18
	v_add_f32_e32 v23, v23, v223
	v_exp_f32_e32 v19, v19
	v_mul_f32_e32 v24, 0xbfb8aa3b, v24
	v_add_f32_e32 v20, v20, v228
	v_mul_f32_e32 v25, 0xbfb8aa3b, v25
	v_add_f32_e32 v21, v21, v229
	v_mul_f32_e32 v22, 0xbfb8aa3b, v22
	v_mul_f32_e32 v23, 0xbfb8aa3b, v23
	v_exp_f32_e32 v24, v24
	v_mul_f32_e32 v20, 0xbfb8aa3b, v20
	v_exp_f32_e32 v25, v25
; DEVI float bf2f(u16 b) { return __uint_as_float(((unsigned)b) << 16); }
; #define PG8_WAIT_V(n) asm volatile("s_waitcnt vmcnt(" #n ")" ::: "memory")
; #define PG8_BAR __builtin_amdgcn_s_barrier()
; template <class Epi>
; DEVI void gemm_phase(LAS unsigned char* lds, const Gemm g, const Epi& E) {
;     ...
;         if (!has_next) break;
; #pragma unroll
;         for (int a = 0; a < 2; ++a)
; #pragma unroll
;             for (int b = 0; b < 2; ++b)
; #pragma unroll
;                 for (int m = 0; m < 4; ++m)
; #pragma unroll
;                     for (int n = 0; n < 2; ++n) acc[a][b][m][n] = (f32x4){0.f, 0.f, 0.f, 0.f};
;         cur = nxt; cA = nA; cB = nB; ++ui;
;     }
;     PG8_WAIT_V(0);
;     if (wr == 0) PG8_BAR;
;     PG8_BAR;
;     DEVI f32x4 load(int r, int c) const { const bf16x4 y = *(const bf16x4*)(Y + (size_t)r * DM + c); return (f32x4){bf2f((u16)y[0]), bf2f((u16)y[1]), bf2f((u16)y[2]), bf2f((u16)y[3])}; }
	v_mul_f32_e32 v21, 0xbfb8aa3b, v21
	v_exp_f32_e32 v22, v22
	v_exp_f32_e32 v23, v23
	v_exp_f32_e32 v20, v20
	v_exp_f32_e32 v21, v21
	v_add_f32_e32 v18, 1.0, v18
	v_add_f32_e32 v19, 1.0, v19
	v_rcp_f32_e32 v18, v18
	v_rcp_f32_e32 v19, v19
	v_add_f32_e32 v24, 1.0, v24
	v_add_f32_e32 v25, 1.0, v25
	v_add_f32_e32 v22, 1.0, v22
	v_add_f32_e32 v23, 1.0, v23
	v_rcp_f32_e32 v24, v24
	v_add_f32_e32 v20, 1.0, v20
	v_rcp_f32_e32 v25, v25
	v_add_f32_e32 v21, 1.0, v21
	v_rcp_f32_e32 v22, v22
	v_rcp_f32_e32 v23, v23
	v_rcp_f32_e32 v20, v20
	v_rcp_f32_e32 v21, v21
	v_and_b32_e32 v27, 0xffff0000, v44
	v_lshlrev_b32_e32 v26, 16, v44
	v_pk_mul_f32 v[18:19], v[18:19], v[26:27]
	v_and_b32_e32 v27, 0xffff0000, v43
	v_lshlrev_b32_e32 v26, 16, v43
	v_pk_mul_f32 v[24:25], v[24:25], v[26:27]
	v_and_b32_e32 v27, 0xffff0000, v45
	v_lshlrev_b32_e32 v26, 16, v45
	v_pk_mul_f32 v[22:23], v[22:23], v[32:33]
	v_pk_mul_f32 v[26:27], v[20:21], v[26:27]
	v_cvt_pk_bf16_f32 v20, v22, v23
	v_cvt_pk_bf16_f32 v21, v24, v25
	v_cvt_pk_bf16_f32 v22, v18, v19
	v_cvt_pk_bf16_f32 v23, v26, v27
	global_store_dwordx4 v[30:31], v[20:23], off offset:256
	s_nop 0
	v_add_f32_e32 v10, v10, v218
	v_add_f32_e32 v11, v11, v219
	v_mul_f32_e32 v10, 0xbfb8aa3b, v10
	v_mul_f32_e32 v11, 0xbfb8aa3b, v11
	v_exp_f32_e32 v10, v10
	v_exp_f32_e32 v11, v11
	v_and_b32_e32 v19, 0xffff0000, v40
	v_lshlrev_b32_e32 v18, 16, v40
	v_add_f32_e32 v10, 1.0, v10
	v_add_f32_e32 v11, 1.0, v11
	v_rcp_f32_e32 v10, v10
	v_rcp_f32_e32 v11, v11
	v_add_f32_e32 v14, v14, v214
	v_add_f32_e32 v15, v15, v215
	v_mul_f32_e32 v14, 0xbfb8aa3b, v14
	v_pk_mul_f32 v[18:19], v[10:11], v[18:19]
	v_add_f32_e32 v11, v12, v220
	v_mul_f32_e32 v11, 0xbfb8aa3b, v11
	v_exp_f32_e32 v11, v11
	v_add_f32_e32 v10, v16, v216
	v_mul_f32_e32 v10, 0xbfb8aa3b, v10
	v_exp_f32_e32 v10, v10
	v_add_f32_e32 v11, 1.0, v11
	v_rcp_f32_e32 v12, v11
	v_add_f32_e32 v11, v17, v217
	v_mul_f32_e32 v11, 0xbfb8aa3b, v11
	v_exp_f32_e32 v11, v11
	v_add_f32_e32 v10, 1.0, v10
	v_rcp_f32_e32 v10, v10
	v_and_b32_e32 v17, 0xffff0000, v39
	v_add_f32_e32 v11, 1.0, v11
	v_rcp_f32_e32 v11, v11
	v_lshlrev_b32_e32 v16, 16, v39
	v_mul_f32_e32 v15, 0xbfb8aa3b, v15
	v_exp_f32_e32 v14, v14
	v_pk_mul_f32 v[16:17], v[10:11], v[16:17]
	v_add_f32_e32 v10, v13, v221
	v_exp_f32_e32 v15, v15
	v_mul_f32_e32 v10, 0xbfb8aa3b, v10
	v_exp_f32_e32 v10, v10
	v_add_f32_e32 v14, 1.0, v14
	v_add_f32_e32 v15, 1.0, v15
	v_rcp_f32_e32 v14, v14
	v_rcp_f32_e32 v15, v15
	v_add_f32_e32 v10, 1.0, v10
	v_rcp_f32_e32 v13, v10
	v_and_b32_e32 v23, 0xffff0000, v38
	v_lshlrev_b32_e32 v22, 16, v38
	v_pk_mul_f32 v[14:15], v[14:15], v[22:23]
	v_and_b32_e32 v11, 0xffff0000, v41
	v_lshlrev_b32_e32 v10, 16, v41
	v_pk_mul_f32 v[20:21], v[12:13], v[10:11]
	v_cvt_pk_bf16_f32 v10, v14, v15
	v_lshl_add_u64 v[14:15], s[64:65], 0, v[54:55]
	v_cvt_pk_bf16_f32 v11, v16, v17
	v_cvt_pk_bf16_f32 v12, v18, v19
	v_cvt_pk_bf16_f32 v13, v20, v21
	v_lshl_add_u64 v[14:15], v[14:15], 0, v[176:177]
	global_store_dwordx4 v[14:15], v[10:13], off
	s_nop 0
	v_add_f32_e32 v0, v0, v226
	v_add_f32_e32 v1, v1, v227
	v_mul_f32_e32 v0, 0xbfb8aa3b, v0
	v_mul_f32_e32 v1, 0xbfb8aa3b, v1
	v_exp_f32_e32 v0, v0
	v_exp_f32_e32 v1, v1
	v_and_b32_e32 v11, 0xffff0000, v36
	v_lshlrev_b32_e32 v10, 16, v36
	v_add_f32_e32 v0, 1.0, v0
	v_add_f32_e32 v1, 1.0, v1
	v_rcp_f32_e32 v0, v0
	v_rcp_f32_e32 v1, v1
	v_add_f32_e32 v4, v4, v222
	v_add_f32_e32 v5, v5, v223
	v_mul_f32_e32 v4, 0xbfb8aa3b, v4
	v_pk_mul_f32 v[10:11], v[0:1], v[10:11]
	v_add_f32_e32 v1, v2, v228
	v_mul_f32_e32 v1, 0xbfb8aa3b, v1
	v_exp_f32_e32 v1, v1
	v_add_f32_e32 v0, v6, v224
	v_mul_f32_e32 v0, 0xbfb8aa3b, v0
	v_exp_f32_e32 v0, v0
	v_add_f32_e32 v1, 1.0, v1
	v_rcp_f32_e32 v2, v1
	v_add_f32_e32 v1, v7, v225
	v_mul_f32_e32 v1, 0xbfb8aa3b, v1
	v_exp_f32_e32 v1, v1
	v_add_f32_e32 v0, 1.0, v0
	v_rcp_f32_e32 v0, v0
	v_and_b32_e32 v7, 0xffff0000, v35
	v_add_f32_e32 v1, 1.0, v1
	v_rcp_f32_e32 v1, v1
	v_lshlrev_b32_e32 v6, 16, v35
	v_mul_f32_e32 v5, 0xbfb8aa3b, v5
	v_exp_f32_e32 v4, v4
	v_pk_mul_f32 v[6:7], v[0:1], v[6:7]
	v_add_f32_e32 v0, v3, v229
	v_mul_f32_e32 v0, 0xbfb8aa3b, v0
	v_exp_f32_e32 v5, v5
	v_exp_f32_e32 v0, v0
	v_add_f32_e32 v4, 1.0, v4
	v_rcp_f32_e32 v4, v4
	v_add_f32_e32 v5, 1.0, v5
	v_add_f32_e32 v0, 1.0, v0
	v_rcp_f32_e32 v5, v5
	v_rcp_f32_e32 v3, v0
	v_and_b32_e32 v17, 0xffff0000, v34
	v_lshlrev_b32_e32 v16, 16, v34
	v_and_b32_e32 v1, 0xffff0000, v37
	v_lshlrev_b32_e32 v0, 16, v37
	v_pk_mul_f32 v[4:5], v[4:5], v[16:17]
	v_pk_mul_f32 v[12:13], v[2:3], v[0:1]
	v_cvt_pk_bf16_f32 v0, v4, v5
	v_cvt_pk_bf16_f32 v1, v6, v7
	v_cvt_pk_bf16_f32 v2, v10, v11
	v_cvt_pk_bf16_f32 v3, v12, v13
	global_store_dwordx4 v[14:15], v[0:3], off offset:256
	s_cbranch_vccz .LBB0_1339
	s_waitcnt vmcnt(0)
	s_cmpk_gt_u32 s46, 0xff
	s_cbranch_scc1 .LBB0_1350
	s_barrier

; DEVI size_t gemm_offB(const Gemm& g, const Unit& u) { return (g.split ? (size_t)(u.b >> 2) * g.sB + (size_t)(u.b & 3) * g.sB_lo : (size_t)u.b * g.sB) + (size_t)(u.pm >> g.pmsh) * g.sBpm; }
; #define PG8_STAGE(bufoff, gbase, voff) do { _Pragma("unroll") for (int _i = 0; _i < 2; ++_i) \
;         __builtin_amdgcn_global_load_lds((const unsigned*)((const char*)(gbase) + (voff)[_i]), (LAS unsigned*)(lds + (bufoff) + ldsw + _i * 8192), 16, 0, 0); } while (0)
; #define PG8_LDA(dst, b, h) do { _Pragma("unroll") for (int m = 0; m < 4; ++m) _Pragma("unroll") for (int k = 0; k < 2; ++k) dst[m][k] = *(const LAS bf16x8*)(lds + PG8_SA(b, h) + aoff + m * 2048 + k * 1024); } while (0)
; #define PG8_LDB(dst, b, h) do { _Pragma("unroll") for (int n = 0; n < 2; ++n) _Pragma("unroll") for (int k = 0; k < 2; ++k) dst[n][k] = *(const LAS bf16x8*)(lds + PG8_SB(b, h) + boff + n * 2048 + k * 1024); } while (0)
; #define PG8_WAIT_L(n) asm volatile("s_waitcnt lgkmcnt(" #n ")" ::: "memory")
; #define PG8_BAR __builtin_amdgcn_s_barrier()
; #define PG8_SCHED __builtin_amdgcn_sched_barrier(0)
; template <class Epi>
; DEVI void gemm_phase(LAS unsigned char* lds, const Gemm g, const Epi& E) {
;     ...
;         const bool has_next = unit_next(g, ui + 1, nxt);
;         const char* nA = has_next ? (const char*)g.A + gemm_offA(g, nxt) * 2 + (size_t)nxt.pm * tstepA : cA;
;         const char* nB = has_next ? (const char*)g.Bt + gemm_offB(g, nxt) * 2 + (size_t)nxt.pn * tstepB : cB;
;         for (int t = 0; t < nt; t += 2) {
;             const bool last = (t == nt - 2);
;             const char* a1 = cA + (size_t)(t + 1) * kstep;
;             const char* a2 = last ? nA : cA + (size_t)(t + 2) * kstep; const char* b2 = last ? nB : cB + (size_t)(t + 2) * kstep;
;             const char* a3 = a2 + kstep; const char* b3 = b2 + kstep;
;             PG8_LDB(B0, 0, 0); PG8_SCHED; PG8_LDA(At, 0, 0); PG8_STAGE(PG8_SA(1, 1), a1 + hstepA, voffA);
;             PG8_WAIT_L(8); PG8_BAR; PG8_WAIT_L(0); PG8_MMA(0, 0, At, B0); PG8_BAR; PG8_SCHED;
;             PG8_LDB(B1, 0, 1); PG8_STAGE(PG8_SB(0, 0), b2, voffB);
;             PG8_BAR; PG8_WAIT_L(0); PG8_MMA(0, 1, At, B1); PG8_BAR;
;             PG8_LDA(At, 0, 1); PG8_STAGE(PG8_SA(0, 0), a2, voffA);
;             PG8_BAR; PG8_WAIT_L(0); PG8_MMA(1, 0, At, B0); PG8_BAR; PG8_SCHED;
.LBB0_1507:
	s_add_u32 s19, s6, 0xfffc0080
	s_addc_u32 s26, s7, -1
	s_add_i32 s27, 0, 0x10000
	v_add_u32_e32 v142, s27, v199
	ds_read_b128 v[130:133], v142
	ds_read_b128 v[134:137], v142 offset:1024
	ds_read_b128 v[138:141], v142 offset:2048
	ds_read_b128 v[142:145], v142 offset:3072
	s_cmp_eq_u32 s18, 12
	s_cselect_b32 s79, s0, s26
	s_cselect_b32 s78, s1, s19
	s_cselect_b32 s69, s15, s13
	s_cselect_b32 s68, s14, s11
	v_lshl_add_u64 v[162:163], s[6:7], 0, v[182:183]
	s_add_i32 m0, s37, 0xc000
	ds_read_b128 v[146:149], v202
	ds_read_b128 v[150:153], v202 offset:1024
	ds_read_b128 v[186:189], v202 offset:2048
	ds_read_b128 v[190:193], v202 offset:3072
	ds_read_b128 v[194:197], v202 offset:4096
	ds_read_b128 v[204:207], v202 offset:5120
	ds_read_b128 v[214:217], v202 offset:6144
	ds_read_b128 v[218:221], v202 offset:7168
	global_load_lds_dwordx4 v[162:163], off
	v_lshl_add_u64 v[162:163], s[6:7], 0, v[184:185]
	s_add_i32 m0, s37, 0xe000
	s_nop 0
	global_load_lds_dwordx4 v[162:163], off
	s_waitcnt lgkmcnt(8)
	s_barrier
	s_waitcnt lgkmcnt(0)
	s_setprio 1
	v_mfma_f32_16x16x32_bf16 v[126:129], v[130:133], v[146:149], v[126:129]
	v_mfma_f32_16x16x32_bf16 v[122:125], v[138:141], v[146:149], v[122:125]
	v_mfma_f32_16x16x32_bf16 v[110:113], v[130:133], v[186:189], v[110:113]
	v_mfma_f32_16x16x32_bf16 v[106:109], v[138:141], v[186:189], v[106:109]
	v_mfma_f32_16x16x32_bf16 v[94:97], v[130:133], v[194:197], v[94:97]
	v_mfma_f32_16x16x32_bf16 v[90:93], v[138:141], v[194:197], v[90:93]
	v_mfma_f32_16x16x32_bf16 v[78:81], v[130:133], v[214:217], v[78:81]
	v_mfma_f32_16x16x32_bf16 v[74:77], v[138:141], v[214:217], v[74:77]
	v_mfma_f32_16x16x32_bf16 v[126:129], v[134:137], v[150:153], v[126:129]
	v_mfma_f32_16x16x32_bf16 v[122:125], v[142:145], v[150:153], v[122:125]
	v_mfma_f32_16x16x32_bf16 v[110:113], v[134:137], v[190:193], v[110:113]
	v_mfma_f32_16x16x32_bf16 v[106:109], v[142:145], v[190:193], v[106:109]
	v_mfma_f32_16x16x32_bf16 v[94:97], v[134:137], v[204:207], v[94:97]
	v_mfma_f32_16x16x32_bf16 v[90:93], v[142:145], v[204:207], v[90:93]
	v_mfma_f32_16x16x32_bf16 v[78:81], v[134:137], v[218:221], v[78:81]
	v_mfma_f32_16x16x32_bf16 v[74:77], v[142:145], v[218:221], v[74:77]
	s_setprio 0
	s_barrier
	s_add_i32 s19, 0, 0x14000
	v_add_u32_e32 v162, s19, v199
	s_add_i32 s26, s27, s80
	ds_read_b128 v[222:225], v162
	ds_read_b128 v[226:229], v162 offset:1024
	ds_read_b128 v[230:233], v162 offset:2048
	ds_read_b128 v[234:237], v162 offset:3072
	v_lshl_add_u64 v[162:163], s[68:69], 0, v[8:9]
	s_mov_b32 m0, s26
	v_lshl_add_u64 v[164:165], s[68:69], 0, v[180:181]
	global_load_lds_dwordx4 v[162:163], off
	s_add_i32 m0, s26, 0x2000
	s_nop 0
	global_load_lds_dwordx4 v[164:165], off
	s_barrier
	s_waitcnt lgkmcnt(0)
	s_setprio 1
	v_mfma_f32_16x16x32_bf16 v[118:121], v[222:225], v[146:149], v[118:121]
	v_mfma_f32_16x16x32_bf16 v[114:117], v[230:233], v[146:149], v[114:117]
	v_mfma_f32_16x16x32_bf16 v[102:105], v[222:225], v[186:189], v[102:105]
	v_mfma_f32_16x16x32_bf16 v[98:101], v[230:233], v[186:189], v[98:101]
	v_mfma_f32_16x16x32_bf16 v[86:89], v[222:225], v[194:197], v[86:89]
	v_mfma_f32_16x16x32_bf16 v[82:85], v[230:233], v[194:197], v[82:85]
	v_mfma_f32_16x16x32_bf16 v[70:73], v[222:225], v[214:217], v[70:73]
	v_mfma_f32_16x16x32_bf16 v[62:65], v[230:233], v[214:217], v[62:65]
	v_mfma_f32_16x16x32_bf16 v[118:121], v[226:229], v[150:153], v[118:121]
	v_mfma_f32_16x16x32_bf16 v[114:117], v[234:237], v[150:153], v[114:117]
	v_mfma_f32_16x16x32_bf16 v[102:105], v[226:229], v[190:193], v[102:105]
	v_mfma_f32_16x16x32_bf16 v[98:101], v[234:237], v[190:193], v[98:101]
	v_mfma_f32_16x16x32_bf16 v[86:89], v[226:229], v[204:207], v[86:89]
	v_mfma_f32_16x16x32_bf16 v[82:85], v[234:237], v[204:207], v[82:85]
	v_mfma_f32_16x16x32_bf16 v[70:73], v[226:229], v[218:221], v[70:73]
	v_mfma_f32_16x16x32_bf16 v[62:65], v[234:237], v[218:221], v[62:65]
	s_setprio 0
	s_mov_b32 m0, s37
	v_lshl_add_u64 v[208:209], s[78:79], 0, v[176:177]
	s_barrier
	ds_read_b128 v[146:149], v202 offset:16384
	ds_read_b128 v[150:153], v202 offset:17408
	ds_read_b128 v[186:189], v202 offset:18432
	ds_read_b128 v[190:193], v202 offset:19456
	ds_read_b128 v[194:197], v202 offset:20480
	ds_read_b128 v[204:207], v202 offset:21504
	ds_read_b128 v[214:217], v202 offset:22528
	ds_read_b128 v[218:221], v202 offset:23552
	global_load_lds_dwordx4 v[208:209], off
	v_lshl_add_u64 v[238:239], s[78:79], 0, v[178:179]
	s_mov_b32 m0, s47
	s_nop 0
	global_load_lds_dwordx4 v[238:239], off
	s_barrier
	s_waitcnt lgkmcnt(0)
	s_setprio 1
	v_mfma_f32_16x16x32_bf16 v[66:69], v[130:133], v[146:149], v[66:69]
	v_mfma_f32_16x16x32_bf16 v[54:57], v[138:141], v[146:149], v[54:57]
	v_mfma_f32_16x16x32_bf16 v[46:49], v[130:133], v[186:189], v[46:49]
	v_mfma_f32_16x16x32_bf16 v[38:41], v[138:141], v[186:189], v[38:41]
	v_mfma_f32_16x16x32_bf16 v[30:33], v[130:133], v[194:197], v[30:33]
	v_mfma_f32_16x16x32_bf16 v[22:25], v[138:141], v[194:197], v[22:25]
	v_mfma_f32_16x16x32_bf16 v[14:17], v[130:133], v[214:217], v[14:17]
	v_mfma_f32_16x16x32_bf16 v[4:7], v[138:141], v[214:217], v[4:7]
	v_mfma_f32_16x16x32_bf16 v[66:69], v[134:137], v[150:153], v[66:69]
	v_mfma_f32_16x16x32_bf16 v[54:57], v[142:145], v[150:153], v[54:57]
	v_mfma_f32_16x16x32_bf16 v[46:49], v[134:137], v[190:193], v[46:49]
	v_mfma_f32_16x16x32_bf16 v[38:41], v[142:145], v[190:193], v[38:41]
	v_mfma_f32_16x16x32_bf16 v[30:33], v[134:137], v[204:207], v[30:33]
	v_mfma_f32_16x16x32_bf16 v[22:25], v[142:145], v[204:207], v[22:25]
	v_mfma_f32_16x16x32_bf16 v[14:17], v[134:137], v[218:221], v[14:17]
	v_mfma_f32_16x16x32_bf16 v[4:7], v[142:145], v[218:221], v[4:7]
	s_setprio 0
	s_barrier
; #define PG8_STAGE(bufoff, gbase, voff) do { _Pragma("unroll") for (int _i = 0; _i < 2; ++_i) \
;         __builtin_amdgcn_global_load_lds((const unsigned*)((const char*)(gbase) + (voff)[_i]), (LAS unsigned*)(lds + (bufoff) + ldsw + _i * 8192), 16, 0, 0); } while (0)
; #define PG8_LDA(dst, b, h) do { _Pragma("unroll") for (int m = 0; m < 4; ++m) _Pragma("unroll") for (int k = 0; k < 2; ++k) dst[m][k] = *(const LAS bf16x8*)(lds + PG8_SA(b, h) + aoff + m * 2048 + k * 1024); } while (0)
; #define PG8_LDB(dst, b, h) do { _Pragma("unroll") for (int n = 0; n < 2; ++n) _Pragma("unroll") for (int k = 0; k < 2; ++k) dst[n][k] = *(const LAS bf16x8*)(lds + PG8_SB(b, h) + boff + n * 2048 + k * 1024); } while (0)
; #define PG8_MMA(ai, bj, At, Bt) do { __builtin_amdgcn_s_setprio(1); _Pragma("unroll") for (int m = 0; m < 4; ++m) _Pragma("unroll") for (int n = 0; n < 2; ++n) _Pragma("unroll") for (int k = 0; k < 2; ++k) \
;         acc[ai][bj][m][n] = __builtin_amdgcn_mfma_f32_16x16x32_bf16(Bt[n][k], At[m][k], acc[ai][bj][m][n], 0, 0, 0); __builtin_amdgcn_s_setprio(0); } while (0)
; #define PG8_WAIT_V(n) asm volatile("s_waitcnt vmcnt(" #n ")" ::: "memory")
; #define PG8_WAIT_L(n) asm volatile("s_waitcnt lgkmcnt(" #n ")" ::: "memory")
; #define PG8_BAR __builtin_amdgcn_s_barrier()
; #define PG8_SCHED __builtin_amdgcn_sched_barrier(0)
; template <class Epi>
; DEVI void gemm_phase(LAS unsigned char* lds, const Gemm g, const Epi& E) {
;     ...
;             PG8_STAGE(PG8_SB(0, 1), b2 + hstepB, voffB);
;             PG8_WAIT_V(6); PG8_BAR; PG8_MMA(1, 1, At, B1); PG8_BAR;
;             PG8_LDB(B0, 1, 0); PG8_SCHED; PG8_LDA(At, 1, 0); PG8_STAGE(PG8_SA(0, 1), a2 + hstepA, voffA);
;             PG8_WAIT_L(8); PG8_BAR; PG8_WAIT_L(0); PG8_MMA(0, 0, At, B0); PG8_BAR; PG8_SCHED;
;             PG8_LDB(B1, 1, 1); PG8_STAGE(PG8_SB(1, 0), b3, voffB);
;             PG8_BAR; PG8_WAIT_L(0); PG8_MMA(0, 1, At, B1); PG8_BAR;
;             PG8_LDA(At, 1, 1); PG8_STAGE(PG8_SA(1, 0), a3, voffA);
;             PG8_BAR; PG8_WAIT_L(0); PG8_MMA(1, 0, At, B0); PG8_BAR; PG8_SCHED;
	s_add_u32 s26, s68, 0x40000
	s_addc_u32 s27, s69, 0
	s_add_i32 s19, s19, s80
	v_lshl_add_u64 v[130:131], s[26:27], 0, v[8:9]
	s_mov_b32 m0, s19
	s_nop 0
	global_load_lds_dwordx4 v[130:131], off
	v_lshl_add_u64 v[130:131], s[26:27], 0, v[180:181]
	s_add_i32 m0, s19, 0x2000
	s_nop 0
	global_load_lds_dwordx4 v[130:131], off
	s_waitcnt vmcnt(6)
	s_barrier
	s_setprio 1
	v_mfma_f32_16x16x32_bf16 v[58:61], v[222:225], v[146:149], v[58:61]
	v_mfma_f32_16x16x32_bf16 v[50:53], v[230:233], v[146:149], v[50:53]
	v_mfma_f32_16x16x32_bf16 v[42:45], v[222:225], v[186:189], v[42:45]
	v_mfma_f32_16x16x32_bf16 v[34:37], v[230:233], v[186:189], v[34:37]
	v_mfma_f32_16x16x32_bf16 v[26:29], v[222:225], v[194:197], v[26:29]
	v_mfma_f32_16x16x32_bf16 v[18:21], v[230:233], v[194:197], v[18:21]
	v_mfma_f32_16x16x32_bf16 v[10:13], v[222:225], v[214:217], v[10:13]
	v_mfma_f32_16x16x32_bf16 v[0:3], v[230:233], v[214:217], v[0:3]
	v_mfma_f32_16x16x32_bf16 v[58:61], v[226:229], v[150:153], v[58:61]
	v_mfma_f32_16x16x32_bf16 v[50:53], v[234:237], v[150:153], v[50:53]
	v_mfma_f32_16x16x32_bf16 v[42:45], v[226:229], v[190:193], v[42:45]
	v_mfma_f32_16x16x32_bf16 v[34:37], v[234:237], v[190:193], v[34:37]
	v_mfma_f32_16x16x32_bf16 v[26:29], v[226:229], v[204:207], v[26:29]
	v_mfma_f32_16x16x32_bf16 v[18:21], v[234:237], v[204:207], v[18:21]
	v_mfma_f32_16x16x32_bf16 v[10:13], v[226:229], v[218:221], v[10:13]
	v_mfma_f32_16x16x32_bf16 v[0:3], v[234:237], v[218:221], v[0:3]
	s_setprio 0
	s_add_i32 s19, 0, 0x18000
	v_add_u32_e32 v142, s19, v199
	s_barrier
	ds_read_b128 v[130:133], v142
	ds_read_b128 v[134:137], v142 offset:1024
	ds_read_b128 v[138:141], v142 offset:2048
	ds_read_b128 v[142:145], v142 offset:3072
	s_add_u32 s26, s78, 0x40000
	s_addc_u32 s27, s79, 0
	s_mov_b32 m0, s81
	v_lshl_add_u64 v[222:223], s[26:27], 0, v[176:177]
	ds_read_b128 v[146:149], v202 offset:32768
	ds_read_b128 v[150:153], v202 offset:33792
	ds_read_b128 v[186:189], v202 offset:34816
	ds_read_b128 v[190:193], v202 offset:35840
	ds_read_b128 v[194:197], v202 offset:36864
	ds_read_b128 v[204:207], v202 offset:37888
	ds_read_b128 v[214:217], v202 offset:38912
	ds_read_b128 v[218:221], v202 offset:39936
	global_load_lds_dwordx4 v[222:223], off
	v_lshl_add_u64 v[222:223], s[26:27], 0, v[178:179]
	s_mov_b32 m0, s82
	s_nop 0
	global_load_lds_dwordx4 v[222:223], off
	s_waitcnt lgkmcnt(8)
	s_barrier
	s_waitcnt lgkmcnt(0)
	s_setprio 1
	v_mfma_f32_16x16x32_bf16 v[126:129], v[130:133], v[146:149], v[126:129]
	v_mfma_f32_16x16x32_bf16 v[122:125], v[138:141], v[146:149], v[122:125]
	v_mfma_f32_16x16x32_bf16 v[110:113], v[130:133], v[186:189], v[110:113]
	v_mfma_f32_16x16x32_bf16 v[106:109], v[138:141], v[186:189], v[106:109]
	v_mfma_f32_16x16x32_bf16 v[94:97], v[130:133], v[194:197], v[94:97]
	v_mfma_f32_16x16x32_bf16 v[90:93], v[138:141], v[194:197], v[90:93]
	v_mfma_f32_16x16x32_bf16 v[78:81], v[130:133], v[214:217], v[78:81]
	v_mfma_f32_16x16x32_bf16 v[74:77], v[138:141], v[214:217], v[74:77]
	v_mfma_f32_16x16x32_bf16 v[126:129], v[134:137], v[150:153], v[126:129]
	v_mfma_f32_16x16x32_bf16 v[122:125], v[142:145], v[150:153], v[122:125]
	v_mfma_f32_16x16x32_bf16 v[110:113], v[134:137], v[190:193], v[110:113]
	v_mfma_f32_16x16x32_bf16 v[106:109], v[142:145], v[190:193], v[106:109]
	v_mfma_f32_16x16x32_bf16 v[94:97], v[134:137], v[204:207], v[94:97]
	v_mfma_f32_16x16x32_bf16 v[90:93], v[142:145], v[204:207], v[90:93]
	v_mfma_f32_16x16x32_bf16 v[78:81], v[134:137], v[218:221], v[78:81]
	v_mfma_f32_16x16x32_bf16 v[74:77], v[142:145], v[218:221], v[74:77]
	s_setprio 0
	s_barrier
	s_add_i32 s38, 0, 0x1c000
	s_add_i32 s19, s19, s80
	v_add_u32_e32 v213, s38, v199
	v_lshl_add_u64 v[162:163], v[162:163], 0, s[70:71]
	s_mov_b32 m0, s19
	ds_read_b128 v[222:225], v213
	ds_read_b128 v[226:229], v213 offset:1024
	ds_read_b128 v[230:233], v213 offset:2048
	ds_read_b128 v[234:237], v213 offset:3072
	global_load_lds_dwordx4 v[162:163], off
	v_lshl_add_u64 v[162:163], v[164:165], 0, s[70:71]
	s_add_i32 m0, s19, 0x2000
	s_nop 0
	global_load_lds_dwordx4 v[162:163], off
	s_barrier
	s_waitcnt lgkmcnt(0)
	s_setprio 1
	v_mfma_f32_16x16x32_bf16 v[118:121], v[222:225], v[146:149], v[118:121]
	v_mfma_f32_16x16x32_bf16 v[114:117], v[230:233], v[146:149], v[114:117]
	v_mfma_f32_16x16x32_bf16 v[102:105], v[222:225], v[186:189], v[102:105]
	v_mfma_f32_16x16x32_bf16 v[98:101], v[230:233], v[186:189], v[98:101]
	v_mfma_f32_16x16x32_bf16 v[86:89], v[222:225], v[194:197], v[86:89]
	v_mfma_f32_16x16x32_bf16 v[82:85], v[230:233], v[194:197], v[82:85]
	v_mfma_f32_16x16x32_bf16 v[70:73], v[222:225], v[214:217], v[70:73]
	v_mfma_f32_16x16x32_bf16 v[62:65], v[230:233], v[214:217], v[62:65]
	v_mfma_f32_16x16x32_bf16 v[118:121], v[226:229], v[150:153], v[118:121]
	v_mfma_f32_16x16x32_bf16 v[114:117], v[234:237], v[150:153], v[114:117]
	v_mfma_f32_16x16x32_bf16 v[102:105], v[226:229], v[190:193], v[102:105]
	v_mfma_f32_16x16x32_bf16 v[98:101], v[234:237], v[190:193], v[98:101]
	v_mfma_f32_16x16x32_bf16 v[86:89], v[226:229], v[204:207], v[86:89]
	v_mfma_f32_16x16x32_bf16 v[82:85], v[234:237], v[204:207], v[82:85]
	v_mfma_f32_16x16x32_bf16 v[70:73], v[226:229], v[218:221], v[70:73]
	v_mfma_f32_16x16x32_bf16 v[62:65], v[234:237], v[218:221], v[62:65]
	s_setprio 0
	s_mov_b32 m0, s83
	v_lshl_add_u64 v[162:163], v[208:209], 0, s[70:71]
	s_barrier
	ds_read_b128 v[146:149], v202 offset:49152
	ds_read_b128 v[150:153], v202 offset:50176
	ds_read_b128 v[186:189], v202 offset:51200
	ds_read_b128 v[190:193], v202 offset:52224
	ds_read_b128 v[194:197], v202 offset:53248
	ds_read_b128 v[204:207], v202 offset:54272
	ds_read_b128 v[214:217], v202 offset:55296
	ds_read_b128 v[218:221], v202 offset:56320
	global_load_lds_dwordx4 v[162:163], off
	v_lshl_add_u64 v[162:163], v[238:239], 0, s[70:71]
	s_mov_b32 m0, s84
	s_nop 0
	global_load_lds_dwordx4 v[162:163], off
	s_barrier
; #define PG8_STAGE(bufoff, gbase, voff) do { _Pragma("unroll") for (int _i = 0; _i < 2; ++_i) \
;         __builtin_amdgcn_global_load_lds((const unsigned*)((const char*)(gbase) + (voff)[_i]), (LAS unsigned*)(lds + (bufoff) + ldsw + _i * 8192), 16, 0, 0); } while (0)
; #define PG8_MMA(ai, bj, At, Bt) do { __builtin_amdgcn_s_setprio(1); _Pragma("unroll") for (int m = 0; m < 4; ++m) _Pragma("unroll") for (int n = 0; n < 2; ++n) _Pragma("unroll") for (int k = 0; k < 2; ++k) \
;         acc[ai][bj][m][n] = __builtin_amdgcn_mfma_f32_16x16x32_bf16(Bt[n][k], At[m][k], acc[ai][bj][m][n], 0, 0, 0); __builtin_amdgcn_s_setprio(0); } while (0)
; #define PG8_WAIT_V(n) asm volatile("s_waitcnt vmcnt(" #n ")" ::: "memory")
; #define PG8_WAIT_L(n) asm volatile("s_waitcnt lgkmcnt(" #n ")" ::: "memory")
; #define PG8_BAR __builtin_amdgcn_s_barrier()
; #define PG8_SCHED __builtin_amdgcn_sched_barrier(0)
; template <class Epi>
; DEVI void gemm_phase(LAS unsigned char* lds, const Gemm g, const Epi& E) {
;     ...
;             PG8_BAR; PG8_WAIT_L(0); PG8_MMA(1, 0, At, B0); PG8_BAR; PG8_SCHED;
;             PG8_STAGE(PG8_SB(1, 1), b3 + hstepB, voffB);
;             PG8_WAIT_V(6); PG8_BAR; PG8_MMA(1, 1, At, B1); PG8_BAR;
;         }
	s_waitcnt lgkmcnt(0)
	s_setprio 1
	v_mfma_f32_16x16x32_bf16 v[66:69], v[130:133], v[146:149], v[66:69]
	v_mfma_f32_16x16x32_bf16 v[54:57], v[138:141], v[146:149], v[54:57]
	v_mfma_f32_16x16x32_bf16 v[46:49], v[130:133], v[186:189], v[46:49]
	v_mfma_f32_16x16x32_bf16 v[38:41], v[138:141], v[186:189], v[38:41]
	v_mfma_f32_16x16x32_bf16 v[30:33], v[130:133], v[194:197], v[30:33]
	v_mfma_f32_16x16x32_bf16 v[22:25], v[138:141], v[194:197], v[22:25]
	v_mfma_f32_16x16x32_bf16 v[14:17], v[130:133], v[214:217], v[14:17]
	v_mfma_f32_16x16x32_bf16 v[4:7], v[138:141], v[214:217], v[4:7]
	v_mfma_f32_16x16x32_bf16 v[66:69], v[134:137], v[150:153], v[66:69]
	v_mfma_f32_16x16x32_bf16 v[54:57], v[142:145], v[150:153], v[54:57]
	v_mfma_f32_16x16x32_bf16 v[46:49], v[134:137], v[190:193], v[46:49]
	v_mfma_f32_16x16x32_bf16 v[38:41], v[142:145], v[190:193], v[38:41]
	v_mfma_f32_16x16x32_bf16 v[30:33], v[134:137], v[204:207], v[30:33]
	v_mfma_f32_16x16x32_bf16 v[22:25], v[142:145], v[204:207], v[22:25]
	v_mfma_f32_16x16x32_bf16 v[14:17], v[134:137], v[218:221], v[14:17]
	v_mfma_f32_16x16x32_bf16 v[4:7], v[142:145], v[218:221], v[4:7]
	s_setprio 0
	s_barrier
	s_add_u32 s26, s68, 0x40080
	s_addc_u32 s27, s69, 0
	s_add_i32 s19, s38, s80
	v_lshl_add_u64 v[130:131], s[26:27], 0, v[8:9]
	s_mov_b32 m0, s19
	s_nop 0
	global_load_lds_dwordx4 v[130:131], off
	v_lshl_add_u64 v[130:131], s[26:27], 0, v[180:181]
	s_add_i32 m0, s19, 0x2000
	s_nop 0
	global_load_lds_dwordx4 v[130:131], off
	s_waitcnt vmcnt(6)
	s_barrier
	s_setprio 1
	v_mfma_f32_16x16x32_bf16 v[58:61], v[222:225], v[146:149], v[58:61]
	v_mfma_f32_16x16x32_bf16 v[50:53], v[230:233], v[146:149], v[50:53]
	v_mfma_f32_16x16x32_bf16 v[42:45], v[222:225], v[186:189], v[42:45]
	v_mfma_f32_16x16x32_bf16 v[34:37], v[230:233], v[186:189], v[34:37]
	v_mfma_f32_16x16x32_bf16 v[26:29], v[222:225], v[194:197], v[26:29]
	v_mfma_f32_16x16x32_bf16 v[18:21], v[230:233], v[194:197], v[18:21]
	v_mfma_f32_16x16x32_bf16 v[10:13], v[222:225], v[214:217], v[10:13]
	v_mfma_f32_16x16x32_bf16 v[0:3], v[230:233], v[214:217], v[0:3]
	v_mfma_f32_16x16x32_bf16 v[58:61], v[226:229], v[150:153], v[58:61]
	v_mfma_f32_16x16x32_bf16 v[50:53], v[234:237], v[150:153], v[50:53]
	v_mfma_f32_16x16x32_bf16 v[42:45], v[226:229], v[190:193], v[42:45]
	v_mfma_f32_16x16x32_bf16 v[34:37], v[234:237], v[190:193], v[34:37]
	v_mfma_f32_16x16x32_bf16 v[26:29], v[226:229], v[204:207], v[26:29]
	v_mfma_f32_16x16x32_bf16 v[18:21], v[234:237], v[204:207], v[18:21]
	v_mfma_f32_16x16x32_bf16 v[10:13], v[226:229], v[218:221], v[10:13]
	v_mfma_f32_16x16x32_bf16 v[0:3], v[234:237], v[218:221], v[0:3]
	s_setprio 0
	s_add_i32 s18, s18, 2
	s_add_u32 s6, s6, 0x100
	s_addc_u32 s7, s7, 0
	s_add_u32 s11, s11, 0x100
	s_addc_u32 s13, s13, 0
	s_cmp_gt_u32 s18, 13
	s_barrier
	s_cbranch_scc0 .LBB0_1507
; #define LAS __attribute__((address_space(3)))
; template <class Epi>
; DEVI void gemm_phase(LAS unsigned char* lds, const Gemm g, const Epi& E) {
;     ...
;             const int row0 = cur.pm * BM + wr * 64 + fr, col0 = cur.pn * BM + wc * 32 + (Epi::PERM ? 8 : 4) * fq; constexpr int NST = Epi::PERM ? 4 : 16;
;             float rsv[8];
;             if constexpr (Epi::RS) { f32x4 q4[8];
; #pragma unroll
;                 for (int i = 0; i < 8; ++i) q4[i] = *(const f32x4*)(E.ssq_in + (size_t)(row0 + (i >> 2) * HALF + (i & 3) * 16) * 4);
; #pragma unroll
;                 for (int i = 0; i < 8; ++i) rsv[i] = rsqrtf((((q4[i][0] + q4[i][1]) + q4[i][2]) + q4[i][3]) * (1.f / DM) + 1e-6f); }
;             if constexpr (Epi::SOFTMAX) {
;                 LAS float* red = (LAS float*)(lds + 131072);
; #pragma unroll
;                 for (int ai = 0; ai < 2; ++ai)
; #pragma unroll
;                     for (int m = 0; m < 4; ++m) { const float sc = rsv[ai * 4 + m] * 0.0625f; float part = 0.f;
; #pragma unroll
;                         for (int bj = 0; bj < 2; ++bj)
; #pragma unroll
;                             for (int n = 0; n < 2; ++n)
; #pragma unroll
;                                 for (int j = 0; j < 4; ++j) { const float e = __expf(fmaxf(fminf(acc[ai][bj][m][n][j] * sc, 80.f), -80.f)); acc[ai][bj][m][n][j] = e; part += e; }
;                         part += __shfl_xor(part, 16); part += __shfl_xor(part, 32);
;                         if (fq == 0) red[(wr * 4 + wc) * 128 + ai * 64 + m * 16 + fr] = part; }
	v_lshl_add_u32 v194, s46, 8, v198
	v_or_b32_e32 v192, 16, v194
	v_ashrrev_i32_e32 v195, 31, v194
	v_ashrrev_i32_e32 v193, 31, v192
	v_lshl_add_u64 v[130:131], v[194:195], 4, s[8:9]
	v_lshl_add_u64 v[134:135], v[192:193], 4, s[8:9]
	global_load_dwordx4 v[130:133], v[130:131], off
	v_and_b32_e32 v139, 64, v155
	global_load_dwordx4 v[134:137], v[134:135], off
	v_add_u32_e32 v138, 0x90, v194
	v_add_u32_e32 v140, 0xa0, v194
	v_add_u32_e32 v205, 64, v139
	v_ashrrev_i32_e32 v139, 31, v138
	v_ashrrev_i32_e32 v141, 31, v140
	v_lshl_add_u64 v[164:165], v[138:139], 4, s[8:9]
	v_lshl_add_u64 v[206:207], v[140:141], 4, s[8:9]
	v_xor_b32_e32 v144, 16, v155
	v_or_b32_e32 v190, 32, v194
	v_or_b32_e32 v188, 48, v194
	v_add_u32_e32 v186, 0x80, v194
	v_cmp_lt_i32_e32 vcc, v144, v205
	v_add_u32_e32 v142, 0xb0, v194
	v_ashrrev_i32_e32 v191, 31, v190
	v_ashrrev_i32_e32 v189, 31, v188
	v_ashrrev_i32_e32 v187, 31, v186
	v_cndmask_b32_e32 v146, v155, v144, vcc
	v_ashrrev_i32_e32 v143, 31, v142
	v_lshl_add_u64 v[144:145], v[190:191], 4, s[8:9]
	v_lshl_add_u64 v[150:151], v[188:189], 4, s[8:9]
	v_lshl_add_u64 v[162:163], v[186:187], 4, s[8:9]
	v_lshl_add_u64 v[208:209], v[142:143], 4, s[8:9]
	v_lshlrev_b32_e32 v204, 2, v146
	global_load_dwordx4 v[146:149], v[144:145], off
	s_nop 0
	global_load_dwordx4 v[150:153], v[150:151], off
	s_waitcnt vmcnt(0)
	v_mov_b32_e32 v139, v130
	v_mov_b32_e32 v141, v132
	v_mov_b32_e32 v138, v134
	v_mov_b32_e32 v130, v135
	v_mov_b32_e32 v140, v136
	v_pk_add_f32 v[130:131], v[138:139], v[130:131]
	v_mov_b32_e32 v132, v137
	v_pk_add_f32 v[130:131], v[140:141], v[130:131]
	s_nop 0
	v_pk_add_f32 v[130:131], v[132:133], v[130:131]
	s_nop 0
	v_pk_fma_f32 v[196:197], v[130:131], s[72:73], v[160:161] op_sel_hi:[1,0,0]
	s_nop 0
	v_mul_f32_e32 v130, 0x4b800000, v197
	v_cmp_gt_f32_e32 vcc, s94, v197
	s_nop 1
	v_cndmask_b32_e32 v130, v197, v130, vcc
	v_rsq_f32_e32 v197, v130
	global_load_dwordx4 v[138:141], v[162:163], off
	global_load_dwordx4 v[142:145], v[164:165], off
	global_load_dwordx4 v[130:133], v[206:207], off
	global_load_dwordx4 v[134:137], v[208:209], off
	v_mul_f32_e32 v162, 0x45800000, v197
	v_cndmask_b32_e32 v162, v197, v162, vcc
	v_mul_f32_e32 v162, 0x3d800000, v162
	v_mul_f32_e32 v126, v126, v162
	v_mul_f32_e32 v127, v127, v162
	v_mul_f32_e32 v124, v124, v162
	v_min_f32_e32 v126, 0x42a00000, v126
	v_mul_f32_e32 v128, v128, v162
	v_mul_f32_e32 v125, v125, v162
	v_min_f32_e32 v127, 0x42a00000, v127
	v_min_f32_e32 v124, 0x42a00000, v124
	v_max_f32_e32 v126, 0xc2a00000, v126
	v_mul_f32_e32 v129, v129, v162
	v_min_f32_e32 v128, 0x42a00000, v128
	v_min_f32_e32 v125, 0x42a00000, v125
	v_max_f32_e32 v127, 0xc2a00000, v127
	v_max_f32_e32 v124, 0xc2a00000, v124
	v_mul_f32_e32 v126, 0x3fb8aa3b, v126
	v_mul_f32_e32 v122, v122, v162
	v_min_f32_e32 v129, 0x42a00000, v129
	v_max_f32_e32 v128, 0xc2a00000, v128
	v_max_f32_e32 v125, 0xc2a00000, v125
	v_mul_f32_e32 v127, 0x3fb8aa3b, v127
	v_mul_f32_e32 v163, 0x3fb8aa3b, v124
	v_exp_f32_e32 v124, v126
	v_mul_f32_e32 v123, v123, v162
	v_min_f32_e32 v122, 0x42a00000, v122
	v_max_f32_e32 v129, 0xc2a00000, v129
	v_mul_f32_e32 v128, 0x3fb8aa3b, v128
	v_mul_f32_e32 v164, 0x3fb8aa3b, v125
	v_exp_f32_e32 v125, v127
	v_min_f32_e32 v123, 0x42a00000, v123
	v_max_f32_e32 v122, 0xc2a00000, v122
	v_mul_f32_e32 v129, 0x3fb8aa3b, v129
	v_exp_f32_e32 v128, v128
	v_max_f32_e32 v123, 0xc2a00000, v123
	v_mul_f32_e32 v122, 0x3fb8aa3b, v122
	v_exp_f32_e32 v129, v129
	v_mul_f32_e32 v118, v118, v162
	v_mul_f32_e32 v123, 0x3fb8aa3b, v123
	v_exp_f32_e32 v122, v122
	v_exp_f32_e32 v126, v163
	v_add_f32_e32 v163, 0, v124
	v_mul_f32_e32 v119, v119, v162
	v_min_f32_e32 v118, 0x42a00000, v118
	v_exp_f32_e32 v123, v123
	v_add_f32_e32 v163, v125, v163
	v_mul_f32_e32 v120, v120, v162
	v_min_f32_e32 v119, 0x42a00000, v119
	v_max_f32_e32 v118, 0xc2a00000, v118
	v_add_f32_e32 v163, v128, v163
	v_max_f32_e32 v119, 0xc2a00000, v119
	v_mul_f32_e32 v118, 0x3fb8aa3b, v118
	v_exp_f32_e32 v127, v164
	v_add_f32_e32 v163, v129, v163
	v_min_f32_e32 v120, 0x42a00000, v120
	v_mul_f32_e32 v121, v121, v162
	v_mul_f32_e32 v119, 0x3fb8aa3b, v119
	v_exp_f32_e32 v118, v118
	v_add_f32_e32 v163, v122, v163
	v_max_f32_e32 v120, 0xc2a00000, v120
	v_min_f32_e32 v121, 0x42a00000, v121
	v_mul_f32_e32 v114, v114, v162
	v_exp_f32_e32 v119, v119
	v_add_f32_e32 v163, v123, v163
	v_mul_f32_e32 v120, 0x3fb8aa3b, v120
	v_max_f32_e32 v121, 0xc2a00000, v121
	v_min_f32_e32 v114, 0x42a00000, v114
	v_mul_f32_e32 v115, v115, v162
	v_add_f32_e32 v163, v126, v163
	v_exp_f32_e32 v120, v120
	v_mul_f32_e32 v121, 0x3fb8aa3b, v121
	v_max_f32_e32 v114, 0xc2a00000, v114
	v_min_f32_e32 v115, 0x42a00000, v115
	v_mul_f32_e32 v116, v116, v162
	v_add_f32_e32 v163, v127, v163
	v_exp_f32_e32 v121, v121
	v_mul_f32_e32 v114, 0x3fb8aa3b, v114
	v_max_f32_e32 v115, 0xc2a00000, v115
	v_min_f32_e32 v116, 0x42a00000, v116
	v_mul_f32_e32 v117, v117, v162
	v_add_f32_e32 v163, v118, v163
	v_exp_f32_e32 v114, v114
	v_mul_f32_e32 v115, 0x3fb8aa3b, v115
	v_max_f32_e32 v116, 0xc2a00000, v116
	v_min_f32_e32 v117, 0x42a00000, v117
	v_add_f32_e32 v163, v119, v163
	v_exp_f32_e32 v115, v115
	v_mul_f32_e32 v116, 0x3fb8aa3b, v116
	v_max_f32_e32 v117, 0xc2a00000, v117
	v_add_f32_e32 v163, v120, v163
	v_exp_f32_e32 v116, v116
	v_mul_f32_e32 v117, 0x3fb8aa3b, v117
	v_add_f32_e32 v163, v121, v163
	v_exp_f32_e32 v117, v117
	v_add_f32_e32 v162, v114, v163
	v_add_f32_e32 v162, v115, v162
	v_add_f32_e32 v162, v116, v162
	v_add_f32_e32 v162, v117, v162
	ds_bpermute_b32 v163, v204, v162
	v_xor_b32_e32 v164, 32, v155
	v_cmp_lt_i32_e32 vcc, v164, v205
	s_waitcnt lgkmcnt(0)
	v_add_f32_e32 v205, v162, v163
	v_cndmask_b32_e32 v164, v155, v164, vcc
	v_lshlrev_b32_e32 v197, 2, v164
	ds_bpermute_b32 v206, v197, v205
	v_cmp_gt_f32_e32 vcc, s94, v196
	s_and_saveexec_b64 s[6:7], s[2:3]
	s_cbranch_execz .LBB0_1510
	s_waitcnt lgkmcnt(0)
	v_add_f32_e32 v162, v205, v206
	ds_write_b32 v201, v162

; #define PG8_STAGE(bufoff, gbase, voff) do { _Pragma("unroll") for (int _i = 0; _i < 2; ++_i) \
;         __builtin_amdgcn_global_load_lds((const unsigned*)((const char*)(gbase) + (voff)[_i]), (LAS unsigned*)(lds + (bufoff) + ldsw + _i * 8192), 16, 0, 0); } while (0)
; #define PG8_LDA(dst, b, h) do { _Pragma("unroll") for (int m = 0; m < 4; ++m) _Pragma("unroll") for (int k = 0; k < 2; ++k) dst[m][k] = *(const LAS bf16x8*)(lds + PG8_SA(b, h) + aoff + m * 2048 + k * 1024); } while (0)
; #define PG8_LDB(dst, b, h) do { _Pragma("unroll") for (int n = 0; n < 2; ++n) _Pragma("unroll") for (int k = 0; k < 2; ++k) dst[n][k] = *(const LAS bf16x8*)(lds + PG8_SB(b, h) + boff + n * 2048 + k * 1024); } while (0)
; #define PG8_MMA(ai, bj, At, Bt) do { __builtin_amdgcn_s_setprio(1); _Pragma("unroll") for (int m = 0; m < 4; ++m) _Pragma("unroll") for (int n = 0; n < 2; ++n) _Pragma("unroll") for (int k = 0; k < 2; ++k) \
;         acc[ai][bj][m][n] = __builtin_amdgcn_mfma_f32_16x16x32_bf16(Bt[n][k], At[m][k], acc[ai][bj][m][n], 0, 0, 0); __builtin_amdgcn_s_setprio(0); } while (0)
; template <class Epi>
; DEVI void gemm_phase(LAS unsigned char* lds, const Gemm g, const Epi& E) {
;     ...
;         for (int t = 0; t < nt; t += 2) {
;             const bool last = (t == nt - 2);
;             const char* a1 = cA + (size_t)(t + 1) * kstep;
;             const char* a2 = last ? nA : cA + (size_t)(t + 2) * kstep; const char* b2 = last ? nB : cB + (size_t)(t + 2) * kstep;
;             const char* a3 = a2 + kstep; const char* b3 = b2 + kstep;
;             PG8_LDB(B0, 0, 0); PG8_SCHED; PG8_LDA(At, 0, 0); PG8_STAGE(PG8_SA(1, 1), a1 + hstepA, voffA);
;             PG8_WAIT_L(8); PG8_BAR; PG8_WAIT_L(0); PG8_MMA(0, 0, At, B0); PG8_BAR; PG8_SCHED;
;             PG8_LDB(B1, 0, 1); PG8_STAGE(PG8_SB(0, 0), b2, voffB);
;             PG8_BAR; PG8_WAIT_L(0); PG8_MMA(0, 1, At, B1); PG8_BAR;
;             PG8_LDA(At, 0, 1); PG8_STAGE(PG8_SA(0, 0), a2, voffA);
;             PG8_BAR; PG8_WAIT_L(0); PG8_MMA(1, 0, At, B0); PG8_BAR; PG8_SCHED;
;             PG8_STAGE(PG8_SB(0, 1), b2 + hstepB, voffB);
;             PG8_WAIT_V(6); PG8_BAR; PG8_MMA(1, 1, At, B1); PG8_BAR;
;             PG8_LDB(B0, 1, 0); PG8_SCHED; PG8_LDA(At, 1, 0); PG8_STAGE(PG8_SA(0, 1), a2 + hstepA, voffA);
;             PG8_WAIT_L(8); PG8_BAR; PG8_WAIT_L(0); PG8_MMA(0, 0, At, B0); PG8_BAR; PG8_SCHED;
.LBB0_1595:
	s_add_u32 s18, s8, 0xfffc0080
	s_addc_u32 s19, s9, -1
	s_add_i32 s26, 0, 0x10000
	v_add_u32_e32 v142, s26, v191
	ds_read_b128 v[130:133], v142
	ds_read_b128 v[134:137], v142 offset:1024
	ds_read_b128 v[138:141], v142 offset:2048
	ds_read_b128 v[142:145], v142 offset:3072
	s_cmp_eq_u32 s17, 12
	s_cselect_b32 s81, s0, s19
	s_cselect_b32 s80, s1, s18
	s_cselect_b32 s79, s37, s15
	s_cselect_b32 s78, s36, s13
	v_lshl_add_u64 v[162:163], s[8:9], 0, v[152:153]
	s_add_i32 m0, s69, 0xc000
	ds_read_b128 v[178:181], v196
	ds_read_b128 v[182:185], v196 offset:1024
	ds_read_b128 v[186:189], v196 offset:2048
	ds_read_b128 v[198:201], v196 offset:3072
	ds_read_b128 v[202:205], v196 offset:4096
	ds_read_b128 v[206:209], v196 offset:5120
	ds_read_b128 v[214:217], v196 offset:6144
	ds_read_b128 v[218:221], v196 offset:7168
	global_load_lds_dwordx4 v[162:163], off
	v_lshl_add_u64 v[162:163], s[8:9], 0, v[176:177]
	s_add_i32 m0, s69, 0xe000
	s_nop 0
	global_load_lds_dwordx4 v[162:163], off
	s_waitcnt lgkmcnt(8)
	s_barrier
	s_waitcnt lgkmcnt(0)
	s_setprio 1
	v_mfma_f32_16x16x32_bf16 v[126:129], v[130:133], v[178:181], v[126:129]
	v_mfma_f32_16x16x32_bf16 v[122:125], v[138:141], v[178:181], v[122:125]
	v_mfma_f32_16x16x32_bf16 v[110:113], v[130:133], v[186:189], v[110:113]
	v_mfma_f32_16x16x32_bf16 v[106:109], v[138:141], v[186:189], v[106:109]
	v_mfma_f32_16x16x32_bf16 v[94:97], v[130:133], v[202:205], v[94:97]
	v_mfma_f32_16x16x32_bf16 v[90:93], v[138:141], v[202:205], v[90:93]
	v_mfma_f32_16x16x32_bf16 v[78:81], v[130:133], v[214:217], v[78:81]
	v_mfma_f32_16x16x32_bf16 v[74:77], v[138:141], v[214:217], v[74:77]
	v_mfma_f32_16x16x32_bf16 v[126:129], v[134:137], v[182:185], v[126:129]
	v_mfma_f32_16x16x32_bf16 v[122:125], v[142:145], v[182:185], v[122:125]
	v_mfma_f32_16x16x32_bf16 v[110:113], v[134:137], v[198:201], v[110:113]
	v_mfma_f32_16x16x32_bf16 v[106:109], v[142:145], v[198:201], v[106:109]
	v_mfma_f32_16x16x32_bf16 v[94:97], v[134:137], v[206:209], v[94:97]
	v_mfma_f32_16x16x32_bf16 v[90:93], v[142:145], v[206:209], v[90:93]
	v_mfma_f32_16x16x32_bf16 v[78:81], v[134:137], v[218:221], v[78:81]
	v_mfma_f32_16x16x32_bf16 v[74:77], v[142:145], v[218:221], v[74:77]
	s_setprio 0
	s_barrier
	s_add_i32 s27, 0, 0x14000
	v_add_u32_e32 v162, s27, v191
	s_add_i32 s18, s26, s82
	ds_read_b128 v[222:225], v162
	ds_read_b128 v[226:229], v162 offset:1024
	ds_read_b128 v[230:233], v162 offset:2048
	ds_read_b128 v[234:237], v162 offset:3072
	v_lshl_add_u64 v[162:163], s[78:79], 0, v[8:9]
	s_mov_b32 m0, s18
	v_lshl_add_u64 v[164:165], s[78:79], 0, v[150:151]
	global_load_lds_dwordx4 v[162:163], off
	s_add_i32 m0, s18, 0x2000
	s_nop 0
	global_load_lds_dwordx4 v[164:165], off
	s_barrier
	s_waitcnt lgkmcnt(0)
	s_setprio 1
	v_mfma_f32_16x16x32_bf16 v[118:121], v[222:225], v[178:181], v[118:121]
	v_mfma_f32_16x16x32_bf16 v[114:117], v[230:233], v[178:181], v[114:117]
	v_mfma_f32_16x16x32_bf16 v[102:105], v[222:225], v[186:189], v[102:105]
	v_mfma_f32_16x16x32_bf16 v[98:101], v[230:233], v[186:189], v[98:101]
	v_mfma_f32_16x16x32_bf16 v[86:89], v[222:225], v[202:205], v[86:89]
	v_mfma_f32_16x16x32_bf16 v[82:85], v[230:233], v[202:205], v[82:85]
	v_mfma_f32_16x16x32_bf16 v[70:73], v[222:225], v[214:217], v[70:73]
	v_mfma_f32_16x16x32_bf16 v[66:69], v[230:233], v[214:217], v[66:69]
	v_mfma_f32_16x16x32_bf16 v[118:121], v[226:229], v[182:185], v[118:121]
	v_mfma_f32_16x16x32_bf16 v[114:117], v[234:237], v[182:185], v[114:117]
	v_mfma_f32_16x16x32_bf16 v[102:105], v[226:229], v[198:201], v[102:105]
	v_mfma_f32_16x16x32_bf16 v[98:101], v[234:237], v[198:201], v[98:101]
	v_mfma_f32_16x16x32_bf16 v[86:89], v[226:229], v[206:209], v[86:89]
	v_mfma_f32_16x16x32_bf16 v[82:85], v[234:237], v[206:209], v[82:85]
	v_mfma_f32_16x16x32_bf16 v[70:73], v[226:229], v[218:221], v[70:73]
	v_mfma_f32_16x16x32_bf16 v[66:69], v[234:237], v[218:221], v[66:69]
	s_setprio 0
	s_mov_b32 m0, s69
	v_lshl_add_u64 v[238:239], s[80:81], 0, v[146:147]
	s_barrier
	ds_read_b128 v[178:181], v196 offset:16384
	ds_read_b128 v[182:185], v196 offset:17408
	ds_read_b128 v[186:189], v196 offset:18432
	ds_read_b128 v[198:201], v196 offset:19456
	ds_read_b128 v[202:205], v196 offset:20480
	ds_read_b128 v[206:209], v196 offset:21504
	ds_read_b128 v[214:217], v196 offset:22528
	ds_read_b128 v[218:221], v196 offset:23552
	global_load_lds_dwordx4 v[238:239], off
	v_lshl_add_u64 v[240:241], s[80:81], 0, v[148:149]
	s_mov_b32 m0, s83
	s_nop 0
	global_load_lds_dwordx4 v[240:241], off
	s_barrier
	s_waitcnt lgkmcnt(0)
	s_setprio 1
	v_mfma_f32_16x16x32_bf16 v[62:65], v[130:133], v[178:181], v[62:65]
	v_mfma_f32_16x16x32_bf16 v[58:61], v[138:141], v[178:181], v[58:61]
	v_mfma_f32_16x16x32_bf16 v[46:49], v[130:133], v[186:189], v[46:49]
	v_mfma_f32_16x16x32_bf16 v[42:45], v[138:141], v[186:189], v[42:45]
	v_mfma_f32_16x16x32_bf16 v[30:33], v[130:133], v[202:205], v[30:33]
	v_mfma_f32_16x16x32_bf16 v[26:29], v[138:141], v[202:205], v[26:29]
	v_mfma_f32_16x16x32_bf16 v[14:17], v[130:133], v[214:217], v[14:17]
	v_mfma_f32_16x16x32_bf16 v[10:13], v[138:141], v[214:217], v[10:13]
	v_mfma_f32_16x16x32_bf16 v[62:65], v[134:137], v[182:185], v[62:65]
	v_mfma_f32_16x16x32_bf16 v[58:61], v[142:145], v[182:185], v[58:61]
	v_mfma_f32_16x16x32_bf16 v[46:49], v[134:137], v[198:201], v[46:49]
	v_mfma_f32_16x16x32_bf16 v[42:45], v[142:145], v[198:201], v[42:45]
	v_mfma_f32_16x16x32_bf16 v[30:33], v[134:137], v[206:209], v[30:33]
	v_mfma_f32_16x16x32_bf16 v[26:29], v[142:145], v[206:209], v[26:29]
	v_mfma_f32_16x16x32_bf16 v[14:17], v[134:137], v[218:221], v[14:17]
	v_mfma_f32_16x16x32_bf16 v[10:13], v[142:145], v[218:221], v[10:13]
	s_setprio 0
	s_barrier
; #define PG8_STAGE(bufoff, gbase, voff) do { _Pragma("unroll") for (int _i = 0; _i < 2; ++_i) \
;         __builtin_amdgcn_global_load_lds((const unsigned*)((const char*)(gbase) + (voff)[_i]), (LAS unsigned*)(lds + (bufoff) + ldsw + _i * 8192), 16, 0, 0); } while (0)
; #define PG8_LDA(dst, b, h) do { _Pragma("unroll") for (int m = 0; m < 4; ++m) _Pragma("unroll") for (int k = 0; k < 2; ++k) dst[m][k] = *(const LAS bf16x8*)(lds + PG8_SA(b, h) + aoff + m * 2048 + k * 1024); } while (0)
; #define PG8_LDB(dst, b, h) do { _Pragma("unroll") for (int n = 0; n < 2; ++n) _Pragma("unroll") for (int k = 0; k < 2; ++k) dst[n][k] = *(const LAS bf16x8*)(lds + PG8_SB(b, h) + boff + n * 2048 + k * 1024); } while (0)
; #define PG8_MMA(ai, bj, At, Bt) do { __builtin_amdgcn_s_setprio(1); _Pragma("unroll") for (int m = 0; m < 4; ++m) _Pragma("unroll") for (int n = 0; n < 2; ++n) _Pragma("unroll") for (int k = 0; k < 2; ++k) \
;         acc[ai][bj][m][n] = __builtin_amdgcn_mfma_f32_16x16x32_bf16(Bt[n][k], At[m][k], acc[ai][bj][m][n], 0, 0, 0); __builtin_amdgcn_s_setprio(0); } while (0)
; #define PG8_WAIT_V(n) asm volatile("s_waitcnt vmcnt(" #n ")" ::: "memory")
; #define PG8_WAIT_L(n) asm volatile("s_waitcnt lgkmcnt(" #n ")" ::: "memory")
; #define PG8_BAR __builtin_amdgcn_s_barrier()
; #define PG8_SCHED __builtin_amdgcn_sched_barrier(0)
; template <class Epi>
; DEVI void gemm_phase(LAS unsigned char* lds, const Gemm g, const Epi& E) {
;     ...
;             PG8_WAIT_V(6); PG8_BAR; PG8_MMA(1, 1, At, B1); PG8_BAR;
;             PG8_LDB(B0, 1, 0); PG8_SCHED; PG8_LDA(At, 1, 0); PG8_STAGE(PG8_SA(0, 1), a2 + hstepA, voffA);
;             PG8_WAIT_L(8); PG8_BAR; PG8_WAIT_L(0); PG8_MMA(0, 0, At, B0); PG8_BAR; PG8_SCHED;
;             PG8_LDB(B1, 1, 1); PG8_STAGE(PG8_SB(1, 0), b3, voffB);
;             PG8_BAR; PG8_WAIT_L(0); PG8_MMA(0, 1, At, B1); PG8_BAR;
;             PG8_LDA(At, 1, 1); PG8_STAGE(PG8_SA(1, 0), a3, voffA);
;             PG8_BAR; PG8_WAIT_L(0); PG8_MMA(1, 0, At, B0); PG8_BAR; PG8_SCHED;
	s_add_u32 s18, s78, 0x40000
	s_addc_u32 s19, s79, 0
	s_add_i32 s26, s27, s82
	v_lshl_add_u64 v[130:131], s[18:19], 0, v[8:9]
	s_mov_b32 m0, s26
	s_nop 0
	global_load_lds_dwordx4 v[130:131], off
	v_lshl_add_u64 v[130:131], s[18:19], 0, v[150:151]
	s_add_i32 m0, s26, 0x2000
	s_nop 0
	global_load_lds_dwordx4 v[130:131], off
	s_waitcnt vmcnt(6)
	s_barrier
	s_setprio 1
	v_mfma_f32_16x16x32_bf16 v[54:57], v[222:225], v[178:181], v[54:57]
	v_mfma_f32_16x16x32_bf16 v[50:53], v[230:233], v[178:181], v[50:53]
	v_mfma_f32_16x16x32_bf16 v[38:41], v[222:225], v[186:189], v[38:41]
	v_mfma_f32_16x16x32_bf16 v[34:37], v[230:233], v[186:189], v[34:37]
	v_mfma_f32_16x16x32_bf16 v[22:25], v[222:225], v[202:205], v[22:25]
	v_mfma_f32_16x16x32_bf16 v[18:21], v[230:233], v[202:205], v[18:21]
	v_mfma_f32_16x16x32_bf16 v[4:7], v[222:225], v[214:217], v[4:7]
	v_mfma_f32_16x16x32_bf16 v[0:3], v[230:233], v[214:217], v[0:3]
	v_mfma_f32_16x16x32_bf16 v[54:57], v[226:229], v[182:185], v[54:57]
	v_mfma_f32_16x16x32_bf16 v[50:53], v[234:237], v[182:185], v[50:53]
	v_mfma_f32_16x16x32_bf16 v[38:41], v[226:229], v[198:201], v[38:41]
	v_mfma_f32_16x16x32_bf16 v[34:37], v[234:237], v[198:201], v[34:37]
	v_mfma_f32_16x16x32_bf16 v[22:25], v[226:229], v[206:209], v[22:25]
	v_mfma_f32_16x16x32_bf16 v[18:21], v[234:237], v[206:209], v[18:21]
	v_mfma_f32_16x16x32_bf16 v[4:7], v[226:229], v[218:221], v[4:7]
	v_mfma_f32_16x16x32_bf16 v[0:3], v[234:237], v[218:221], v[0:3]
	s_setprio 0
	s_add_i32 s26, 0, 0x18000
	v_add_u32_e32 v142, s26, v191
	s_barrier
	ds_read_b128 v[130:133], v142
	ds_read_b128 v[134:137], v142 offset:1024
	ds_read_b128 v[138:141], v142 offset:2048
	ds_read_b128 v[142:145], v142 offset:3072
	s_add_u32 s18, s80, 0x40000
	s_addc_u32 s19, s81, 0
	s_mov_b32 m0, s84
	v_lshl_add_u64 v[222:223], s[18:19], 0, v[146:147]
	ds_read_b128 v[178:181], v196 offset:32768
	ds_read_b128 v[182:185], v196 offset:33792
	ds_read_b128 v[186:189], v196 offset:34816
	ds_read_b128 v[198:201], v196 offset:35840
	ds_read_b128 v[202:205], v196 offset:36864
	ds_read_b128 v[206:209], v196 offset:37888
	ds_read_b128 v[214:217], v196 offset:38912
	ds_read_b128 v[218:221], v196 offset:39936
	global_load_lds_dwordx4 v[222:223], off
	v_lshl_add_u64 v[222:223], s[18:19], 0, v[148:149]
	s_mov_b32 m0, s85
	s_nop 0
	global_load_lds_dwordx4 v[222:223], off
	s_waitcnt lgkmcnt(8)
	s_barrier
	s_waitcnt lgkmcnt(0)
	s_setprio 1
	v_mfma_f32_16x16x32_bf16 v[126:129], v[130:133], v[178:181], v[126:129]
	v_mfma_f32_16x16x32_bf16 v[122:125], v[138:141], v[178:181], v[122:125]
	v_mfma_f32_16x16x32_bf16 v[110:113], v[130:133], v[186:189], v[110:113]
	v_mfma_f32_16x16x32_bf16 v[106:109], v[138:141], v[186:189], v[106:109]
	v_mfma_f32_16x16x32_bf16 v[94:97], v[130:133], v[202:205], v[94:97]
	v_mfma_f32_16x16x32_bf16 v[90:93], v[138:141], v[202:205], v[90:93]
	v_mfma_f32_16x16x32_bf16 v[78:81], v[130:133], v[214:217], v[78:81]
	v_mfma_f32_16x16x32_bf16 v[74:77], v[138:141], v[214:217], v[74:77]
	v_mfma_f32_16x16x32_bf16 v[126:129], v[134:137], v[182:185], v[126:129]
	v_mfma_f32_16x16x32_bf16 v[122:125], v[142:145], v[182:185], v[122:125]
	v_mfma_f32_16x16x32_bf16 v[110:113], v[134:137], v[198:201], v[110:113]
	v_mfma_f32_16x16x32_bf16 v[106:109], v[142:145], v[198:201], v[106:109]
	v_mfma_f32_16x16x32_bf16 v[94:97], v[134:137], v[206:209], v[94:97]
	v_mfma_f32_16x16x32_bf16 v[90:93], v[142:145], v[206:209], v[90:93]
	v_mfma_f32_16x16x32_bf16 v[78:81], v[134:137], v[218:221], v[78:81]
	v_mfma_f32_16x16x32_bf16 v[74:77], v[142:145], v[218:221], v[74:77]
	s_setprio 0
	s_barrier
	s_add_i32 s27, 0, 0x1c000
	s_add_i32 s18, s26, s82
	v_add_u32_e32 v197, s27, v191
	v_lshl_add_u64 v[162:163], v[162:163], 0, s[70:71]
	s_mov_b32 m0, s18
	ds_read_b128 v[222:225], v197
	ds_read_b128 v[226:229], v197 offset:1024
	ds_read_b128 v[230:233], v197 offset:2048
	ds_read_b128 v[234:237], v197 offset:3072
	global_load_lds_dwordx4 v[162:163], off
	v_lshl_add_u64 v[162:163], v[164:165], 0, s[70:71]
	s_add_i32 m0, s18, 0x2000
	s_nop 0
	global_load_lds_dwordx4 v[162:163], off
	s_barrier
	s_waitcnt lgkmcnt(0)
	s_setprio 1
	v_mfma_f32_16x16x32_bf16 v[118:121], v[222:225], v[178:181], v[118:121]
	v_mfma_f32_16x16x32_bf16 v[114:117], v[230:233], v[178:181], v[114:117]
	v_mfma_f32_16x16x32_bf16 v[102:105], v[222:225], v[186:189], v[102:105]
	v_mfma_f32_16x16x32_bf16 v[98:101], v[230:233], v[186:189], v[98:101]
	v_mfma_f32_16x16x32_bf16 v[86:89], v[222:225], v[202:205], v[86:89]
	v_mfma_f32_16x16x32_bf16 v[82:85], v[230:233], v[202:205], v[82:85]
	v_mfma_f32_16x16x32_bf16 v[70:73], v[222:225], v[214:217], v[70:73]
	v_mfma_f32_16x16x32_bf16 v[66:69], v[230:233], v[214:217], v[66:69]
	v_mfma_f32_16x16x32_bf16 v[118:121], v[226:229], v[182:185], v[118:121]
	v_mfma_f32_16x16x32_bf16 v[114:117], v[234:237], v[182:185], v[114:117]
	v_mfma_f32_16x16x32_bf16 v[102:105], v[226:229], v[198:201], v[102:105]
	v_mfma_f32_16x16x32_bf16 v[98:101], v[234:237], v[198:201], v[98:101]
	v_mfma_f32_16x16x32_bf16 v[86:89], v[226:229], v[206:209], v[86:89]
	v_mfma_f32_16x16x32_bf16 v[82:85], v[234:237], v[206:209], v[82:85]
	v_mfma_f32_16x16x32_bf16 v[70:73], v[226:229], v[218:221], v[70:73]
	v_mfma_f32_16x16x32_bf16 v[66:69], v[234:237], v[218:221], v[66:69]
	s_setprio 0
	s_mov_b32 m0, s86
	v_lshl_add_u64 v[162:163], v[238:239], 0, s[70:71]
	s_barrier
	ds_read_b128 v[178:181], v196 offset:49152
	ds_read_b128 v[182:185], v196 offset:50176
	ds_read_b128 v[186:189], v196 offset:51200
	ds_read_b128 v[198:201], v196 offset:52224
	ds_read_b128 v[202:205], v196 offset:53248
	ds_read_b128 v[206:209], v196 offset:54272
	ds_read_b128 v[214:217], v196 offset:55296
	ds_read_b128 v[218:221], v196 offset:56320
	global_load_lds_dwordx4 v[162:163], off
	v_lshl_add_u64 v[162:163], v[240:241], 0, s[70:71]
	s_mov_b32 m0, s87
	s_nop 0
	global_load_lds_dwordx4 v[162:163], off
	s_barrier
; #define PG8_STAGE(bufoff, gbase, voff) do { _Pragma("unroll") for (int _i = 0; _i < 2; ++_i) \
;         __builtin_amdgcn_global_load_lds((const unsigned*)((const char*)(gbase) + (voff)[_i]), (LAS unsigned*)(lds + (bufoff) + ldsw + _i * 8192), 16, 0, 0); } while (0)
; #define PG8_LDA(dst, b, h) do { _Pragma("unroll") for (int m = 0; m < 4; ++m) _Pragma("unroll") for (int k = 0; k < 2; ++k) dst[m][k] = *(const LAS bf16x8*)(lds + PG8_SA(b, h) + aoff + m * 2048 + k * 1024); } while (0)
; #define PG8_LDB(dst, b, h) do { _Pragma("unroll") for (int n = 0; n < 2; ++n) _Pragma("unroll") for (int k = 0; k < 2; ++k) dst[n][k] = *(const LAS bf16x8*)(lds + PG8_SB(b, h) + boff + n * 2048 + k * 1024); } while (0)
; #define PG8_MMA(ai, bj, At, Bt) do { __builtin_amdgcn_s_setprio(1); _Pragma("unroll") for (int m = 0; m < 4; ++m) _Pragma("unroll") for (int n = 0; n < 2; ++n) _Pragma("unroll") for (int k = 0; k < 2; ++k) \
;         acc[ai][bj][m][n] = __builtin_amdgcn_mfma_f32_16x16x32_bf16(Bt[n][k], At[m][k], acc[ai][bj][m][n], 0, 0, 0); __builtin_amdgcn_s_setprio(0); } while (0)
; #define PG8_WAIT_V(n) asm volatile("s_waitcnt vmcnt(" #n ")" ::: "memory")
; #define PG8_WAIT_L(n) asm volatile("s_waitcnt lgkmcnt(" #n ")" ::: "memory")
; #define PG8_BAR __builtin_amdgcn_s_barrier()
; #define PG8_SCHED __builtin_amdgcn_sched_barrier(0)
; template <class Epi>
; DEVI void gemm_phase(LAS unsigned char* lds, const Gemm g, const Epi& E) {
;     ...
;             PG8_WAIT_L(8); PG8_BAR; PG8_WAIT_L(0); PG8_MMA(0, 0, At, B0); PG8_BAR; PG8_SCHED;
;             PG8_LDB(B1, 1, 1); PG8_STAGE(PG8_SB(1, 0), b3, voffB);
;             PG8_BAR; PG8_WAIT_L(0); PG8_MMA(0, 1, At, B1); PG8_BAR;
;             PG8_LDA(At, 1, 1); PG8_STAGE(PG8_SA(1, 0), a3, voffA);
;             PG8_BAR; PG8_WAIT_L(0); PG8_MMA(1, 0, At, B0); PG8_BAR; PG8_SCHED;
;             PG8_STAGE(PG8_SB(1, 1), b3 + hstepB, voffB);
;             PG8_WAIT_V(6); PG8_BAR; PG8_MMA(1, 1, At, B1); PG8_BAR;
	s_waitcnt lgkmcnt(0)
	s_setprio 1
	v_mfma_f32_16x16x32_bf16 v[62:65], v[130:133], v[178:181], v[62:65]
	v_mfma_f32_16x16x32_bf16 v[58:61], v[138:141], v[178:181], v[58:61]
	v_mfma_f32_16x16x32_bf16 v[46:49], v[130:133], v[186:189], v[46:49]
	v_mfma_f32_16x16x32_bf16 v[42:45], v[138:141], v[186:189], v[42:45]
	v_mfma_f32_16x16x32_bf16 v[30:33], v[130:133], v[202:205], v[30:33]
	v_mfma_f32_16x16x32_bf16 v[26:29], v[138:141], v[202:205], v[26:29]
	v_mfma_f32_16x16x32_bf16 v[14:17], v[130:133], v[214:217], v[14:17]
	v_mfma_f32_16x16x32_bf16 v[10:13], v[138:141], v[214:217], v[10:13]
	v_mfma_f32_16x16x32_bf16 v[62:65], v[134:137], v[182:185], v[62:65]
	v_mfma_f32_16x16x32_bf16 v[58:61], v[142:145], v[182:185], v[58:61]
	v_mfma_f32_16x16x32_bf16 v[46:49], v[134:137], v[198:201], v[46:49]
	v_mfma_f32_16x16x32_bf16 v[42:45], v[142:145], v[198:201], v[42:45]
	v_mfma_f32_16x16x32_bf16 v[30:33], v[134:137], v[206:209], v[30:33]
	v_mfma_f32_16x16x32_bf16 v[26:29], v[142:145], v[206:209], v[26:29]
	v_mfma_f32_16x16x32_bf16 v[14:17], v[134:137], v[218:221], v[14:17]
	v_mfma_f32_16x16x32_bf16 v[10:13], v[142:145], v[218:221], v[10:13]
	s_setprio 0
	s_barrier
	s_add_u32 s18, s78, 0x40080
	s_addc_u32 s19, s79, 0
	s_add_i32 s26, s27, s82
	v_lshl_add_u64 v[130:131], s[18:19], 0, v[8:9]
	s_mov_b32 m0, s26
	s_nop 0
	global_load_lds_dwordx4 v[130:131], off
	v_lshl_add_u64 v[130:131], s[18:19], 0, v[150:151]
	s_add_i32 m0, s26, 0x2000
	s_nop 0
	global_load_lds_dwordx4 v[130:131], off
	s_waitcnt vmcnt(6)
	s_barrier
	s_setprio 1
	v_mfma_f32_16x16x32_bf16 v[54:57], v[222:225], v[178:181], v[54:57]
	v_mfma_f32_16x16x32_bf16 v[50:53], v[230:233], v[178:181], v[50:53]
	v_mfma_f32_16x16x32_bf16 v[38:41], v[222:225], v[186:189], v[38:41]
	v_mfma_f32_16x16x32_bf16 v[34:37], v[230:233], v[186:189], v[34:37]
	v_mfma_f32_16x16x32_bf16 v[22:25], v[222:225], v[202:205], v[22:25]
	v_mfma_f32_16x16x32_bf16 v[18:21], v[230:233], v[202:205], v[18:21]
	v_mfma_f32_16x16x32_bf16 v[4:7], v[222:225], v[214:217], v[4:7]
	v_mfma_f32_16x16x32_bf16 v[0:3], v[230:233], v[214:217], v[0:3]
	v_mfma_f32_16x16x32_bf16 v[54:57], v[226:229], v[182:185], v[54:57]
	v_mfma_f32_16x16x32_bf16 v[50:53], v[234:237], v[182:185], v[50:53]
	v_mfma_f32_16x16x32_bf16 v[38:41], v[226:229], v[198:201], v[38:41]
	v_mfma_f32_16x16x32_bf16 v[34:37], v[234:237], v[198:201], v[34:37]
	v_mfma_f32_16x16x32_bf16 v[22:25], v[226:229], v[206:209], v[22:25]
	v_mfma_f32_16x16x32_bf16 v[18:21], v[234:237], v[206:209], v[18:21]
	v_mfma_f32_16x16x32_bf16 v[4:7], v[226:229], v[218:221], v[4:7]
	v_mfma_f32_16x16x32_bf16 v[0:3], v[234:237], v[218:221], v[0:3]
	s_setprio 0
	s_add_i32 s17, s17, 2
	s_add_u32 s8, s8, 0x100
	s_addc_u32 s9, s9, 0
	s_add_u32 s13, s13, 0x100
	s_addc_u32 s15, s15, 0
	s_cmp_gt_u32 s17, 13
	s_barrier
	s_cbranch_scc0 .LBB0_1595
	s_lshl_b32 s0, s68, 8
	v_add_u32_e32 v182, s0, v190
	v_lshl_or_b32 v180, s12, 8, v195
	v_ashrrev_i32_e32 v183, 31, v182
	v_lshlrev_b64 v[130:131], 12, v[182:183]
	v_ashrrev_i32_e32 v181, 31, v180
	v_lshl_add_u64 v[130:131], s[30:31], 0, v[130:131]
	v_lshlrev_b64 v[184:185], 2, v[180:181]
	v_lshl_add_u64 v[162:163], v[130:131], 0, v[184:185]
	global_load_dwordx4 v[200:203], v[162:163], off
	global_load_dwordx4 v[204:207], v[162:163], off offset:16
	global_load_dwordx4 v[214:217], v[162:163], off offset:512
	global_load_dwordx4 v[218:221], v[162:163], off offset:528
	v_or_b32_e32 v188, 16, v182
	v_ashrrev_i32_e32 v189, 31, v188
	v_lshlrev_b64 v[130:131], 12, v[188:189]
	v_lshl_add_u64 v[130:131], s[30:31], 0, v[130:131]
	v_lshl_add_u64 v[186:187], v[130:131], 0, v[184:185]
	global_load_dwordx4 v[138:141], v[186:187], off offset:16
	global_load_dwordx4 v[142:145], v[186:187], off
	global_load_dwordx4 v[130:133], v[186:187], off offset:528
	global_load_dwordx4 v[134:137], v[186:187], off offset:512
	v_and_b32_e32 v165, 64, v155
	v_xor_b32_e32 v164, 16, v155
	v_add_u32_e32 v165, 64, v165
	v_xor_b32_e32 v179, 32, v155
	v_cmp_lt_i32_e32 vcc, v164, v165
	v_or_b32_e32 v178, 0x80, v180
	s_waitcnt vmcnt(0)
	v_pk_add_f32 v[128:129], v[128:129], v[202:203]
	v_cndmask_b32_e32 v164, v155, v164, vcc
	v_cmp_lt_i32_e32 vcc, v179, v165
	v_lshlrev_b32_e32 v198, 2, v164
	v_pk_add_f32 v[126:127], v[126:127], v[200:201]
	v_cndmask_b32_e32 v165, v155, v179, vcc
	v_lshlrev_b32_e32 v197, 2, v165
	v_lshlrev_b64 v[164:165], 10, v[182:183]
	v_pk_add_f32 v[124:125], v[124:125], v[206:207]
	v_pk_add_f32 v[122:123], v[122:123], v[204:205]
	v_pk_add_f32 v[120:121], v[120:121], v[216:217]
	v_pk_add_f32 v[118:119], v[118:119], v[214:215]
	v_pk_add_f32 v[202:203], v[116:117], v[220:221]
	v_pk_add_f32 v[200:201], v[114:115], v[218:219]
	v_lshl_add_u64 v[208:209], v[164:165], 0, v[180:181]
	global_store_dwordx4 v[162:163], v[126:129], off
	global_store_dwordx4 v[162:163], v[122:125], off offset:16
	v_cvt_pk_bf16_f32 v114, v126, v127
	v_cvt_pk_bf16_f32 v115, v128, v129
	v_cvt_pk_bf16_f32 v116, v122, v123
	v_cvt_pk_bf16_f32 v117, v124, v125
	v_mul_f32_e32 v127, v127, v127
	v_mul_f32_e32 v129, v129, v129
	v_mul_f32_e32 v123, v123, v123
	v_mul_f32_e32 v125, v125, v125
	v_mul_f32_e32 v183, v119, v119
	v_mul_f32_e32 v199, v121, v121
	v_mul_f32_e32 v204, v201, v201
	v_mul_f32_e32 v205, v203, v203
	v_lshl_add_u64 v[208:209], v[208:209], 1, s[24:25]
	v_fmac_f32_e32 v127, v126, v126
	v_fmac_f32_e32 v129, v128, v128
	v_fmac_f32_e32 v123, v122, v122
	v_fmac_f32_e32 v125, v124, v124
	v_fmac_f32_e32 v183, v118, v118
	v_fmac_f32_e32 v199, v120, v120
	v_fmac_f32_e32 v204, v200, v200
	v_fmac_f32_e32 v205, v202, v202
	global_store_dwordx4 v[208:209], v[114:117], off
	v_ashrrev_i32_e32 v179, 31, v178
	v_lshl_add_u64 v[164:165], v[164:165], 0, v[178:179]
	v_add_f32_e32 v114, v127, v129
	v_add_f32_e32 v115, v123, v125
	v_add_f32_e32 v116, v183, v199
	v_add_f32_e32 v117, v204, v205
	v_add_f32_e32 v114, v114, v115
	v_add_f32_e32 v115, v116, v117
	v_add_f32_e32 v114, v114, v115
	ds_bpermute_b32 v115, v198, v114
	global_store_dwordx4 v[162:163], v[118:121], off offset:512
	global_store_dwordx4 v[162:163], v[200:203], off offset:528
	v_cvt_pk_bf16_f32 v116, v118, v119
	v_cvt_pk_bf16_f32 v117, v120, v121
	v_cvt_pk_bf16_f32 v118, v200, v201
	s_waitcnt lgkmcnt(0)
	v_add_f32_e32 v114, v114, v115
	ds_bpermute_b32 v115, v197, v114
	v_cvt_pk_bf16_f32 v119, v202, v203
	v_lshl_add_u64 v[120:121], v[164:165], 1, s[24:25]
	global_store_dwordx4 v[120:121], v[116:119], off
	s_and_saveexec_b64 s[8:9], s[2:3]
	s_cbranch_execz .LBB0_1598
	s_waitcnt lgkmcnt(0)
	v_add_f32_e32 v114, v114, v115
	ds_write_b32 v192, v114

; #define PG8_STAGE(bufoff, gbase, voff) do { _Pragma("unroll") for (int _i = 0; _i < 2; ++_i) \
;         __builtin_amdgcn_global_load_lds((const unsigned*)((const char*)(gbase) + (voff)[_i]), (LAS unsigned*)(lds + (bufoff) + ldsw + _i * 8192), 16, 0, 0); } while (0)
; #define PG8_LDA(dst, b, h) do { _Pragma("unroll") for (int m = 0; m < 4; ++m) _Pragma("unroll") for (int k = 0; k < 2; ++k) dst[m][k] = *(const LAS bf16x8*)(lds + PG8_SA(b, h) + aoff + m * 2048 + k * 1024); } while (0)
; #define PG8_LDB(dst, b, h) do { _Pragma("unroll") for (int n = 0; n < 2; ++n) _Pragma("unroll") for (int k = 0; k < 2; ++k) dst[n][k] = *(const LAS bf16x8*)(lds + PG8_SB(b, h) + boff + n * 2048 + k * 1024); } while (0)
; #define PG8_MMA(ai, bj, At, Bt) do { __builtin_amdgcn_s_setprio(1); _Pragma("unroll") for (int m = 0; m < 4; ++m) _Pragma("unroll") for (int n = 0; n < 2; ++n) _Pragma("unroll") for (int k = 0; k < 2; ++k) \
;         acc[ai][bj][m][n] = __builtin_amdgcn_mfma_f32_16x16x32_bf16(Bt[n][k], At[m][k], acc[ai][bj][m][n], 0, 0, 0); __builtin_amdgcn_s_setprio(0); } while (0)
; template <class Epi>
; DEVI void gemm_phase(LAS unsigned char* lds, const Gemm g, const Epi& E) {
;     ...
;         for (int t = 0; t < nt; t += 2) {
;             const bool last = (t == nt - 2);
;             const char* a1 = cA + (size_t)(t + 1) * kstep;
;             const char* a2 = last ? nA : cA + (size_t)(t + 2) * kstep; const char* b2 = last ? nB : cB + (size_t)(t + 2) * kstep;
;             const char* a3 = a2 + kstep; const char* b3 = b2 + kstep;
;             PG8_LDB(B0, 0, 0); PG8_SCHED; PG8_LDA(At, 0, 0); PG8_STAGE(PG8_SA(1, 1), a1 + hstepA, voffA);
;             PG8_WAIT_L(8); PG8_BAR; PG8_WAIT_L(0); PG8_MMA(0, 0, At, B0); PG8_BAR; PG8_SCHED;
;             PG8_LDB(B1, 0, 1); PG8_STAGE(PG8_SB(0, 0), b2, voffB);
;             PG8_BAR; PG8_WAIT_L(0); PG8_MMA(0, 1, At, B1); PG8_BAR;
;             PG8_LDA(At, 0, 1); PG8_STAGE(PG8_SA(0, 0), a2, voffA);
;             PG8_BAR; PG8_WAIT_L(0); PG8_MMA(1, 0, At, B0); PG8_BAR; PG8_SCHED;
;             PG8_STAGE(PG8_SB(0, 1), b2 + hstepB, voffB);
;             PG8_WAIT_V(6); PG8_BAR; PG8_MMA(1, 1, At, B1); PG8_BAR;
;             PG8_LDB(B0, 1, 0); PG8_SCHED; PG8_LDA(At, 1, 0); PG8_STAGE(PG8_SA(0, 1), a2 + hstepA, voffA);
;             PG8_WAIT_L(8); PG8_BAR; PG8_WAIT_L(0); PG8_MMA(0, 0, At, B0); PG8_BAR; PG8_SCHED;
.LBB0_1672:
	s_add_u32 s26, s16, 0xfffc0080
	s_addc_u32 s27, s17, -1
	s_add_i32 s38, 0, 0x10000
	v_add_u32_e32 v142, s38, v197
	ds_read_b128 v[130:133], v142
	ds_read_b128 v[134:137], v142 offset:1024
	ds_read_b128 v[138:141], v142 offset:2048
	ds_read_b128 v[142:145], v142 offset:3072
	s_cmp_eq_u32 s19, 12
	s_cselect_b32 s47, s0, s27
	s_cselect_b32 s46, s1, s26
	s_cselect_b32 s37, s5, s18
	s_cselect_b32 s36, s7, s9
	v_lshl_add_u64 v[162:163], s[16:17], 0, v[152:153]
	s_add_i32 m0, s79, 0xc000
	ds_read_b128 v[178:181], v201
	ds_read_b128 v[182:185], v201 offset:1024
	ds_read_b128 v[186:189], v201 offset:2048
	ds_read_b128 v[202:205], v201 offset:3072
	ds_read_b128 v[206:209], v201 offset:4096
	ds_read_b128 v[214:217], v201 offset:5120
	ds_read_b128 v[218:221], v201 offset:6144
	ds_read_b128 v[222:225], v201 offset:7168
	global_load_lds_dwordx4 v[162:163], off
	v_lshl_add_u64 v[162:163], s[16:17], 0, v[176:177]
	s_add_i32 m0, s79, 0xe000
	s_nop 0
	global_load_lds_dwordx4 v[162:163], off
	s_waitcnt lgkmcnt(8)
	s_barrier
	s_waitcnt lgkmcnt(0)
	s_setprio 1
	v_mfma_f32_16x16x32_bf16 v[126:129], v[130:133], v[178:181], v[126:129]
	v_mfma_f32_16x16x32_bf16 v[122:125], v[138:141], v[178:181], v[122:125]
	v_mfma_f32_16x16x32_bf16 v[110:113], v[130:133], v[186:189], v[110:113]
	v_mfma_f32_16x16x32_bf16 v[106:109], v[138:141], v[186:189], v[106:109]
	v_mfma_f32_16x16x32_bf16 v[94:97], v[130:133], v[206:209], v[94:97]
	v_mfma_f32_16x16x32_bf16 v[90:93], v[138:141], v[206:209], v[90:93]
	v_mfma_f32_16x16x32_bf16 v[78:81], v[130:133], v[218:221], v[78:81]
	v_mfma_f32_16x16x32_bf16 v[74:77], v[138:141], v[218:221], v[74:77]
	v_mfma_f32_16x16x32_bf16 v[126:129], v[134:137], v[182:185], v[126:129]
	v_mfma_f32_16x16x32_bf16 v[122:125], v[142:145], v[182:185], v[122:125]
	v_mfma_f32_16x16x32_bf16 v[110:113], v[134:137], v[202:205], v[110:113]
	v_mfma_f32_16x16x32_bf16 v[106:109], v[142:145], v[202:205], v[106:109]
	v_mfma_f32_16x16x32_bf16 v[94:97], v[134:137], v[214:217], v[94:97]
	v_mfma_f32_16x16x32_bf16 v[90:93], v[142:145], v[214:217], v[90:93]
	v_mfma_f32_16x16x32_bf16 v[78:81], v[134:137], v[222:225], v[78:81]
	v_mfma_f32_16x16x32_bf16 v[74:77], v[142:145], v[222:225], v[74:77]
	s_setprio 0
	s_barrier
	s_add_i32 s39, 0, 0x14000
	v_add_u32_e32 v162, s39, v197
	s_add_i32 s26, s38, s78
	ds_read_b128 v[226:229], v162
	ds_read_b128 v[230:233], v162 offset:1024
	ds_read_b128 v[234:237], v162 offset:2048
	ds_read_b128 v[238:241], v162 offset:3072
	v_lshl_add_u64 v[162:163], s[36:37], 0, v[8:9]
	s_mov_b32 m0, s26
	v_lshl_add_u64 v[164:165], s[36:37], 0, v[146:147]
	global_load_lds_dwordx4 v[162:163], off
	s_add_i32 m0, s26, 0x2000
	s_nop 0
	global_load_lds_dwordx4 v[164:165], off
	s_barrier
	s_waitcnt lgkmcnt(0)
	s_setprio 1
	v_mfma_f32_16x16x32_bf16 v[118:121], v[226:229], v[178:181], v[118:121]
	v_mfma_f32_16x16x32_bf16 v[114:117], v[234:237], v[178:181], v[114:117]
	v_mfma_f32_16x16x32_bf16 v[102:105], v[226:229], v[186:189], v[102:105]
	v_mfma_f32_16x16x32_bf16 v[98:101], v[234:237], v[186:189], v[98:101]
	v_mfma_f32_16x16x32_bf16 v[86:89], v[226:229], v[206:209], v[86:89]
	v_mfma_f32_16x16x32_bf16 v[82:85], v[234:237], v[206:209], v[82:85]
	v_mfma_f32_16x16x32_bf16 v[70:73], v[226:229], v[218:221], v[70:73]
	v_mfma_f32_16x16x32_bf16 v[66:69], v[234:237], v[218:221], v[66:69]
	v_mfma_f32_16x16x32_bf16 v[118:121], v[230:233], v[182:185], v[118:121]
	v_mfma_f32_16x16x32_bf16 v[114:117], v[238:241], v[182:185], v[114:117]
	v_mfma_f32_16x16x32_bf16 v[102:105], v[230:233], v[202:205], v[102:105]
	v_mfma_f32_16x16x32_bf16 v[98:101], v[238:241], v[202:205], v[98:101]
	v_mfma_f32_16x16x32_bf16 v[86:89], v[230:233], v[214:217], v[86:89]
	v_mfma_f32_16x16x32_bf16 v[82:85], v[238:241], v[214:217], v[82:85]
	v_mfma_f32_16x16x32_bf16 v[70:73], v[230:233], v[222:225], v[70:73]
	v_mfma_f32_16x16x32_bf16 v[66:69], v[238:241], v[222:225], v[66:69]
	s_setprio 0
	s_mov_b32 m0, s79
	v_lshl_add_u64 v[190:191], s[46:47], 0, v[150:151]
	s_barrier
	ds_read_b128 v[178:181], v201 offset:16384
	ds_read_b128 v[182:185], v201 offset:17408
	ds_read_b128 v[186:189], v201 offset:18432
	ds_read_b128 v[202:205], v201 offset:19456
	ds_read_b128 v[206:209], v201 offset:20480
	ds_read_b128 v[214:217], v201 offset:21504
	ds_read_b128 v[218:221], v201 offset:22528
	ds_read_b128 v[222:225], v201 offset:23552
	global_load_lds_dwordx4 v[190:191], off
	v_lshl_add_u64 v[194:195], s[46:47], 0, v[148:149]
	s_mov_b32 m0, s80
	s_nop 0
	global_load_lds_dwordx4 v[194:195], off
	s_barrier
	s_waitcnt lgkmcnt(0)
	s_setprio 1
	v_mfma_f32_16x16x32_bf16 v[50:53], v[130:133], v[178:181], v[50:53]
	v_mfma_f32_16x16x32_bf16 v[54:57], v[138:141], v[178:181], v[54:57]
	v_mfma_f32_16x16x32_bf16 v[34:37], v[130:133], v[186:189], v[34:37]
	v_mfma_f32_16x16x32_bf16 v[38:41], v[138:141], v[186:189], v[38:41]
	v_mfma_f32_16x16x32_bf16 v[18:21], v[130:133], v[206:209], v[18:21]
	v_mfma_f32_16x16x32_bf16 v[22:25], v[138:141], v[206:209], v[22:25]
	v_mfma_f32_16x16x32_bf16 v[0:3], v[130:133], v[218:221], v[0:3]
	v_mfma_f32_16x16x32_bf16 v[4:7], v[138:141], v[218:221], v[4:7]
	v_mfma_f32_16x16x32_bf16 v[50:53], v[134:137], v[182:185], v[50:53]
	v_mfma_f32_16x16x32_bf16 v[54:57], v[142:145], v[182:185], v[54:57]
	v_mfma_f32_16x16x32_bf16 v[34:37], v[134:137], v[202:205], v[34:37]
	v_mfma_f32_16x16x32_bf16 v[38:41], v[142:145], v[202:205], v[38:41]
	v_mfma_f32_16x16x32_bf16 v[18:21], v[134:137], v[214:217], v[18:21]
	v_mfma_f32_16x16x32_bf16 v[22:25], v[142:145], v[214:217], v[22:25]
	v_mfma_f32_16x16x32_bf16 v[0:3], v[134:137], v[222:225], v[0:3]
	v_mfma_f32_16x16x32_bf16 v[4:7], v[142:145], v[222:225], v[4:7]
	s_setprio 0
	s_barrier
; #define PG8_STAGE(bufoff, gbase, voff) do { _Pragma("unroll") for (int _i = 0; _i < 2; ++_i) \
;         __builtin_amdgcn_global_load_lds((const unsigned*)((const char*)(gbase) + (voff)[_i]), (LAS unsigned*)(lds + (bufoff) + ldsw + _i * 8192), 16, 0, 0); } while (0)
; #define PG8_LDA(dst, b, h) do { _Pragma("unroll") for (int m = 0; m < 4; ++m) _Pragma("unroll") for (int k = 0; k < 2; ++k) dst[m][k] = *(const LAS bf16x8*)(lds + PG8_SA(b, h) + aoff + m * 2048 + k * 1024); } while (0)
; #define PG8_LDB(dst, b, h) do { _Pragma("unroll") for (int n = 0; n < 2; ++n) _Pragma("unroll") for (int k = 0; k < 2; ++k) dst[n][k] = *(const LAS bf16x8*)(lds + PG8_SB(b, h) + boff + n * 2048 + k * 1024); } while (0)
; #define PG8_MMA(ai, bj, At, Bt) do { __builtin_amdgcn_s_setprio(1); _Pragma("unroll") for (int m = 0; m < 4; ++m) _Pragma("unroll") for (int n = 0; n < 2; ++n) _Pragma("unroll") for (int k = 0; k < 2; ++k) \
;         acc[ai][bj][m][n] = __builtin_amdgcn_mfma_f32_16x16x32_bf16(Bt[n][k], At[m][k], acc[ai][bj][m][n], 0, 0, 0); __builtin_amdgcn_s_setprio(0); } while (0)
; #define PG8_WAIT_V(n) asm volatile("s_waitcnt vmcnt(" #n ")" ::: "memory")
; #define PG8_WAIT_L(n) asm volatile("s_waitcnt lgkmcnt(" #n ")" ::: "memory")
; #define PG8_BAR __builtin_amdgcn_s_barrier()
; #define PG8_SCHED __builtin_amdgcn_sched_barrier(0)
; template <class Epi>
; DEVI void gemm_phase(LAS unsigned char* lds, const Gemm g, const Epi& E) {
;     ...
;             PG8_WAIT_V(6); PG8_BAR; PG8_MMA(1, 1, At, B1); PG8_BAR;
;             PG8_LDB(B0, 1, 0); PG8_SCHED; PG8_LDA(At, 1, 0); PG8_STAGE(PG8_SA(0, 1), a2 + hstepA, voffA);
;             PG8_WAIT_L(8); PG8_BAR; PG8_WAIT_L(0); PG8_MMA(0, 0, At, B0); PG8_BAR; PG8_SCHED;
;             PG8_LDB(B1, 1, 1); PG8_STAGE(PG8_SB(1, 0), b3, voffB);
;             PG8_BAR; PG8_WAIT_L(0); PG8_MMA(0, 1, At, B1); PG8_BAR;
;             PG8_LDA(At, 1, 1); PG8_STAGE(PG8_SA(1, 0), a3, voffA);
;             PG8_BAR; PG8_WAIT_L(0); PG8_MMA(1, 0, At, B0); PG8_BAR; PG8_SCHED;
	s_add_u32 s26, s36, 0x40000
	s_addc_u32 s27, s37, 0
	s_add_i32 s38, s39, s78
	v_lshl_add_u64 v[130:131], s[26:27], 0, v[8:9]
	s_mov_b32 m0, s38
	s_nop 0
	global_load_lds_dwordx4 v[130:131], off
	v_lshl_add_u64 v[130:131], s[26:27], 0, v[146:147]
	s_add_i32 m0, s38, 0x2000
	s_nop 0
	global_load_lds_dwordx4 v[130:131], off
	s_waitcnt vmcnt(6)
	s_barrier
	s_setprio 1
	v_mfma_f32_16x16x32_bf16 v[58:61], v[226:229], v[178:181], v[58:61]
	v_mfma_f32_16x16x32_bf16 v[62:65], v[234:237], v[178:181], v[62:65]
	v_mfma_f32_16x16x32_bf16 v[42:45], v[226:229], v[186:189], v[42:45]
	v_mfma_f32_16x16x32_bf16 v[46:49], v[234:237], v[186:189], v[46:49]
	v_mfma_f32_16x16x32_bf16 v[26:29], v[226:229], v[206:209], v[26:29]
	v_mfma_f32_16x16x32_bf16 v[30:33], v[234:237], v[206:209], v[30:33]
	v_mfma_f32_16x16x32_bf16 v[10:13], v[226:229], v[218:221], v[10:13]
	v_mfma_f32_16x16x32_bf16 v[14:17], v[234:237], v[218:221], v[14:17]
	v_mfma_f32_16x16x32_bf16 v[58:61], v[230:233], v[182:185], v[58:61]
	v_mfma_f32_16x16x32_bf16 v[62:65], v[238:241], v[182:185], v[62:65]
	v_mfma_f32_16x16x32_bf16 v[42:45], v[230:233], v[202:205], v[42:45]
	v_mfma_f32_16x16x32_bf16 v[46:49], v[238:241], v[202:205], v[46:49]
	v_mfma_f32_16x16x32_bf16 v[26:29], v[230:233], v[214:217], v[26:29]
	v_mfma_f32_16x16x32_bf16 v[30:33], v[238:241], v[214:217], v[30:33]
	v_mfma_f32_16x16x32_bf16 v[10:13], v[230:233], v[222:225], v[10:13]
	v_mfma_f32_16x16x32_bf16 v[14:17], v[238:241], v[222:225], v[14:17]
	s_setprio 0
	s_add_i32 s38, 0, 0x18000
	v_add_u32_e32 v142, s38, v197
	s_barrier
	ds_read_b128 v[130:133], v142
	ds_read_b128 v[134:137], v142 offset:1024
	ds_read_b128 v[138:141], v142 offset:2048
	ds_read_b128 v[142:145], v142 offset:3072
	s_add_u32 s26, s46, 0x40000
	s_addc_u32 s27, s47, 0
	s_mov_b32 m0, s81
	v_lshl_add_u64 v[226:227], s[26:27], 0, v[150:151]
	ds_read_b128 v[178:181], v201 offset:32768
	ds_read_b128 v[182:185], v201 offset:33792
	ds_read_b128 v[186:189], v201 offset:34816
	ds_read_b128 v[202:205], v201 offset:35840
	ds_read_b128 v[206:209], v201 offset:36864
	ds_read_b128 v[214:217], v201 offset:37888
	ds_read_b128 v[218:221], v201 offset:38912
	ds_read_b128 v[222:225], v201 offset:39936
	global_load_lds_dwordx4 v[226:227], off
	v_lshl_add_u64 v[226:227], s[26:27], 0, v[148:149]
	s_mov_b32 m0, s82
	s_nop 0
	global_load_lds_dwordx4 v[226:227], off
	s_waitcnt lgkmcnt(8)
	s_barrier
	s_waitcnt lgkmcnt(0)
	s_setprio 1
	v_mfma_f32_16x16x32_bf16 v[126:129], v[130:133], v[178:181], v[126:129]
	v_mfma_f32_16x16x32_bf16 v[122:125], v[138:141], v[178:181], v[122:125]
	v_mfma_f32_16x16x32_bf16 v[110:113], v[130:133], v[186:189], v[110:113]
	v_mfma_f32_16x16x32_bf16 v[106:109], v[138:141], v[186:189], v[106:109]
	v_mfma_f32_16x16x32_bf16 v[94:97], v[130:133], v[206:209], v[94:97]
	v_mfma_f32_16x16x32_bf16 v[90:93], v[138:141], v[206:209], v[90:93]
	v_mfma_f32_16x16x32_bf16 v[78:81], v[130:133], v[218:221], v[78:81]
	v_mfma_f32_16x16x32_bf16 v[74:77], v[138:141], v[218:221], v[74:77]
	v_mfma_f32_16x16x32_bf16 v[126:129], v[134:137], v[182:185], v[126:129]
	v_mfma_f32_16x16x32_bf16 v[122:125], v[142:145], v[182:185], v[122:125]
	v_mfma_f32_16x16x32_bf16 v[110:113], v[134:137], v[202:205], v[110:113]
	v_mfma_f32_16x16x32_bf16 v[106:109], v[142:145], v[202:205], v[106:109]
	v_mfma_f32_16x16x32_bf16 v[94:97], v[134:137], v[214:217], v[94:97]
	v_mfma_f32_16x16x32_bf16 v[90:93], v[142:145], v[214:217], v[90:93]
	v_mfma_f32_16x16x32_bf16 v[78:81], v[134:137], v[222:225], v[78:81]
	v_mfma_f32_16x16x32_bf16 v[74:77], v[142:145], v[222:225], v[74:77]
	s_setprio 0
	s_barrier
	s_add_i32 s39, 0, 0x1c000
	s_add_i32 s26, s38, s78
	v_add_u32_e32 v192, s39, v197
	v_lshl_add_u64 v[162:163], v[162:163], 0, s[70:71]
	s_mov_b32 m0, s26
	ds_read_b128 v[226:229], v192
	ds_read_b128 v[230:233], v192 offset:1024
	ds_read_b128 v[234:237], v192 offset:2048
	ds_read_b128 v[238:241], v192 offset:3072
	global_load_lds_dwordx4 v[162:163], off
	v_lshl_add_u64 v[162:163], v[164:165], 0, s[70:71]
	s_add_i32 m0, s26, 0x2000
	s_nop 0
	global_load_lds_dwordx4 v[162:163], off
	s_barrier
	s_waitcnt lgkmcnt(0)
	s_setprio 1
	v_mfma_f32_16x16x32_bf16 v[118:121], v[226:229], v[178:181], v[118:121]
	v_mfma_f32_16x16x32_bf16 v[114:117], v[234:237], v[178:181], v[114:117]
	v_mfma_f32_16x16x32_bf16 v[102:105], v[226:229], v[186:189], v[102:105]
	v_mfma_f32_16x16x32_bf16 v[98:101], v[234:237], v[186:189], v[98:101]
	v_mfma_f32_16x16x32_bf16 v[86:89], v[226:229], v[206:209], v[86:89]
	v_mfma_f32_16x16x32_bf16 v[82:85], v[234:237], v[206:209], v[82:85]
	v_mfma_f32_16x16x32_bf16 v[70:73], v[226:229], v[218:221], v[70:73]
	v_mfma_f32_16x16x32_bf16 v[66:69], v[234:237], v[218:221], v[66:69]
	v_mfma_f32_16x16x32_bf16 v[118:121], v[230:233], v[182:185], v[118:121]
	v_mfma_f32_16x16x32_bf16 v[114:117], v[238:241], v[182:185], v[114:117]
	v_mfma_f32_16x16x32_bf16 v[102:105], v[230:233], v[202:205], v[102:105]
	v_mfma_f32_16x16x32_bf16 v[98:101], v[238:241], v[202:205], v[98:101]
	v_mfma_f32_16x16x32_bf16 v[86:89], v[230:233], v[214:217], v[86:89]
	v_mfma_f32_16x16x32_bf16 v[82:85], v[238:241], v[214:217], v[82:85]
	v_mfma_f32_16x16x32_bf16 v[70:73], v[230:233], v[222:225], v[70:73]
	v_mfma_f32_16x16x32_bf16 v[66:69], v[238:241], v[222:225], v[66:69]
	s_setprio 0
	s_mov_b32 m0, s83
	v_lshl_add_u64 v[162:163], v[190:191], 0, s[70:71]
	s_barrier
	ds_read_b128 v[178:181], v201 offset:49152
	ds_read_b128 v[182:185], v201 offset:50176
	ds_read_b128 v[186:189], v201 offset:51200
	ds_read_b128 v[202:205], v201 offset:52224
	ds_read_b128 v[206:209], v201 offset:53248
	ds_read_b128 v[214:217], v201 offset:54272
	ds_read_b128 v[218:221], v201 offset:55296
	ds_read_b128 v[222:225], v201 offset:56320
	global_load_lds_dwordx4 v[162:163], off
	v_lshl_add_u64 v[162:163], v[194:195], 0, s[70:71]
	s_mov_b32 m0, s84
	s_nop 0
	global_load_lds_dwordx4 v[162:163], off
	s_barrier
; #define PG8_STAGE(bufoff, gbase, voff) do { _Pragma("unroll") for (int _i = 0; _i < 2; ++_i) \
;         __builtin_amdgcn_global_load_lds((const unsigned*)((const char*)(gbase) + (voff)[_i]), (LAS unsigned*)(lds + (bufoff) + ldsw + _i * 8192), 16, 0, 0); } while (0)
; #define PG8_LDA(dst, b, h) do { _Pragma("unroll") for (int m = 0; m < 4; ++m) _Pragma("unroll") for (int k = 0; k < 2; ++k) dst[m][k] = *(const LAS bf16x8*)(lds + PG8_SA(b, h) + aoff + m * 2048 + k * 1024); } while (0)
; #define PG8_LDB(dst, b, h) do { _Pragma("unroll") for (int n = 0; n < 2; ++n) _Pragma("unroll") for (int k = 0; k < 2; ++k) dst[n][k] = *(const LAS bf16x8*)(lds + PG8_SB(b, h) + boff + n * 2048 + k * 1024); } while (0)
; #define PG8_MMA(ai, bj, At, Bt) do { __builtin_amdgcn_s_setprio(1); _Pragma("unroll") for (int m = 0; m < 4; ++m) _Pragma("unroll") for (int n = 0; n < 2; ++n) _Pragma("unroll") for (int k = 0; k < 2; ++k) \
;         acc[ai][bj][m][n] = __builtin_amdgcn_mfma_f32_16x16x32_bf16(Bt[n][k], At[m][k], acc[ai][bj][m][n], 0, 0, 0); __builtin_amdgcn_s_setprio(0); } while (0)
; #define PG8_WAIT_V(n) asm volatile("s_waitcnt vmcnt(" #n ")" ::: "memory")
; #define PG8_BAR __builtin_amdgcn_s_barrier()
; template <class Epi>
; DEVI void gemm_phase(LAS unsigned char* lds, const Gemm g, const Epi& E) {
;     ...
;             PG8_WAIT_L(8); PG8_BAR; PG8_WAIT_L(0); PG8_MMA(0, 0, At, B0); PG8_BAR; PG8_SCHED;
;             PG8_LDB(B1, 1, 1); PG8_STAGE(PG8_SB(1, 0), b3, voffB);
;             PG8_BAR; PG8_WAIT_L(0); PG8_MMA(0, 1, At, B1); PG8_BAR;
;             PG8_LDA(At, 1, 1); PG8_STAGE(PG8_SA(1, 0), a3, voffA);
;             PG8_BAR; PG8_WAIT_L(0); PG8_MMA(1, 0, At, B0); PG8_BAR; PG8_SCHED;
;             PG8_STAGE(PG8_SB(1, 1), b3 + hstepB, voffB);
;             PG8_WAIT_V(6); PG8_BAR; PG8_MMA(1, 1, At, B1); PG8_BAR;
;         }
;         {
;             const int row0 = cur.pm * BM + wr * 64 + fr, col0 = cur.pn * BM + wc * 32 + (Epi::PERM ? 8 : 4) * fq; constexpr int NST = Epi::PERM ? 4 : 16;
;             float rsv[8];
;             if constexpr (Epi::RS) { f32x4 q4[8];
; #pragma unroll
;                 for (int i = 0; i < 8; ++i) q4[i] = *(const f32x4*)(E.ssq_in + (size_t)(row0 + (i >> 2) * HALF + (i & 3) * 16) * 4);
; #pragma unroll
;                 for (int i = 0; i < 8; ++i) rsv[i] = rsqrtf((((q4[i][0] + q4[i][1]) + q4[i][2]) + q4[i][3]) * (1.f / DM) + 1e-6f); }
	s_waitcnt lgkmcnt(0)
	s_setprio 1
	v_mfma_f32_16x16x32_bf16 v[50:53], v[130:133], v[178:181], v[50:53]
	v_mfma_f32_16x16x32_bf16 v[54:57], v[138:141], v[178:181], v[54:57]
	v_mfma_f32_16x16x32_bf16 v[34:37], v[130:133], v[186:189], v[34:37]
	v_mfma_f32_16x16x32_bf16 v[38:41], v[138:141], v[186:189], v[38:41]
	v_mfma_f32_16x16x32_bf16 v[18:21], v[130:133], v[206:209], v[18:21]
	v_mfma_f32_16x16x32_bf16 v[22:25], v[138:141], v[206:209], v[22:25]
	v_mfma_f32_16x16x32_bf16 v[0:3], v[130:133], v[218:221], v[0:3]
	v_mfma_f32_16x16x32_bf16 v[4:7], v[138:141], v[218:221], v[4:7]
	v_mfma_f32_16x16x32_bf16 v[50:53], v[134:137], v[182:185], v[50:53]
	v_mfma_f32_16x16x32_bf16 v[54:57], v[142:145], v[182:185], v[54:57]
	v_mfma_f32_16x16x32_bf16 v[34:37], v[134:137], v[202:205], v[34:37]
	v_mfma_f32_16x16x32_bf16 v[38:41], v[142:145], v[202:205], v[38:41]
	v_mfma_f32_16x16x32_bf16 v[18:21], v[134:137], v[214:217], v[18:21]
	v_mfma_f32_16x16x32_bf16 v[22:25], v[142:145], v[214:217], v[22:25]
	v_mfma_f32_16x16x32_bf16 v[0:3], v[134:137], v[222:225], v[0:3]
	v_mfma_f32_16x16x32_bf16 v[4:7], v[142:145], v[222:225], v[4:7]
	s_setprio 0
	s_barrier
	s_add_u32 s26, s36, 0x40080
	s_addc_u32 s27, s37, 0
	s_add_i32 s36, s39, s78
	v_lshl_add_u64 v[130:131], s[26:27], 0, v[8:9]
	s_mov_b32 m0, s36
	s_nop 0
	global_load_lds_dwordx4 v[130:131], off
	v_lshl_add_u64 v[130:131], s[26:27], 0, v[146:147]
	s_add_i32 m0, s36, 0x2000
	s_nop 0
	global_load_lds_dwordx4 v[130:131], off
	s_waitcnt vmcnt(6)
	s_barrier
	s_setprio 1
	v_mfma_f32_16x16x32_bf16 v[58:61], v[226:229], v[178:181], v[58:61]
	v_mfma_f32_16x16x32_bf16 v[62:65], v[234:237], v[178:181], v[62:65]
	v_mfma_f32_16x16x32_bf16 v[42:45], v[226:229], v[186:189], v[42:45]
	v_mfma_f32_16x16x32_bf16 v[46:49], v[234:237], v[186:189], v[46:49]
	v_mfma_f32_16x16x32_bf16 v[26:29], v[226:229], v[206:209], v[26:29]
	v_mfma_f32_16x16x32_bf16 v[30:33], v[234:237], v[206:209], v[30:33]
	v_mfma_f32_16x16x32_bf16 v[10:13], v[226:229], v[218:221], v[10:13]
	v_mfma_f32_16x16x32_bf16 v[14:17], v[234:237], v[218:221], v[14:17]
	v_mfma_f32_16x16x32_bf16 v[58:61], v[230:233], v[182:185], v[58:61]
	v_mfma_f32_16x16x32_bf16 v[62:65], v[238:241], v[182:185], v[62:65]
	v_mfma_f32_16x16x32_bf16 v[42:45], v[230:233], v[202:205], v[42:45]
	v_mfma_f32_16x16x32_bf16 v[46:49], v[238:241], v[202:205], v[46:49]
	v_mfma_f32_16x16x32_bf16 v[26:29], v[230:233], v[214:217], v[26:29]
	v_mfma_f32_16x16x32_bf16 v[30:33], v[238:241], v[214:217], v[30:33]
	v_mfma_f32_16x16x32_bf16 v[10:13], v[230:233], v[222:225], v[10:13]
	v_mfma_f32_16x16x32_bf16 v[14:17], v[238:241], v[222:225], v[14:17]
	s_setprio 0
	s_add_i32 s19, s19, 2
	s_add_u32 s16, s16, 0x100
	s_addc_u32 s17, s17, 0
	s_add_u32 s9, s9, 0x100
	s_addc_u32 s18, s18, 0
	s_cmp_gt_u32 s19, 13
	s_barrier
	s_cbranch_scc0 .LBB0_1672
	v_lshl_add_u32 v194, s4, 8, v193
	v_add_u32_e32 v178, 0xb0, v194
	v_ashrrev_i32_e32 v195, 31, v194
	v_or_b32_e32 v190, 16, v194
	v_ashrrev_i32_e32 v179, 31, v178
	v_lshl_add_u64 v[130:131], v[194:195], 4, s[10:11]
	v_ashrrev_i32_e32 v191, 31, v190
	v_lshl_add_u64 v[134:135], v[178:179], 4, s[10:11]
	global_load_dwordx4 v[202:205], v[130:131], off
	v_or_b32_e32 v188, 32, v194
	global_load_dwordx4 v[134:137], v[134:135], off
	v_lshl_add_u64 v[130:131], v[190:191], 4, s[10:11]
	global_load_dwordx4 v[206:209], v[130:131], off
	v_ashrrev_i32_e32 v189, 31, v188
	v_or_b32_e32 v186, 48, v194
	v_lshl_add_u64 v[130:131], v[188:189], 4, s[10:11]
	v_ashrrev_i32_e32 v187, 31, v186
	global_load_dwordx4 v[214:217], v[130:131], off
	v_lshl_add_u64 v[130:131], v[186:187], 4, s[10:11]
	global_load_dwordx4 v[218:221], v[130:131], off
	v_add_u32_e32 v184, 0x80, v194
	v_ashrrev_i32_e32 v185, 31, v184
	v_add_u32_e32 v182, 0x90, v194
	v_lshl_add_u64 v[130:131], v[184:185], 4, s[10:11]
	v_ashrrev_i32_e32 v183, 31, v182
	global_load_dwordx4 v[138:141], v[130:131], off
	v_lshl_add_u64 v[130:131], v[182:183], 4, s[10:11]
	v_add_u32_e32 v180, 0xa0, v194
	global_load_dwordx4 v[142:145], v[130:131], off
	v_ashrrev_i32_e32 v181, 31, v180
	v_lshl_add_u64 v[130:131], v[180:181], 4, s[10:11]
	global_load_dwordx4 v[130:133], v[130:131], off
	s_mov_b32 s0, 0x358637bd
	s_mov_b64 s[36:37], s[14:15]
	s_mov_b64 s[16:17], s[12:13]
	s_waitcnt vmcnt(0)
; template <class Epi>
; DEVI void gemm_phase(LAS unsigned char* lds, const Gemm g, const Epi& E) {
;     ...
;             if constexpr (Epi::RS) { f32x4 q4[8];
; #pragma unroll
;                 for (int i = 0; i < 8; ++i) q4[i] = *(const f32x4*)(E.ssq_in + (size_t)(row0 + (i >> 2) * HALF + (i & 3) * 16) * 4);
; #pragma unroll
;                 for (int i = 0; i < 8; ++i) rsv[i] = rsqrtf((((q4[i][0] + q4[i][1]) + q4[i][2]) + q4[i][3]) * (1.f / DM) + 1e-6f); }
	v_mov_b32_e32 v163, v202
	v_mov_b32_e32 v165, v204
	v_mov_b32_e32 v162, v206
	v_mov_b32_e32 v202, v207
	v_pk_add_f32 v[162:163], v[162:163], v[202:203]
	v_mov_b32_e32 v164, v208
	v_pk_add_f32 v[162:163], v[164:165], v[162:163]
	v_mov_b32_e32 v204, v209
	v_pk_add_f32 v[162:163], v[204:205], v[162:163]
	v_mov_b64_e32 v[202:203], s[0:1]
	v_pk_fma_f32 v[162:163], v[162:163], s[72:73], v[202:203] op_sel_hi:[1,0,0]
	v_mov_b32_e32 v165, v216
	v_mul_f32_e32 v164, 0x4b800000, v163
	v_cmp_gt_f32_e64 s[4:5], s94, v163
	v_cmp_gt_f32_e32 vcc, s94, v162
	v_mov_b32_e32 v216, v221
	v_cndmask_b32_e64 v163, v163, v164, s[4:5]
	v_rsq_f32_e32 v163, v163
	s_nop 0
	v_mul_f32_e32 v164, 0x45800000, v163
	v_cndmask_b32_e64 v200, v163, v164, s[4:5]
	v_mul_f32_e32 v163, 0x4b800000, v162
	v_cndmask_b32_e32 v162, v162, v163, vcc
	v_rsq_f32_e32 v162, v162
	v_mov_b32_e32 v164, v220
	v_pk_mul_f32 v[126:127], v[126:127], v[200:201] op_sel_hi:[1,0]
	v_pk_mul_f32 v[122:123], v[122:123], v[200:201] op_sel_hi:[1,0]
	v_mul_f32_e32 v163, 0x45800000, v162
	v_cndmask_b32_e32 v198, v162, v163, vcc
	v_mov_b32_e32 v162, v218
	v_mov_b32_e32 v163, v214
	v_mov_b32_e32 v214, v219
	v_pk_add_f32 v[162:163], v[162:163], v[214:215]
	v_pk_mul_f32 v[118:119], v[118:119], v[200:201] op_sel_hi:[1,0]
	v_pk_add_f32 v[162:163], v[164:165], v[162:163]
	v_pk_mul_f32 v[124:125], v[124:125], v[200:201] op_sel_hi:[1,0]
	v_pk_add_f32 v[162:163], v[216:217], v[162:163]
	v_pk_mul_f32 v[114:115], v[114:115], v[200:201] op_sel_hi:[1,0]
	v_pk_fma_f32 v[162:163], v[162:163], s[72:73], v[202:203] op_sel_hi:[1,0,0]
	v_pk_mul_f32 v[128:129], v[128:129], v[200:201] op_sel_hi:[1,0]
	v_mul_f32_e32 v164, 0x4b800000, v163
	v_cmp_gt_f32_e64 s[4:5], s94, v163
	v_cmp_gt_f32_e32 vcc, s94, v162
	v_pk_mul_f32 v[120:121], v[120:121], v[200:201] op_sel_hi:[1,0]
	v_cndmask_b32_e64 v163, v163, v164, s[4:5]
	v_rsq_f32_e32 v163, v163
	v_pk_mul_f32 v[116:117], v[116:117], v[200:201] op_sel_hi:[1,0]
	v_pk_mul_f32 v[106:107], v[106:107], v[198:199] op_sel_hi:[1,0]
	v_pk_mul_f32 v[110:111], v[110:111], v[198:199] op_sel_hi:[1,0]
	v_mul_f32_e32 v164, 0x45800000, v163
	v_cndmask_b32_e64 v196, v163, v164, s[4:5]
	v_mul_f32_e32 v163, 0x4b800000, v162
	v_cndmask_b32_e32 v162, v162, v163, vcc
	v_rsq_f32_e32 v162, v162
	v_pk_mul_f32 v[102:103], v[102:103], v[198:199] op_sel_hi:[1,0]
	v_pk_mul_f32 v[108:109], v[108:109], v[198:199] op_sel_hi:[1,0]
	v_pk_mul_f32 v[98:99], v[98:99], v[198:199] op_sel_hi:[1,0]
	v_mul_f32_e32 v163, 0x45800000, v162
	v_cndmask_b32_e32 v192, v162, v163, vcc
	v_mov_b32_e32 v162, v142
	v_mov_b32_e32 v163, v138
	v_mov_b32_e32 v138, v143
	v_pk_add_f32 v[138:139], v[162:163], v[138:139]
	v_mov_b32_e32 v142, v144
	v_mov_b32_e32 v143, v140
	v_pk_add_f32 v[138:139], v[142:143], v[138:139]
	v_mov_b32_e32 v142, v134
	v_mov_b32_e32 v143, v130
	v_mov_b32_e32 v130, v135
	v_pk_add_f32 v[130:131], v[142:143], v[130:131]
	v_mov_b32_e32 v134, v136
	v_mov_b32_e32 v135, v132
	v_pk_add_f32 v[130:131], v[134:135], v[130:131]
	v_mov_b32_e32 v132, v137
	v_pk_add_f32 v[130:131], v[132:133], v[130:131]
	v_mul_f32_e32 v133, 0xbfb8aa3b, v126
	v_exp_f32_e32 v133, v133
	v_mov_b32_e32 v140, v145
	v_pk_add_f32 v[138:139], v[140:141], v[138:139]
	v_pk_fma_f32 v[130:131], v[130:131], s[72:73], v[202:203] op_sel_hi:[1,0,0]
	v_add_f32_e32 v133, 1.0, v133
	v_rcp_f32_e32 v136, v133
	v_mul_f32_e32 v133, 0xbfb8aa3b, v122
	v_exp_f32_e32 v133, v133
	v_pk_fma_f32 v[138:139], v[138:139], s[72:73], v[202:203] op_sel_hi:[1,0,0]
	v_mul_f32_e32 v132, 0x4b800000, v131
	v_mul_f32_e32 v140, 0x4b800000, v139
	v_add_f32_e32 v133, 1.0, v133
	v_rcp_f32_e32 v142, v133
	v_mul_f32_e32 v133, 0xbfb8aa3b, v127
	v_exp_f32_e32 v133, v133
	v_cmp_gt_f32_e64 s[4:5], s94, v139
	v_cmp_gt_f32_e32 vcc, s94, v138
	v_pk_mul_f32 v[112:113], v[112:113], v[198:199] op_sel_hi:[1,0]
	v_add_f32_e32 v133, 1.0, v133
	v_rcp_f32_e32 v137, v133
	v_cndmask_b32_e64 v139, v139, v140, s[4:5]
	v_rsq_f32_e32 v139, v139
	v_pk_mul_f32 v[104:105], v[104:105], v[198:199] op_sel_hi:[1,0]
	v_pk_mul_f32 v[126:127], v[126:127], v[136:137]
	v_pk_mul_f32 v[100:101], v[100:101], v[198:199] op_sel_hi:[1,0]
	v_pk_mul_f32 v[118:119], v[118:119], v[126:127]
	v_mul_f32_e32 v126, 0xbfb8aa3b, v123
	v_exp_f32_e32 v126, v126
	v_mul_f32_e32 v140, 0x45800000, v139
	v_cndmask_b32_e64 v140, v139, v140, s[4:5]
	v_mul_f32_e32 v139, 0x4b800000, v138
	v_add_f32_e32 v126, 1.0, v126
	v_rcp_f32_e32 v143, v126
	v_cmp_gt_f32_e64 s[4:5], s94, v131
	v_cndmask_b32_e32 v138, v138, v139, vcc
	v_rsq_f32_e32 v138, v138
	v_pk_mul_f32 v[122:123], v[122:123], v[142:143]
	v_cndmask_b32_e64 v131, v131, v132, s[4:5]
	v_pk_mul_f32 v[122:123], v[114:115], v[122:123]
	v_mul_f32_e32 v115, 0xbfb8aa3b, v124
	v_exp_f32_e32 v115, v115
	v_mul_f32_e32 v114, 0xbfb8aa3b, v128
	v_exp_f32_e32 v114, v114
	v_rsq_f32_e32 v131, v131
	v_add_f32_e32 v115, 1.0, v115
	v_rcp_f32_e32 v126, v115
	v_mul_f32_e32 v115, 0xbfb8aa3b, v129
	v_exp_f32_e32 v115, v115
	v_add_f32_e32 v114, 1.0, v114
	v_rcp_f32_e32 v114, v114
	v_mul_f32_e32 v139, 0x45800000, v138
	v_add_f32_e32 v115, 1.0, v115
	v_rcp_f32_e32 v115, v115
	v_mul_f32_e32 v132, 0x45800000, v131
	v_cndmask_b32_e32 v138, v138, v139, vcc
	v_cmp_gt_f32_e32 vcc, s94, v130
	v_pk_mul_f32 v[114:115], v[128:129], v[114:115]
	v_cndmask_b32_e64 v134, v131, v132, s[4:5]
	v_pk_mul_f32 v[120:121], v[120:121], v[114:115]
	v_mul_f32_e32 v114, 0xbfb8aa3b, v125
	v_exp_f32_e32 v114, v114
	v_mul_f32_e32 v131, 0x4b800000, v130
	v_cndmask_b32_e32 v130, v130, v131, vcc
	v_rsq_f32_e32 v130, v130
	v_add_f32_e32 v114, 1.0, v114
	v_rcp_f32_e32 v127, v114
	v_pk_mul_f32 v[90:91], v[90:91], v[196:197] op_sel_hi:[1,0]
	v_mul_f32_e32 v131, 0x45800000, v130
; template <class Epi>
; DEVI void gemm_phase(LAS unsigned char* lds, const Gemm g, const Epi& E) {
;     ...
;                 for (int mm = 0; mm < 2; ++mm) {
;                     const int m = m0 + mm;
;                     const int r = row0 + ai * HALF + m * 16; float rs = 1.f, part = 0.f;
;                     if constexpr (Epi::RS) rs = rsv[ai * 4 + m];
;                     if constexpr (Epi::PAIR) E.pair8(cur.b, r, cur.pn * HALF + wc * 32 + 8 * fq, acc[ai][0][m][0] * rs, acc[ai][0][m][1] * rs, acc[ai][1][m][0] * rs, acc[ai][1][m][1] * rs);
	v_cndmask_b32_e32 v132, v130, v131, vcc
	v_lshl_or_b32 v130, s86, 7, v199
	v_ashrrev_i32_e32 v131, 31, v130
	v_pk_mul_f32 v[114:115], v[124:125], v[126:127]
	v_lshl_add_u64 v[130:131], v[130:131], 1, s[28:29]
	v_pk_mul_f32 v[124:125], v[116:117], v[114:115]
	v_cvt_pk_bf16_f32 v114, v118, v119
	v_cvt_pk_bf16_f32 v115, v120, v121
	v_cvt_pk_bf16_f32 v116, v122, v123
	v_cvt_pk_bf16_f32 v117, v124, v125
	v_mad_i64_i32 v[118:119], s[0:1], v194, s35, v[130:131]
	global_store_dwordx4 v[118:119], v[114:117], off
	v_pk_mul_f32 v[94:95], v[94:95], v[196:197] op_sel_hi:[1,0]
	v_pk_mul_f32 v[86:87], v[86:87], v[196:197] op_sel_hi:[1,0]
	v_mul_f32_e32 v115, 0xbfb8aa3b, v106
	v_exp_f32_e32 v115, v115
	v_mul_f32_e32 v114, 0xbfb8aa3b, v110
	v_exp_f32_e32 v114, v114
	v_pk_mul_f32 v[92:93], v[92:93], v[196:197] op_sel_hi:[1,0]
	v_add_f32_e32 v115, 1.0, v115
	v_rcp_f32_e32 v116, v115
	v_mul_f32_e32 v115, 0xbfb8aa3b, v111
	v_exp_f32_e32 v115, v115
	v_add_f32_e32 v114, 1.0, v114
	v_rcp_f32_e32 v114, v114
	v_pk_mul_f32 v[82:83], v[82:83], v[196:197] op_sel_hi:[1,0]
	v_add_f32_e32 v115, 1.0, v115
	v_rcp_f32_e32 v115, v115
	v_pk_mul_f32 v[96:97], v[96:97], v[196:197] op_sel_hi:[1,0]
	v_pk_mul_f32 v[88:89], v[88:89], v[196:197] op_sel_hi:[1,0]
	v_pk_mul_f32 v[84:85], v[84:85], v[196:197] op_sel_hi:[1,0]
	v_pk_mul_f32 v[110:111], v[110:111], v[114:115]
	v_pk_mul_f32 v[74:75], v[74:75], v[192:193] op_sel_hi:[1,0]
	v_pk_mul_f32 v[102:103], v[102:103], v[110:111]
	v_mul_f32_e32 v110, 0xbfb8aa3b, v107
	v_exp_f32_e32 v110, v110
	v_pk_mul_f32 v[78:79], v[78:79], v[192:193] op_sel_hi:[1,0]
	v_pk_mul_f32 v[70:71], v[70:71], v[192:193] op_sel_hi:[1,0]
	v_pk_mul_f32 v[76:77], v[76:77], v[192:193] op_sel_hi:[1,0]
	v_add_f32_e32 v110, 1.0, v110
	v_rcp_f32_e32 v117, v110
	v_pk_mul_f32 v[66:67], v[66:67], v[192:193] op_sel_hi:[1,0]
	v_pk_mul_f32 v[80:81], v[80:81], v[192:193] op_sel_hi:[1,0]
	v_pk_mul_f32 v[72:73], v[72:73], v[192:193] op_sel_hi:[1,0]
	v_pk_mul_f32 v[106:107], v[106:107], v[116:117]
	v_pk_mul_f32 v[68:69], v[68:69], v[192:193] op_sel_hi:[1,0]
	v_pk_mul_f32 v[106:107], v[98:99], v[106:107]
	v_mul_f32_e32 v99, 0xbfb8aa3b, v108
	v_exp_f32_e32 v99, v99
	v_mul_f32_e32 v98, 0xbfb8aa3b, v112
	v_exp_f32_e32 v98, v98
	v_pk_mul_f32 v[54:55], v[54:55], v[140:141] op_sel_hi:[1,0]
	v_add_f32_e32 v99, 1.0, v99
	v_rcp_f32_e32 v110, v99
	v_mul_f32_e32 v99, 0xbfb8aa3b, v113
	v_exp_f32_e32 v99, v99
	v_add_f32_e32 v98, 1.0, v98
	v_rcp_f32_e32 v98, v98
	v_pk_mul_f32 v[50:51], v[50:51], v[140:141] op_sel_hi:[1,0]
	v_add_f32_e32 v99, 1.0, v99
	v_rcp_f32_e32 v99, v99
	v_pk_mul_f32 v[58:59], v[58:59], v[140:141] op_sel_hi:[1,0]
	v_pk_mul_f32 v[56:57], v[56:57], v[140:141] op_sel_hi:[1,0]
	v_pk_mul_f32 v[52:53], v[52:53], v[140:141] op_sel_hi:[1,0]
	v_pk_mul_f32 v[98:99], v[112:113], v[98:99]
	v_pk_mul_f32 v[62:63], v[62:63], v[140:141] op_sel_hi:[1,0]
	v_pk_mul_f32 v[104:105], v[104:105], v[98:99]
	v_mul_f32_e32 v98, 0xbfb8aa3b, v109
	v_exp_f32_e32 v98, v98
	v_pk_mul_f32 v[60:61], v[60:61], v[140:141] op_sel_hi:[1,0]
	v_pk_mul_f32 v[64:65], v[64:65], v[140:141] op_sel_hi:[1,0]
	v_pk_mul_f32 v[38:39], v[38:39], v[138:139] op_sel_hi:[1,0]
	v_add_f32_e32 v98, 1.0, v98
	v_rcp_f32_e32 v111, v98
	v_pk_mul_f32 v[34:35], v[34:35], v[138:139] op_sel_hi:[1,0]
	v_pk_mul_f32 v[42:43], v[42:43], v[138:139] op_sel_hi:[1,0]
	v_pk_mul_f32 v[40:41], v[40:41], v[138:139] op_sel_hi:[1,0]
	v_pk_mul_f32 v[98:99], v[108:109], v[110:111]
	v_pk_mul_f32 v[36:37], v[36:37], v[138:139] op_sel_hi:[1,0]
	v_pk_mul_f32 v[108:109], v[100:101], v[98:99]
	v_cvt_pk_bf16_f32 v98, v102, v103
	v_cvt_pk_bf16_f32 v99, v104, v105
	v_cvt_pk_bf16_f32 v100, v106, v107
	v_cvt_pk_bf16_f32 v101, v108, v109
	v_mad_i64_i32 v[102:103], s[0:1], v190, s35, v[130:131]
	global_store_dwordx4 v[102:103], v[98:101], off
	v_pk_mul_f32 v[46:47], v[46:47], v[138:139] op_sel_hi:[1,0]
	v_pk_mul_f32 v[44:45], v[44:45], v[138:139] op_sel_hi:[1,0]
	v_mul_f32_e32 v99, 0xbfb8aa3b, v90
	v_exp_f32_e32 v99, v99
	v_mul_f32_e32 v98, 0xbfb8aa3b, v94
	v_exp_f32_e32 v98, v98
	v_pk_mul_f32 v[48:49], v[48:49], v[138:139] op_sel_hi:[1,0]
	v_add_f32_e32 v99, 1.0, v99
	v_rcp_f32_e32 v100, v99
	v_mul_f32_e32 v99, 0xbfb8aa3b, v95
	v_exp_f32_e32 v99, v99
	v_add_f32_e32 v98, 1.0, v98
	v_rcp_f32_e32 v98, v98
	v_pk_mul_f32 v[22:23], v[22:23], v[134:135] op_sel_hi:[1,0]
	v_add_f32_e32 v99, 1.0, v99
	v_rcp_f32_e32 v99, v99
	v_pk_mul_f32 v[18:19], v[18:19], v[134:135] op_sel_hi:[1,0]
	v_pk_mul_f32 v[26:27], v[26:27], v[134:135] op_sel_hi:[1,0]
	v_pk_mul_f32 v[24:25], v[24:25], v[134:135] op_sel_hi:[1,0]
	v_pk_mul_f32 v[94:95], v[94:95], v[98:99]
	v_pk_mul_f32 v[20:21], v[20:21], v[134:135] op_sel_hi:[1,0]
	v_pk_mul_f32 v[86:87], v[86:87], v[94:95]
	v_mul_f32_e32 v94, 0xbfb8aa3b, v91
	v_exp_f32_e32 v94, v94
	v_pk_mul_f32 v[30:31], v[30:31], v[134:135] op_sel_hi:[1,0]
	v_pk_mul_f32 v[28:29], v[28:29], v[134:135] op_sel_hi:[1,0]
	v_pk_mul_f32 v[32:33], v[32:33], v[134:135] op_sel_hi:[1,0]
	v_add_f32_e32 v94, 1.0, v94
	v_rcp_f32_e32 v101, v94
	v_pk_mul_f32 v[4:5], v[4:5], v[132:133] op_sel_hi:[1,0]
	v_pk_mul_f32 v[0:1], v[0:1], v[132:133] op_sel_hi:[1,0]
	v_pk_mul_f32 v[10:11], v[10:11], v[132:133] op_sel_hi:[1,0]
	v_pk_mul_f32 v[90:91], v[90:91], v[100:101]
	v_pk_mul_f32 v[6:7], v[6:7], v[132:133] op_sel_hi:[1,0]
	v_pk_mul_f32 v[90:91], v[82:83], v[90:91]
	v_mul_f32_e32 v83, 0xbfb8aa3b, v92
	v_exp_f32_e32 v83, v83
	v_mul_f32_e32 v82, 0xbfb8aa3b, v96
	v_exp_f32_e32 v82, v82
	v_pk_mul_f32 v[2:3], v[2:3], v[132:133] op_sel_hi:[1,0]
	v_add_f32_e32 v83, 1.0, v83
	v_rcp_f32_e32 v94, v83
	v_mul_f32_e32 v83, 0xbfb8aa3b, v97
	v_exp_f32_e32 v83, v83
	v_add_f32_e32 v82, 1.0, v82
; template <class Epi>
; DEVI void gemm_phase(LAS unsigned char* lds, const Gemm g, const Epi& E) {
;     ...
;         if (!has_next) break;
; #pragma unroll
;         for (int a = 0; a < 2; ++a)
; #pragma unroll
;             for (int b = 0; b < 2; ++b)
; #pragma unroll
;                 for (int m = 0; m < 4; ++m)
; #pragma unroll
;                     for (int n = 0; n < 2; ++n) acc[a][b][m][n] = (f32x4){0.f, 0.f, 0.f, 0.f};
;         cur = nxt; cA = nA; cB = nB; ++ui;
	v_rcp_f32_e32 v82, v82
	v_pk_mul_f32 v[14:15], v[14:15], v[132:133] op_sel_hi:[1,0]
	v_add_f32_e32 v83, 1.0, v83
	v_rcp_f32_e32 v83, v83
	v_pk_mul_f32 v[12:13], v[12:13], v[132:133] op_sel_hi:[1,0]
	v_pk_mul_f32 v[16:17], v[16:17], v[132:133] op_sel_hi:[1,0]
	s_and_b64 vcc, exec, s[2:3]
	v_pk_mul_f32 v[82:83], v[96:97], v[82:83]
	s_mov_b32 s86, s8
	v_pk_mul_f32 v[88:89], v[88:89], v[82:83]
	v_mul_f32_e32 v82, 0xbfb8aa3b, v93
	v_exp_f32_e32 v82, v82
	s_mov_b32 s4, s6
	v_add_f32_e32 v82, 1.0, v82
	v_rcp_f32_e32 v95, v82
	s_nop 0
	v_pk_mul_f32 v[82:83], v[92:93], v[94:95]
	s_nop 0
	v_pk_mul_f32 v[92:93], v[84:85], v[82:83]
	v_cvt_pk_bf16_f32 v82, v86, v87
	v_cvt_pk_bf16_f32 v83, v88, v89
	v_cvt_pk_bf16_f32 v84, v90, v91
	v_cvt_pk_bf16_f32 v85, v92, v93
	v_mad_i64_i32 v[86:87], s[0:1], v188, s35, v[130:131]
	global_store_dwordx4 v[86:87], v[82:85], off
	s_nop 1
	v_mul_f32_e32 v83, 0xbfb8aa3b, v74
	v_exp_f32_e32 v83, v83
	v_mul_f32_e32 v82, 0xbfb8aa3b, v78
	v_exp_f32_e32 v82, v82
	v_add_f32_e32 v83, 1.0, v83
	v_rcp_f32_e32 v84, v83
	v_mul_f32_e32 v83, 0xbfb8aa3b, v79
	v_exp_f32_e32 v83, v83
	v_add_f32_e32 v82, 1.0, v82
	v_rcp_f32_e32 v82, v82
	v_add_f32_e32 v83, 1.0, v83
	v_rcp_f32_e32 v83, v83
	s_nop 0
	v_pk_mul_f32 v[78:79], v[78:79], v[82:83]
	s_nop 0
	v_pk_mul_f32 v[70:71], v[70:71], v[78:79]
	v_mul_f32_e32 v78, 0xbfb8aa3b, v75
	v_exp_f32_e32 v78, v78
	s_nop 0
	v_add_f32_e32 v78, 1.0, v78
	v_rcp_f32_e32 v85, v78
	s_nop 0
	v_pk_mul_f32 v[74:75], v[74:75], v[84:85]
	s_nop 0
	v_pk_mul_f32 v[74:75], v[66:67], v[74:75]
	v_mul_f32_e32 v67, 0xbfb8aa3b, v76
	v_exp_f32_e32 v67, v67
	v_mul_f32_e32 v66, 0xbfb8aa3b, v80
	v_exp_f32_e32 v66, v66
	v_add_f32_e32 v67, 1.0, v67
	v_rcp_f32_e32 v78, v67
	v_mul_f32_e32 v67, 0xbfb8aa3b, v81
	v_exp_f32_e32 v67, v67
	v_add_f32_e32 v66, 1.0, v66
	v_rcp_f32_e32 v66, v66
	v_add_f32_e32 v67, 1.0, v67
	v_rcp_f32_e32 v67, v67
	s_nop 0
	v_pk_mul_f32 v[66:67], v[80:81], v[66:67]
	s_nop 0
	v_pk_mul_f32 v[72:73], v[72:73], v[66:67]
	v_mul_f32_e32 v66, 0xbfb8aa3b, v77
	v_exp_f32_e32 v66, v66
	s_nop 0
	v_add_f32_e32 v66, 1.0, v66
	v_rcp_f32_e32 v79, v66
	s_nop 0
	v_pk_mul_f32 v[66:67], v[76:77], v[78:79]
	s_nop 0
	v_pk_mul_f32 v[76:77], v[68:69], v[66:67]
	v_cvt_pk_bf16_f32 v66, v70, v71
	v_cvt_pk_bf16_f32 v67, v72, v73
	v_cvt_pk_bf16_f32 v68, v74, v75
	v_cvt_pk_bf16_f32 v69, v76, v77
	v_mad_i64_i32 v[70:71], s[0:1], v186, s35, v[130:131]
	global_store_dwordx4 v[70:71], v[66:69], off
	s_nop 1
	v_mul_f32_e32 v67, 0xbfb8aa3b, v54
	v_exp_f32_e32 v67, v67
	v_mul_f32_e32 v66, 0xbfb8aa3b, v50
	v_exp_f32_e32 v66, v66
	v_add_f32_e32 v67, 1.0, v67
	v_rcp_f32_e32 v68, v67
	v_mul_f32_e32 v67, 0xbfb8aa3b, v51
	v_exp_f32_e32 v67, v67
	v_add_f32_e32 v66, 1.0, v66
	v_rcp_f32_e32 v66, v66
	v_add_f32_e32 v67, 1.0, v67
	v_rcp_f32_e32 v67, v67
	s_nop 0
	v_pk_mul_f32 v[50:51], v[50:51], v[66:67]
	s_nop 0
	v_pk_mul_f32 v[50:51], v[58:59], v[50:51]
	v_mul_f32_e32 v58, 0xbfb8aa3b, v55
	v_exp_f32_e32 v58, v58
	v_mul_f32_e32 v59, 0xbfb8aa3b, v56
	v_exp_f32_e32 v59, v59
	v_cvt_pk_bf16_f32 v50, v50, v51
	v_add_f32_e32 v58, 1.0, v58
	v_rcp_f32_e32 v69, v58
	v_add_f32_e32 v59, 1.0, v59
	v_mul_f32_e32 v58, 0xbfb8aa3b, v52
	v_exp_f32_e32 v58, v58
	v_pk_mul_f32 v[54:55], v[54:55], v[68:69]
	v_add_f32_e32 v58, 1.0, v58
	v_pk_mul_f32 v[54:55], v[62:63], v[54:55]
	v_rcp_f32_e32 v62, v59
	v_mul_f32_e32 v59, 0xbfb8aa3b, v53
	v_exp_f32_e32 v59, v59
	v_rcp_f32_e32 v58, v58
	v_add_f32_e32 v59, 1.0, v59
	v_rcp_f32_e32 v59, v59
	s_nop 0
	v_pk_mul_f32 v[52:53], v[52:53], v[58:59]
	v_mul_f32_e32 v58, 0xbfb8aa3b, v57
	v_exp_f32_e32 v58, v58
	v_pk_mul_f32 v[52:53], v[60:61], v[52:53]
	v_add_f32_e32 v58, 1.0, v58
	v_rcp_f32_e32 v63, v58
	v_cvt_pk_bf16_f32 v51, v52, v53
	v_cvt_pk_bf16_f32 v52, v54, v55
	v_mad_i64_i32 v[54:55], s[0:1], v184, s35, v[130:131]
	v_pk_mul_f32 v[56:57], v[56:57], v[62:63]
	s_nop 0
	v_pk_mul_f32 v[56:57], v[64:65], v[56:57]
	s_nop 0
	v_cvt_pk_bf16_f32 v53, v56, v57
	global_store_dwordx4 v[54:55], v[50:53], off
	s_nop 1
	v_mul_f32_e32 v51, 0xbfb8aa3b, v38
	v_exp_f32_e32 v51, v51
	v_mul_f32_e32 v50, 0xbfb8aa3b, v34
	v_exp_f32_e32 v50, v50
	v_add_f32_e32 v51, 1.0, v51
	v_rcp_f32_e32 v52, v51
	v_mul_f32_e32 v51, 0xbfb8aa3b, v35
	v_exp_f32_e32 v51, v51
	v_add_f32_e32 v50, 1.0, v50
	v_rcp_f32_e32 v50, v50
	v_add_f32_e32 v51, 1.0, v51
	v_rcp_f32_e32 v51, v51
; #define PG8_WAIT_V(n) asm volatile("s_waitcnt vmcnt(" #n ")" ::: "memory")
; #define PG8_BAR __builtin_amdgcn_s_barrier()
; template <class Epi>
; DEVI void gemm_phase(LAS unsigned char* lds, const Gemm g, const Epi& E) {
;     ...
;         if (!has_next) break;
; #pragma unroll
;         for (int a = 0; a < 2; ++a)
; #pragma unroll
;             for (int b = 0; b < 2; ++b)
; #pragma unroll
;                 for (int m = 0; m < 4; ++m)
; #pragma unroll
;                     for (int n = 0; n < 2; ++n) acc[a][b][m][n] = (f32x4){0.f, 0.f, 0.f, 0.f};
;         cur = nxt; cA = nA; cB = nB; ++ui;
;     }
;     PG8_WAIT_V(0);
;     if (wr == 0) PG8_BAR;
;     PG8_BAR;
	s_nop 0
	v_pk_mul_f32 v[34:35], v[34:35], v[50:51]
	s_nop 0
	v_pk_mul_f32 v[34:35], v[42:43], v[34:35]
	v_mul_f32_e32 v42, 0xbfb8aa3b, v39
	v_exp_f32_e32 v42, v42
	v_mul_f32_e32 v43, 0xbfb8aa3b, v40
	v_exp_f32_e32 v43, v43
	v_cvt_pk_bf16_f32 v34, v34, v35
	v_add_f32_e32 v42, 1.0, v42
	v_rcp_f32_e32 v53, v42
	v_add_f32_e32 v43, 1.0, v43
	v_mul_f32_e32 v42, 0xbfb8aa3b, v36
	v_exp_f32_e32 v42, v42
	v_pk_mul_f32 v[38:39], v[38:39], v[52:53]
	v_add_f32_e32 v42, 1.0, v42
	v_pk_mul_f32 v[38:39], v[46:47], v[38:39]
	v_rcp_f32_e32 v46, v43
	v_mul_f32_e32 v43, 0xbfb8aa3b, v37
	v_exp_f32_e32 v43, v43
	v_rcp_f32_e32 v42, v42
	v_add_f32_e32 v43, 1.0, v43
	v_rcp_f32_e32 v43, v43
	s_nop 0
	v_pk_mul_f32 v[36:37], v[36:37], v[42:43]
	v_mul_f32_e32 v42, 0xbfb8aa3b, v41
	v_exp_f32_e32 v42, v42
	v_pk_mul_f32 v[36:37], v[44:45], v[36:37]
	v_add_f32_e32 v42, 1.0, v42
	v_rcp_f32_e32 v47, v42
	v_cvt_pk_bf16_f32 v35, v36, v37
	v_cvt_pk_bf16_f32 v36, v38, v39
	v_mad_i64_i32 v[38:39], s[0:1], v182, s35, v[130:131]
	v_pk_mul_f32 v[40:41], v[40:41], v[46:47]
	s_nop 0
	v_pk_mul_f32 v[40:41], v[48:49], v[40:41]
	s_nop 0
	v_cvt_pk_bf16_f32 v37, v40, v41
	global_store_dwordx4 v[38:39], v[34:37], off
	s_nop 1
	v_mul_f32_e32 v35, 0xbfb8aa3b, v22
	v_exp_f32_e32 v35, v35
	v_mul_f32_e32 v34, 0xbfb8aa3b, v18
	v_exp_f32_e32 v34, v34
	v_add_f32_e32 v35, 1.0, v35
	v_rcp_f32_e32 v36, v35
	v_mul_f32_e32 v35, 0xbfb8aa3b, v19
	v_exp_f32_e32 v35, v35
	v_add_f32_e32 v34, 1.0, v34
	v_rcp_f32_e32 v34, v34
	v_add_f32_e32 v35, 1.0, v35
	v_rcp_f32_e32 v35, v35
	s_nop 0
	v_pk_mul_f32 v[18:19], v[18:19], v[34:35]
	s_nop 0
	v_pk_mul_f32 v[18:19], v[26:27], v[18:19]
	v_mul_f32_e32 v26, 0xbfb8aa3b, v23
	v_exp_f32_e32 v26, v26
	v_mul_f32_e32 v27, 0xbfb8aa3b, v24
	v_exp_f32_e32 v27, v27
	v_cvt_pk_bf16_f32 v18, v18, v19
	v_add_f32_e32 v26, 1.0, v26
	v_rcp_f32_e32 v37, v26
	v_add_f32_e32 v27, 1.0, v27
	v_mul_f32_e32 v26, 0xbfb8aa3b, v20
	v_exp_f32_e32 v26, v26
	v_pk_mul_f32 v[22:23], v[22:23], v[36:37]
	v_add_f32_e32 v26, 1.0, v26
	v_pk_mul_f32 v[22:23], v[30:31], v[22:23]
	v_rcp_f32_e32 v30, v27
	v_mul_f32_e32 v27, 0xbfb8aa3b, v21
	v_exp_f32_e32 v27, v27
	v_rcp_f32_e32 v26, v26
	v_add_f32_e32 v27, 1.0, v27
	v_rcp_f32_e32 v27, v27
	s_nop 0
	v_pk_mul_f32 v[20:21], v[20:21], v[26:27]
	v_mul_f32_e32 v26, 0xbfb8aa3b, v25
	v_exp_f32_e32 v26, v26
	v_pk_mul_f32 v[20:21], v[28:29], v[20:21]
	v_add_f32_e32 v26, 1.0, v26
	v_rcp_f32_e32 v31, v26
	v_cvt_pk_bf16_f32 v19, v20, v21
	v_cvt_pk_bf16_f32 v20, v22, v23
	v_mad_i64_i32 v[22:23], s[0:1], v180, s35, v[130:131]
	v_pk_mul_f32 v[24:25], v[24:25], v[30:31]
	s_nop 0
	v_pk_mul_f32 v[24:25], v[32:33], v[24:25]
	s_nop 0
	v_cvt_pk_bf16_f32 v21, v24, v25
	global_store_dwordx4 v[22:23], v[18:21], off
	s_nop 1
	v_mul_f32_e32 v19, 0xbfb8aa3b, v4
	v_exp_f32_e32 v19, v19
	v_mul_f32_e32 v18, 0xbfb8aa3b, v0
	v_exp_f32_e32 v18, v18
	v_add_f32_e32 v19, 1.0, v19
	v_rcp_f32_e32 v20, v19
	v_mul_f32_e32 v19, 0xbfb8aa3b, v1
	v_exp_f32_e32 v19, v19
	v_add_f32_e32 v18, 1.0, v18
	v_rcp_f32_e32 v18, v18
	v_add_f32_e32 v19, 1.0, v19
	v_rcp_f32_e32 v19, v19
	s_nop 0
	v_pk_mul_f32 v[0:1], v[0:1], v[18:19]
	s_nop 0
	v_pk_mul_f32 v[0:1], v[10:11], v[0:1]
	v_mul_f32_e32 v10, 0xbfb8aa3b, v5
	v_exp_f32_e32 v10, v10
	v_mul_f32_e32 v11, 0xbfb8aa3b, v6
	v_exp_f32_e32 v11, v11
	v_cvt_pk_bf16_f32 v0, v0, v1
	v_add_f32_e32 v10, 1.0, v10
	v_rcp_f32_e32 v21, v10
	v_add_f32_e32 v11, 1.0, v11
	v_mul_f32_e32 v10, 0xbfb8aa3b, v2
	v_exp_f32_e32 v10, v10
	v_pk_mul_f32 v[4:5], v[4:5], v[20:21]
	v_add_f32_e32 v10, 1.0, v10
	v_pk_mul_f32 v[4:5], v[14:15], v[4:5]
	v_rcp_f32_e32 v14, v11
	v_mul_f32_e32 v11, 0xbfb8aa3b, v3
	v_exp_f32_e32 v11, v11
	v_rcp_f32_e32 v10, v10
	v_add_f32_e32 v11, 1.0, v11
	v_rcp_f32_e32 v11, v11
	s_nop 0
	v_pk_mul_f32 v[2:3], v[2:3], v[10:11]
	v_mul_f32_e32 v10, 0xbfb8aa3b, v7
	v_exp_f32_e32 v10, v10
	v_pk_mul_f32 v[2:3], v[12:13], v[2:3]
	v_add_f32_e32 v10, 1.0, v10
	v_rcp_f32_e32 v15, v10
	v_cvt_pk_bf16_f32 v1, v2, v3
	v_cvt_pk_bf16_f32 v2, v4, v5
	v_mad_i64_i32 v[4:5], s[0:1], v178, s35, v[130:131]
	v_pk_mul_f32 v[6:7], v[6:7], v[14:15]
	s_nop 0
	v_pk_mul_f32 v[6:7], v[16:17], v[6:7]
	s_nop 0
	v_cvt_pk_bf16_f32 v3, v6, v7
	global_store_dwordx4 v[4:5], v[0:3], off
	s_cbranch_vccz .LBB0_1669
	s_waitcnt vmcnt(0)
	s_cmpk_gt_u32 s66, 0xff
	s_cbranch_scc1 .LBB0_1676
	s_barrier

; #define PG8_STAGE(bufoff, gbase, voff) do { _Pragma("unroll") for (int _i = 0; _i < 2; ++_i) \
;         __builtin_amdgcn_global_load_lds((const unsigned*)((const char*)(gbase) + (voff)[_i]), (LAS unsigned*)(lds + (bufoff) + ldsw + _i * 8192), 16, 0, 0); } while (0)
; #define PG8_LDA(dst, b, h) do { _Pragma("unroll") for (int m = 0; m < 4; ++m) _Pragma("unroll") for (int k = 0; k < 2; ++k) dst[m][k] = *(const LAS bf16x8*)(lds + PG8_SA(b, h) + aoff + m * 2048 + k * 1024); } while (0)
; #define PG8_LDB(dst, b, h) do { _Pragma("unroll") for (int n = 0; n < 2; ++n) _Pragma("unroll") for (int k = 0; k < 2; ++k) dst[n][k] = *(const LAS bf16x8*)(lds + PG8_SB(b, h) + boff + n * 2048 + k * 1024); } while (0)
; #define PG8_MMA(ai, bj, At, Bt) do { __builtin_amdgcn_s_setprio(1); _Pragma("unroll") for (int m = 0; m < 4; ++m) _Pragma("unroll") for (int n = 0; n < 2; ++n) _Pragma("unroll") for (int k = 0; k < 2; ++k) \
;         acc[ai][bj][m][n] = __builtin_amdgcn_mfma_f32_16x16x32_bf16(Bt[n][k], At[m][k], acc[ai][bj][m][n], 0, 0, 0); __builtin_amdgcn_s_setprio(0); } while (0)
; template <class Epi>
; DEVI void gemm_phase(LAS unsigned char* lds, const Gemm g, const Epi& E) {
;     ...
;         for (int t = 0; t < nt; t += 2) {
;             const bool last = (t == nt - 2);
;             const char* a1 = cA + (size_t)(t + 1) * kstep;
;             const char* a2 = last ? nA : cA + (size_t)(t + 2) * kstep; const char* b2 = last ? nB : cB + (size_t)(t + 2) * kstep;
;             const char* a3 = a2 + kstep; const char* b3 = b2 + kstep;
;             PG8_LDB(B0, 0, 0); PG8_SCHED; PG8_LDA(At, 0, 0); PG8_STAGE(PG8_SA(1, 1), a1 + hstepA, voffA);
;             PG8_WAIT_L(8); PG8_BAR; PG8_WAIT_L(0); PG8_MMA(0, 0, At, B0); PG8_BAR; PG8_SCHED;
;             PG8_LDB(B1, 0, 1); PG8_STAGE(PG8_SB(0, 0), b2, voffB);
;             PG8_BAR; PG8_WAIT_L(0); PG8_MMA(0, 1, At, B1); PG8_BAR;
;             PG8_LDA(At, 0, 1); PG8_STAGE(PG8_SA(0, 0), a2, voffA);
;             PG8_BAR; PG8_WAIT_L(0); PG8_MMA(1, 0, At, B0); PG8_BAR; PG8_SCHED;
;             PG8_STAGE(PG8_SB(0, 1), b2 + hstepB, voffB);
;             PG8_WAIT_V(6); PG8_BAR; PG8_MMA(1, 1, At, B1); PG8_BAR;
;             PG8_LDB(B0, 1, 0); PG8_SCHED; PG8_LDA(At, 1, 0); PG8_STAGE(PG8_SA(0, 1), a2 + hstepA, voffA);
;             PG8_WAIT_L(8); PG8_BAR; PG8_WAIT_L(0); PG8_MMA(0, 0, At, B0); PG8_BAR; PG8_SCHED;
.LBB0_1747:
	s_add_u32 s36, s16, 0x100
	s_addc_u32 s37, s17, 0
	s_add_i32 s19, 0, 0x10000
	v_add_u32_e32 v142, s19, v191
	ds_read_b128 v[130:133], v142
	ds_read_b128 v[134:137], v142 offset:1024
	ds_read_b128 v[138:141], v142 offset:2048
	ds_read_b128 v[142:145], v142 offset:3072
	s_cmp_eq_u32 s18, 40
	s_cselect_b32 s69, s9, s37
	s_cselect_b32 s68, s8, s36
	s_cselect_b32 s47, s11, s13
	s_cselect_b32 s46, s10, s1
	v_lshl_add_u64 v[162:163], s[16:17], 0, v[152:153]
	s_add_i32 m0, s81, 0xc000
	ds_read_b128 v[178:181], v196
	ds_read_b128 v[182:185], v196 offset:1024
	ds_read_b128 v[186:189], v196 offset:2048
	ds_read_b128 v[198:201], v196 offset:3072
	ds_read_b128 v[202:205], v196 offset:4096
	ds_read_b128 v[206:209], v196 offset:5120
	ds_read_b128 v[214:217], v196 offset:6144
	ds_read_b128 v[218:221], v196 offset:7168
	global_load_lds_dwordx4 v[162:163], off
	v_lshl_add_u64 v[162:163], s[16:17], 0, v[176:177]
	s_add_i32 m0, s81, 0xe000
	s_nop 0
	global_load_lds_dwordx4 v[162:163], off
	s_waitcnt lgkmcnt(8)
	s_barrier
	s_waitcnt lgkmcnt(0)
	s_setprio 1
	v_mfma_f32_16x16x32_bf16 v[126:129], v[130:133], v[178:181], v[126:129]
	v_mfma_f32_16x16x32_bf16 v[122:125], v[138:141], v[178:181], v[122:125]
	v_mfma_f32_16x16x32_bf16 v[110:113], v[130:133], v[186:189], v[110:113]
	v_mfma_f32_16x16x32_bf16 v[106:109], v[138:141], v[186:189], v[106:109]
	v_mfma_f32_16x16x32_bf16 v[94:97], v[130:133], v[202:205], v[94:97]
	v_mfma_f32_16x16x32_bf16 v[90:93], v[138:141], v[202:205], v[90:93]
	v_mfma_f32_16x16x32_bf16 v[78:81], v[130:133], v[214:217], v[78:81]
	v_mfma_f32_16x16x32_bf16 v[74:77], v[138:141], v[214:217], v[74:77]
	v_mfma_f32_16x16x32_bf16 v[126:129], v[134:137], v[182:185], v[126:129]
	v_mfma_f32_16x16x32_bf16 v[122:125], v[142:145], v[182:185], v[122:125]
	v_mfma_f32_16x16x32_bf16 v[110:113], v[134:137], v[198:201], v[110:113]
	v_mfma_f32_16x16x32_bf16 v[106:109], v[142:145], v[198:201], v[106:109]
	v_mfma_f32_16x16x32_bf16 v[94:97], v[134:137], v[206:209], v[94:97]
	v_mfma_f32_16x16x32_bf16 v[90:93], v[142:145], v[206:209], v[90:93]
	v_mfma_f32_16x16x32_bf16 v[78:81], v[134:137], v[218:221], v[78:81]
	v_mfma_f32_16x16x32_bf16 v[74:77], v[142:145], v[218:221], v[74:77]
	s_setprio 0
	s_barrier
	s_add_i32 s26, 0, 0x14000
	v_add_u32_e32 v162, s26, v191
	s_add_i32 s16, s19, s80
	ds_read_b128 v[222:225], v162
	ds_read_b128 v[226:229], v162 offset:1024
	ds_read_b128 v[230:233], v162 offset:2048
	ds_read_b128 v[234:237], v162 offset:3072
	v_lshl_add_u64 v[162:163], s[46:47], 0, v[8:9]
	s_mov_b32 m0, s16
	v_lshl_add_u64 v[164:165], s[46:47], 0, v[150:151]
	global_load_lds_dwordx4 v[162:163], off
	s_add_i32 m0, s16, 0x2000
	s_nop 0
	global_load_lds_dwordx4 v[164:165], off
	s_barrier
	s_waitcnt lgkmcnt(0)
	s_setprio 1
	v_mfma_f32_16x16x32_bf16 v[118:121], v[222:225], v[178:181], v[118:121]
	v_mfma_f32_16x16x32_bf16 v[114:117], v[230:233], v[178:181], v[114:117]
	v_mfma_f32_16x16x32_bf16 v[102:105], v[222:225], v[186:189], v[102:105]
	v_mfma_f32_16x16x32_bf16 v[98:101], v[230:233], v[186:189], v[98:101]
	v_mfma_f32_16x16x32_bf16 v[86:89], v[222:225], v[202:205], v[86:89]
	v_mfma_f32_16x16x32_bf16 v[82:85], v[230:233], v[202:205], v[82:85]
	v_mfma_f32_16x16x32_bf16 v[70:73], v[222:225], v[214:217], v[70:73]
	v_mfma_f32_16x16x32_bf16 v[66:69], v[230:233], v[214:217], v[66:69]
	v_mfma_f32_16x16x32_bf16 v[118:121], v[226:229], v[182:185], v[118:121]
	v_mfma_f32_16x16x32_bf16 v[114:117], v[234:237], v[182:185], v[114:117]
	v_mfma_f32_16x16x32_bf16 v[102:105], v[226:229], v[198:201], v[102:105]
	v_mfma_f32_16x16x32_bf16 v[98:101], v[234:237], v[198:201], v[98:101]
	v_mfma_f32_16x16x32_bf16 v[86:89], v[226:229], v[206:209], v[86:89]
	v_mfma_f32_16x16x32_bf16 v[82:85], v[234:237], v[206:209], v[82:85]
	v_mfma_f32_16x16x32_bf16 v[70:73], v[226:229], v[218:221], v[70:73]
	v_mfma_f32_16x16x32_bf16 v[66:69], v[234:237], v[218:221], v[66:69]
	s_setprio 0
	s_mov_b32 m0, s81
	v_lshl_add_u64 v[238:239], s[68:69], 0, v[146:147]
	s_barrier
	ds_read_b128 v[178:181], v196 offset:16384
	ds_read_b128 v[182:185], v196 offset:17408
	ds_read_b128 v[186:189], v196 offset:18432
	ds_read_b128 v[198:201], v196 offset:19456
	ds_read_b128 v[202:205], v196 offset:20480
	ds_read_b128 v[206:209], v196 offset:21504
	ds_read_b128 v[214:217], v196 offset:22528
	ds_read_b128 v[218:221], v196 offset:23552
	global_load_lds_dwordx4 v[238:239], off
	v_lshl_add_u64 v[240:241], s[68:69], 0, v[148:149]
	s_mov_b32 m0, s82
	s_nop 0
	global_load_lds_dwordx4 v[240:241], off
	s_barrier
	s_waitcnt lgkmcnt(0)
	s_setprio 1
	v_mfma_f32_16x16x32_bf16 v[62:65], v[130:133], v[178:181], v[62:65]
	v_mfma_f32_16x16x32_bf16 v[58:61], v[138:141], v[178:181], v[58:61]
	v_mfma_f32_16x16x32_bf16 v[46:49], v[130:133], v[186:189], v[46:49]
	v_mfma_f32_16x16x32_bf16 v[42:45], v[138:141], v[186:189], v[42:45]
	v_mfma_f32_16x16x32_bf16 v[30:33], v[130:133], v[202:205], v[30:33]
	v_mfma_f32_16x16x32_bf16 v[26:29], v[138:141], v[202:205], v[26:29]
	v_mfma_f32_16x16x32_bf16 v[14:17], v[130:133], v[214:217], v[14:17]
	v_mfma_f32_16x16x32_bf16 v[10:13], v[138:141], v[214:217], v[10:13]
	v_mfma_f32_16x16x32_bf16 v[62:65], v[134:137], v[182:185], v[62:65]
	v_mfma_f32_16x16x32_bf16 v[58:61], v[142:145], v[182:185], v[58:61]
	v_mfma_f32_16x16x32_bf16 v[46:49], v[134:137], v[198:201], v[46:49]
	v_mfma_f32_16x16x32_bf16 v[42:45], v[142:145], v[198:201], v[42:45]
	v_mfma_f32_16x16x32_bf16 v[30:33], v[134:137], v[206:209], v[30:33]
	v_mfma_f32_16x16x32_bf16 v[26:29], v[142:145], v[206:209], v[26:29]
	v_mfma_f32_16x16x32_bf16 v[14:17], v[134:137], v[218:221], v[14:17]
	v_mfma_f32_16x16x32_bf16 v[10:13], v[142:145], v[218:221], v[10:13]
	s_setprio 0
	s_barrier
; #define PG8_STAGE(bufoff, gbase, voff) do { _Pragma("unroll") for (int _i = 0; _i < 2; ++_i) \
;         __builtin_amdgcn_global_load_lds((const unsigned*)((const char*)(gbase) + (voff)[_i]), (LAS unsigned*)(lds + (bufoff) + ldsw + _i * 8192), 16, 0, 0); } while (0)
; #define PG8_LDA(dst, b, h) do { _Pragma("unroll") for (int m = 0; m < 4; ++m) _Pragma("unroll") for (int k = 0; k < 2; ++k) dst[m][k] = *(const LAS bf16x8*)(lds + PG8_SA(b, h) + aoff + m * 2048 + k * 1024); } while (0)
; #define PG8_LDB(dst, b, h) do { _Pragma("unroll") for (int n = 0; n < 2; ++n) _Pragma("unroll") for (int k = 0; k < 2; ++k) dst[n][k] = *(const LAS bf16x8*)(lds + PG8_SB(b, h) + boff + n * 2048 + k * 1024); } while (0)
; #define PG8_MMA(ai, bj, At, Bt) do { __builtin_amdgcn_s_setprio(1); _Pragma("unroll") for (int m = 0; m < 4; ++m) _Pragma("unroll") for (int n = 0; n < 2; ++n) _Pragma("unroll") for (int k = 0; k < 2; ++k) \
;         acc[ai][bj][m][n] = __builtin_amdgcn_mfma_f32_16x16x32_bf16(Bt[n][k], At[m][k], acc[ai][bj][m][n], 0, 0, 0); __builtin_amdgcn_s_setprio(0); } while (0)
; #define PG8_WAIT_V(n) asm volatile("s_waitcnt vmcnt(" #n ")" ::: "memory")
; #define PG8_WAIT_L(n) asm volatile("s_waitcnt lgkmcnt(" #n ")" ::: "memory")
; #define PG8_BAR __builtin_amdgcn_s_barrier()
; #define PG8_SCHED __builtin_amdgcn_sched_barrier(0)
; template <class Epi>
; DEVI void gemm_phase(LAS unsigned char* lds, const Gemm g, const Epi& E) {
;     ...
;             PG8_WAIT_V(6); PG8_BAR; PG8_MMA(1, 1, At, B1); PG8_BAR;
;             PG8_LDB(B0, 1, 0); PG8_SCHED; PG8_LDA(At, 1, 0); PG8_STAGE(PG8_SA(0, 1), a2 + hstepA, voffA);
;             PG8_WAIT_L(8); PG8_BAR; PG8_WAIT_L(0); PG8_MMA(0, 0, At, B0); PG8_BAR; PG8_SCHED;
;             PG8_LDB(B1, 1, 1); PG8_STAGE(PG8_SB(1, 0), b3, voffB);
;             PG8_BAR; PG8_WAIT_L(0); PG8_MMA(0, 1, At, B1); PG8_BAR;
;             PG8_LDA(At, 1, 1); PG8_STAGE(PG8_SA(1, 0), a3, voffA);
;             PG8_BAR; PG8_WAIT_L(0); PG8_MMA(1, 0, At, B0); PG8_BAR; PG8_SCHED;
	s_add_u32 s16, s46, 0xb0000
	s_addc_u32 s17, s47, 0
	s_add_i32 s19, s26, s80
	v_lshl_add_u64 v[130:131], s[16:17], 0, v[8:9]
	s_mov_b32 m0, s19
	s_nop 0
	global_load_lds_dwordx4 v[130:131], off
	v_lshl_add_u64 v[130:131], s[16:17], 0, v[150:151]
	s_add_i32 m0, s19, 0x2000
	s_nop 0
	global_load_lds_dwordx4 v[130:131], off
	s_waitcnt vmcnt(6)
	s_barrier
	s_setprio 1
	v_mfma_f32_16x16x32_bf16 v[54:57], v[222:225], v[178:181], v[54:57]
	v_mfma_f32_16x16x32_bf16 v[50:53], v[230:233], v[178:181], v[50:53]
	v_mfma_f32_16x16x32_bf16 v[38:41], v[222:225], v[186:189], v[38:41]
	v_mfma_f32_16x16x32_bf16 v[34:37], v[230:233], v[186:189], v[34:37]
	v_mfma_f32_16x16x32_bf16 v[22:25], v[222:225], v[202:205], v[22:25]
	v_mfma_f32_16x16x32_bf16 v[18:21], v[230:233], v[202:205], v[18:21]
	v_mfma_f32_16x16x32_bf16 v[4:7], v[222:225], v[214:217], v[4:7]
	v_mfma_f32_16x16x32_bf16 v[0:3], v[230:233], v[214:217], v[0:3]
	v_mfma_f32_16x16x32_bf16 v[54:57], v[226:229], v[182:185], v[54:57]
	v_mfma_f32_16x16x32_bf16 v[50:53], v[234:237], v[182:185], v[50:53]
	v_mfma_f32_16x16x32_bf16 v[38:41], v[226:229], v[198:201], v[38:41]
	v_mfma_f32_16x16x32_bf16 v[34:37], v[234:237], v[198:201], v[34:37]
	v_mfma_f32_16x16x32_bf16 v[22:25], v[226:229], v[206:209], v[22:25]
	v_mfma_f32_16x16x32_bf16 v[18:21], v[234:237], v[206:209], v[18:21]
	v_mfma_f32_16x16x32_bf16 v[4:7], v[226:229], v[218:221], v[4:7]
	v_mfma_f32_16x16x32_bf16 v[0:3], v[234:237], v[218:221], v[0:3]
	s_setprio 0
	s_add_i32 s19, 0, 0x18000
	v_add_u32_e32 v142, s19, v191
	s_barrier
	ds_read_b128 v[130:133], v142
	ds_read_b128 v[134:137], v142 offset:1024
	ds_read_b128 v[138:141], v142 offset:2048
	ds_read_b128 v[142:145], v142 offset:3072
	s_add_u32 s16, s68, 0xb0000
	s_addc_u32 s17, s69, 0
	s_mov_b32 m0, s83
	v_lshl_add_u64 v[222:223], s[16:17], 0, v[146:147]
	ds_read_b128 v[178:181], v196 offset:32768
	ds_read_b128 v[182:185], v196 offset:33792
	ds_read_b128 v[186:189], v196 offset:34816
	ds_read_b128 v[198:201], v196 offset:35840
	ds_read_b128 v[202:205], v196 offset:36864
	ds_read_b128 v[206:209], v196 offset:37888
	ds_read_b128 v[214:217], v196 offset:38912
	ds_read_b128 v[218:221], v196 offset:39936
	global_load_lds_dwordx4 v[222:223], off
	v_lshl_add_u64 v[222:223], s[16:17], 0, v[148:149]
	s_mov_b32 m0, s84
	s_nop 0
	global_load_lds_dwordx4 v[222:223], off
	s_waitcnt lgkmcnt(8)
	s_barrier
	s_waitcnt lgkmcnt(0)
	s_setprio 1
	v_mfma_f32_16x16x32_bf16 v[126:129], v[130:133], v[178:181], v[126:129]
	v_mfma_f32_16x16x32_bf16 v[122:125], v[138:141], v[178:181], v[122:125]
	v_mfma_f32_16x16x32_bf16 v[110:113], v[130:133], v[186:189], v[110:113]
	v_mfma_f32_16x16x32_bf16 v[106:109], v[138:141], v[186:189], v[106:109]
	v_mfma_f32_16x16x32_bf16 v[94:97], v[130:133], v[202:205], v[94:97]
	v_mfma_f32_16x16x32_bf16 v[90:93], v[138:141], v[202:205], v[90:93]
	v_mfma_f32_16x16x32_bf16 v[78:81], v[130:133], v[214:217], v[78:81]
	v_mfma_f32_16x16x32_bf16 v[74:77], v[138:141], v[214:217], v[74:77]
	v_mfma_f32_16x16x32_bf16 v[126:129], v[134:137], v[182:185], v[126:129]
	v_mfma_f32_16x16x32_bf16 v[122:125], v[142:145], v[182:185], v[122:125]
	v_mfma_f32_16x16x32_bf16 v[110:113], v[134:137], v[198:201], v[110:113]
	v_mfma_f32_16x16x32_bf16 v[106:109], v[142:145], v[198:201], v[106:109]
	v_mfma_f32_16x16x32_bf16 v[94:97], v[134:137], v[206:209], v[94:97]
	v_mfma_f32_16x16x32_bf16 v[90:93], v[142:145], v[206:209], v[90:93]
	v_mfma_f32_16x16x32_bf16 v[78:81], v[134:137], v[218:221], v[78:81]
	v_mfma_f32_16x16x32_bf16 v[74:77], v[142:145], v[218:221], v[74:77]
	s_setprio 0
	s_barrier
	s_add_i32 s26, 0, 0x1c000
	s_add_i32 s16, s19, s80
	v_add_u32_e32 v197, s26, v191
	v_lshl_add_u64 v[162:163], v[162:163], 0, s[70:71]
	s_mov_b32 m0, s16
	ds_read_b128 v[222:225], v197
	ds_read_b128 v[226:229], v197 offset:1024
	ds_read_b128 v[230:233], v197 offset:2048
	ds_read_b128 v[234:237], v197 offset:3072
	global_load_lds_dwordx4 v[162:163], off
	v_lshl_add_u64 v[162:163], v[164:165], 0, s[70:71]
	s_add_i32 m0, s16, 0x2000
	s_nop 0
	global_load_lds_dwordx4 v[162:163], off
	s_barrier
	s_waitcnt lgkmcnt(0)
	s_setprio 1
	v_mfma_f32_16x16x32_bf16 v[118:121], v[222:225], v[178:181], v[118:121]
	v_mfma_f32_16x16x32_bf16 v[114:117], v[230:233], v[178:181], v[114:117]
	v_mfma_f32_16x16x32_bf16 v[102:105], v[222:225], v[186:189], v[102:105]
	v_mfma_f32_16x16x32_bf16 v[98:101], v[230:233], v[186:189], v[98:101]
	v_mfma_f32_16x16x32_bf16 v[86:89], v[222:225], v[202:205], v[86:89]
	v_mfma_f32_16x16x32_bf16 v[82:85], v[230:233], v[202:205], v[82:85]
	v_mfma_f32_16x16x32_bf16 v[70:73], v[222:225], v[214:217], v[70:73]
	v_mfma_f32_16x16x32_bf16 v[66:69], v[230:233], v[214:217], v[66:69]
	v_mfma_f32_16x16x32_bf16 v[118:121], v[226:229], v[182:185], v[118:121]
	v_mfma_f32_16x16x32_bf16 v[114:117], v[234:237], v[182:185], v[114:117]
	v_mfma_f32_16x16x32_bf16 v[102:105], v[226:229], v[198:201], v[102:105]
	v_mfma_f32_16x16x32_bf16 v[98:101], v[234:237], v[198:201], v[98:101]
	v_mfma_f32_16x16x32_bf16 v[86:89], v[226:229], v[206:209], v[86:89]
	v_mfma_f32_16x16x32_bf16 v[82:85], v[234:237], v[206:209], v[82:85]
	v_mfma_f32_16x16x32_bf16 v[70:73], v[226:229], v[218:221], v[70:73]
	v_mfma_f32_16x16x32_bf16 v[66:69], v[234:237], v[218:221], v[66:69]
	s_setprio 0
	s_mov_b32 m0, s76
	v_lshl_add_u64 v[162:163], v[238:239], 0, s[70:71]
	s_barrier
	ds_read_b128 v[178:181], v196 offset:49152
	ds_read_b128 v[182:185], v196 offset:50176
	ds_read_b128 v[186:189], v196 offset:51200
	ds_read_b128 v[198:201], v196 offset:52224
	ds_read_b128 v[202:205], v196 offset:53248
	ds_read_b128 v[206:209], v196 offset:54272
	ds_read_b128 v[214:217], v196 offset:55296
	ds_read_b128 v[218:221], v196 offset:56320
	global_load_lds_dwordx4 v[162:163], off
	v_lshl_add_u64 v[162:163], v[240:241], 0, s[70:71]
	s_mov_b32 m0, s77
	s_nop 0
	global_load_lds_dwordx4 v[162:163], off
	s_barrier
; #define PG8_STAGE(bufoff, gbase, voff) do { _Pragma("unroll") for (int _i = 0; _i < 2; ++_i) \
;         __builtin_amdgcn_global_load_lds((const unsigned*)((const char*)(gbase) + (voff)[_i]), (LAS unsigned*)(lds + (bufoff) + ldsw + _i * 8192), 16, 0, 0); } while (0)
; #define PG8_LDA(dst, b, h) do { _Pragma("unroll") for (int m = 0; m < 4; ++m) _Pragma("unroll") for (int k = 0; k < 2; ++k) dst[m][k] = *(const LAS bf16x8*)(lds + PG8_SA(b, h) + aoff + m * 2048 + k * 1024); } while (0)
; #define PG8_LDB(dst, b, h) do { _Pragma("unroll") for (int n = 0; n < 2; ++n) _Pragma("unroll") for (int k = 0; k < 2; ++k) dst[n][k] = *(const LAS bf16x8*)(lds + PG8_SB(b, h) + boff + n * 2048 + k * 1024); } while (0)
; #define PG8_MMA(ai, bj, At, Bt) do { __builtin_amdgcn_s_setprio(1); _Pragma("unroll") for (int m = 0; m < 4; ++m) _Pragma("unroll") for (int n = 0; n < 2; ++n) _Pragma("unroll") for (int k = 0; k < 2; ++k) \
;         acc[ai][bj][m][n] = __builtin_amdgcn_mfma_f32_16x16x32_bf16(Bt[n][k], At[m][k], acc[ai][bj][m][n], 0, 0, 0); __builtin_amdgcn_s_setprio(0); } while (0)
; #define PG8_WAIT_V(n) asm volatile("s_waitcnt vmcnt(" #n ")" ::: "memory")
; #define PG8_WAIT_L(n) asm volatile("s_waitcnt lgkmcnt(" #n ")" ::: "memory")
; #define PG8_BAR __builtin_amdgcn_s_barrier()
; #define PG8_SCHED __builtin_amdgcn_sched_barrier(0)
; template <class Epi>
; DEVI void gemm_phase(LAS unsigned char* lds, const Gemm g, const Epi& E) {
;     ...
;             PG8_WAIT_L(8); PG8_BAR; PG8_WAIT_L(0); PG8_MMA(0, 0, At, B0); PG8_BAR; PG8_SCHED;
;             PG8_LDB(B1, 1, 1); PG8_STAGE(PG8_SB(1, 0), b3, voffB);
;             PG8_BAR; PG8_WAIT_L(0); PG8_MMA(0, 1, At, B1); PG8_BAR;
;             PG8_LDA(At, 1, 1); PG8_STAGE(PG8_SA(1, 0), a3, voffA);
;             PG8_BAR; PG8_WAIT_L(0); PG8_MMA(1, 0, At, B0); PG8_BAR; PG8_SCHED;
;             PG8_STAGE(PG8_SB(1, 1), b3 + hstepB, voffB);
;             PG8_WAIT_V(6); PG8_BAR; PG8_MMA(1, 1, At, B1); PG8_BAR;
	s_waitcnt lgkmcnt(0)
	s_setprio 1
	v_mfma_f32_16x16x32_bf16 v[62:65], v[130:133], v[178:181], v[62:65]
	v_mfma_f32_16x16x32_bf16 v[58:61], v[138:141], v[178:181], v[58:61]
	v_mfma_f32_16x16x32_bf16 v[46:49], v[130:133], v[186:189], v[46:49]
	v_mfma_f32_16x16x32_bf16 v[42:45], v[138:141], v[186:189], v[42:45]
	v_mfma_f32_16x16x32_bf16 v[30:33], v[130:133], v[202:205], v[30:33]
	v_mfma_f32_16x16x32_bf16 v[26:29], v[138:141], v[202:205], v[26:29]
	v_mfma_f32_16x16x32_bf16 v[14:17], v[130:133], v[214:217], v[14:17]
	v_mfma_f32_16x16x32_bf16 v[10:13], v[138:141], v[214:217], v[10:13]
	v_mfma_f32_16x16x32_bf16 v[62:65], v[134:137], v[182:185], v[62:65]
	v_mfma_f32_16x16x32_bf16 v[58:61], v[142:145], v[182:185], v[58:61]
	v_mfma_f32_16x16x32_bf16 v[46:49], v[134:137], v[198:201], v[46:49]
	v_mfma_f32_16x16x32_bf16 v[42:45], v[142:145], v[198:201], v[42:45]
	v_mfma_f32_16x16x32_bf16 v[30:33], v[134:137], v[206:209], v[30:33]
	v_mfma_f32_16x16x32_bf16 v[26:29], v[142:145], v[206:209], v[26:29]
	v_mfma_f32_16x16x32_bf16 v[14:17], v[134:137], v[218:221], v[14:17]
	v_mfma_f32_16x16x32_bf16 v[10:13], v[142:145], v[218:221], v[10:13]
	s_setprio 0
	s_barrier
	s_add_u32 s16, s46, 0xb0080
	s_addc_u32 s17, s47, 0
	s_add_i32 s19, s26, s80
	v_lshl_add_u64 v[130:131], s[16:17], 0, v[8:9]
	s_mov_b32 m0, s19
	s_nop 0
	global_load_lds_dwordx4 v[130:131], off
	v_lshl_add_u64 v[130:131], s[16:17], 0, v[150:151]
	s_add_i32 m0, s19, 0x2000
	s_nop 0
	global_load_lds_dwordx4 v[130:131], off
	s_waitcnt vmcnt(6)
	s_barrier
	s_setprio 1
	v_mfma_f32_16x16x32_bf16 v[54:57], v[222:225], v[178:181], v[54:57]
	v_mfma_f32_16x16x32_bf16 v[50:53], v[230:233], v[178:181], v[50:53]
	v_mfma_f32_16x16x32_bf16 v[38:41], v[222:225], v[186:189], v[38:41]
	v_mfma_f32_16x16x32_bf16 v[34:37], v[230:233], v[186:189], v[34:37]
	v_mfma_f32_16x16x32_bf16 v[22:25], v[222:225], v[202:205], v[22:25]
	v_mfma_f32_16x16x32_bf16 v[18:21], v[230:233], v[202:205], v[18:21]
	v_mfma_f32_16x16x32_bf16 v[4:7], v[222:225], v[214:217], v[4:7]
	v_mfma_f32_16x16x32_bf16 v[0:3], v[230:233], v[214:217], v[0:3]
	v_mfma_f32_16x16x32_bf16 v[54:57], v[226:229], v[182:185], v[54:57]
	v_mfma_f32_16x16x32_bf16 v[50:53], v[234:237], v[182:185], v[50:53]
	v_mfma_f32_16x16x32_bf16 v[38:41], v[226:229], v[198:201], v[38:41]
	v_mfma_f32_16x16x32_bf16 v[34:37], v[234:237], v[198:201], v[34:37]
	v_mfma_f32_16x16x32_bf16 v[22:25], v[226:229], v[206:209], v[22:25]
	v_mfma_f32_16x16x32_bf16 v[18:21], v[234:237], v[206:209], v[18:21]
	v_mfma_f32_16x16x32_bf16 v[4:7], v[226:229], v[218:221], v[4:7]
	v_mfma_f32_16x16x32_bf16 v[0:3], v[234:237], v[218:221], v[0:3]
	s_setprio 0
	s_add_i32 s18, s18, 2
	s_add_u32 s1, s1, 0x100
	s_addc_u32 s13, s13, 0
	s_cmp_gt_u32 s18, 41
	s_mov_b64 s[16:17], s[36:37]
	s_barrier
	s_cbranch_scc0 .LBB0_1747
	s_lshl_b32 s0, s0, 8
	v_add_u32_e32 v182, s0, v190
	v_lshl_or_b32 v180, s12, 8, v195
	v_ashrrev_i32_e32 v183, 31, v182
	v_lshlrev_b64 v[130:131], 12, v[182:183]
	v_ashrrev_i32_e32 v181, 31, v180
	v_lshl_add_u64 v[130:131], s[30:31], 0, v[130:131]
	v_lshlrev_b64 v[184:185], 2, v[180:181]
	v_lshl_add_u64 v[162:163], v[130:131], 0, v[184:185]
	global_load_dwordx4 v[200:203], v[162:163], off
	global_load_dwordx4 v[204:207], v[162:163], off offset:16
	global_load_dwordx4 v[214:217], v[162:163], off offset:512
	global_load_dwordx4 v[218:221], v[162:163], off offset:528
	v_or_b32_e32 v188, 16, v182
	v_ashrrev_i32_e32 v189, 31, v188
	v_lshlrev_b64 v[130:131], 12, v[188:189]
	v_lshl_add_u64 v[130:131], s[30:31], 0, v[130:131]
	v_lshl_add_u64 v[186:187], v[130:131], 0, v[184:185]
	global_load_dwordx4 v[138:141], v[186:187], off offset:16
	global_load_dwordx4 v[142:145], v[186:187], off
	global_load_dwordx4 v[130:133], v[186:187], off offset:528
	global_load_dwordx4 v[134:137], v[186:187], off offset:512
	v_and_b32_e32 v165, 64, v155
	v_xor_b32_e32 v164, 16, v155
	v_add_u32_e32 v165, 64, v165
	v_xor_b32_e32 v179, 32, v155
	v_cmp_lt_i32_e32 vcc, v164, v165
	v_or_b32_e32 v178, 0x80, v180
	s_waitcnt vmcnt(0)
	v_pk_add_f32 v[128:129], v[128:129], v[202:203]
	v_cndmask_b32_e32 v164, v155, v164, vcc
	v_cmp_lt_i32_e32 vcc, v179, v165
	v_lshlrev_b32_e32 v198, 2, v164
	v_pk_add_f32 v[126:127], v[126:127], v[200:201]
	v_cndmask_b32_e32 v165, v155, v179, vcc
	v_lshlrev_b32_e32 v197, 2, v165
	v_lshlrev_b64 v[164:165], 10, v[182:183]
	v_pk_add_f32 v[124:125], v[124:125], v[206:207]
	v_pk_add_f32 v[122:123], v[122:123], v[204:205]
	v_pk_add_f32 v[120:121], v[120:121], v[216:217]
	v_pk_add_f32 v[118:119], v[118:119], v[214:215]
	v_pk_add_f32 v[202:203], v[116:117], v[220:221]
	v_pk_add_f32 v[200:201], v[114:115], v[218:219]
	v_lshl_add_u64 v[208:209], v[164:165], 0, v[180:181]
	global_store_dwordx4 v[162:163], v[126:129], off
	global_store_dwordx4 v[162:163], v[122:125], off offset:16
	v_cvt_pk_bf16_f32 v114, v126, v127
	v_cvt_pk_bf16_f32 v115, v128, v129
	v_cvt_pk_bf16_f32 v116, v122, v123
	v_cvt_pk_bf16_f32 v117, v124, v125
	v_mul_f32_e32 v127, v127, v127
	v_mul_f32_e32 v129, v129, v129
	v_mul_f32_e32 v123, v123, v123
	v_mul_f32_e32 v125, v125, v125
	v_mul_f32_e32 v183, v119, v119
	v_mul_f32_e32 v199, v121, v121
	v_mul_f32_e32 v204, v201, v201
	v_mul_f32_e32 v205, v203, v203
	v_lshl_add_u64 v[208:209], v[208:209], 1, s[24:25]
	v_fmac_f32_e32 v127, v126, v126
	v_fmac_f32_e32 v129, v128, v128
	v_fmac_f32_e32 v123, v122, v122
	v_fmac_f32_e32 v125, v124, v124
	v_fmac_f32_e32 v183, v118, v118
	v_fmac_f32_e32 v199, v120, v120
	v_fmac_f32_e32 v204, v200, v200
	v_fmac_f32_e32 v205, v202, v202
	global_store_dwordx4 v[208:209], v[114:117], off
	v_ashrrev_i32_e32 v179, 31, v178
	v_lshl_add_u64 v[164:165], v[164:165], 0, v[178:179]
	v_add_f32_e32 v114, v127, v129
	v_add_f32_e32 v115, v123, v125
	v_add_f32_e32 v116, v183, v199
	v_add_f32_e32 v117, v204, v205
	v_add_f32_e32 v114, v114, v115
	v_add_f32_e32 v115, v116, v117
	v_add_f32_e32 v114, v114, v115
	ds_bpermute_b32 v115, v198, v114
	global_store_dwordx4 v[162:163], v[118:121], off offset:512
	global_store_dwordx4 v[162:163], v[200:203], off offset:528
	v_cvt_pk_bf16_f32 v116, v118, v119
	v_cvt_pk_bf16_f32 v117, v120, v121
	v_cvt_pk_bf16_f32 v118, v200, v201
	s_waitcnt lgkmcnt(0)
	v_add_f32_e32 v114, v114, v115
	ds_bpermute_b32 v115, v197, v114
	v_cvt_pk_bf16_f32 v119, v202, v203
	v_lshl_add_u64 v[120:121], v[164:165], 1, s[24:25]
	global_store_dwordx4 v[120:121], v[116:119], off
	s_and_saveexec_b64 s[16:17], s[2:3]
	s_cbranch_execz .LBB0_1750
	s_waitcnt lgkmcnt(0)
	v_add_f32_e32 v114, v114, v115
	ds_write_b32 v192, v114
